# static s_setprio 1 for waves 4-7 during the attention phase only (everything else identical to baseline)
# baseline (speedup 1.0000x reference)
; #define LAS __attribute__((address_space(3)))
; #define FRESH() do { int t_ = threadIdx.x; asm volatile("" : "+v"(t_)); C.tid = t_; C.lane = t_ & 63; C.wave = __builtin_amdgcn_readfirstlane(t_ >> 6); } while (0)
; __global__ void __launch_bounds__(NTHR, 2) mega_fwd(Args a) {
;     ...
;     Ctx C; C.lds = (LAS unsigned char*)lds_raw; C.G = gridDim.x; C.bid = blockIdx.x;
;     ...
;     FRESH();
;     ...
;     unsigned char* ws = a.ws; unsigned char* act = ws + WS_ACT;
;     unsigned* barw = (unsigned*)(ws + 4096);
;     volatile LAS unsigned* bst = (volatile LAS unsigned*)(C.lds + 131072 + 64);
;     if (C.tid < 2) bst[C.tid] = 0u;
;     if (C.bid == 0) for (int i = C.tid; i < XCD_BAR_WORDS; i += NTHR) barw[i] = 0u;
_Z8mega_fwd4Args:
	v_readfirstlane_b32 s98, v0
	s_nop 3
	s_and_b32 s98, s98, 0x3ff
	s_lshr_b32 s98, s98, 8
	s_load_dword s71, s[0:1], 0xd8
	s_load_dwordx4 s[88:91], s[0:1], 0xc0
	s_load_dwordx2 s[76:77], s[0:1], 0xd0
	v_and_b32_e32 v192, 0x3ff, v0
	s_add_u32 s4, s0, 0xd0
	v_mov_b32_e32 v34, v192
	s_mov_b32 s74, s2
	s_addc_u32 s5, s1, 0
	s_nop 0
	v_readfirstlane_b32 s2, v34
	v_cmp_gt_i32_e32 vcc, 2, v34
	s_and_saveexec_b64 s[6:7], vcc
	v_lshl_add_u32 v1, v34, 2, 0
	v_add_u32_e32 v1, 0x20040, v1
	v_mov_b32_e32 v2, 0
	ds_write_b32 v1, v2
	s_or_b64 exec, exec, s[6:7]
	s_waitcnt lgkmcnt(0)
	s_add_u32 s72, s90, 0x1000
	s_addc_u32 s73, s91, 0
	s_cmp_eq_u32 s74, 0
	s_movk_i32 s3, 0xd80
	s_cselect_b64 s[6:7], -1, 0
	v_cmp_gt_i32_e32 vcc, s3, v34
	s_and_b64 s[8:9], s[6:7], vcc
	s_and_saveexec_b64 s[6:7], s[8:9]
	s_cbranch_execz .LBB0_10
	v_max_i32_e32 v1, 0xb80, v34
	v_sub_u32_e32 v1, v1, v34
	s_movk_i32 s3, 0x1ff
	v_add_u32_e32 v1, 0x1ff, v1
	v_cmp_lt_u32_e32 vcc, s3, v1
	s_mov_b64 s[10:11], -1
	v_mov_b32_e32 v2, v34
	s_and_saveexec_b64 s[8:9], vcc
	s_cbranch_execz .LBB0_7
	v_lshrrev_b32_e32 v1, 9, v1
	v_add_u32_e32 v1, 1, v1
	v_and_b32_e32 v4, 0xfffffe, v1
	v_add_u32_e32 v35, 0x200, v34
	s_mov_b64 s[10:11], 0
	v_mov_b32_e32 v5, 0
	v_mov_b32_e32 v6, v4
	v_mov_b64_e32 v[2:3], v[34:35]

; #define PG8_STAGE(bufoff, gbase, voff) do { _Pragma("unroll") for (int _i = 0; _i < 2; ++_i) \
;         __builtin_amdgcn_global_load_lds((const unsigned*)((const char*)(gbase) + (voff)[_i]), (PG8_LAS unsigned*)(lds + (bufoff) + ldsw + _i * 8192), 16, 0, 0); } while (0)
; #define PG8_LDA(dst, b, h) do { _Pragma("unroll") for (int m = 0; m < 4; ++m) _Pragma("unroll") for (int k = 0; k < 2; ++k) dst[m][k] = *(const PG8_LAS bf16x8*)(lds + PG8_SA(b, h) + aoff + m * 2048 + k * 1024); } while (0)
; #define PG8_LDB(dst, b, h) do { _Pragma("unroll") for (int n = 0; n < 2; ++n) _Pragma("unroll") for (int k = 0; k < 2; ++k) dst[n][k] = *(const PG8_LAS bf16x8*)(lds + PG8_SB(b, h) + boff + n * 2048 + k * 1024); } while (0)
; #define PG8_MMA(ai, bj, At, Bt) do { __builtin_amdgcn_s_setprio(1); _Pragma("unroll") for (int m = 0; m < 4; ++m) _Pragma("unroll") for (int n = 0; n < 2; ++n) _Pragma("unroll") for (int k = 0; k < 2; ++k) \
;         acc[ai][bj][m][n] = __builtin_amdgcn_mfma_f32_16x16x32_bf16(Bt[n][k], At[m][k], acc[ai][bj][m][n], 0, 0, 0); __builtin_amdgcn_s_setprio(0); } while (0)
; #define PG8_WAIT_V(n) asm volatile("s_waitcnt vmcnt(" #n ")" ::: "memory")
; #define PG8_WAIT_L(n) asm volatile("s_waitcnt lgkmcnt(" #n ")" ::: "memory")
; #define PG8_BAR __builtin_amdgcn_s_barrier()
; #define PG8_SCHED __builtin_amdgcn_sched_barrier(0)
; template <class Epi, class Sched, bool ALIGN_EPI = false, bool SP2 = false>
; __device__ __forceinline__ void gemm_phase(PG8_LAS unsigned char* lds, const Gemm g, const Sched& S, const Epi& E) {
;     ...
;             const char* a2 = last ? nA : cA + (size_t)(t + 2) * kstep; const char* b2 = last ? nB : cB + (size_t)(t + 2) * kstep;
;             const char* a3 = a2 + kstep; const char* b3 = b2 + kstep;
;             if (last && has_next) S.a_ready(nxt);
;             if constexpr (SP2) {
;             PG8_LDB(B0, 0, 0); PG8_LDB(B1, 0, 1); PG8_SCHED; PG8_LDA(At, 0, 0); PG8_STAGE(PG8_SA(1, 1), a1 + hstep, voffA);
;             PG8_WAIT_V(8); PG8_WAIT_L(0); PG8_BAR; PG8_MMA(0, 0, At, B0); PG8_MMA(0, 1, At, B1); PG8_BAR; PG8_SCHED;
;             PG8_LDA(At, 0, 1); PG8_STAGE(PG8_SB(0, 0), b2, voffB); PG8_STAGE(PG8_SB(0, 1), b2 + hstep, voffB); PG8_STAGE(PG8_SA(0, 0), a2, voffA);
;             PG8_WAIT_V(8); PG8_WAIT_L(0); PG8_BAR; PG8_MMA(1, 0, At, B0); PG8_MMA(1, 1, At, B1); PG8_BAR; PG8_SCHED;
.LBB0_73:
	ds_read_b128 v[150:153], v147
	ds_read_b128 v[154:157], v147 offset:1024
	ds_read_b128 v[158:161], v147 offset:2048
	ds_read_b128 v[162:165], v147 offset:3072
	ds_read_b128 v[166:169], v148
	ds_read_b128 v[170:173], v148 offset:1024
	ds_read_b128 v[174:177], v148 offset:2048
	ds_read_b128 v[178:181], v148 offset:3072
	s_add_u32 s42, s40, 0xfff80080
	s_addc_u32 s43, s41, -1
	s_cmp_eq_u32 s62, 28
	s_cselect_b32 s45, s31, s43
	s_cselect_b32 s44, s58, s42
	s_cselect_b32 s43, s29, s61
	s_cselect_b32 s42, s59, s60
	v_lshl_add_u64 v[190:191], s[40:41], 0, v[136:137]
	s_add_i32 m0, s33, 0xc000
	ds_read_b128 v[182:185], v149
	ds_read_b128 v[186:189], v149 offset:1024
	ds_read_b128 v[194:197], v149 offset:2048
	ds_read_b128 v[198:201], v149 offset:3072
	ds_read_b128 v[202:205], v149 offset:4096
	ds_read_b128 v[206:209], v149 offset:5120
	ds_read_b128 v[210:213], v149 offset:6144
	ds_read_b128 v[214:217], v149 offset:7168
	global_load_lds_dwordx4 v[190:191], off
	v_lshl_add_u64 v[190:191], s[40:41], 0, v[138:139]
	s_add_i32 m0, s33, 0xe000
	s_nop 0
	global_load_lds_dwordx4 v[190:191], off
	s_waitcnt vmcnt(8)
	s_waitcnt lgkmcnt(0)
	s_barrier
	s_setprio 1
	s_waitcnt lgkmcnt(0)
	v_mfma_f32_16x16x32_bf16 v[124:127], v[150:153], v[182:185], v[124:127]
	v_mfma_f32_16x16x32_bf16 v[120:123], v[158:161], v[182:185], v[120:123]
	v_mfma_f32_16x16x32_bf16 v[108:111], v[150:153], v[194:197], v[108:111]
	v_mfma_f32_16x16x32_bf16 v[104:107], v[158:161], v[194:197], v[104:107]
	v_mfma_f32_16x16x32_bf16 v[92:95], v[150:153], v[202:205], v[92:95]
	v_mfma_f32_16x16x32_bf16 v[88:91], v[158:161], v[202:205], v[88:91]
	v_mfma_f32_16x16x32_bf16 v[76:79], v[150:153], v[210:213], v[76:79]
	v_mfma_f32_16x16x32_bf16 v[72:75], v[158:161], v[210:213], v[72:75]
	v_mfma_f32_16x16x32_bf16 v[124:127], v[154:157], v[186:189], v[124:127]
	v_mfma_f32_16x16x32_bf16 v[120:123], v[162:165], v[186:189], v[120:123]
	v_mfma_f32_16x16x32_bf16 v[108:111], v[154:157], v[198:201], v[108:111]
	v_mfma_f32_16x16x32_bf16 v[104:107], v[162:165], v[198:201], v[104:107]
	v_mfma_f32_16x16x32_bf16 v[92:95], v[154:157], v[206:209], v[92:95]
	v_mfma_f32_16x16x32_bf16 v[88:91], v[162:165], v[206:209], v[88:91]
	v_mfma_f32_16x16x32_bf16 v[76:79], v[154:157], v[214:217], v[76:79]
	v_mfma_f32_16x16x32_bf16 v[72:75], v[162:165], v[214:217], v[72:75]
	s_setprio 0
	s_setprio 1
	v_mfma_f32_16x16x32_bf16 v[116:119], v[166:169], v[182:185], v[116:119]
	v_mfma_f32_16x16x32_bf16 v[112:115], v[174:177], v[182:185], v[112:115]
	v_mfma_f32_16x16x32_bf16 v[100:103], v[166:169], v[194:197], v[100:103]
	v_mfma_f32_16x16x32_bf16 v[96:99], v[174:177], v[194:197], v[96:99]
	v_mfma_f32_16x16x32_bf16 v[84:87], v[166:169], v[202:205], v[84:87]
	v_mfma_f32_16x16x32_bf16 v[80:83], v[174:177], v[202:205], v[80:83]
	v_mfma_f32_16x16x32_bf16 v[68:71], v[166:169], v[210:213], v[68:71]
	v_mfma_f32_16x16x32_bf16 v[64:67], v[174:177], v[210:213], v[64:67]
	v_mfma_f32_16x16x32_bf16 v[116:119], v[170:173], v[186:189], v[116:119]
	v_mfma_f32_16x16x32_bf16 v[112:115], v[178:181], v[186:189], v[112:115]
	v_mfma_f32_16x16x32_bf16 v[100:103], v[170:173], v[198:201], v[100:103]
	v_mfma_f32_16x16x32_bf16 v[96:99], v[178:181], v[198:201], v[96:99]
	v_mfma_f32_16x16x32_bf16 v[84:87], v[170:173], v[206:209], v[84:87]
	v_mfma_f32_16x16x32_bf16 v[80:83], v[178:181], v[206:209], v[80:83]
	v_mfma_f32_16x16x32_bf16 v[68:71], v[170:173], v[214:217], v[68:71]
	v_mfma_f32_16x16x32_bf16 v[64:67], v[178:181], v[214:217], v[64:67]
	s_setprio 0
	s_barrier
	s_add_i32 s63, s54, s46
	v_lshl_add_u64 v[190:191], s[42:43], 0, v[132:133]
	s_mov_b32 m0, s63
	ds_read_b128 v[182:185], v149 offset:16384
	ds_read_b128 v[186:189], v149 offset:17408
	ds_read_b128 v[194:197], v149 offset:18432
	ds_read_b128 v[198:201], v149 offset:19456
	ds_read_b128 v[202:205], v149 offset:20480
	ds_read_b128 v[206:209], v149 offset:21504
	ds_read_b128 v[210:213], v149 offset:22528
	ds_read_b128 v[214:217], v149 offset:23552
	global_load_lds_dwordx4 v[190:191], off
	s_add_i32 m0, s63, 0x2000
	s_add_u32 s64, s42, 0x80000
	v_lshl_add_u64 v[218:219], s[42:43], 0, v[128:129]
	s_addc_u32 s65, s43, 0
	s_add_i32 s63, s55, s46
	global_load_lds_dwordx4 v[218:219], off
	v_lshl_add_u64 v[220:221], s[64:65], 0, v[132:133]
	s_mov_b32 m0, s63
	v_lshl_add_u64 v[222:223], s[44:45], 0, v[130:131]
	global_load_lds_dwordx4 v[220:221], off
	v_lshl_add_u64 v[220:221], s[64:65], 0, v[128:129]
	s_add_i32 m0, s63, 0x2000
	s_nop 0
	global_load_lds_dwordx4 v[220:221], off
	v_lshl_add_u64 v[220:221], s[44:45], 0, v[134:135]
	s_mov_b32 m0, s33
	s_nop 0
	global_load_lds_dwordx4 v[220:221], off
	s_mov_b32 m0, s39
	s_nop 0
	global_load_lds_dwordx4 v[222:223], off
	s_waitcnt vmcnt(8)
	s_waitcnt lgkmcnt(0)
	s_barrier
; #define PG8_STAGE(bufoff, gbase, voff) do { _Pragma("unroll") for (int _i = 0; _i < 2; ++_i) \
;         __builtin_amdgcn_global_load_lds((const unsigned*)((const char*)(gbase) + (voff)[_i]), (PG8_LAS unsigned*)(lds + (bufoff) + ldsw + _i * 8192), 16, 0, 0); } while (0)
; #define PG8_LDA(dst, b, h) do { _Pragma("unroll") for (int m = 0; m < 4; ++m) _Pragma("unroll") for (int k = 0; k < 2; ++k) dst[m][k] = *(const PG8_LAS bf16x8*)(lds + PG8_SA(b, h) + aoff + m * 2048 + k * 1024); } while (0)
; #define PG8_LDB(dst, b, h) do { _Pragma("unroll") for (int n = 0; n < 2; ++n) _Pragma("unroll") for (int k = 0; k < 2; ++k) dst[n][k] = *(const PG8_LAS bf16x8*)(lds + PG8_SB(b, h) + boff + n * 2048 + k * 1024); } while (0)
; #define PG8_MMA(ai, bj, At, Bt) do { __builtin_amdgcn_s_setprio(1); _Pragma("unroll") for (int m = 0; m < 4; ++m) _Pragma("unroll") for (int n = 0; n < 2; ++n) _Pragma("unroll") for (int k = 0; k < 2; ++k) \
;         acc[ai][bj][m][n] = __builtin_amdgcn_mfma_f32_16x16x32_bf16(Bt[n][k], At[m][k], acc[ai][bj][m][n], 0, 0, 0); __builtin_amdgcn_s_setprio(0); } while (0)
; #define PG8_WAIT_V(n) asm volatile("s_waitcnt vmcnt(" #n ")" ::: "memory")
; #define PG8_WAIT_L(n) asm volatile("s_waitcnt lgkmcnt(" #n ")" ::: "memory")
; #define PG8_BAR __builtin_amdgcn_s_barrier()
; #define PG8_SCHED __builtin_amdgcn_sched_barrier(0)
; template <class Epi, class Sched, bool ALIGN_EPI = false, bool SP2 = false>
; __device__ __forceinline__ void gemm_phase(PG8_LAS unsigned char* lds, const Gemm g, const Sched& S, const Epi& E) {
;     ...
;             PG8_WAIT_V(8); PG8_WAIT_L(0); PG8_BAR; PG8_MMA(1, 0, At, B0); PG8_MMA(1, 1, At, B1); PG8_BAR; PG8_SCHED;
;             PG8_LDB(B0, 1, 0); PG8_LDB(B1, 1, 1); PG8_SCHED; PG8_LDA(At, 1, 0); PG8_STAGE(PG8_SA(0, 1), a2 + hstep, voffA);
;             PG8_WAIT_V(8); PG8_WAIT_L(0); PG8_BAR; PG8_MMA(0, 0, At, B0); PG8_MMA(0, 1, At, B1); PG8_BAR; PG8_SCHED;
	s_setprio 1
	s_waitcnt lgkmcnt(0)
	v_mfma_f32_16x16x32_bf16 v[60:63], v[150:153], v[182:185], v[60:63]
	v_mfma_f32_16x16x32_bf16 v[56:59], v[158:161], v[182:185], v[56:59]
	v_mfma_f32_16x16x32_bf16 v[44:47], v[150:153], v[194:197], v[44:47]
	v_mfma_f32_16x16x32_bf16 v[40:43], v[158:161], v[194:197], v[40:43]
	v_mfma_f32_16x16x32_bf16 v[28:31], v[150:153], v[202:205], v[28:31]
	v_mfma_f32_16x16x32_bf16 v[24:27], v[158:161], v[202:205], v[24:27]
	v_mfma_f32_16x16x32_bf16 v[12:15], v[150:153], v[210:213], v[12:15]
	v_mfma_f32_16x16x32_bf16 v[8:11], v[158:161], v[210:213], v[8:11]
	v_mfma_f32_16x16x32_bf16 v[60:63], v[154:157], v[186:189], v[60:63]
	v_mfma_f32_16x16x32_bf16 v[56:59], v[162:165], v[186:189], v[56:59]
	v_mfma_f32_16x16x32_bf16 v[44:47], v[154:157], v[198:201], v[44:47]
	v_mfma_f32_16x16x32_bf16 v[40:43], v[162:165], v[198:201], v[40:43]
	v_mfma_f32_16x16x32_bf16 v[28:31], v[154:157], v[206:209], v[28:31]
	v_mfma_f32_16x16x32_bf16 v[24:27], v[162:165], v[206:209], v[24:27]
	v_mfma_f32_16x16x32_bf16 v[12:15], v[154:157], v[214:217], v[12:15]
	v_mfma_f32_16x16x32_bf16 v[8:11], v[162:165], v[214:217], v[8:11]
	s_setprio 0
	s_setprio 1
	v_mfma_f32_16x16x32_bf16 v[52:55], v[166:169], v[182:185], v[52:55]
	v_mfma_f32_16x16x32_bf16 v[48:51], v[174:177], v[182:185], v[48:51]
	v_mfma_f32_16x16x32_bf16 v[36:39], v[166:169], v[194:197], v[36:39]
	v_mfma_f32_16x16x32_bf16 v[32:35], v[174:177], v[194:197], v[32:35]
	v_mfma_f32_16x16x32_bf16 v[20:23], v[166:169], v[202:205], v[20:23]
	v_mfma_f32_16x16x32_bf16 v[16:19], v[174:177], v[202:205], v[16:19]
	v_mfma_f32_16x16x32_bf16 v[4:7], v[166:169], v[210:213], v[4:7]
	v_mfma_f32_16x16x32_bf16 v[0:3], v[174:177], v[210:213], v[0:3]
	v_mfma_f32_16x16x32_bf16 v[52:55], v[170:173], v[186:189], v[52:55]
	v_mfma_f32_16x16x32_bf16 v[48:51], v[178:181], v[186:189], v[48:51]
	v_mfma_f32_16x16x32_bf16 v[36:39], v[170:173], v[198:201], v[36:39]
	v_mfma_f32_16x16x32_bf16 v[32:35], v[178:181], v[198:201], v[32:35]
	v_mfma_f32_16x16x32_bf16 v[20:23], v[170:173], v[206:209], v[20:23]
	v_mfma_f32_16x16x32_bf16 v[16:19], v[178:181], v[206:209], v[16:19]
	v_mfma_f32_16x16x32_bf16 v[4:7], v[170:173], v[214:217], v[4:7]
	v_mfma_f32_16x16x32_bf16 v[0:3], v[178:181], v[214:217], v[0:3]
	s_setprio 0
	s_barrier
	s_add_i32 s63, 0, 0x18000
	s_add_i32 s64, 0, 0x1c000
	v_add_u32_e32 v162, s63, v145
	v_add_u32_e32 v178, s64, v145
	ds_read_b128 v[150:153], v162
	ds_read_b128 v[154:157], v162 offset:1024
	ds_read_b128 v[158:161], v162 offset:2048
	ds_read_b128 v[162:165], v162 offset:3072
	ds_read_b128 v[166:169], v178
	ds_read_b128 v[170:173], v178 offset:1024
	ds_read_b128 v[174:177], v178 offset:2048
	ds_read_b128 v[178:181], v178 offset:3072
	s_add_u32 s44, s44, 0x80000
	s_addc_u32 s45, s45, 0
	s_mov_b32 m0, s47
	v_lshl_add_u64 v[224:225], s[44:45], 0, v[134:135]
	ds_read_b128 v[182:185], v149 offset:32768
	ds_read_b128 v[186:189], v149 offset:33792
	ds_read_b128 v[194:197], v149 offset:34816
	ds_read_b128 v[198:201], v149 offset:35840
	ds_read_b128 v[202:205], v149 offset:36864
	ds_read_b128 v[206:209], v149 offset:37888
	ds_read_b128 v[210:213], v149 offset:38912
	ds_read_b128 v[214:217], v149 offset:39936
	global_load_lds_dwordx4 v[224:225], off
	v_lshl_add_u64 v[224:225], s[44:45], 0, v[130:131]
	s_mov_b32 m0, s48
	s_nop 0
	global_load_lds_dwordx4 v[224:225], off
	s_waitcnt vmcnt(8)
	s_waitcnt lgkmcnt(0)
	s_barrier
	s_setprio 1
	s_waitcnt lgkmcnt(0)
	v_mfma_f32_16x16x32_bf16 v[124:127], v[150:153], v[182:185], v[124:127]
	v_mfma_f32_16x16x32_bf16 v[120:123], v[158:161], v[182:185], v[120:123]
	v_mfma_f32_16x16x32_bf16 v[108:111], v[150:153], v[194:197], v[108:111]
	v_mfma_f32_16x16x32_bf16 v[104:107], v[158:161], v[194:197], v[104:107]
	v_mfma_f32_16x16x32_bf16 v[92:95], v[150:153], v[202:205], v[92:95]
	v_mfma_f32_16x16x32_bf16 v[88:91], v[158:161], v[202:205], v[88:91]
	v_mfma_f32_16x16x32_bf16 v[76:79], v[150:153], v[210:213], v[76:79]
	v_mfma_f32_16x16x32_bf16 v[72:75], v[158:161], v[210:213], v[72:75]
	v_mfma_f32_16x16x32_bf16 v[124:127], v[154:157], v[186:189], v[124:127]
	v_mfma_f32_16x16x32_bf16 v[120:123], v[162:165], v[186:189], v[120:123]
	v_mfma_f32_16x16x32_bf16 v[108:111], v[154:157], v[198:201], v[108:111]
	v_mfma_f32_16x16x32_bf16 v[104:107], v[162:165], v[198:201], v[104:107]
	v_mfma_f32_16x16x32_bf16 v[92:95], v[154:157], v[206:209], v[92:95]
	v_mfma_f32_16x16x32_bf16 v[88:91], v[162:165], v[206:209], v[88:91]
	v_mfma_f32_16x16x32_bf16 v[76:79], v[154:157], v[214:217], v[76:79]
	v_mfma_f32_16x16x32_bf16 v[72:75], v[162:165], v[214:217], v[72:75]
	s_setprio 0
	s_setprio 1
	v_mfma_f32_16x16x32_bf16 v[116:119], v[166:169], v[182:185], v[116:119]
	v_mfma_f32_16x16x32_bf16 v[112:115], v[174:177], v[182:185], v[112:115]
	v_mfma_f32_16x16x32_bf16 v[100:103], v[166:169], v[194:197], v[100:103]
	v_mfma_f32_16x16x32_bf16 v[96:99], v[174:177], v[194:197], v[96:99]
	v_mfma_f32_16x16x32_bf16 v[84:87], v[166:169], v[202:205], v[84:87]
	v_mfma_f32_16x16x32_bf16 v[80:83], v[174:177], v[202:205], v[80:83]
	v_mfma_f32_16x16x32_bf16 v[68:71], v[166:169], v[210:213], v[68:71]
	v_mfma_f32_16x16x32_bf16 v[64:67], v[174:177], v[210:213], v[64:67]
	v_mfma_f32_16x16x32_bf16 v[116:119], v[170:173], v[186:189], v[116:119]
	v_mfma_f32_16x16x32_bf16 v[112:115], v[178:181], v[186:189], v[112:115]
	v_mfma_f32_16x16x32_bf16 v[100:103], v[170:173], v[198:201], v[100:103]
	v_mfma_f32_16x16x32_bf16 v[96:99], v[178:181], v[198:201], v[96:99]
	v_mfma_f32_16x16x32_bf16 v[84:87], v[170:173], v[206:209], v[84:87]
	v_mfma_f32_16x16x32_bf16 v[80:83], v[178:181], v[206:209], v[80:83]
	v_mfma_f32_16x16x32_bf16 v[68:71], v[170:173], v[214:217], v[68:71]
	v_mfma_f32_16x16x32_bf16 v[64:67], v[178:181], v[214:217], v[64:67]
	s_setprio 0
	s_barrier
; #define PG8_STAGE(bufoff, gbase, voff) do { _Pragma("unroll") for (int _i = 0; _i < 2; ++_i) \
;         __builtin_amdgcn_global_load_lds((const unsigned*)((const char*)(gbase) + (voff)[_i]), (PG8_LAS unsigned*)(lds + (bufoff) + ldsw + _i * 8192), 16, 0, 0); } while (0)
; #define PG8_LDA(dst, b, h) do { _Pragma("unroll") for (int m = 0; m < 4; ++m) _Pragma("unroll") for (int k = 0; k < 2; ++k) dst[m][k] = *(const PG8_LAS bf16x8*)(lds + PG8_SA(b, h) + aoff + m * 2048 + k * 1024); } while (0)
; #define PG8_MMA(ai, bj, At, Bt) do { __builtin_amdgcn_s_setprio(1); _Pragma("unroll") for (int m = 0; m < 4; ++m) _Pragma("unroll") for (int n = 0; n < 2; ++n) _Pragma("unroll") for (int k = 0; k < 2; ++k) \
;         acc[ai][bj][m][n] = __builtin_amdgcn_mfma_f32_16x16x32_bf16(Bt[n][k], At[m][k], acc[ai][bj][m][n], 0, 0, 0); __builtin_amdgcn_s_setprio(0); } while (0)
; #define PG8_WAIT_V(n) asm volatile("s_waitcnt vmcnt(" #n ")" ::: "memory")
; #define PG8_WAIT_L(n) asm volatile("s_waitcnt lgkmcnt(" #n ")" ::: "memory")
; #define PG8_BAR __builtin_amdgcn_s_barrier()
; #define PG8_SCHED __builtin_amdgcn_sched_barrier(0)
; template <class Epi, class Sched, bool ALIGN_EPI = false, bool SP2 = false>
; __device__ __forceinline__ void gemm_phase(PG8_LAS unsigned char* lds, const Gemm g, const Sched& S, const Epi& E) {
;     ...
;             PG8_LDA(At, 1, 1); PG8_STAGE(PG8_SB(1, 0), b3, voffB); PG8_STAGE(PG8_SB(1, 1), b3 + hstep, voffB); PG8_STAGE(PG8_SA(1, 0), a3, voffA);
;             PG8_WAIT_V(8); PG8_WAIT_L(0); PG8_BAR; PG8_MMA(1, 0, At, B0); PG8_MMA(1, 1, At, B1); PG8_BAR; PG8_SCHED;
;     ...
;         if constexpr (ALIGN_EPI) { if (wr == 0) PG8_BAR; }
;         if constexpr (!Epi::AFTER_DRAIN) { E(acc, cur, wr, wc, fr, fq); S.done(cur); }
;         if (!has_next) break;
	s_add_i32 s44, s63, s46
	v_lshl_add_u64 v[190:191], v[190:191], 0, s[6:7]
	s_mov_b32 m0, s44
	ds_read_b128 v[182:185], v149 offset:49152
	ds_read_b128 v[186:189], v149 offset:50176
	ds_read_b128 v[194:197], v149 offset:51200
	ds_read_b128 v[198:201], v149 offset:52224
	ds_read_b128 v[202:205], v149 offset:53248
	ds_read_b128 v[206:209], v149 offset:54272
	ds_read_b128 v[210:213], v149 offset:55296
	ds_read_b128 v[214:217], v149 offset:56320
	global_load_lds_dwordx4 v[190:191], off
	s_add_i32 m0, s44, 0x2000
	s_add_u32 s42, s42, 0x80080
	v_lshl_add_u64 v[190:191], v[218:219], 0, s[6:7]
	s_addc_u32 s43, s43, 0
	s_add_i32 s44, s64, s46
	global_load_lds_dwordx4 v[190:191], off
	v_lshl_add_u64 v[190:191], s[42:43], 0, v[132:133]
	s_mov_b32 m0, s44
	s_nop 0
	global_load_lds_dwordx4 v[190:191], off
	v_lshl_add_u64 v[190:191], s[42:43], 0, v[128:129]
	s_add_i32 m0, s44, 0x2000
	s_nop 0
	global_load_lds_dwordx4 v[190:191], off
	v_lshl_add_u64 v[190:191], v[220:221], 0, s[6:7]
	s_mov_b32 m0, s50
	s_nop 0
	global_load_lds_dwordx4 v[190:191], off
	v_lshl_add_u64 v[190:191], v[222:223], 0, s[6:7]
	s_mov_b32 m0, s51
	s_nop 0
	global_load_lds_dwordx4 v[190:191], off
	s_waitcnt vmcnt(8)
	s_waitcnt lgkmcnt(0)
	s_barrier
	s_setprio 1
	s_waitcnt lgkmcnt(0)
	v_mfma_f32_16x16x32_bf16 v[60:63], v[150:153], v[182:185], v[60:63]
	v_mfma_f32_16x16x32_bf16 v[56:59], v[158:161], v[182:185], v[56:59]
	v_mfma_f32_16x16x32_bf16 v[44:47], v[150:153], v[194:197], v[44:47]
	v_mfma_f32_16x16x32_bf16 v[40:43], v[158:161], v[194:197], v[40:43]
	v_mfma_f32_16x16x32_bf16 v[28:31], v[150:153], v[202:205], v[28:31]
	v_mfma_f32_16x16x32_bf16 v[24:27], v[158:161], v[202:205], v[24:27]
	v_mfma_f32_16x16x32_bf16 v[12:15], v[150:153], v[210:213], v[12:15]
	v_mfma_f32_16x16x32_bf16 v[8:11], v[158:161], v[210:213], v[8:11]
	v_mfma_f32_16x16x32_bf16 v[60:63], v[154:157], v[186:189], v[60:63]
	v_mfma_f32_16x16x32_bf16 v[56:59], v[162:165], v[186:189], v[56:59]
	v_mfma_f32_16x16x32_bf16 v[44:47], v[154:157], v[198:201], v[44:47]
	v_mfma_f32_16x16x32_bf16 v[40:43], v[162:165], v[198:201], v[40:43]
	v_mfma_f32_16x16x32_bf16 v[28:31], v[154:157], v[206:209], v[28:31]
	v_mfma_f32_16x16x32_bf16 v[24:27], v[162:165], v[206:209], v[24:27]
	v_mfma_f32_16x16x32_bf16 v[12:15], v[154:157], v[214:217], v[12:15]
	v_mfma_f32_16x16x32_bf16 v[8:11], v[162:165], v[214:217], v[8:11]
	s_setprio 0
	s_setprio 1
	v_mfma_f32_16x16x32_bf16 v[52:55], v[166:169], v[182:185], v[52:55]
	v_mfma_f32_16x16x32_bf16 v[48:51], v[174:177], v[182:185], v[48:51]
	v_mfma_f32_16x16x32_bf16 v[36:39], v[166:169], v[194:197], v[36:39]
	v_mfma_f32_16x16x32_bf16 v[32:35], v[174:177], v[194:197], v[32:35]
	v_mfma_f32_16x16x32_bf16 v[20:23], v[166:169], v[202:205], v[20:23]
	v_mfma_f32_16x16x32_bf16 v[16:19], v[174:177], v[202:205], v[16:19]
	v_mfma_f32_16x16x32_bf16 v[4:7], v[166:169], v[210:213], v[4:7]
	v_mfma_f32_16x16x32_bf16 v[0:3], v[174:177], v[210:213], v[0:3]
	v_mfma_f32_16x16x32_bf16 v[52:55], v[170:173], v[186:189], v[52:55]
	v_mfma_f32_16x16x32_bf16 v[48:51], v[178:181], v[186:189], v[48:51]
	v_mfma_f32_16x16x32_bf16 v[36:39], v[170:173], v[198:201], v[36:39]
	v_mfma_f32_16x16x32_bf16 v[32:35], v[178:181], v[198:201], v[32:35]
	v_mfma_f32_16x16x32_bf16 v[20:23], v[170:173], v[206:209], v[20:23]
	v_mfma_f32_16x16x32_bf16 v[16:19], v[178:181], v[206:209], v[16:19]
	v_mfma_f32_16x16x32_bf16 v[4:7], v[170:173], v[214:217], v[4:7]
	v_mfma_f32_16x16x32_bf16 v[0:3], v[178:181], v[214:217], v[0:3]
	s_setprio 0
	s_barrier
	s_add_i32 s62, s62, 2
	s_add_u32 s40, s40, 0x100
	s_addc_u32 s41, s41, 0
	s_add_u32 s60, s60, 0x100
	s_addc_u32 s61, s61, 0
	s_cmp_gt_u32 s62, 29
	s_cbranch_scc0 .LBB0_73
	s_and_b64 vcc, exec, s[24:25]
	s_cbranch_vccz .LBB0_76
	s_barrier

; #define PG8_STAGE(bufoff, gbase, voff) do { _Pragma("unroll") for (int _i = 0; _i < 2; ++_i) \
;         __builtin_amdgcn_global_load_lds((const unsigned*)((const char*)(gbase) + (voff)[_i]), (PG8_LAS unsigned*)(lds + (bufoff) + ldsw + _i * 8192), 16, 0, 0); } while (0)
; #define PG8_LDA(dst, b, h) do { _Pragma("unroll") for (int m = 0; m < 4; ++m) _Pragma("unroll") for (int k = 0; k < 2; ++k) dst[m][k] = *(const PG8_LAS bf16x8*)(lds + PG8_SA(b, h) + aoff + m * 2048 + k * 1024); } while (0)
; #define PG8_LDB(dst, b, h) do { _Pragma("unroll") for (int n = 0; n < 2; ++n) _Pragma("unroll") for (int k = 0; k < 2; ++k) dst[n][k] = *(const PG8_LAS bf16x8*)(lds + PG8_SB(b, h) + boff + n * 2048 + k * 1024); } while (0)
; #define PG8_MMA(ai, bj, At, Bt) do { __builtin_amdgcn_s_setprio(1); _Pragma("unroll") for (int m = 0; m < 4; ++m) _Pragma("unroll") for (int n = 0; n < 2; ++n) _Pragma("unroll") for (int k = 0; k < 2; ++k) \
;         acc[ai][bj][m][n] = __builtin_amdgcn_mfma_f32_16x16x32_bf16(Bt[n][k], At[m][k], acc[ai][bj][m][n], 0, 0, 0); __builtin_amdgcn_s_setprio(0); } while (0)
; #define PG8_WAIT_V(n) asm volatile("s_waitcnt vmcnt(" #n ")" ::: "memory")
; #define PG8_WAIT_L(n) asm volatile("s_waitcnt lgkmcnt(" #n ")" ::: "memory")
; #define PG8_BAR __builtin_amdgcn_s_barrier()
; #define PG8_SCHED __builtin_amdgcn_sched_barrier(0)
; template <class Epi, class Sched, bool ALIGN_EPI = false, bool SP2 = false>
; __device__ __forceinline__ void gemm_phase(PG8_LAS unsigned char* lds, const Gemm g, const Sched& S, const Epi& E) {
;     ...
;             const char* a2 = last ? nA : cA + (size_t)(t + 2) * kstep; const char* b2 = last ? nB : cB + (size_t)(t + 2) * kstep;
;             const char* a3 = a2 + kstep; const char* b3 = b2 + kstep;
;             if (last && has_next) S.a_ready(nxt);
;             if constexpr (SP2) {
;             PG8_LDB(B0, 0, 0); PG8_LDB(B1, 0, 1); PG8_SCHED; PG8_LDA(At, 0, 0); PG8_STAGE(PG8_SA(1, 1), a1 + hstep, voffA);
;             PG8_WAIT_V(8); PG8_WAIT_L(0); PG8_BAR; PG8_MMA(0, 0, At, B0); PG8_MMA(0, 1, At, B1); PG8_BAR; PG8_SCHED;
;             PG8_LDA(At, 0, 1); PG8_STAGE(PG8_SB(0, 0), b2, voffB); PG8_STAGE(PG8_SB(0, 1), b2 + hstep, voffB); PG8_STAGE(PG8_SA(0, 0), a2, voffA);
;             PG8_WAIT_V(8); PG8_WAIT_L(0); PG8_BAR; PG8_MMA(1, 0, At, B0); PG8_MMA(1, 1, At, B1); PG8_BAR; PG8_SCHED;
.LBB0_145:
	ds_read_b128 v[150:153], v147
	ds_read_b128 v[154:157], v147 offset:1024
	ds_read_b128 v[158:161], v147 offset:2048
	ds_read_b128 v[162:165], v147 offset:3072
	ds_read_b128 v[166:169], v148
	ds_read_b128 v[170:173], v148 offset:1024
	ds_read_b128 v[174:177], v148 offset:2048
	ds_read_b128 v[178:181], v148 offset:3072
	s_add_u32 s40, s38, 0x100
	s_addc_u32 s41, s39, 0
	s_cmpk_eq_i32 s62, 0x54
	s_cselect_b32 s45, s5, s41
	s_cselect_b32 s44, s4, s40
	s_cselect_b32 s43, s37, s61
	s_cselect_b32 s42, s36, s60
	v_lshl_add_u64 v[190:191], s[38:39], 0, v[136:137]
	s_add_i32 m0, s33, 0xc000
	ds_read_b128 v[182:185], v149
	ds_read_b128 v[186:189], v149 offset:1024
	ds_read_b128 v[194:197], v149 offset:2048
	ds_read_b128 v[198:201], v149 offset:3072
	ds_read_b128 v[202:205], v149 offset:4096
	ds_read_b128 v[206:209], v149 offset:5120
	ds_read_b128 v[210:213], v149 offset:6144
	ds_read_b128 v[214:217], v149 offset:7168
	global_load_lds_dwordx4 v[190:191], off
	v_lshl_add_u64 v[190:191], s[38:39], 0, v[138:139]
	s_add_i32 m0, s33, 0xe000
	s_nop 0
	global_load_lds_dwordx4 v[190:191], off
	s_waitcnt vmcnt(8)
	s_waitcnt lgkmcnt(0)
	s_barrier
	s_setprio 1
	s_waitcnt lgkmcnt(0)
	v_mfma_f32_16x16x32_bf16 v[124:127], v[150:153], v[182:185], v[124:127]
	v_mfma_f32_16x16x32_bf16 v[120:123], v[158:161], v[182:185], v[120:123]
	v_mfma_f32_16x16x32_bf16 v[116:119], v[150:153], v[194:197], v[116:119]
	v_mfma_f32_16x16x32_bf16 v[112:115], v[158:161], v[194:197], v[112:115]
	v_mfma_f32_16x16x32_bf16 v[100:103], v[150:153], v[202:205], v[100:103]
	v_mfma_f32_16x16x32_bf16 v[96:99], v[158:161], v[202:205], v[96:99]
	v_mfma_f32_16x16x32_bf16 v[84:87], v[150:153], v[210:213], v[84:87]
	v_mfma_f32_16x16x32_bf16 v[80:83], v[158:161], v[210:213], v[80:83]
	v_mfma_f32_16x16x32_bf16 v[124:127], v[154:157], v[186:189], v[124:127]
	v_mfma_f32_16x16x32_bf16 v[120:123], v[162:165], v[186:189], v[120:123]
	v_mfma_f32_16x16x32_bf16 v[116:119], v[154:157], v[198:201], v[116:119]
	v_mfma_f32_16x16x32_bf16 v[112:115], v[162:165], v[198:201], v[112:115]
	v_mfma_f32_16x16x32_bf16 v[100:103], v[154:157], v[206:209], v[100:103]
	v_mfma_f32_16x16x32_bf16 v[96:99], v[162:165], v[206:209], v[96:99]
	v_mfma_f32_16x16x32_bf16 v[84:87], v[154:157], v[214:217], v[84:87]
	v_mfma_f32_16x16x32_bf16 v[80:83], v[162:165], v[214:217], v[80:83]
	s_setprio 0
	s_setprio 1
	v_mfma_f32_16x16x32_bf16 v[108:111], v[166:169], v[182:185], v[108:111]
	v_mfma_f32_16x16x32_bf16 v[104:107], v[174:177], v[182:185], v[104:107]
	v_mfma_f32_16x16x32_bf16 v[92:95], v[166:169], v[194:197], v[92:95]
	v_mfma_f32_16x16x32_bf16 v[88:91], v[174:177], v[194:197], v[88:91]
	v_mfma_f32_16x16x32_bf16 v[76:79], v[166:169], v[202:205], v[76:79]
	v_mfma_f32_16x16x32_bf16 v[72:75], v[174:177], v[202:205], v[72:75]
	v_mfma_f32_16x16x32_bf16 v[68:71], v[166:169], v[210:213], v[68:71]
	v_mfma_f32_16x16x32_bf16 v[64:67], v[174:177], v[210:213], v[64:67]
	v_mfma_f32_16x16x32_bf16 v[108:111], v[170:173], v[186:189], v[108:111]
	v_mfma_f32_16x16x32_bf16 v[104:107], v[178:181], v[186:189], v[104:107]
	v_mfma_f32_16x16x32_bf16 v[92:95], v[170:173], v[198:201], v[92:95]
	v_mfma_f32_16x16x32_bf16 v[88:91], v[178:181], v[198:201], v[88:91]
	v_mfma_f32_16x16x32_bf16 v[76:79], v[170:173], v[206:209], v[76:79]
	v_mfma_f32_16x16x32_bf16 v[72:75], v[178:181], v[206:209], v[72:75]
	v_mfma_f32_16x16x32_bf16 v[68:71], v[170:173], v[214:217], v[68:71]
	v_mfma_f32_16x16x32_bf16 v[64:67], v[178:181], v[214:217], v[64:67]
	s_setprio 0
	s_barrier
	s_add_i32 s38, s55, s2
	v_lshl_add_u64 v[190:191], s[42:43], 0, v[132:133]
	s_mov_b32 m0, s38
	ds_read_b128 v[182:185], v149 offset:16384
	ds_read_b128 v[186:189], v149 offset:17408
	ds_read_b128 v[194:197], v149 offset:18432
	ds_read_b128 v[198:201], v149 offset:19456
	ds_read_b128 v[202:205], v149 offset:20480
	ds_read_b128 v[206:209], v149 offset:21504
	ds_read_b128 v[210:213], v149 offset:22528
	ds_read_b128 v[214:217], v149 offset:23552
	global_load_lds_dwordx4 v[190:191], off
	s_add_i32 m0, s38, 0x2000
	s_add_u32 s38, s42, 0x160000
	v_lshl_add_u64 v[218:219], s[42:43], 0, v[128:129]
	s_addc_u32 s39, s43, 0
	s_add_i32 s63, s56, s2
	global_load_lds_dwordx4 v[218:219], off
	v_lshl_add_u64 v[220:221], s[38:39], 0, v[132:133]
	s_mov_b32 m0, s63
	v_lshl_add_u64 v[222:223], s[44:45], 0, v[130:131]
	global_load_lds_dwordx4 v[220:221], off
	v_lshl_add_u64 v[220:221], s[38:39], 0, v[128:129]
	s_add_i32 m0, s63, 0x2000
	s_nop 0
	global_load_lds_dwordx4 v[220:221], off
	v_lshl_add_u64 v[220:221], s[44:45], 0, v[134:135]
	s_mov_b32 m0, s33
	s_nop 0
	global_load_lds_dwordx4 v[220:221], off
	s_mov_b32 m0, s46
	s_nop 0
	global_load_lds_dwordx4 v[222:223], off
	s_waitcnt vmcnt(8)
	s_waitcnt lgkmcnt(0)
	s_barrier
; #define PG8_STAGE(bufoff, gbase, voff) do { _Pragma("unroll") for (int _i = 0; _i < 2; ++_i) \
;         __builtin_amdgcn_global_load_lds((const unsigned*)((const char*)(gbase) + (voff)[_i]), (PG8_LAS unsigned*)(lds + (bufoff) + ldsw + _i * 8192), 16, 0, 0); } while (0)
; #define PG8_LDA(dst, b, h) do { _Pragma("unroll") for (int m = 0; m < 4; ++m) _Pragma("unroll") for (int k = 0; k < 2; ++k) dst[m][k] = *(const PG8_LAS bf16x8*)(lds + PG8_SA(b, h) + aoff + m * 2048 + k * 1024); } while (0)
; #define PG8_LDB(dst, b, h) do { _Pragma("unroll") for (int n = 0; n < 2; ++n) _Pragma("unroll") for (int k = 0; k < 2; ++k) dst[n][k] = *(const PG8_LAS bf16x8*)(lds + PG8_SB(b, h) + boff + n * 2048 + k * 1024); } while (0)
; #define PG8_MMA(ai, bj, At, Bt) do { __builtin_amdgcn_s_setprio(1); _Pragma("unroll") for (int m = 0; m < 4; ++m) _Pragma("unroll") for (int n = 0; n < 2; ++n) _Pragma("unroll") for (int k = 0; k < 2; ++k) \
;         acc[ai][bj][m][n] = __builtin_amdgcn_mfma_f32_16x16x32_bf16(Bt[n][k], At[m][k], acc[ai][bj][m][n], 0, 0, 0); __builtin_amdgcn_s_setprio(0); } while (0)
; #define PG8_WAIT_V(n) asm volatile("s_waitcnt vmcnt(" #n ")" ::: "memory")
; #define PG8_WAIT_L(n) asm volatile("s_waitcnt lgkmcnt(" #n ")" ::: "memory")
; #define PG8_BAR __builtin_amdgcn_s_barrier()
; #define PG8_SCHED __builtin_amdgcn_sched_barrier(0)
; template <class Epi, class Sched, bool ALIGN_EPI = false, bool SP2 = false>
; __device__ __forceinline__ void gemm_phase(PG8_LAS unsigned char* lds, const Gemm g, const Sched& S, const Epi& E) {
;     ...
;             PG8_WAIT_V(8); PG8_WAIT_L(0); PG8_BAR; PG8_MMA(1, 0, At, B0); PG8_MMA(1, 1, At, B1); PG8_BAR; PG8_SCHED;
;             PG8_LDB(B0, 1, 0); PG8_LDB(B1, 1, 1); PG8_SCHED; PG8_LDA(At, 1, 0); PG8_STAGE(PG8_SA(0, 1), a2 + hstep, voffA);
;             PG8_WAIT_V(8); PG8_WAIT_L(0); PG8_BAR; PG8_MMA(0, 0, At, B0); PG8_MMA(0, 1, At, B1); PG8_BAR; PG8_SCHED;
	s_setprio 1
	s_waitcnt lgkmcnt(0)
	v_mfma_f32_16x16x32_bf16 v[60:63], v[150:153], v[182:185], v[60:63]
	v_mfma_f32_16x16x32_bf16 v[56:59], v[158:161], v[182:185], v[56:59]
	v_mfma_f32_16x16x32_bf16 v[52:55], v[150:153], v[194:197], v[52:55]
	v_mfma_f32_16x16x32_bf16 v[48:51], v[158:161], v[194:197], v[48:51]
	v_mfma_f32_16x16x32_bf16 v[36:39], v[150:153], v[202:205], v[36:39]
	v_mfma_f32_16x16x32_bf16 v[32:35], v[158:161], v[202:205], v[32:35]
	v_mfma_f32_16x16x32_bf16 v[20:23], v[150:153], v[210:213], v[20:23]
	v_mfma_f32_16x16x32_bf16 v[16:19], v[158:161], v[210:213], v[16:19]
	v_mfma_f32_16x16x32_bf16 v[60:63], v[154:157], v[186:189], v[60:63]
	v_mfma_f32_16x16x32_bf16 v[56:59], v[162:165], v[186:189], v[56:59]
	v_mfma_f32_16x16x32_bf16 v[52:55], v[154:157], v[198:201], v[52:55]
	v_mfma_f32_16x16x32_bf16 v[48:51], v[162:165], v[198:201], v[48:51]
	v_mfma_f32_16x16x32_bf16 v[36:39], v[154:157], v[206:209], v[36:39]
	v_mfma_f32_16x16x32_bf16 v[32:35], v[162:165], v[206:209], v[32:35]
	v_mfma_f32_16x16x32_bf16 v[20:23], v[154:157], v[214:217], v[20:23]
	v_mfma_f32_16x16x32_bf16 v[16:19], v[162:165], v[214:217], v[16:19]
	s_setprio 0
	s_setprio 1
	v_mfma_f32_16x16x32_bf16 v[44:47], v[166:169], v[182:185], v[44:47]
	v_mfma_f32_16x16x32_bf16 v[40:43], v[174:177], v[182:185], v[40:43]
	v_mfma_f32_16x16x32_bf16 v[28:31], v[166:169], v[194:197], v[28:31]
	v_mfma_f32_16x16x32_bf16 v[24:27], v[174:177], v[194:197], v[24:27]
	v_mfma_f32_16x16x32_bf16 v[12:15], v[166:169], v[202:205], v[12:15]
	v_mfma_f32_16x16x32_bf16 v[8:11], v[174:177], v[202:205], v[8:11]
	v_mfma_f32_16x16x32_bf16 v[4:7], v[166:169], v[210:213], v[4:7]
	v_mfma_f32_16x16x32_bf16 v[0:3], v[174:177], v[210:213], v[0:3]
	v_mfma_f32_16x16x32_bf16 v[44:47], v[170:173], v[186:189], v[44:47]
	v_mfma_f32_16x16x32_bf16 v[40:43], v[178:181], v[186:189], v[40:43]
	v_mfma_f32_16x16x32_bf16 v[28:31], v[170:173], v[198:201], v[28:31]
	v_mfma_f32_16x16x32_bf16 v[24:27], v[178:181], v[198:201], v[24:27]
	v_mfma_f32_16x16x32_bf16 v[12:15], v[170:173], v[206:209], v[12:15]
	v_mfma_f32_16x16x32_bf16 v[8:11], v[178:181], v[206:209], v[8:11]
	v_mfma_f32_16x16x32_bf16 v[4:7], v[170:173], v[214:217], v[4:7]
	v_mfma_f32_16x16x32_bf16 v[0:3], v[178:181], v[214:217], v[0:3]
	s_setprio 0
	s_barrier
	s_add_i32 s63, 0, 0x18000
	s_add_i32 s64, 0, 0x1c000
	v_add_u32_e32 v162, s63, v145
	v_add_u32_e32 v178, s64, v145
	ds_read_b128 v[150:153], v162
	ds_read_b128 v[154:157], v162 offset:1024
	ds_read_b128 v[158:161], v162 offset:2048
	ds_read_b128 v[162:165], v162 offset:3072
	ds_read_b128 v[166:169], v178
	ds_read_b128 v[170:173], v178 offset:1024
	ds_read_b128 v[174:177], v178 offset:2048
	ds_read_b128 v[178:181], v178 offset:3072
	s_add_u32 s38, s44, 0x160000
	s_addc_u32 s39, s45, 0
	s_mov_b32 m0, s47
	v_lshl_add_u64 v[224:225], s[38:39], 0, v[134:135]
	ds_read_b128 v[182:185], v149 offset:32768
	ds_read_b128 v[186:189], v149 offset:33792
	ds_read_b128 v[194:197], v149 offset:34816
	ds_read_b128 v[198:201], v149 offset:35840
	ds_read_b128 v[202:205], v149 offset:36864
	ds_read_b128 v[206:209], v149 offset:37888
	ds_read_b128 v[210:213], v149 offset:38912
	ds_read_b128 v[214:217], v149 offset:39936
	global_load_lds_dwordx4 v[224:225], off
	v_lshl_add_u64 v[224:225], s[38:39], 0, v[130:131]
	s_mov_b32 m0, s48
	s_nop 0
	global_load_lds_dwordx4 v[224:225], off
	s_waitcnt vmcnt(8)
	s_waitcnt lgkmcnt(0)
	s_barrier
	s_setprio 1
	s_waitcnt lgkmcnt(0)
	v_mfma_f32_16x16x32_bf16 v[124:127], v[150:153], v[182:185], v[124:127]
	v_mfma_f32_16x16x32_bf16 v[120:123], v[158:161], v[182:185], v[120:123]
	v_mfma_f32_16x16x32_bf16 v[116:119], v[150:153], v[194:197], v[116:119]
	v_mfma_f32_16x16x32_bf16 v[112:115], v[158:161], v[194:197], v[112:115]
	v_mfma_f32_16x16x32_bf16 v[100:103], v[150:153], v[202:205], v[100:103]
	v_mfma_f32_16x16x32_bf16 v[96:99], v[158:161], v[202:205], v[96:99]
	v_mfma_f32_16x16x32_bf16 v[84:87], v[150:153], v[210:213], v[84:87]
	v_mfma_f32_16x16x32_bf16 v[80:83], v[158:161], v[210:213], v[80:83]
	v_mfma_f32_16x16x32_bf16 v[124:127], v[154:157], v[186:189], v[124:127]
	v_mfma_f32_16x16x32_bf16 v[120:123], v[162:165], v[186:189], v[120:123]
	v_mfma_f32_16x16x32_bf16 v[116:119], v[154:157], v[198:201], v[116:119]
	v_mfma_f32_16x16x32_bf16 v[112:115], v[162:165], v[198:201], v[112:115]
	v_mfma_f32_16x16x32_bf16 v[100:103], v[154:157], v[206:209], v[100:103]
	v_mfma_f32_16x16x32_bf16 v[96:99], v[162:165], v[206:209], v[96:99]
	v_mfma_f32_16x16x32_bf16 v[84:87], v[154:157], v[214:217], v[84:87]
	v_mfma_f32_16x16x32_bf16 v[80:83], v[162:165], v[214:217], v[80:83]
	s_setprio 0
	s_setprio 1
	v_mfma_f32_16x16x32_bf16 v[108:111], v[166:169], v[182:185], v[108:111]
	v_mfma_f32_16x16x32_bf16 v[104:107], v[174:177], v[182:185], v[104:107]
	v_mfma_f32_16x16x32_bf16 v[92:95], v[166:169], v[194:197], v[92:95]
	v_mfma_f32_16x16x32_bf16 v[88:91], v[174:177], v[194:197], v[88:91]
	v_mfma_f32_16x16x32_bf16 v[76:79], v[166:169], v[202:205], v[76:79]
	v_mfma_f32_16x16x32_bf16 v[72:75], v[174:177], v[202:205], v[72:75]
	v_mfma_f32_16x16x32_bf16 v[68:71], v[166:169], v[210:213], v[68:71]
	v_mfma_f32_16x16x32_bf16 v[64:67], v[174:177], v[210:213], v[64:67]
	v_mfma_f32_16x16x32_bf16 v[108:111], v[170:173], v[186:189], v[108:111]
	v_mfma_f32_16x16x32_bf16 v[104:107], v[178:181], v[186:189], v[104:107]
	v_mfma_f32_16x16x32_bf16 v[92:95], v[170:173], v[198:201], v[92:95]
	v_mfma_f32_16x16x32_bf16 v[88:91], v[178:181], v[198:201], v[88:91]
	v_mfma_f32_16x16x32_bf16 v[76:79], v[170:173], v[206:209], v[76:79]
	v_mfma_f32_16x16x32_bf16 v[72:75], v[178:181], v[206:209], v[72:75]
	v_mfma_f32_16x16x32_bf16 v[68:71], v[170:173], v[214:217], v[68:71]
	v_mfma_f32_16x16x32_bf16 v[64:67], v[178:181], v[214:217], v[64:67]
	s_setprio 0
	s_barrier
; #define PG8_STAGE(bufoff, gbase, voff) do { _Pragma("unroll") for (int _i = 0; _i < 2; ++_i) \
;         __builtin_amdgcn_global_load_lds((const unsigned*)((const char*)(gbase) + (voff)[_i]), (PG8_LAS unsigned*)(lds + (bufoff) + ldsw + _i * 8192), 16, 0, 0); } while (0)
; #define PG8_LDA(dst, b, h) do { _Pragma("unroll") for (int m = 0; m < 4; ++m) _Pragma("unroll") for (int k = 0; k < 2; ++k) dst[m][k] = *(const PG8_LAS bf16x8*)(lds + PG8_SA(b, h) + aoff + m * 2048 + k * 1024); } while (0)
; #define PG8_MMA(ai, bj, At, Bt) do { __builtin_amdgcn_s_setprio(1); _Pragma("unroll") for (int m = 0; m < 4; ++m) _Pragma("unroll") for (int n = 0; n < 2; ++n) _Pragma("unroll") for (int k = 0; k < 2; ++k) \
;         acc[ai][bj][m][n] = __builtin_amdgcn_mfma_f32_16x16x32_bf16(Bt[n][k], At[m][k], acc[ai][bj][m][n], 0, 0, 0); __builtin_amdgcn_s_setprio(0); } while (0)
; #define PG8_WAIT_V(n) asm volatile("s_waitcnt vmcnt(" #n ")" ::: "memory")
; #define PG8_WAIT_L(n) asm volatile("s_waitcnt lgkmcnt(" #n ")" ::: "memory")
; #define PG8_BAR __builtin_amdgcn_s_barrier()
; #define PG8_SCHED __builtin_amdgcn_sched_barrier(0)
; template <class Epi, class Sched, bool ALIGN_EPI = false, bool SP2 = false>
; __device__ __forceinline__ void gemm_phase(PG8_LAS unsigned char* lds, const Gemm g, const Sched& S, const Epi& E) {
;     ...
;             PG8_LDA(At, 1, 1); PG8_STAGE(PG8_SB(1, 0), b3, voffB); PG8_STAGE(PG8_SB(1, 1), b3 + hstep, voffB); PG8_STAGE(PG8_SA(1, 0), a3, voffA);
;             PG8_WAIT_V(8); PG8_WAIT_L(0); PG8_BAR; PG8_MMA(1, 0, At, B0); PG8_MMA(1, 1, At, B1); PG8_BAR; PG8_SCHED;
;     ...
;         if constexpr (ALIGN_EPI) { if (wr == 0) PG8_BAR; }
	s_add_i32 s38, s63, s2
	v_lshl_add_u64 v[190:191], v[190:191], 0, s[30:31]
	s_mov_b32 m0, s38
	ds_read_b128 v[182:185], v149 offset:49152
	ds_read_b128 v[186:189], v149 offset:50176
	ds_read_b128 v[194:197], v149 offset:51200
	ds_read_b128 v[198:201], v149 offset:52224
	ds_read_b128 v[202:205], v149 offset:53248
	ds_read_b128 v[206:209], v149 offset:54272
	ds_read_b128 v[210:213], v149 offset:55296
	ds_read_b128 v[214:217], v149 offset:56320
	global_load_lds_dwordx4 v[190:191], off
	s_add_i32 m0, s38, 0x2000
	s_add_u32 s38, s42, 0x160080
	v_lshl_add_u64 v[190:191], v[218:219], 0, s[30:31]
	s_addc_u32 s39, s43, 0
	s_add_i32 s42, s64, s2
	global_load_lds_dwordx4 v[190:191], off
	v_lshl_add_u64 v[190:191], s[38:39], 0, v[132:133]
	s_mov_b32 m0, s42
	s_nop 0
	global_load_lds_dwordx4 v[190:191], off
	v_lshl_add_u64 v[190:191], s[38:39], 0, v[128:129]
	s_add_i32 m0, s42, 0x2000
	s_nop 0
	global_load_lds_dwordx4 v[190:191], off
	v_lshl_add_u64 v[190:191], v[220:221], 0, s[30:31]
	s_mov_b32 m0, s50
	s_nop 0
	global_load_lds_dwordx4 v[190:191], off
	v_lshl_add_u64 v[190:191], v[222:223], 0, s[30:31]
	s_mov_b32 m0, s51
	s_nop 0
	global_load_lds_dwordx4 v[190:191], off
	s_waitcnt vmcnt(8)
	s_waitcnt lgkmcnt(0)
	s_barrier
	s_setprio 1
	s_waitcnt lgkmcnt(0)
	v_mfma_f32_16x16x32_bf16 v[60:63], v[150:153], v[182:185], v[60:63]
	v_mfma_f32_16x16x32_bf16 v[56:59], v[158:161], v[182:185], v[56:59]
	v_mfma_f32_16x16x32_bf16 v[52:55], v[150:153], v[194:197], v[52:55]
	v_mfma_f32_16x16x32_bf16 v[48:51], v[158:161], v[194:197], v[48:51]
	v_mfma_f32_16x16x32_bf16 v[36:39], v[150:153], v[202:205], v[36:39]
	v_mfma_f32_16x16x32_bf16 v[32:35], v[158:161], v[202:205], v[32:35]
	v_mfma_f32_16x16x32_bf16 v[20:23], v[150:153], v[210:213], v[20:23]
	v_mfma_f32_16x16x32_bf16 v[16:19], v[158:161], v[210:213], v[16:19]
	v_mfma_f32_16x16x32_bf16 v[60:63], v[154:157], v[186:189], v[60:63]
	v_mfma_f32_16x16x32_bf16 v[56:59], v[162:165], v[186:189], v[56:59]
	v_mfma_f32_16x16x32_bf16 v[52:55], v[154:157], v[198:201], v[52:55]
	v_mfma_f32_16x16x32_bf16 v[48:51], v[162:165], v[198:201], v[48:51]
	v_mfma_f32_16x16x32_bf16 v[36:39], v[154:157], v[206:209], v[36:39]
	v_mfma_f32_16x16x32_bf16 v[32:35], v[162:165], v[206:209], v[32:35]
	v_mfma_f32_16x16x32_bf16 v[20:23], v[154:157], v[214:217], v[20:23]
	v_mfma_f32_16x16x32_bf16 v[16:19], v[162:165], v[214:217], v[16:19]
	s_setprio 0
	s_setprio 1
	v_mfma_f32_16x16x32_bf16 v[44:47], v[166:169], v[182:185], v[44:47]
	v_mfma_f32_16x16x32_bf16 v[40:43], v[174:177], v[182:185], v[40:43]
	v_mfma_f32_16x16x32_bf16 v[28:31], v[166:169], v[194:197], v[28:31]
	v_mfma_f32_16x16x32_bf16 v[24:27], v[174:177], v[194:197], v[24:27]
	v_mfma_f32_16x16x32_bf16 v[12:15], v[166:169], v[202:205], v[12:15]
	v_mfma_f32_16x16x32_bf16 v[8:11], v[174:177], v[202:205], v[8:11]
	v_mfma_f32_16x16x32_bf16 v[4:7], v[166:169], v[210:213], v[4:7]
	v_mfma_f32_16x16x32_bf16 v[0:3], v[174:177], v[210:213], v[0:3]
	v_mfma_f32_16x16x32_bf16 v[44:47], v[170:173], v[186:189], v[44:47]
	v_mfma_f32_16x16x32_bf16 v[40:43], v[178:181], v[186:189], v[40:43]
	v_mfma_f32_16x16x32_bf16 v[28:31], v[170:173], v[198:201], v[28:31]
	v_mfma_f32_16x16x32_bf16 v[24:27], v[178:181], v[198:201], v[24:27]
	v_mfma_f32_16x16x32_bf16 v[12:15], v[170:173], v[206:209], v[12:15]
	v_mfma_f32_16x16x32_bf16 v[8:11], v[178:181], v[206:209], v[8:11]
	v_mfma_f32_16x16x32_bf16 v[4:7], v[170:173], v[214:217], v[4:7]
	v_mfma_f32_16x16x32_bf16 v[0:3], v[178:181], v[214:217], v[0:3]
	s_setprio 0
	s_barrier
	s_add_i32 s62, s62, 2
	s_add_u32 s60, s60, 0x100
	s_addc_u32 s61, s61, 0
	s_cmpk_gt_u32 s62, 0x55
	s_mov_b64 s[38:39], s[40:41]
	s_cbranch_scc0 .LBB0_145
	s_and_b64 vcc, exec, s[34:35]
	s_cbranch_vccz .LBB0_148
	s_barrier

; #define LAS __attribute__((address_space(3)))
;     LAS float* scr = (LAS float*)(C.lds + C.wave * 16384);
;     const int gw = (C.bid - b0) * NWAVES + C.wave, NGW = (C.G - b0) * NWAVES;
;     if (C.bid < b0) return;
;     constexpr int KB1 = D / 64, I_GU = (11264 / 32) * KB1, KB2 = FF / 64, I_D = (D / 32) * KB2;
;     for (int it = gw; it < I_GU + I_D; it += NGW) {
;         if (it < I_GU) { const int g = it / KB1, kb = it % KB1; const int tile = g >> 3, w = (g & 7) * 32;
.LBB0_209:
	v_mov_b32_e32 v0, v192
	s_nop 0
	v_readfirstlane_b32 s0, v0
	s_ashr_i32 s0, s0, 6
	s_add_i32 s2, s0, s70
	s_cmpk_lt_i32 s2, 0x4200
	s_cselect_b64 s[4:5], -1, 0
	s_and_b64 s[4:5], s[26:27], s[4:5]
	s_andn2_b64 vcc, exec, s[4:5]
	s_cbranch_vccnz .LBB0_216
	s_lshl_b32 s0, s0, 14
	v_bfe_u32 v8, v0, 5, 1
	v_and_b32_e32 v6, 31, v0
	v_bfe_u32 v9, v0, 3, 3
	v_lshlrev_b32_e32 v0, 3, v0
	s_add_i32 s0, s0, 0
	v_and_b32_e32 v0, 56, v0
	v_mov_b32_e32 v1, 0
	v_lshl_add_u32 v7, v6, 2, s0
	v_mul_u32_u24_e32 v15, 0x84, v8
	v_mul_u32_u24_e32 v4, 0x84, v0
	v_lshlrev_b32_e32 v0, 1, v0
	v_lshlrev_b32_e32 v5, 2, v9
	v_lshl_add_u64 v[2:3], s[66:67], 0, v[0:1]
	v_add3_u32 v10, s0, v4, v5
	v_lshl_add_u64 v[4:5], s[68:69], 0, v[0:1]
	s_mul_i32 s0, s2, 0x160000
	v_mul_u32_u24_e32 v0, 0x5800, v8
	v_add_u32_e32 v15, v7, v15
	s_mov_b32 s1, 0
	v_or_b32_e32 v11, 8, v9
	v_or_b32_e32 v12, 16, v9
	v_or_b32_e32 v13, 24, v9
	v_or_b32_e32 v14, s0, v0
	s_lshl_b32 s3, s2, 6
	s_lshl_b32 s6, s92, 6
	s_mov_b32 s7, 0x2c000
	s_mov_b32 s8, 0x58000
	s_mov_b32 s9, 0x21000
	s_mov_b32 s20, 0x37000
	s_mov_b32 s21, 0x42000
	s_mov_b32 s22, 0x4d000
	s_mov_b32 s23, 0x63000
	s_mov_b32 s26, 0x6e000
	s_mov_b32 s27, 0x79000
	s_mov_b32 s28, 0x84000
	s_mov_b32 s29, 0x8f000
	s_mov_b32 s30, 0x9a000
	s_mov_b32 s31, 0xa5000
	s_mov_b32 s33, 0xb0000
	s_mov_b32 s34, 0xbb000
	s_mov_b32 s35, 0xc6000
	s_mov_b32 s36, 0xd1000
	s_mov_b32 s37, 0xdc000
	s_mov_b32 s38, 0xe7000
	s_mov_b32 s39, 0xf2000
	s_mov_b32 s40, 0xfd000
	s_mov_b32 s41, 0x108000
	s_mov_b32 s42, 0x113000
	s_mov_b32 s43, 0x11e000
	s_mov_b32 s44, 0x129000
	s_mov_b32 s45, 0x134000
	s_mov_b32 s46, 0x13f000
	s_mov_b32 s47, 0x14a000
	s_mov_b32 s48, 0x155000
	v_lshlrev_b32_e32 v0, 2, v6
	v_add_u32_e32 v16, 0x400, v15
	v_add_u32_e32 v17, 0x800, v15
	v_add_u32_e32 v18, 0xc00, v15
	v_add_u32_e32 v19, 0x1000, v15
	v_add_u32_e32 v20, 0x1400, v15
	v_add_u32_e32 v21, 0x1800, v15
	v_add_u32_e32 v22, 0x1c00, v15
	s_branch .LBB0_212
.LBB0_211:
	s_add_i32 s2, s2, s92
	s_add_i32 s3, s3, s6
	s_cmpk_lt_i32 s2, 0x4200
	v_add_u32_e32 v14, s96, v14
	s_cbranch_scc0 .LBB0_216

; #define LAS __attribute__((address_space(3)))
; __device__ __forceinline__ void conv_item(const float* W, int K, int N, int scol0, bf16* WT, int drow0, int k0, LAS float* scr, int lane) {
;     float wv[32];
;     { const float* src = W + (size_t)(k0 + (lane >> 5)) * N + scol0 + (lane & 31);
; #pragma unroll
;       for (int i = 0; i < 32; ++i) wv[i] = src[(size_t)(2 * i) * N]; }
;     ...
;         if (it < I_GU) { const int g = it / KB1, kb = it % KB1; const int tile = g >> 3, w = (g & 7) * 32;
;             const float* src = (w < 128) ? wg : wu; const int scol = tile * 128 + (w & 127);
;             conv_item(src, D, FF, scol, WGU, 32 * g, 64 * kb, scr, C.lane); }
.LBB0_214:
	s_andn2_b64 vcc, exec, s[4:5]
	s_cbranch_vccnz .LBB0_211
	s_ashr_i32 s0, s2, 31
	s_lshr_b32 s0, s0, 27
	v_readlane_b32 s52, v232, 24
	s_add_i32 s5, s2, s0
	v_readlane_b32 s53, v232, 25
	v_readlane_b32 s54, v232, 26
	v_readlane_b32 s55, v232, 27
	v_readlane_b32 s56, v232, 28
	v_readlane_b32 s57, v232, 29
	v_readlane_b32 s58, v232, 30
	v_readlane_b32 s59, v232, 31
	v_readlane_b32 s60, v232, 32
	v_readlane_b32 s61, v232, 33
	v_readlane_b32 s62, v232, 34
	v_readlane_b32 s63, v232, 35
	s_ashr_i32 s4, s5, 5
	s_and_b32 s0, s5, 0xffffffe0
	v_readlane_b32 s64, v232, 36
	v_readlane_b32 s65, v232, 37
	v_readlane_b32 s66, v232, 38
	v_readlane_b32 s67, v232, 39
	s_mov_b64 s[52:53], s[56:57]
	s_bitcmp0_b32 s4, 2
	s_mov_b64 s[54:55], s[58:59]
	s_mov_b64 s[56:57], s[60:61]
	s_mov_b64 s[58:59], s[62:63]
	s_cselect_b32 s51, s57, s59
	s_cselect_b32 s50, s56, s58
	s_lshl_b32 s49, s4, 4
	s_and_b32 s49, s49, 0xffffff80
	s_and_b32 s5, s5, 0x60
	s_or_b32 s52, s49, s5
	s_mul_i32 s5, s4, 0xfd400000
	v_add_u32_e32 v6, s5, v14
	v_ashrrev_i32_e32 v7, 31, v6
	v_lshl_add_u64 v[6:7], s[50:51], 0, v[6:7]
	s_ashr_i32 s53, s52, 31
	v_lshl_add_u64 v[6:7], s[52:53], 2, v[6:7]
	v_lshl_add_u64 v[6:7], v[6:7], 0, v[0:1]
	s_mov_b32 s5, 0xb000
	v_add_co_u32_e32 v24, vcc, s5, v6
	s_mov_b32 s5, 0x16000
	s_nop 0
	v_addc_co_u32_e32 v25, vcc, 0, v7, vcc
	v_add_co_u32_e32 v26, vcc, s5, v6
	s_lshl_b32 s4, s4, 11
	s_nop 0
	v_addc_co_u32_e32 v27, vcc, 0, v7, vcc
	v_add_co_u32_e32 v28, vcc, s9, v6
	s_sub_i32 s4, s3, s4
	s_nop 0
	v_addc_co_u32_e32 v29, vcc, 0, v7, vcc
	v_add_co_u32_e32 v30, vcc, s7, v6
	s_ashr_i32 s5, s4, 31
	s_nop 0
	v_addc_co_u32_e32 v31, vcc, 0, v7, vcc
	v_add_co_u32_e32 v32, vcc, s20, v6
	s_mov_b64 s[60:61], s[64:65]
	s_nop 0
	v_addc_co_u32_e32 v33, vcc, 0, v7, vcc
	v_add_co_u32_e32 v34, vcc, s21, v6
	s_mov_b64 s[62:63], s[66:67]
	s_nop 0
	v_addc_co_u32_e32 v35, vcc, 0, v7, vcc
	v_add_co_u32_e32 v36, vcc, s22, v6
	s_nop 1
	v_addc_co_u32_e32 v37, vcc, 0, v7, vcc
	global_load_dword v23, v[6:7], off
	global_load_dword v40, v[24:25], off
	global_load_dword v41, v[26:27], off
	global_load_dword v42, v[28:29], off
	global_load_dword v43, v[30:31], off
	global_load_dword v44, v[32:33], off
	global_load_dword v45, v[34:35], off
	global_load_dword v46, v[36:37], off
	v_add_co_u32_e32 v24, vcc, s8, v6
	s_nop 1
	v_addc_co_u32_e32 v25, vcc, 0, v7, vcc
	v_add_co_u32_e32 v26, vcc, s23, v6
	s_nop 1
	v_addc_co_u32_e32 v27, vcc, 0, v7, vcc
	v_add_co_u32_e32 v28, vcc, s26, v6
	s_nop 1
	v_addc_co_u32_e32 v29, vcc, 0, v7, vcc
	v_add_co_u32_e32 v30, vcc, s27, v6
	s_nop 1
	v_addc_co_u32_e32 v31, vcc, 0, v7, vcc
	v_add_co_u32_e32 v32, vcc, s28, v6
	s_nop 1
	v_addc_co_u32_e32 v33, vcc, 0, v7, vcc
	v_add_co_u32_e32 v34, vcc, s29, v6
	s_nop 1
	v_addc_co_u32_e32 v35, vcc, 0, v7, vcc
	v_add_co_u32_e32 v36, vcc, s30, v6
	s_nop 1
	v_addc_co_u32_e32 v37, vcc, 0, v7, vcc
	v_add_co_u32_e32 v38, vcc, s31, v6
	s_nop 1
	v_addc_co_u32_e32 v39, vcc, 0, v7, vcc
	global_load_dword v47, v[24:25], off
	global_load_dword v48, v[26:27], off
	global_load_dword v49, v[28:29], off
	global_load_dword v50, v[30:31], off
	global_load_dword v51, v[32:33], off
	global_load_dword v52, v[34:35], off
	global_load_dword v53, v[36:37], off
	global_load_dword v54, v[38:39], off
	v_add_co_u32_e32 v24, vcc, s33, v6
	s_nop 1
	v_addc_co_u32_e32 v25, vcc, 0, v7, vcc
	v_add_co_u32_e32 v26, vcc, s34, v6
	s_nop 1
	v_addc_co_u32_e32 v27, vcc, 0, v7, vcc
	v_add_co_u32_e32 v28, vcc, s35, v6
	s_nop 1
	v_addc_co_u32_e32 v29, vcc, 0, v7, vcc
	v_add_co_u32_e32 v30, vcc, s36, v6
	s_nop 1
	v_addc_co_u32_e32 v31, vcc, 0, v7, vcc
	v_add_co_u32_e32 v32, vcc, s37, v6
	s_nop 1
	v_addc_co_u32_e32 v33, vcc, 0, v7, vcc
	v_add_co_u32_e32 v34, vcc, s38, v6
	s_nop 1
	v_addc_co_u32_e32 v35, vcc, 0, v7, vcc
	v_add_co_u32_e32 v36, vcc, s39, v6
	s_nop 1
	v_addc_co_u32_e32 v37, vcc, 0, v7, vcc
	v_add_co_u32_e32 v38, vcc, s40, v6
	s_nop 1
	v_addc_co_u32_e32 v39, vcc, 0, v7, vcc
	global_load_dword v55, v[24:25], off
	global_load_dword v56, v[26:27], off
	global_load_dword v57, v[28:29], off
	global_load_dword v58, v[30:31], off
	global_load_dword v59, v[32:33], off
	global_load_dword v60, v[34:35], off
	global_load_dword v61, v[36:37], off
	s_nop 0
	global_load_dword v38, v[38:39], off
	v_add_co_u32_e32 v24, vcc, s41, v6
	s_nop 1
	v_addc_co_u32_e32 v25, vcc, 0, v7, vcc
	v_add_co_u32_e32 v26, vcc, s42, v6
	s_nop 1
	v_addc_co_u32_e32 v27, vcc, 0, v7, vcc
	v_add_co_u32_e32 v28, vcc, s43, v6
	s_nop 1
	v_addc_co_u32_e32 v29, vcc, 0, v7, vcc
	v_add_co_u32_e32 v30, vcc, s44, v6
	s_nop 1
	v_addc_co_u32_e32 v31, vcc, 0, v7, vcc
	v_add_co_u32_e32 v32, vcc, s45, v6
	s_nop 1
	v_addc_co_u32_e32 v33, vcc, 0, v7, vcc
	v_add_co_u32_e32 v34, vcc, s46, v6
	s_nop 1
	v_addc_co_u32_e32 v35, vcc, 0, v7, vcc
	v_add_co_u32_e32 v36, vcc, s47, v6
	s_nop 1
	v_addc_co_u32_e32 v37, vcc, 0, v7, vcc
	v_add_co_u32_e32 v6, vcc, s48, v6
	s_nop 1
	v_addc_co_u32_e32 v7, vcc, 0, v7, vcc
	global_load_dword v24, v[24:25], off
	s_nop 0
	global_load_dword v25, v[26:27], off
	s_nop 0
	global_load_dword v26, v[28:29], off
	global_load_dword v27, v[30:31], off
	s_nop 0
	global_load_dword v28, v[32:33], off
	global_load_dword v29, v[34:35], off
	global_load_dword v30, v[36:37], off
	s_nop 0
	global_load_dword v6, v[6:7], off
	s_waitcnt vmcnt(30)
; #define GAS __attribute__((address_space(1)))
; #define LAS __attribute__((address_space(3)))
; #define LDS_WAIT() asm volatile("s_waitcnt lgkmcnt(0)" ::: "memory")
; __device__ __forceinline__ unsigned pk2(float lo, float hi) { f32x2_t v = {lo, hi}; bf16x2_t b = __builtin_convertvector(v, bf16x2_t); return __builtin_bit_cast(unsigned, b); }
; __device__ __forceinline__ void conv_item(const float* W, int K, int N, int scol0, bf16* WT, int drow0, int k0, LAS float* scr, int lane) {
;     ...
; #pragma unroll
;     for (int i = 0; i < 32; ++i) scr[(2 * i + (lane >> 5)) * 33 + (lane & 31)] = wv[i];
;     LDS_WAIT(); asm volatile("" ::: "memory");
;     const int c = lane & 7;
; #pragma unroll
;     for (int j = 0; j < 4; ++j) { const int n = (lane >> 3) + 8 * j; const LAS float* s = scr + (8 * c) * 33 + n;
;         v4u o; o.x = pk2(s[0 * 33], s[1 * 33]); o.y = pk2(s[2 * 33], s[3 * 33]); o.z = pk2(s[4 * 33], s[5 * 33]); o.w = pk2(s[6 * 33], s[7 * 33]);
;         *(GAS v4u*)(WT + (size_t)(drow0 + n) * K + k0 + 8 * c) = o; }
;     LDS_WAIT(); asm volatile("" ::: "memory");
; }
; __device__ __forceinline__ void xcd_barrier(const XcdBarrier& b) {
;     asm volatile("s_waitcnt vmcnt(0)" ::: "memory");
;     __syncthreads();
;     if (threadIdx.x == 0) {
;         unsigned* bar = b.bar;
;         __builtin_amdgcn_s_waitcnt(0);
;         unsigned nloc = b.st[0], nx = b.st[1];
;         if (nloc == 0u) { xcd_barrier_complete(bar, b.x, nloc, nx); b.st[0] = nloc; b.st[1] = nx; }
	ds_write2_b32 v15, v23, v40 offset1:66
	s_waitcnt vmcnt(28)
	ds_write2_b32 v15, v41, v42 offset0:132 offset1:198
	s_waitcnt vmcnt(26)
	ds_write2_b32 v16, v43, v44 offset0:8 offset1:74
	s_waitcnt vmcnt(24)
	ds_write2_b32 v16, v45, v46 offset0:140 offset1:206
	s_waitcnt vmcnt(22)
	ds_write2_b32 v17, v47, v48 offset0:16 offset1:82
	s_waitcnt vmcnt(20)
	ds_write2_b32 v17, v49, v50 offset0:148 offset1:214
	s_waitcnt vmcnt(18)
	ds_write2_b32 v18, v51, v52 offset0:24 offset1:90
	s_waitcnt vmcnt(16)
	ds_write2_b32 v18, v53, v54 offset0:156 offset1:222
	s_waitcnt vmcnt(14)
	ds_write2_b32 v19, v55, v56 offset0:32 offset1:98
	s_waitcnt vmcnt(12)
	ds_write2_b32 v19, v57, v58 offset0:164 offset1:230
	s_waitcnt vmcnt(10)
	ds_write2_b32 v20, v59, v60 offset0:40 offset1:106
	s_waitcnt vmcnt(8)
	ds_write2_b32 v20, v61, v38 offset0:172 offset1:238
	s_waitcnt vmcnt(6)
	ds_write2_b32 v21, v24, v25 offset0:48 offset1:114
	s_waitcnt vmcnt(4)
	ds_write2_b32 v21, v26, v27 offset0:180 offset1:246
	s_waitcnt vmcnt(2)
	ds_write2_b32 v22, v28, v29 offset0:56 offset1:122
	s_waitcnt vmcnt(0)
	ds_write2_b32 v22, v30, v6 offset0:188 offset1:254
	s_waitcnt lgkmcnt(0)
	ds_read2_b32 v[6:7], v10 offset0:33 offset1:41
	ds_read2_b32 v[28:29], v10 offset1:8
	ds_read2_b32 v[30:31], v10 offset0:66 offset1:74
	ds_read2_b32 v[32:33], v10 offset0:99 offset1:107
	ds_read2_b32 v[34:35], v10 offset0:132 offset1:140
	ds_read2_b32 v[36:37], v10 offset0:165 offset1:173
	ds_read2_b32 v[38:39], v10 offset0:198 offset1:206
	ds_read2_b32 v[40:41], v10 offset0:231 offset1:239
	v_or_b32_e32 v44, s0, v9
	v_ashrrev_i32_e32 v45, 31, v44
	v_lshl_add_u64 v[42:43], s[4:5], 1, v[4:5]
	v_lshlrev_b64 v[44:45], 12, v[44:45]
	s_waitcnt lgkmcnt(6)
	v_cvt_pk_bf16_f32 v24, v28, v6
	s_waitcnt lgkmcnt(4)
	v_cvt_pk_bf16_f32 v25, v30, v32
	s_waitcnt lgkmcnt(2)
	v_cvt_pk_bf16_f32 v26, v34, v36
	s_waitcnt lgkmcnt(0)
	v_cvt_pk_bf16_f32 v27, v38, v40
	v_lshl_add_u64 v[44:45], v[42:43], 0, v[44:45]
	v_or_b32_e32 v6, s0, v11
	global_store_dwordx4 v[44:45], v[24:27], off
	s_nop 1
	v_cvt_pk_bf16_f32 v24, v29, v7
	v_ashrrev_i32_e32 v7, 31, v6
	v_cvt_pk_bf16_f32 v25, v31, v33
	v_cvt_pk_bf16_f32 v26, v35, v37
	v_cvt_pk_bf16_f32 v27, v39, v41
	v_lshlrev_b64 v[6:7], 12, v[6:7]
	ds_read2_b32 v[28:29], v10 offset0:49 offset1:57
	ds_read2_b32 v[30:31], v10 offset0:16 offset1:24
	ds_read2_b32 v[32:33], v10 offset0:82 offset1:90
	ds_read2_b32 v[34:35], v10 offset0:115 offset1:123
	ds_read2_b32 v[36:37], v10 offset0:148 offset1:156
	ds_read2_b32 v[38:39], v10 offset0:181 offset1:189
	ds_read2_b32 v[40:41], v10 offset0:214 offset1:222
	ds_read2_b32 v[44:45], v10 offset0:247 offset1:255
	v_lshl_add_u64 v[6:7], v[42:43], 0, v[6:7]
	global_store_dwordx4 v[6:7], v[24:27], off
	v_or_b32_e32 v6, s0, v12
	v_ashrrev_i32_e32 v7, 31, v6
	v_lshlrev_b64 v[6:7], 12, v[6:7]
	s_waitcnt lgkmcnt(6)
	v_cvt_pk_bf16_f32 v24, v30, v28
	s_waitcnt lgkmcnt(4)
	v_cvt_pk_bf16_f32 v25, v32, v34
	s_waitcnt lgkmcnt(2)
	v_cvt_pk_bf16_f32 v26, v36, v38
	s_waitcnt lgkmcnt(0)
	v_cvt_pk_bf16_f32 v27, v40, v44
	v_lshl_add_u64 v[6:7], v[42:43], 0, v[6:7]
	global_store_dwordx4 v[6:7], v[24:27], off
	v_or_b32_e32 v6, s0, v13
	v_ashrrev_i32_e32 v7, 31, v6
	v_lshlrev_b64 v[6:7], 12, v[6:7]
	v_cvt_pk_bf16_f32 v24, v31, v29
	v_cvt_pk_bf16_f32 v25, v33, v35
	v_cvt_pk_bf16_f32 v26, v37, v39
	v_cvt_pk_bf16_f32 v27, v41, v45
	v_lshl_add_u64 v[6:7], v[42:43], 0, v[6:7]
	global_store_dwordx4 v[6:7], v[24:27], off
	s_waitcnt lgkmcnt(0)
	s_branch .LBB0_211
.LBB0_216:
	s_waitcnt vmcnt(0)
	s_barrier
	s_and_saveexec_b64 s[0:1], s[78:79]
	s_cbranch_execz .LBB0_268
	s_add_i32 s2, 0, 0x20040
	v_mov_b32_e32 v0, s2
	s_waitcnt vmcnt(0) expcnt(0) lgkmcnt(0)
	ds_read_b32 v2, v0
	s_add_i32 s2, 0, 0x20044
	v_mov_b32_e32 v0, s2
	ds_read_b32 v0, v0
	s_waitcnt lgkmcnt(1)
	v_cmp_ne_u32_e32 vcc, 0, v2
	s_cbranch_vccnz .LBB0_232
	s_add_u32 s4, s90, 0x1200
	s_addc_u32 s5, s91, 0
	s_add_u32 s6, s90, 0x1400
	s_addc_u32 s7, s91, 0
	s_add_u32 s8, s90, 0x1500
	s_addc_u32 s9, s91, 0
	s_add_u32 s20, s90, 0x1600
	s_addc_u32 s21, s91, 0
	s_add_u32 s22, s90, 0x1700
	s_addc_u32 s23, s91, 0
	s_add_u32 s26, s90, 0x1800
	s_addc_u32 s27, s91, 0
	s_add_u32 s28, s90, 0x1900
	s_addc_u32 s29, s91, 0
	s_add_u32 s30, s90, 0x1a00
	s_addc_u32 s31, s91, 0
	s_add_u32 s34, s90, 0x1b00
	s_addc_u32 s35, s91, 0
	s_add_u32 s36, s90, 0x1c00
	s_addc_u32 s37, s91, 0
	s_add_u32 s38, s90, 0x1d00
	s_addc_u32 s39, s91, 0
	s_add_u32 s40, s90, 0x1e00
	s_addc_u32 s41, s91, 0
	s_add_u32 s42, s90, 0x1f00
	s_addc_u32 s43, s91, 0
	s_add_u32 s44, s90, 0x2000
	s_addc_u32 s45, s91, 0
	s_add_u32 s46, s90, 0x2100
	s_addc_u32 s47, s91, 0
	s_add_u32 s48, s90, 0x2200
	s_addc_u32 s49, s91, 0
	s_mul_i32 s2, s77, s71
	s_add_u32 s50, s90, 0x2300
	s_mul_i32 s2, s2, s76
	s_addc_u32 s51, s91, 0
	s_mov_b32 s3, 1
	v_mov_b32_e32 v16, 0
	s_branch .LBB0_220

; #define PG8_STAGE(bufoff, gbase, voff) do { _Pragma("unroll") for (int _i = 0; _i < 2; ++_i) \
;         __builtin_amdgcn_global_load_lds((const unsigned*)((const char*)(gbase) + (voff)[_i]), (PG8_LAS unsigned*)(lds + (bufoff) + ldsw + _i * 8192), 16, 0, 0); } while (0)
; #define PG8_LDA(dst, b, h) do { _Pragma("unroll") for (int m = 0; m < 4; ++m) _Pragma("unroll") for (int k = 0; k < 2; ++k) dst[m][k] = *(const PG8_LAS bf16x8*)(lds + PG8_SA(b, h) + aoff + m * 2048 + k * 1024); } while (0)
; #define PG8_LDB(dst, b, h) do { _Pragma("unroll") for (int n = 0; n < 2; ++n) _Pragma("unroll") for (int k = 0; k < 2; ++k) dst[n][k] = *(const PG8_LAS bf16x8*)(lds + PG8_SB(b, h) + boff + n * 2048 + k * 1024); } while (0)
; #define PG8_MMA(ai, bj, At, Bt) do { __builtin_amdgcn_s_setprio(1); _Pragma("unroll") for (int m = 0; m < 4; ++m) _Pragma("unroll") for (int n = 0; n < 2; ++n) _Pragma("unroll") for (int k = 0; k < 2; ++k) \
;         acc[ai][bj][m][n] = __builtin_amdgcn_mfma_f32_16x16x32_bf16(Bt[n][k], At[m][k], acc[ai][bj][m][n], 0, 0, 0); __builtin_amdgcn_s_setprio(0); } while (0)
; #define PG8_WAIT_V(n) asm volatile("s_waitcnt vmcnt(" #n ")" ::: "memory")
; #define PG8_BAR __builtin_amdgcn_s_barrier()
; template <class Epi, class Sched, bool ALIGN_EPI = false, bool SP2 = false>
; __device__ __forceinline__ void gemm_phase(PG8_LAS unsigned char* lds, const Gemm g, const Sched& S, const Epi& E) {
;     ...
;         for (int t = 0; t < nt; t += 2) {
;             const bool last = (t == nt - 2);
;             const char* a1 = cA + (size_t)(t + 1) * kstep;
;             const char* a2 = last ? nA : cA + (size_t)(t + 2) * kstep; const char* b2 = last ? nB : cB + (size_t)(t + 2) * kstep;
;             const char* a3 = a2 + kstep; const char* b3 = b2 + kstep;
;             if (last && has_next) S.a_ready(nxt);
;             if constexpr (SP2) {
;             PG8_LDB(B0, 0, 0); PG8_LDB(B1, 0, 1); PG8_SCHED; PG8_LDA(At, 0, 0); PG8_STAGE(PG8_SA(1, 1), a1 + hstep, voffA);
;             PG8_WAIT_V(8); PG8_WAIT_L(0); PG8_BAR; PG8_MMA(0, 0, At, B0); PG8_MMA(0, 1, At, B1); PG8_BAR; PG8_SCHED;
;             PG8_LDA(At, 0, 1); PG8_STAGE(PG8_SB(0, 0), b2, voffB); PG8_STAGE(PG8_SB(0, 1), b2 + hstep, voffB); PG8_STAGE(PG8_SA(0, 0), a2, voffA);
;             PG8_WAIT_V(8); PG8_WAIT_L(0); PG8_BAR; PG8_MMA(1, 0, At, B0); PG8_MMA(1, 1, At, B1); PG8_BAR; PG8_SCHED;
.LBB0_277:
	ds_read_b128 v[150:153], v147
	ds_read_b128 v[154:157], v147 offset:1024
	ds_read_b128 v[158:161], v147 offset:2048
	ds_read_b128 v[162:165], v147 offset:3072
	ds_read_b128 v[166:169], v148
	ds_read_b128 v[170:173], v148 offset:1024
	ds_read_b128 v[174:177], v148 offset:2048
	ds_read_b128 v[178:181], v148 offset:3072
	s_add_u32 s36, s34, 0xfff80080
	s_addc_u32 s37, s35, -1
	s_cmp_eq_u32 s57, 28
	s_cselect_b32 s39, s27, s37
	s_cselect_b32 s38, s53, s36
	s_cselect_b32 s37, s23, s56
	s_cselect_b32 s36, s54, s55
	v_lshl_add_u64 v[190:191], s[34:35], 0, v[136:137]
	s_add_i32 m0, s21, 0xc000
	ds_read_b128 v[182:185], v149
	ds_read_b128 v[186:189], v149 offset:1024
	ds_read_b128 v[194:197], v149 offset:2048
	ds_read_b128 v[198:201], v149 offset:3072
	ds_read_b128 v[202:205], v149 offset:4096
	ds_read_b128 v[206:209], v149 offset:5120
	ds_read_b128 v[210:213], v149 offset:6144
	ds_read_b128 v[214:217], v149 offset:7168
	global_load_lds_dwordx4 v[190:191], off
	v_lshl_add_u64 v[190:191], s[34:35], 0, v[138:139]
	s_add_i32 m0, s21, 0xe000
	s_nop 0
	global_load_lds_dwordx4 v[190:191], off
	s_waitcnt vmcnt(8)
	s_waitcnt lgkmcnt(0)
	s_barrier
	s_setprio 1
	s_waitcnt lgkmcnt(0)
	v_mfma_f32_16x16x32_bf16 v[124:127], v[150:153], v[182:185], v[124:127]
	v_mfma_f32_16x16x32_bf16 v[120:123], v[158:161], v[182:185], v[120:123]
	v_mfma_f32_16x16x32_bf16 v[116:119], v[150:153], v[194:197], v[116:119]
	v_mfma_f32_16x16x32_bf16 v[112:115], v[158:161], v[194:197], v[112:115]
	v_mfma_f32_16x16x32_bf16 v[100:103], v[150:153], v[202:205], v[100:103]
	v_mfma_f32_16x16x32_bf16 v[96:99], v[158:161], v[202:205], v[96:99]
	v_mfma_f32_16x16x32_bf16 v[84:87], v[150:153], v[210:213], v[84:87]
	v_mfma_f32_16x16x32_bf16 v[80:83], v[158:161], v[210:213], v[80:83]
	v_mfma_f32_16x16x32_bf16 v[124:127], v[154:157], v[186:189], v[124:127]
	v_mfma_f32_16x16x32_bf16 v[120:123], v[162:165], v[186:189], v[120:123]
	v_mfma_f32_16x16x32_bf16 v[116:119], v[154:157], v[198:201], v[116:119]
	v_mfma_f32_16x16x32_bf16 v[112:115], v[162:165], v[198:201], v[112:115]
	v_mfma_f32_16x16x32_bf16 v[100:103], v[154:157], v[206:209], v[100:103]
	v_mfma_f32_16x16x32_bf16 v[96:99], v[162:165], v[206:209], v[96:99]
	v_mfma_f32_16x16x32_bf16 v[84:87], v[154:157], v[214:217], v[84:87]
	v_mfma_f32_16x16x32_bf16 v[80:83], v[162:165], v[214:217], v[80:83]
	s_setprio 0
	s_setprio 1
	v_mfma_f32_16x16x32_bf16 v[108:111], v[166:169], v[182:185], v[108:111]
	v_mfma_f32_16x16x32_bf16 v[104:107], v[174:177], v[182:185], v[104:107]
	v_mfma_f32_16x16x32_bf16 v[92:95], v[166:169], v[194:197], v[92:95]
	v_mfma_f32_16x16x32_bf16 v[88:91], v[174:177], v[194:197], v[88:91]
	v_mfma_f32_16x16x32_bf16 v[76:79], v[166:169], v[202:205], v[76:79]
	v_mfma_f32_16x16x32_bf16 v[72:75], v[174:177], v[202:205], v[72:75]
	v_mfma_f32_16x16x32_bf16 v[68:71], v[166:169], v[210:213], v[68:71]
	v_mfma_f32_16x16x32_bf16 v[64:67], v[174:177], v[210:213], v[64:67]
	v_mfma_f32_16x16x32_bf16 v[108:111], v[170:173], v[186:189], v[108:111]
	v_mfma_f32_16x16x32_bf16 v[104:107], v[178:181], v[186:189], v[104:107]
	v_mfma_f32_16x16x32_bf16 v[92:95], v[170:173], v[198:201], v[92:95]
	v_mfma_f32_16x16x32_bf16 v[88:91], v[178:181], v[198:201], v[88:91]
	v_mfma_f32_16x16x32_bf16 v[76:79], v[170:173], v[206:209], v[76:79]
	v_mfma_f32_16x16x32_bf16 v[72:75], v[178:181], v[206:209], v[72:75]
	v_mfma_f32_16x16x32_bf16 v[68:71], v[170:173], v[214:217], v[68:71]
	v_mfma_f32_16x16x32_bf16 v[64:67], v[178:181], v[214:217], v[64:67]
	s_setprio 0
	s_barrier
	s_add_i32 s58, s49, s33
	v_lshl_add_u64 v[190:191], s[36:37], 0, v[132:133]
	s_mov_b32 m0, s58
	ds_read_b128 v[182:185], v149 offset:16384
	ds_read_b128 v[186:189], v149 offset:17408
	ds_read_b128 v[194:197], v149 offset:18432
	ds_read_b128 v[198:201], v149 offset:19456
	ds_read_b128 v[202:205], v149 offset:20480
	ds_read_b128 v[206:209], v149 offset:21504
	ds_read_b128 v[210:213], v149 offset:22528
	ds_read_b128 v[214:217], v149 offset:23552
	global_load_lds_dwordx4 v[190:191], off
	s_add_i32 m0, s58, 0x2000
	s_add_u32 s58, s36, 0x80000
	v_lshl_add_u64 v[218:219], s[36:37], 0, v[128:129]
	s_addc_u32 s59, s37, 0
	s_add_i32 s60, s50, s33
	global_load_lds_dwordx4 v[218:219], off
	v_lshl_add_u64 v[220:221], s[58:59], 0, v[132:133]
	s_mov_b32 m0, s60
	v_lshl_add_u64 v[222:223], s[38:39], 0, v[130:131]
	global_load_lds_dwordx4 v[220:221], off
	v_lshl_add_u64 v[220:221], s[58:59], 0, v[128:129]
	s_add_i32 m0, s60, 0x2000
	s_nop 0
	global_load_lds_dwordx4 v[220:221], off
	v_lshl_add_u64 v[220:221], s[38:39], 0, v[134:135]
	s_mov_b32 m0, s21
	s_nop 0
	global_load_lds_dwordx4 v[220:221], off
	s_mov_b32 m0, s41
	s_nop 0
	global_load_lds_dwordx4 v[222:223], off
	s_waitcnt vmcnt(8)
	s_waitcnt lgkmcnt(0)
	s_barrier
; #define PG8_STAGE(bufoff, gbase, voff) do { _Pragma("unroll") for (int _i = 0; _i < 2; ++_i) \
;         __builtin_amdgcn_global_load_lds((const unsigned*)((const char*)(gbase) + (voff)[_i]), (PG8_LAS unsigned*)(lds + (bufoff) + ldsw + _i * 8192), 16, 0, 0); } while (0)
; #define PG8_LDA(dst, b, h) do { _Pragma("unroll") for (int m = 0; m < 4; ++m) _Pragma("unroll") for (int k = 0; k < 2; ++k) dst[m][k] = *(const PG8_LAS bf16x8*)(lds + PG8_SA(b, h) + aoff + m * 2048 + k * 1024); } while (0)
; #define PG8_LDB(dst, b, h) do { _Pragma("unroll") for (int n = 0; n < 2; ++n) _Pragma("unroll") for (int k = 0; k < 2; ++k) dst[n][k] = *(const PG8_LAS bf16x8*)(lds + PG8_SB(b, h) + boff + n * 2048 + k * 1024); } while (0)
; #define PG8_MMA(ai, bj, At, Bt) do { __builtin_amdgcn_s_setprio(1); _Pragma("unroll") for (int m = 0; m < 4; ++m) _Pragma("unroll") for (int n = 0; n < 2; ++n) _Pragma("unroll") for (int k = 0; k < 2; ++k) \
;         acc[ai][bj][m][n] = __builtin_amdgcn_mfma_f32_16x16x32_bf16(Bt[n][k], At[m][k], acc[ai][bj][m][n], 0, 0, 0); __builtin_amdgcn_s_setprio(0); } while (0)
; #define PG8_WAIT_V(n) asm volatile("s_waitcnt vmcnt(" #n ")" ::: "memory")
; #define PG8_WAIT_L(n) asm volatile("s_waitcnt lgkmcnt(" #n ")" ::: "memory")
; #define PG8_BAR __builtin_amdgcn_s_barrier()
; #define PG8_SCHED __builtin_amdgcn_sched_barrier(0)
; template <class Epi, class Sched, bool ALIGN_EPI = false, bool SP2 = false>
; __device__ __forceinline__ void gemm_phase(PG8_LAS unsigned char* lds, const Gemm g, const Sched& S, const Epi& E) {
;     ...
;             PG8_WAIT_V(8); PG8_WAIT_L(0); PG8_BAR; PG8_MMA(1, 0, At, B0); PG8_MMA(1, 1, At, B1); PG8_BAR; PG8_SCHED;
;             PG8_LDB(B0, 1, 0); PG8_LDB(B1, 1, 1); PG8_SCHED; PG8_LDA(At, 1, 0); PG8_STAGE(PG8_SA(0, 1), a2 + hstep, voffA);
;             PG8_WAIT_V(8); PG8_WAIT_L(0); PG8_BAR; PG8_MMA(0, 0, At, B0); PG8_MMA(0, 1, At, B1); PG8_BAR; PG8_SCHED;
	s_setprio 1
	s_waitcnt lgkmcnt(0)
	v_mfma_f32_16x16x32_bf16 v[60:63], v[150:153], v[182:185], v[60:63]
	v_mfma_f32_16x16x32_bf16 v[56:59], v[158:161], v[182:185], v[56:59]
	v_mfma_f32_16x16x32_bf16 v[52:55], v[150:153], v[194:197], v[52:55]
	v_mfma_f32_16x16x32_bf16 v[48:51], v[158:161], v[194:197], v[48:51]
	v_mfma_f32_16x16x32_bf16 v[36:39], v[150:153], v[202:205], v[36:39]
	v_mfma_f32_16x16x32_bf16 v[32:35], v[158:161], v[202:205], v[32:35]
	v_mfma_f32_16x16x32_bf16 v[20:23], v[150:153], v[210:213], v[20:23]
	v_mfma_f32_16x16x32_bf16 v[16:19], v[158:161], v[210:213], v[16:19]
	v_mfma_f32_16x16x32_bf16 v[60:63], v[154:157], v[186:189], v[60:63]
	v_mfma_f32_16x16x32_bf16 v[56:59], v[162:165], v[186:189], v[56:59]
	v_mfma_f32_16x16x32_bf16 v[52:55], v[154:157], v[198:201], v[52:55]
	v_mfma_f32_16x16x32_bf16 v[48:51], v[162:165], v[198:201], v[48:51]
	v_mfma_f32_16x16x32_bf16 v[36:39], v[154:157], v[206:209], v[36:39]
	v_mfma_f32_16x16x32_bf16 v[32:35], v[162:165], v[206:209], v[32:35]
	v_mfma_f32_16x16x32_bf16 v[20:23], v[154:157], v[214:217], v[20:23]
	v_mfma_f32_16x16x32_bf16 v[16:19], v[162:165], v[214:217], v[16:19]
	s_setprio 0
	s_setprio 1
	v_mfma_f32_16x16x32_bf16 v[44:47], v[166:169], v[182:185], v[44:47]
	v_mfma_f32_16x16x32_bf16 v[40:43], v[174:177], v[182:185], v[40:43]
	v_mfma_f32_16x16x32_bf16 v[28:31], v[166:169], v[194:197], v[28:31]
	v_mfma_f32_16x16x32_bf16 v[24:27], v[174:177], v[194:197], v[24:27]
	v_mfma_f32_16x16x32_bf16 v[12:15], v[166:169], v[202:205], v[12:15]
	v_mfma_f32_16x16x32_bf16 v[8:11], v[174:177], v[202:205], v[8:11]
	v_mfma_f32_16x16x32_bf16 v[4:7], v[166:169], v[210:213], v[4:7]
	v_mfma_f32_16x16x32_bf16 v[0:3], v[174:177], v[210:213], v[0:3]
	v_mfma_f32_16x16x32_bf16 v[44:47], v[170:173], v[186:189], v[44:47]
	v_mfma_f32_16x16x32_bf16 v[40:43], v[178:181], v[186:189], v[40:43]
	v_mfma_f32_16x16x32_bf16 v[28:31], v[170:173], v[198:201], v[28:31]
	v_mfma_f32_16x16x32_bf16 v[24:27], v[178:181], v[198:201], v[24:27]
	v_mfma_f32_16x16x32_bf16 v[12:15], v[170:173], v[206:209], v[12:15]
	v_mfma_f32_16x16x32_bf16 v[8:11], v[178:181], v[206:209], v[8:11]
	v_mfma_f32_16x16x32_bf16 v[4:7], v[170:173], v[214:217], v[4:7]
	v_mfma_f32_16x16x32_bf16 v[0:3], v[178:181], v[214:217], v[0:3]
	s_setprio 0
	s_barrier
	s_add_i32 s58, 0, 0x18000
	s_add_i32 s59, 0, 0x1c000
	v_add_u32_e32 v162, s58, v145
	v_add_u32_e32 v178, s59, v145
	ds_read_b128 v[150:153], v162
	ds_read_b128 v[154:157], v162 offset:1024
	ds_read_b128 v[158:161], v162 offset:2048
	ds_read_b128 v[162:165], v162 offset:3072
	ds_read_b128 v[166:169], v178
	ds_read_b128 v[170:173], v178 offset:1024
	ds_read_b128 v[174:177], v178 offset:2048
	ds_read_b128 v[178:181], v178 offset:3072
	s_add_u32 s38, s38, 0x80000
	s_addc_u32 s39, s39, 0
	s_mov_b32 m0, s42
	v_lshl_add_u64 v[224:225], s[38:39], 0, v[134:135]
	ds_read_b128 v[182:185], v149 offset:32768
	ds_read_b128 v[186:189], v149 offset:33792
	ds_read_b128 v[194:197], v149 offset:34816
	ds_read_b128 v[198:201], v149 offset:35840
	ds_read_b128 v[202:205], v149 offset:36864
	ds_read_b128 v[206:209], v149 offset:37888
	ds_read_b128 v[210:213], v149 offset:38912
	ds_read_b128 v[214:217], v149 offset:39936
	global_load_lds_dwordx4 v[224:225], off
	v_lshl_add_u64 v[224:225], s[38:39], 0, v[130:131]
	s_mov_b32 m0, s43
	s_nop 0
	global_load_lds_dwordx4 v[224:225], off
	s_waitcnt vmcnt(8)
	s_waitcnt lgkmcnt(0)
	s_barrier
	s_setprio 1
	s_waitcnt lgkmcnt(0)
	v_mfma_f32_16x16x32_bf16 v[124:127], v[150:153], v[182:185], v[124:127]
	v_mfma_f32_16x16x32_bf16 v[120:123], v[158:161], v[182:185], v[120:123]
	v_mfma_f32_16x16x32_bf16 v[116:119], v[150:153], v[194:197], v[116:119]
	v_mfma_f32_16x16x32_bf16 v[112:115], v[158:161], v[194:197], v[112:115]
	v_mfma_f32_16x16x32_bf16 v[100:103], v[150:153], v[202:205], v[100:103]
	v_mfma_f32_16x16x32_bf16 v[96:99], v[158:161], v[202:205], v[96:99]
	v_mfma_f32_16x16x32_bf16 v[84:87], v[150:153], v[210:213], v[84:87]
	v_mfma_f32_16x16x32_bf16 v[80:83], v[158:161], v[210:213], v[80:83]
	v_mfma_f32_16x16x32_bf16 v[124:127], v[154:157], v[186:189], v[124:127]
	v_mfma_f32_16x16x32_bf16 v[120:123], v[162:165], v[186:189], v[120:123]
	v_mfma_f32_16x16x32_bf16 v[116:119], v[154:157], v[198:201], v[116:119]
	v_mfma_f32_16x16x32_bf16 v[112:115], v[162:165], v[198:201], v[112:115]
	v_mfma_f32_16x16x32_bf16 v[100:103], v[154:157], v[206:209], v[100:103]
	v_mfma_f32_16x16x32_bf16 v[96:99], v[162:165], v[206:209], v[96:99]
	v_mfma_f32_16x16x32_bf16 v[84:87], v[154:157], v[214:217], v[84:87]
	v_mfma_f32_16x16x32_bf16 v[80:83], v[162:165], v[214:217], v[80:83]
	s_setprio 0
	s_setprio 1
	v_mfma_f32_16x16x32_bf16 v[108:111], v[166:169], v[182:185], v[108:111]
	v_mfma_f32_16x16x32_bf16 v[104:107], v[174:177], v[182:185], v[104:107]
	v_mfma_f32_16x16x32_bf16 v[92:95], v[166:169], v[194:197], v[92:95]
	v_mfma_f32_16x16x32_bf16 v[88:91], v[174:177], v[194:197], v[88:91]
	v_mfma_f32_16x16x32_bf16 v[76:79], v[166:169], v[202:205], v[76:79]
	v_mfma_f32_16x16x32_bf16 v[72:75], v[174:177], v[202:205], v[72:75]
	v_mfma_f32_16x16x32_bf16 v[68:71], v[166:169], v[210:213], v[68:71]
	v_mfma_f32_16x16x32_bf16 v[64:67], v[174:177], v[210:213], v[64:67]
	v_mfma_f32_16x16x32_bf16 v[108:111], v[170:173], v[186:189], v[108:111]
	v_mfma_f32_16x16x32_bf16 v[104:107], v[178:181], v[186:189], v[104:107]
	v_mfma_f32_16x16x32_bf16 v[92:95], v[170:173], v[198:201], v[92:95]
	v_mfma_f32_16x16x32_bf16 v[88:91], v[178:181], v[198:201], v[88:91]
	v_mfma_f32_16x16x32_bf16 v[76:79], v[170:173], v[206:209], v[76:79]
	v_mfma_f32_16x16x32_bf16 v[72:75], v[178:181], v[206:209], v[72:75]
	v_mfma_f32_16x16x32_bf16 v[68:71], v[170:173], v[214:217], v[68:71]
	v_mfma_f32_16x16x32_bf16 v[64:67], v[178:181], v[214:217], v[64:67]
	s_setprio 0
	s_barrier
; #define PG8_STAGE(bufoff, gbase, voff) do { _Pragma("unroll") for (int _i = 0; _i < 2; ++_i) \
;         __builtin_amdgcn_global_load_lds((const unsigned*)((const char*)(gbase) + (voff)[_i]), (PG8_LAS unsigned*)(lds + (bufoff) + ldsw + _i * 8192), 16, 0, 0); } while (0)
; #define PG8_LDA(dst, b, h) do { _Pragma("unroll") for (int m = 0; m < 4; ++m) _Pragma("unroll") for (int k = 0; k < 2; ++k) dst[m][k] = *(const PG8_LAS bf16x8*)(lds + PG8_SA(b, h) + aoff + m * 2048 + k * 1024); } while (0)
; #define PG8_MMA(ai, bj, At, Bt) do { __builtin_amdgcn_s_setprio(1); _Pragma("unroll") for (int m = 0; m < 4; ++m) _Pragma("unroll") for (int n = 0; n < 2; ++n) _Pragma("unroll") for (int k = 0; k < 2; ++k) \
;         acc[ai][bj][m][n] = __builtin_amdgcn_mfma_f32_16x16x32_bf16(Bt[n][k], At[m][k], acc[ai][bj][m][n], 0, 0, 0); __builtin_amdgcn_s_setprio(0); } while (0)
; #define PG8_WAIT_V(n) asm volatile("s_waitcnt vmcnt(" #n ")" ::: "memory")
; #define PG8_WAIT_L(n) asm volatile("s_waitcnt lgkmcnt(" #n ")" ::: "memory")
; #define PG8_BAR __builtin_amdgcn_s_barrier()
; #define PG8_SCHED __builtin_amdgcn_sched_barrier(0)
; template <class Epi, class Sched, bool ALIGN_EPI = false, bool SP2 = false>
; __device__ __forceinline__ void gemm_phase(PG8_LAS unsigned char* lds, const Gemm g, const Sched& S, const Epi& E) {
;     ...
;             PG8_LDA(At, 1, 1); PG8_STAGE(PG8_SB(1, 0), b3, voffB); PG8_STAGE(PG8_SB(1, 1), b3 + hstep, voffB); PG8_STAGE(PG8_SA(1, 0), a3, voffA);
;             PG8_WAIT_V(8); PG8_WAIT_L(0); PG8_BAR; PG8_MMA(1, 0, At, B0); PG8_MMA(1, 1, At, B1); PG8_BAR; PG8_SCHED;
;     ...
;         if constexpr (ALIGN_EPI) { if (wr == 0) PG8_BAR; }
	s_add_i32 s38, s58, s33
	v_lshl_add_u64 v[190:191], v[190:191], 0, s[6:7]
	s_mov_b32 m0, s38
	ds_read_b128 v[182:185], v149 offset:49152
	ds_read_b128 v[186:189], v149 offset:50176
	ds_read_b128 v[194:197], v149 offset:51200
	ds_read_b128 v[198:201], v149 offset:52224
	ds_read_b128 v[202:205], v149 offset:53248
	ds_read_b128 v[206:209], v149 offset:54272
	ds_read_b128 v[210:213], v149 offset:55296
	ds_read_b128 v[214:217], v149 offset:56320
	global_load_lds_dwordx4 v[190:191], off
	s_add_i32 m0, s38, 0x2000
	s_add_u32 s36, s36, 0x80080
	v_lshl_add_u64 v[190:191], v[218:219], 0, s[6:7]
	s_addc_u32 s37, s37, 0
	s_add_i32 s38, s59, s33
	global_load_lds_dwordx4 v[190:191], off
	v_lshl_add_u64 v[190:191], s[36:37], 0, v[132:133]
	s_mov_b32 m0, s38
	s_nop 0
	global_load_lds_dwordx4 v[190:191], off
	v_lshl_add_u64 v[190:191], s[36:37], 0, v[128:129]
	s_add_i32 m0, s38, 0x2000
	s_nop 0
	global_load_lds_dwordx4 v[190:191], off
	v_lshl_add_u64 v[190:191], v[220:221], 0, s[6:7]
	s_mov_b32 m0, s45
	s_nop 0
	global_load_lds_dwordx4 v[190:191], off
	v_lshl_add_u64 v[190:191], v[222:223], 0, s[6:7]
	s_mov_b32 m0, s46
	s_nop 0
	global_load_lds_dwordx4 v[190:191], off
	s_waitcnt vmcnt(8)
	s_waitcnt lgkmcnt(0)
	s_barrier
	s_setprio 1
	s_waitcnt lgkmcnt(0)
	v_mfma_f32_16x16x32_bf16 v[60:63], v[150:153], v[182:185], v[60:63]
	v_mfma_f32_16x16x32_bf16 v[56:59], v[158:161], v[182:185], v[56:59]
	v_mfma_f32_16x16x32_bf16 v[52:55], v[150:153], v[194:197], v[52:55]
	v_mfma_f32_16x16x32_bf16 v[48:51], v[158:161], v[194:197], v[48:51]
	v_mfma_f32_16x16x32_bf16 v[36:39], v[150:153], v[202:205], v[36:39]
	v_mfma_f32_16x16x32_bf16 v[32:35], v[158:161], v[202:205], v[32:35]
	v_mfma_f32_16x16x32_bf16 v[20:23], v[150:153], v[210:213], v[20:23]
	v_mfma_f32_16x16x32_bf16 v[16:19], v[158:161], v[210:213], v[16:19]
	v_mfma_f32_16x16x32_bf16 v[60:63], v[154:157], v[186:189], v[60:63]
	v_mfma_f32_16x16x32_bf16 v[56:59], v[162:165], v[186:189], v[56:59]
	v_mfma_f32_16x16x32_bf16 v[52:55], v[154:157], v[198:201], v[52:55]
	v_mfma_f32_16x16x32_bf16 v[48:51], v[162:165], v[198:201], v[48:51]
	v_mfma_f32_16x16x32_bf16 v[36:39], v[154:157], v[206:209], v[36:39]
	v_mfma_f32_16x16x32_bf16 v[32:35], v[162:165], v[206:209], v[32:35]
	v_mfma_f32_16x16x32_bf16 v[20:23], v[154:157], v[214:217], v[20:23]
	v_mfma_f32_16x16x32_bf16 v[16:19], v[162:165], v[214:217], v[16:19]
	s_setprio 0
	s_setprio 1
	v_mfma_f32_16x16x32_bf16 v[44:47], v[166:169], v[182:185], v[44:47]
	v_mfma_f32_16x16x32_bf16 v[40:43], v[174:177], v[182:185], v[40:43]
	v_mfma_f32_16x16x32_bf16 v[28:31], v[166:169], v[194:197], v[28:31]
	v_mfma_f32_16x16x32_bf16 v[24:27], v[174:177], v[194:197], v[24:27]
	v_mfma_f32_16x16x32_bf16 v[12:15], v[166:169], v[202:205], v[12:15]
	v_mfma_f32_16x16x32_bf16 v[8:11], v[174:177], v[202:205], v[8:11]
	v_mfma_f32_16x16x32_bf16 v[4:7], v[166:169], v[210:213], v[4:7]
	v_mfma_f32_16x16x32_bf16 v[0:3], v[174:177], v[210:213], v[0:3]
	v_mfma_f32_16x16x32_bf16 v[44:47], v[170:173], v[186:189], v[44:47]
	v_mfma_f32_16x16x32_bf16 v[40:43], v[178:181], v[186:189], v[40:43]
	v_mfma_f32_16x16x32_bf16 v[28:31], v[170:173], v[198:201], v[28:31]
	v_mfma_f32_16x16x32_bf16 v[24:27], v[178:181], v[198:201], v[24:27]
	v_mfma_f32_16x16x32_bf16 v[12:15], v[170:173], v[206:209], v[12:15]
	v_mfma_f32_16x16x32_bf16 v[8:11], v[178:181], v[206:209], v[8:11]
	v_mfma_f32_16x16x32_bf16 v[4:7], v[170:173], v[214:217], v[4:7]
	v_mfma_f32_16x16x32_bf16 v[0:3], v[178:181], v[214:217], v[0:3]
	s_setprio 0
	s_barrier
	s_add_i32 s57, s57, 2
	s_add_u32 s34, s34, 0x100
	s_addc_u32 s35, s35, 0
	s_add_u32 s55, s55, 0x100
	s_addc_u32 s56, s56, 0
	s_cmp_gt_u32 s57, 29
	s_cbranch_scc0 .LBB0_277
	s_and_b64 vcc, exec, s[8:9]
	s_cbranch_vccz .LBB0_280
	s_barrier

; #define PG8_WAIT_V(n) asm volatile("s_waitcnt vmcnt(" #n ")" ::: "memory")
; #define PG8_BAR __builtin_amdgcn_s_barrier()
; template <class Epi, class Sched, bool ALIGN_EPI = false, bool SP2 = false>
; __device__ __forceinline__ void gemm_phase(PG8_LAS unsigned char* lds, const Gemm g, const Sched& S, const Epi& E) {
;     ...
;     PG8_WAIT_V(0);
;     if constexpr (!ALIGN_EPI) { if (wr == 0) PG8_BAR; }
;     PG8_BAR;
; __device__ __forceinline__ void xcd_barrier(const XcdBarrier& b) {
;     asm volatile("s_waitcnt vmcnt(0)" ::: "memory");
;     __syncthreads();
;     if (threadIdx.x == 0) {
;         unsigned* bar = b.bar;
;         __builtin_amdgcn_s_waitcnt(0);
;         unsigned nloc = b.st[0], nx = b.st[1];
;         if (nloc == 0u) { xcd_barrier_complete(bar, b.x, nloc, nx); b.st[0] = nloc; b.st[1] = nx; }
.LBB0_283:
	s_waitcnt vmcnt(0)
	s_barrier
.LBB0_284:
	s_waitcnt vmcnt(0)
	s_waitcnt vmcnt(0)
	s_barrier
	s_and_saveexec_b64 s[0:1], s[78:79]
	s_cbranch_execz .LBB0_336
	s_add_i32 s2, 0, 0x20040
	v_mov_b32_e32 v0, s2
	s_waitcnt vmcnt(0) expcnt(0) lgkmcnt(0)
	ds_read_b32 v2, v0
	s_add_i32 s2, 0, 0x20044
	v_mov_b32_e32 v0, s2
	ds_read_b32 v0, v0
	s_waitcnt lgkmcnt(1)
	v_cmp_ne_u32_e32 vcc, 0, v2
	s_cbranch_vccnz .LBB0_300
	s_add_u32 s4, s90, 0x1200
	s_addc_u32 s5, s91, 0
	s_add_u32 s6, s90, 0x1400
	s_addc_u32 s7, s91, 0
	s_add_u32 s8, s90, 0x1500
	s_addc_u32 s9, s91, 0
	s_add_u32 s20, s90, 0x1600
	s_addc_u32 s21, s91, 0
	s_add_u32 s22, s90, 0x1700
	s_addc_u32 s23, s91, 0
	s_add_u32 s26, s90, 0x1800
	s_addc_u32 s27, s91, 0
	s_add_u32 s28, s90, 0x1900
	s_addc_u32 s29, s91, 0
	s_add_u32 s30, s90, 0x1a00
	s_addc_u32 s31, s91, 0
	s_add_u32 s34, s90, 0x1b00
	s_addc_u32 s35, s91, 0
	s_add_u32 s36, s90, 0x1c00
	s_addc_u32 s37, s91, 0
	s_add_u32 s38, s90, 0x1d00
	s_addc_u32 s39, s91, 0
	s_add_u32 s40, s90, 0x1e00
	s_addc_u32 s41, s91, 0
	s_add_u32 s42, s90, 0x1f00
	s_addc_u32 s43, s91, 0
	s_add_u32 s44, s90, 0x2000
	s_addc_u32 s45, s91, 0
	s_add_u32 s46, s90, 0x2100
	s_addc_u32 s47, s91, 0
	s_add_u32 s48, s90, 0x2200
	s_addc_u32 s49, s91, 0
	s_mul_i32 s2, s77, s71
	s_add_u32 s50, s90, 0x2300
	s_mul_i32 s2, s2, s76
	s_addc_u32 s51, s91, 0
	s_mov_b32 s3, 1
	v_mov_b32_e32 v16, 0
	s_branch .LBB0_288

; #define PG8_STAGE(bufoff, gbase, voff) do { _Pragma("unroll") for (int _i = 0; _i < 2; ++_i) \
;         __builtin_amdgcn_global_load_lds((const unsigned*)((const char*)(gbase) + (voff)[_i]), (PG8_LAS unsigned*)(lds + (bufoff) + ldsw + _i * 8192), 16, 0, 0); } while (0)
; #define PG8_LDA(dst, b, h) do { _Pragma("unroll") for (int m = 0; m < 4; ++m) _Pragma("unroll") for (int k = 0; k < 2; ++k) dst[m][k] = *(const PG8_LAS bf16x8*)(lds + PG8_SA(b, h) + aoff + m * 2048 + k * 1024); } while (0)
; #define PG8_LDB(dst, b, h) do { _Pragma("unroll") for (int n = 0; n < 2; ++n) _Pragma("unroll") for (int k = 0; k < 2; ++k) dst[n][k] = *(const PG8_LAS bf16x8*)(lds + PG8_SB(b, h) + boff + n * 2048 + k * 1024); } while (0)
; #define PG8_MMA(ai, bj, At, Bt) do { __builtin_amdgcn_s_setprio(1); _Pragma("unroll") for (int m = 0; m < 4; ++m) _Pragma("unroll") for (int n = 0; n < 2; ++n) _Pragma("unroll") for (int k = 0; k < 2; ++k) \
;         acc[ai][bj][m][n] = __builtin_amdgcn_mfma_f32_16x16x32_bf16(Bt[n][k], At[m][k], acc[ai][bj][m][n], 0, 0, 0); __builtin_amdgcn_s_setprio(0); } while (0)
; #define PG8_WAIT_V(n) asm volatile("s_waitcnt vmcnt(" #n ")" ::: "memory")
; #define PG8_BAR __builtin_amdgcn_s_barrier()
; template <class Epi, class Sched, bool ALIGN_EPI = false, bool SP2 = false>
; __device__ __forceinline__ void gemm_phase(PG8_LAS unsigned char* lds, const Gemm g, const Sched& S, const Epi& E) {
;     ...
;         for (int t = 0; t < nt; t += 2) {
;             const bool last = (t == nt - 2);
;             const char* a1 = cA + (size_t)(t + 1) * kstep;
;             const char* a2 = last ? nA : cA + (size_t)(t + 2) * kstep; const char* b2 = last ? nB : cB + (size_t)(t + 2) * kstep;
;             const char* a3 = a2 + kstep; const char* b3 = b2 + kstep;
;             if (last && has_next) S.a_ready(nxt);
;             if constexpr (SP2) {
;             PG8_LDB(B0, 0, 0); PG8_LDB(B1, 0, 1); PG8_SCHED; PG8_LDA(At, 0, 0); PG8_STAGE(PG8_SA(1, 1), a1 + hstep, voffA);
;             PG8_WAIT_V(8); PG8_WAIT_L(0); PG8_BAR; PG8_MMA(0, 0, At, B0); PG8_MMA(0, 1, At, B1); PG8_BAR; PG8_SCHED;
;             PG8_LDA(At, 0, 1); PG8_STAGE(PG8_SB(0, 0), b2, voffB); PG8_STAGE(PG8_SB(0, 1), b2 + hstep, voffB); PG8_STAGE(PG8_SA(0, 0), a2, voffA);
;             PG8_WAIT_V(8); PG8_WAIT_L(0); PG8_BAR; PG8_MMA(1, 0, At, B0); PG8_MMA(1, 1, At, B1); PG8_BAR; PG8_SCHED;
.LBB0_402:
	ds_read_b128 v[152:155], v171
	ds_read_b128 v[156:159], v171 offset:1024
	ds_read_b128 v[160:163], v171 offset:2048
	ds_read_b128 v[164:167], v171 offset:3072
	ds_read_b128 v[174:177], v172
	ds_read_b128 v[178:181], v172 offset:1024
	ds_read_b128 v[182:185], v172 offset:2048
	ds_read_b128 v[186:189], v172 offset:3072
	s_add_u32 s38, s36, 0xfffe0080
	s_addc_u32 s39, s37, -1
	s_cmp_eq_u32 s60, 4
	s_cselect_b32 s41, s1, s39
	s_cselect_b32 s40, s3, s38
	s_cselect_b32 s39, s27, s59
	s_cselect_b32 s38, s29, s33
	v_lshl_add_u64 v[168:169], s[36:37], 0, v[144:145]
	s_add_i32 m0, s46, 0xc000
	ds_read_b128 v[194:197], v173
	ds_read_b128 v[198:201], v173 offset:1024
	ds_read_b128 v[202:205], v173 offset:2048
	ds_read_b128 v[206:209], v173 offset:3072
	ds_read_b128 v[210:213], v173 offset:4096
	ds_read_b128 v[214:217], v173 offset:5120
	ds_read_b128 v[218:221], v173 offset:6144
	ds_read_b128 v[222:225], v173 offset:7168
	global_load_lds_dwordx4 v[168:169], off
	v_lshl_add_u64 v[168:169], s[36:37], 0, v[146:147]
	s_add_i32 m0, s46, 0xe000
	s_nop 0
	global_load_lds_dwordx4 v[168:169], off
	s_waitcnt vmcnt(8)
	s_waitcnt lgkmcnt(0)
	s_barrier
	s_setprio 1
	s_waitcnt lgkmcnt(0)
	v_mfma_f32_16x16x32_bf16 v[124:127], v[152:155], v[194:197], v[124:127]
	v_mfma_f32_16x16x32_bf16 v[120:123], v[160:163], v[194:197], v[120:123]
	v_mfma_f32_16x16x32_bf16 v[116:119], v[152:155], v[202:205], v[116:119]
	v_mfma_f32_16x16x32_bf16 v[108:111], v[160:163], v[202:205], v[108:111]
	v_mfma_f32_16x16x32_bf16 v[100:103], v[152:155], v[210:213], v[100:103]
	v_mfma_f32_16x16x32_bf16 v[92:95], v[160:163], v[210:213], v[92:95]
	v_mfma_f32_16x16x32_bf16 v[84:87], v[152:155], v[218:221], v[84:87]
	v_mfma_f32_16x16x32_bf16 v[76:79], v[160:163], v[218:221], v[76:79]
	v_mfma_f32_16x16x32_bf16 v[124:127], v[156:159], v[198:201], v[124:127]
	v_mfma_f32_16x16x32_bf16 v[120:123], v[164:167], v[198:201], v[120:123]
	v_mfma_f32_16x16x32_bf16 v[116:119], v[156:159], v[206:209], v[116:119]
	v_mfma_f32_16x16x32_bf16 v[108:111], v[164:167], v[206:209], v[108:111]
	v_mfma_f32_16x16x32_bf16 v[100:103], v[156:159], v[214:217], v[100:103]
	v_mfma_f32_16x16x32_bf16 v[92:95], v[164:167], v[214:217], v[92:95]
	v_mfma_f32_16x16x32_bf16 v[84:87], v[156:159], v[222:225], v[84:87]
	v_mfma_f32_16x16x32_bf16 v[76:79], v[164:167], v[222:225], v[76:79]
	s_setprio 0
	s_setprio 1
	v_mfma_f32_16x16x32_bf16 v[112:115], v[174:177], v[194:197], v[112:115]
	v_mfma_f32_16x16x32_bf16 v[104:107], v[182:185], v[194:197], v[104:107]
	v_mfma_f32_16x16x32_bf16 v[96:99], v[174:177], v[202:205], v[96:99]
	v_mfma_f32_16x16x32_bf16 v[88:91], v[182:185], v[202:205], v[88:91]
	v_mfma_f32_16x16x32_bf16 v[80:83], v[174:177], v[210:213], v[80:83]
	v_mfma_f32_16x16x32_bf16 v[72:75], v[182:185], v[210:213], v[72:75]
	v_mfma_f32_16x16x32_bf16 v[68:71], v[174:177], v[218:221], v[68:71]
	v_mfma_f32_16x16x32_bf16 v[64:67], v[182:185], v[218:221], v[64:67]
	v_mfma_f32_16x16x32_bf16 v[112:115], v[178:181], v[198:201], v[112:115]
	v_mfma_f32_16x16x32_bf16 v[104:107], v[186:189], v[198:201], v[104:107]
	v_mfma_f32_16x16x32_bf16 v[96:99], v[178:181], v[206:209], v[96:99]
	v_mfma_f32_16x16x32_bf16 v[88:91], v[186:189], v[206:209], v[88:91]
	v_mfma_f32_16x16x32_bf16 v[80:83], v[178:181], v[214:217], v[80:83]
	v_mfma_f32_16x16x32_bf16 v[72:75], v[186:189], v[214:217], v[72:75]
	v_mfma_f32_16x16x32_bf16 v[68:71], v[178:181], v[222:225], v[68:71]
	v_mfma_f32_16x16x32_bf16 v[64:67], v[186:189], v[222:225], v[64:67]
	s_setprio 0
	s_barrier
	s_add_i32 s61, s55, s23
	v_lshl_add_u64 v[168:169], s[38:39], 0, v[132:133]
	s_mov_b32 m0, s61
	ds_read_b128 v[194:197], v173 offset:16384
	ds_read_b128 v[198:201], v173 offset:17408
	ds_read_b128 v[202:205], v173 offset:18432
	ds_read_b128 v[206:209], v173 offset:19456
	ds_read_b128 v[210:213], v173 offset:20480
	ds_read_b128 v[214:217], v173 offset:21504
	ds_read_b128 v[218:221], v173 offset:22528
	ds_read_b128 v[222:225], v173 offset:23552
	global_load_lds_dwordx4 v[168:169], off
	s_add_i32 m0, s61, 0x2000
	s_add_u32 s62, s38, 0x20000
	v_lshl_add_u64 v[190:191], s[38:39], 0, v[128:129]
	s_addc_u32 s63, s39, 0
	s_add_i32 s61, s56, s23
	global_load_lds_dwordx4 v[190:191], off
	v_lshl_add_u64 v[226:227], s[62:63], 0, v[132:133]
	s_mov_b32 m0, s61
	v_lshl_add_u64 v[228:229], s[40:41], 0, v[130:131]
	global_load_lds_dwordx4 v[226:227], off
	v_lshl_add_u64 v[226:227], s[62:63], 0, v[128:129]
	s_add_i32 m0, s61, 0x2000
	s_nop 0
	global_load_lds_dwordx4 v[226:227], off
	v_lshl_add_u64 v[226:227], s[40:41], 0, v[134:135]
	s_mov_b32 m0, s46
	s_nop 0
	global_load_lds_dwordx4 v[226:227], off
	s_mov_b32 m0, s47
	s_nop 0
	global_load_lds_dwordx4 v[228:229], off
	s_waitcnt vmcnt(8)
	s_waitcnt lgkmcnt(0)
	s_barrier
; #define PG8_STAGE(bufoff, gbase, voff) do { _Pragma("unroll") for (int _i = 0; _i < 2; ++_i) \
;         __builtin_amdgcn_global_load_lds((const unsigned*)((const char*)(gbase) + (voff)[_i]), (PG8_LAS unsigned*)(lds + (bufoff) + ldsw + _i * 8192), 16, 0, 0); } while (0)
; #define PG8_LDA(dst, b, h) do { _Pragma("unroll") for (int m = 0; m < 4; ++m) _Pragma("unroll") for (int k = 0; k < 2; ++k) dst[m][k] = *(const PG8_LAS bf16x8*)(lds + PG8_SA(b, h) + aoff + m * 2048 + k * 1024); } while (0)
; #define PG8_LDB(dst, b, h) do { _Pragma("unroll") for (int n = 0; n < 2; ++n) _Pragma("unroll") for (int k = 0; k < 2; ++k) dst[n][k] = *(const PG8_LAS bf16x8*)(lds + PG8_SB(b, h) + boff + n * 2048 + k * 1024); } while (0)
; #define PG8_MMA(ai, bj, At, Bt) do { __builtin_amdgcn_s_setprio(1); _Pragma("unroll") for (int m = 0; m < 4; ++m) _Pragma("unroll") for (int n = 0; n < 2; ++n) _Pragma("unroll") for (int k = 0; k < 2; ++k) \
;         acc[ai][bj][m][n] = __builtin_amdgcn_mfma_f32_16x16x32_bf16(Bt[n][k], At[m][k], acc[ai][bj][m][n], 0, 0, 0); __builtin_amdgcn_s_setprio(0); } while (0)
; #define PG8_WAIT_V(n) asm volatile("s_waitcnt vmcnt(" #n ")" ::: "memory")
; #define PG8_WAIT_L(n) asm volatile("s_waitcnt lgkmcnt(" #n ")" ::: "memory")
; #define PG8_BAR __builtin_amdgcn_s_barrier()
; #define PG8_SCHED __builtin_amdgcn_sched_barrier(0)
; template <class Epi, class Sched, bool ALIGN_EPI = false, bool SP2 = false>
; __device__ __forceinline__ void gemm_phase(PG8_LAS unsigned char* lds, const Gemm g, const Sched& S, const Epi& E) {
;     ...
;             PG8_WAIT_V(8); PG8_WAIT_L(0); PG8_BAR; PG8_MMA(1, 0, At, B0); PG8_MMA(1, 1, At, B1); PG8_BAR; PG8_SCHED;
;             PG8_LDB(B0, 1, 0); PG8_LDB(B1, 1, 1); PG8_SCHED; PG8_LDA(At, 1, 0); PG8_STAGE(PG8_SA(0, 1), a2 + hstep, voffA);
;             PG8_WAIT_V(8); PG8_WAIT_L(0); PG8_BAR; PG8_MMA(0, 0, At, B0); PG8_MMA(0, 1, At, B1); PG8_BAR; PG8_SCHED;
	s_setprio 1
	s_waitcnt lgkmcnt(0)
	v_mfma_f32_16x16x32_bf16 v[60:63], v[152:155], v[194:197], v[60:63]
	v_mfma_f32_16x16x32_bf16 v[56:59], v[160:163], v[194:197], v[56:59]
	v_mfma_f32_16x16x32_bf16 v[52:55], v[152:155], v[202:205], v[52:55]
	v_mfma_f32_16x16x32_bf16 v[44:47], v[160:163], v[202:205], v[44:47]
	v_mfma_f32_16x16x32_bf16 v[36:39], v[152:155], v[210:213], v[36:39]
	v_mfma_f32_16x16x32_bf16 v[28:31], v[160:163], v[210:213], v[28:31]
	v_mfma_f32_16x16x32_bf16 v[20:23], v[152:155], v[218:221], v[20:23]
	v_mfma_f32_16x16x32_bf16 v[12:15], v[160:163], v[218:221], v[12:15]
	v_mfma_f32_16x16x32_bf16 v[60:63], v[156:159], v[198:201], v[60:63]
	v_mfma_f32_16x16x32_bf16 v[56:59], v[164:167], v[198:201], v[56:59]
	v_mfma_f32_16x16x32_bf16 v[52:55], v[156:159], v[206:209], v[52:55]
	v_mfma_f32_16x16x32_bf16 v[44:47], v[164:167], v[206:209], v[44:47]
	v_mfma_f32_16x16x32_bf16 v[36:39], v[156:159], v[214:217], v[36:39]
	v_mfma_f32_16x16x32_bf16 v[28:31], v[164:167], v[214:217], v[28:31]
	v_mfma_f32_16x16x32_bf16 v[20:23], v[156:159], v[222:225], v[20:23]
	v_mfma_f32_16x16x32_bf16 v[12:15], v[164:167], v[222:225], v[12:15]
	s_setprio 0
	s_setprio 1
	v_mfma_f32_16x16x32_bf16 v[48:51], v[174:177], v[194:197], v[48:51]
	v_mfma_f32_16x16x32_bf16 v[40:43], v[182:185], v[194:197], v[40:43]
	v_mfma_f32_16x16x32_bf16 v[32:35], v[174:177], v[202:205], v[32:35]
	v_mfma_f32_16x16x32_bf16 v[24:27], v[182:185], v[202:205], v[24:27]
	v_mfma_f32_16x16x32_bf16 v[16:19], v[174:177], v[210:213], v[16:19]
	v_mfma_f32_16x16x32_bf16 v[8:11], v[182:185], v[210:213], v[8:11]
	v_mfma_f32_16x16x32_bf16 v[4:7], v[174:177], v[218:221], v[4:7]
	v_mfma_f32_16x16x32_bf16 v[0:3], v[182:185], v[218:221], v[0:3]
	v_mfma_f32_16x16x32_bf16 v[48:51], v[178:181], v[198:201], v[48:51]
	v_mfma_f32_16x16x32_bf16 v[40:43], v[186:189], v[198:201], v[40:43]
	v_mfma_f32_16x16x32_bf16 v[32:35], v[178:181], v[206:209], v[32:35]
	v_mfma_f32_16x16x32_bf16 v[24:27], v[186:189], v[206:209], v[24:27]
	v_mfma_f32_16x16x32_bf16 v[16:19], v[178:181], v[214:217], v[16:19]
	v_mfma_f32_16x16x32_bf16 v[8:11], v[186:189], v[214:217], v[8:11]
	v_mfma_f32_16x16x32_bf16 v[4:7], v[178:181], v[222:225], v[4:7]
	v_mfma_f32_16x16x32_bf16 v[0:3], v[186:189], v[222:225], v[0:3]
	s_setprio 0
	s_barrier
	s_add_i32 s61, 0, 0x18000
	v_add_u32_e32 v136, s61, v170
	s_add_i32 s62, 0, 0x1c000
	ds_read_b128 v[152:155], v136
	ds_read_b128 v[156:159], v136 offset:1024
	ds_read_b128 v[160:163], v136 offset:2048
	ds_read_b128 v[164:167], v136 offset:3072
	v_add_u32_e32 v136, s62, v170
	ds_read_b128 v[174:177], v136
	ds_read_b128 v[178:181], v136 offset:1024
	ds_read_b128 v[182:185], v136 offset:2048
	ds_read_b128 v[186:189], v136 offset:3072
	s_add_u32 s40, s40, 0x20000
	s_addc_u32 s41, s41, 0
	s_mov_b32 m0, s48
	v_lshl_add_u64 v[230:231], s[40:41], 0, v[134:135]
	ds_read_b128 v[194:197], v173 offset:32768
	ds_read_b128 v[198:201], v173 offset:33792
	ds_read_b128 v[202:205], v173 offset:34816
	ds_read_b128 v[206:209], v173 offset:35840
	ds_read_b128 v[210:213], v173 offset:36864
	ds_read_b128 v[214:217], v173 offset:37888
	ds_read_b128 v[218:221], v173 offset:38912
	ds_read_b128 v[222:225], v173 offset:39936
	global_load_lds_dwordx4 v[230:231], off
	v_lshl_add_u64 v[230:231], s[40:41], 0, v[130:131]
	s_mov_b32 m0, s49
	s_nop 0
	global_load_lds_dwordx4 v[230:231], off
	s_waitcnt vmcnt(8)
	s_waitcnt lgkmcnt(0)
	s_barrier
	s_setprio 1
	s_waitcnt lgkmcnt(0)
	v_mfma_f32_16x16x32_bf16 v[124:127], v[152:155], v[194:197], v[124:127]
	v_mfma_f32_16x16x32_bf16 v[120:123], v[160:163], v[194:197], v[120:123]
	v_mfma_f32_16x16x32_bf16 v[116:119], v[152:155], v[202:205], v[116:119]
	v_mfma_f32_16x16x32_bf16 v[108:111], v[160:163], v[202:205], v[108:111]
	v_mfma_f32_16x16x32_bf16 v[100:103], v[152:155], v[210:213], v[100:103]
	v_mfma_f32_16x16x32_bf16 v[92:95], v[160:163], v[210:213], v[92:95]
	v_mfma_f32_16x16x32_bf16 v[84:87], v[152:155], v[218:221], v[84:87]
	v_mfma_f32_16x16x32_bf16 v[76:79], v[160:163], v[218:221], v[76:79]
	v_mfma_f32_16x16x32_bf16 v[124:127], v[156:159], v[198:201], v[124:127]
	v_mfma_f32_16x16x32_bf16 v[120:123], v[164:167], v[198:201], v[120:123]
	v_mfma_f32_16x16x32_bf16 v[116:119], v[156:159], v[206:209], v[116:119]
	v_mfma_f32_16x16x32_bf16 v[108:111], v[164:167], v[206:209], v[108:111]
	v_mfma_f32_16x16x32_bf16 v[100:103], v[156:159], v[214:217], v[100:103]
	v_mfma_f32_16x16x32_bf16 v[92:95], v[164:167], v[214:217], v[92:95]
	v_mfma_f32_16x16x32_bf16 v[84:87], v[156:159], v[222:225], v[84:87]
	v_mfma_f32_16x16x32_bf16 v[76:79], v[164:167], v[222:225], v[76:79]
	s_setprio 0
	s_setprio 1
	v_mfma_f32_16x16x32_bf16 v[112:115], v[174:177], v[194:197], v[112:115]
	v_mfma_f32_16x16x32_bf16 v[104:107], v[182:185], v[194:197], v[104:107]
	v_mfma_f32_16x16x32_bf16 v[96:99], v[174:177], v[202:205], v[96:99]
	v_mfma_f32_16x16x32_bf16 v[88:91], v[182:185], v[202:205], v[88:91]
	v_mfma_f32_16x16x32_bf16 v[80:83], v[174:177], v[210:213], v[80:83]
	v_mfma_f32_16x16x32_bf16 v[72:75], v[182:185], v[210:213], v[72:75]
	v_mfma_f32_16x16x32_bf16 v[68:71], v[174:177], v[218:221], v[68:71]
	v_mfma_f32_16x16x32_bf16 v[64:67], v[182:185], v[218:221], v[64:67]
	v_mfma_f32_16x16x32_bf16 v[112:115], v[178:181], v[198:201], v[112:115]
	v_mfma_f32_16x16x32_bf16 v[104:107], v[186:189], v[198:201], v[104:107]
	v_mfma_f32_16x16x32_bf16 v[96:99], v[178:181], v[206:209], v[96:99]
	v_mfma_f32_16x16x32_bf16 v[88:91], v[186:189], v[206:209], v[88:91]
	v_mfma_f32_16x16x32_bf16 v[80:83], v[178:181], v[214:217], v[80:83]
	v_mfma_f32_16x16x32_bf16 v[72:75], v[186:189], v[214:217], v[72:75]
	v_mfma_f32_16x16x32_bf16 v[68:71], v[178:181], v[222:225], v[68:71]
	v_mfma_f32_16x16x32_bf16 v[64:67], v[186:189], v[222:225], v[64:67]
	s_setprio 0
	s_barrier
; #define PG8_STAGE(bufoff, gbase, voff) do { _Pragma("unroll") for (int _i = 0; _i < 2; ++_i) \
;         __builtin_amdgcn_global_load_lds((const unsigned*)((const char*)(gbase) + (voff)[_i]), (PG8_LAS unsigned*)(lds + (bufoff) + ldsw + _i * 8192), 16, 0, 0); } while (0)
; #define PG8_LDA(dst, b, h) do { _Pragma("unroll") for (int m = 0; m < 4; ++m) _Pragma("unroll") for (int k = 0; k < 2; ++k) dst[m][k] = *(const PG8_LAS bf16x8*)(lds + PG8_SA(b, h) + aoff + m * 2048 + k * 1024); } while (0)
; #define PG8_MMA(ai, bj, At, Bt) do { __builtin_amdgcn_s_setprio(1); _Pragma("unroll") for (int m = 0; m < 4; ++m) _Pragma("unroll") for (int n = 0; n < 2; ++n) _Pragma("unroll") for (int k = 0; k < 2; ++k) \
;         acc[ai][bj][m][n] = __builtin_amdgcn_mfma_f32_16x16x32_bf16(Bt[n][k], At[m][k], acc[ai][bj][m][n], 0, 0, 0); __builtin_amdgcn_s_setprio(0); } while (0)
; #define PG8_WAIT_V(n) asm volatile("s_waitcnt vmcnt(" #n ")" ::: "memory")
; #define PG8_WAIT_L(n) asm volatile("s_waitcnt lgkmcnt(" #n ")" ::: "memory")
; #define PG8_BAR __builtin_amdgcn_s_barrier()
; #define PG8_SCHED __builtin_amdgcn_sched_barrier(0)
; template <class Epi, class Sched, bool ALIGN_EPI = false, bool SP2 = false>
; __device__ __forceinline__ void gemm_phase(PG8_LAS unsigned char* lds, const Gemm g, const Sched& S, const Epi& E) {
;     ...
;             PG8_LDA(At, 1, 1); PG8_STAGE(PG8_SB(1, 0), b3, voffB); PG8_STAGE(PG8_SB(1, 1), b3 + hstep, voffB); PG8_STAGE(PG8_SA(1, 0), a3, voffA);
;             PG8_WAIT_V(8); PG8_WAIT_L(0); PG8_BAR; PG8_MMA(1, 0, At, B0); PG8_MMA(1, 1, At, B1); PG8_BAR; PG8_SCHED;
;     ...
;         if constexpr (ALIGN_EPI) { if (wr == 0) PG8_BAR; }
	s_add_i32 s40, s61, s23
	v_lshl_add_u64 v[168:169], v[168:169], 0, s[10:11]
	s_mov_b32 m0, s40
	ds_read_b128 v[194:197], v173 offset:49152
	ds_read_b128 v[198:201], v173 offset:50176
	ds_read_b128 v[202:205], v173 offset:51200
	ds_read_b128 v[206:209], v173 offset:52224
	ds_read_b128 v[210:213], v173 offset:53248
	ds_read_b128 v[214:217], v173 offset:54272
	ds_read_b128 v[218:221], v173 offset:55296
	ds_read_b128 v[222:225], v173 offset:56320
	global_load_lds_dwordx4 v[168:169], off
	s_add_i32 m0, s40, 0x2000
	s_add_u32 s38, s38, 0x20080
	v_lshl_add_u64 v[168:169], v[190:191], 0, s[10:11]
	s_addc_u32 s39, s39, 0
	s_add_i32 s40, s62, s23
	global_load_lds_dwordx4 v[168:169], off
	v_lshl_add_u64 v[168:169], s[38:39], 0, v[132:133]
	s_mov_b32 m0, s40
	s_nop 0
	global_load_lds_dwordx4 v[168:169], off
	v_lshl_add_u64 v[168:169], s[38:39], 0, v[128:129]
	s_add_i32 m0, s40, 0x2000
	s_nop 0
	global_load_lds_dwordx4 v[168:169], off
	v_lshl_add_u64 v[168:169], v[226:227], 0, s[10:11]
	s_mov_b32 m0, s50
	s_nop 0
	global_load_lds_dwordx4 v[168:169], off
	v_lshl_add_u64 v[168:169], v[228:229], 0, s[10:11]
	s_mov_b32 m0, s51
	s_nop 0
	global_load_lds_dwordx4 v[168:169], off
	s_waitcnt vmcnt(8)
	s_waitcnt lgkmcnt(0)
	s_barrier
	s_setprio 1
	s_waitcnt lgkmcnt(0)
	v_mfma_f32_16x16x32_bf16 v[60:63], v[152:155], v[194:197], v[60:63]
	v_mfma_f32_16x16x32_bf16 v[56:59], v[160:163], v[194:197], v[56:59]
	v_mfma_f32_16x16x32_bf16 v[52:55], v[152:155], v[202:205], v[52:55]
	v_mfma_f32_16x16x32_bf16 v[44:47], v[160:163], v[202:205], v[44:47]
	v_mfma_f32_16x16x32_bf16 v[36:39], v[152:155], v[210:213], v[36:39]
	v_mfma_f32_16x16x32_bf16 v[28:31], v[160:163], v[210:213], v[28:31]
	v_mfma_f32_16x16x32_bf16 v[20:23], v[152:155], v[218:221], v[20:23]
	v_mfma_f32_16x16x32_bf16 v[12:15], v[160:163], v[218:221], v[12:15]
	v_mfma_f32_16x16x32_bf16 v[60:63], v[156:159], v[198:201], v[60:63]
	v_mfma_f32_16x16x32_bf16 v[56:59], v[164:167], v[198:201], v[56:59]
	v_mfma_f32_16x16x32_bf16 v[52:55], v[156:159], v[206:209], v[52:55]
	v_mfma_f32_16x16x32_bf16 v[44:47], v[164:167], v[206:209], v[44:47]
	v_mfma_f32_16x16x32_bf16 v[36:39], v[156:159], v[214:217], v[36:39]
	v_mfma_f32_16x16x32_bf16 v[28:31], v[164:167], v[214:217], v[28:31]
	v_mfma_f32_16x16x32_bf16 v[20:23], v[156:159], v[222:225], v[20:23]
	v_mfma_f32_16x16x32_bf16 v[12:15], v[164:167], v[222:225], v[12:15]
	s_setprio 0
	s_setprio 1
	v_mfma_f32_16x16x32_bf16 v[48:51], v[174:177], v[194:197], v[48:51]
	v_mfma_f32_16x16x32_bf16 v[40:43], v[182:185], v[194:197], v[40:43]
	v_mfma_f32_16x16x32_bf16 v[32:35], v[174:177], v[202:205], v[32:35]
	v_mfma_f32_16x16x32_bf16 v[24:27], v[182:185], v[202:205], v[24:27]
	v_mfma_f32_16x16x32_bf16 v[16:19], v[174:177], v[210:213], v[16:19]
	v_mfma_f32_16x16x32_bf16 v[8:11], v[182:185], v[210:213], v[8:11]
	v_mfma_f32_16x16x32_bf16 v[4:7], v[174:177], v[218:221], v[4:7]
	v_mfma_f32_16x16x32_bf16 v[0:3], v[182:185], v[218:221], v[0:3]
	v_mfma_f32_16x16x32_bf16 v[48:51], v[178:181], v[198:201], v[48:51]
	v_mfma_f32_16x16x32_bf16 v[40:43], v[186:189], v[198:201], v[40:43]
	v_mfma_f32_16x16x32_bf16 v[32:35], v[178:181], v[206:209], v[32:35]
	v_mfma_f32_16x16x32_bf16 v[24:27], v[186:189], v[206:209], v[24:27]
	v_mfma_f32_16x16x32_bf16 v[16:19], v[178:181], v[214:217], v[16:19]
	v_mfma_f32_16x16x32_bf16 v[8:11], v[186:189], v[214:217], v[8:11]
	v_mfma_f32_16x16x32_bf16 v[4:7], v[178:181], v[222:225], v[4:7]
	v_mfma_f32_16x16x32_bf16 v[0:3], v[186:189], v[222:225], v[0:3]
	s_setprio 0
	s_barrier
	s_add_i32 s60, s60, 2
	s_add_u32 s36, s36, 0x100
	s_addc_u32 s37, s37, 0
	s_add_u32 s33, s33, 0x100
	s_addc_u32 s59, s59, 0
	s_cmp_gt_u32 s60, 5
	s_cbranch_scc0 .LBB0_402
	s_and_b64 vcc, exec, s[20:21]
	s_cbranch_vccz .LBB0_405
	s_barrier

; #define PG8_STAGE(bufoff, gbase, voff) do { _Pragma("unroll") for (int _i = 0; _i < 2; ++_i) \
;         __builtin_amdgcn_global_load_lds((const unsigned*)((const char*)(gbase) + (voff)[_i]), (PG8_LAS unsigned*)(lds + (bufoff) + ldsw + _i * 8192), 16, 0, 0); } while (0)
; #define PG8_LDA(dst, b, h) do { _Pragma("unroll") for (int m = 0; m < 4; ++m) _Pragma("unroll") for (int k = 0; k < 2; ++k) dst[m][k] = *(const PG8_LAS bf16x8*)(lds + PG8_SA(b, h) + aoff + m * 2048 + k * 1024); } while (0)
; #define PG8_LDB(dst, b, h) do { _Pragma("unroll") for (int n = 0; n < 2; ++n) _Pragma("unroll") for (int k = 0; k < 2; ++k) dst[n][k] = *(const PG8_LAS bf16x8*)(lds + PG8_SB(b, h) + boff + n * 2048 + k * 1024); } while (0)
; #define PG8_MMA(ai, bj, At, Bt) do { __builtin_amdgcn_s_setprio(1); _Pragma("unroll") for (int m = 0; m < 4; ++m) _Pragma("unroll") for (int n = 0; n < 2; ++n) _Pragma("unroll") for (int k = 0; k < 2; ++k) \
;         acc[ai][bj][m][n] = __builtin_amdgcn_mfma_f32_16x16x32_bf16(Bt[n][k], At[m][k], acc[ai][bj][m][n], 0, 0, 0); __builtin_amdgcn_s_setprio(0); } while (0)
; #define PG8_WAIT_V(n) asm volatile("s_waitcnt vmcnt(" #n ")" ::: "memory")
; #define PG8_BAR __builtin_amdgcn_s_barrier()
; template <class Epi, class Sched, bool ALIGN_EPI = false, bool SP2 = false>
; __device__ __forceinline__ void gemm_phase(PG8_LAS unsigned char* lds, const Gemm g, const Sched& S, const Epi& E) {
;     ...
;         for (int t = 0; t < nt; t += 2) {
;             const bool last = (t == nt - 2);
;             const char* a1 = cA + (size_t)(t + 1) * kstep;
;             const char* a2 = last ? nA : cA + (size_t)(t + 2) * kstep; const char* b2 = last ? nB : cB + (size_t)(t + 2) * kstep;
;             const char* a3 = a2 + kstep; const char* b3 = b2 + kstep;
;             if (last && has_next) S.a_ready(nxt);
;             if constexpr (SP2) {
;             PG8_LDB(B0, 0, 0); PG8_LDB(B1, 0, 1); PG8_SCHED; PG8_LDA(At, 0, 0); PG8_STAGE(PG8_SA(1, 1), a1 + hstep, voffA);
;             PG8_WAIT_V(8); PG8_WAIT_L(0); PG8_BAR; PG8_MMA(0, 0, At, B0); PG8_MMA(0, 1, At, B1); PG8_BAR; PG8_SCHED;
;             PG8_LDA(At, 0, 1); PG8_STAGE(PG8_SB(0, 0), b2, voffB); PG8_STAGE(PG8_SB(0, 1), b2 + hstep, voffB); PG8_STAGE(PG8_SA(0, 0), a2, voffA);
;             PG8_WAIT_V(8); PG8_WAIT_L(0); PG8_BAR; PG8_MMA(1, 0, At, B0); PG8_MMA(1, 1, At, B1); PG8_BAR; PG8_SCHED;
.LBB0_430:
	ds_read_b128 v[150:153], v147
	ds_read_b128 v[154:157], v147 offset:1024
	ds_read_b128 v[158:161], v147 offset:2048
	ds_read_b128 v[162:165], v147 offset:3072
	ds_read_b128 v[166:169], v148
	ds_read_b128 v[170:173], v148 offset:1024
	ds_read_b128 v[174:177], v148 offset:2048
	ds_read_b128 v[178:181], v148 offset:3072
	s_add_u32 s38, s36, 0xfffe0080
	s_addc_u32 s39, s37, -1
	s_cmp_eq_u32 s58, 4
	s_cselect_b32 s41, s29, s39
	s_cselect_b32 s40, s54, s38
	s_cselect_b32 s39, s27, s57
	s_cselect_b32 s38, s55, s56
	v_lshl_add_u64 v[190:191], s[36:37], 0, v[138:139]
	s_add_i32 m0, s23, 0xc000
	ds_read_b128 v[182:185], v149
	ds_read_b128 v[186:189], v149 offset:1024
	ds_read_b128 v[194:197], v149 offset:2048
	ds_read_b128 v[198:201], v149 offset:3072
	ds_read_b128 v[202:205], v149 offset:4096
	ds_read_b128 v[206:209], v149 offset:5120
	ds_read_b128 v[210:213], v149 offset:6144
	ds_read_b128 v[214:217], v149 offset:7168
	global_load_lds_dwordx4 v[190:191], off
	v_lshl_add_u64 v[190:191], s[36:37], 0, v[140:141]
	s_add_i32 m0, s23, 0xe000
	s_nop 0
	global_load_lds_dwordx4 v[190:191], off
	s_waitcnt vmcnt(8)
	s_waitcnt lgkmcnt(0)
	s_barrier
	s_setprio 1
	s_waitcnt lgkmcnt(0)
	v_mfma_f32_16x16x32_bf16 v[124:127], v[150:153], v[182:185], v[124:127]
	v_mfma_f32_16x16x32_bf16 v[120:123], v[158:161], v[182:185], v[120:123]
	v_mfma_f32_16x16x32_bf16 v[116:119], v[150:153], v[194:197], v[116:119]
	v_mfma_f32_16x16x32_bf16 v[112:115], v[158:161], v[194:197], v[112:115]
	v_mfma_f32_16x16x32_bf16 v[100:103], v[150:153], v[202:205], v[100:103]
	v_mfma_f32_16x16x32_bf16 v[96:99], v[158:161], v[202:205], v[96:99]
	v_mfma_f32_16x16x32_bf16 v[84:87], v[150:153], v[210:213], v[84:87]
	v_mfma_f32_16x16x32_bf16 v[80:83], v[158:161], v[210:213], v[80:83]
	v_mfma_f32_16x16x32_bf16 v[124:127], v[154:157], v[186:189], v[124:127]
	v_mfma_f32_16x16x32_bf16 v[120:123], v[162:165], v[186:189], v[120:123]
	v_mfma_f32_16x16x32_bf16 v[116:119], v[154:157], v[198:201], v[116:119]
	v_mfma_f32_16x16x32_bf16 v[112:115], v[162:165], v[198:201], v[112:115]
	v_mfma_f32_16x16x32_bf16 v[100:103], v[154:157], v[206:209], v[100:103]
	v_mfma_f32_16x16x32_bf16 v[96:99], v[162:165], v[206:209], v[96:99]
	v_mfma_f32_16x16x32_bf16 v[84:87], v[154:157], v[214:217], v[84:87]
	v_mfma_f32_16x16x32_bf16 v[80:83], v[162:165], v[214:217], v[80:83]
	s_setprio 0
	s_setprio 1
	v_mfma_f32_16x16x32_bf16 v[108:111], v[166:169], v[182:185], v[108:111]
	v_mfma_f32_16x16x32_bf16 v[104:107], v[174:177], v[182:185], v[104:107]
	v_mfma_f32_16x16x32_bf16 v[92:95], v[166:169], v[194:197], v[92:95]
	v_mfma_f32_16x16x32_bf16 v[88:91], v[174:177], v[194:197], v[88:91]
	v_mfma_f32_16x16x32_bf16 v[76:79], v[166:169], v[202:205], v[76:79]
	v_mfma_f32_16x16x32_bf16 v[72:75], v[174:177], v[202:205], v[72:75]
	v_mfma_f32_16x16x32_bf16 v[68:71], v[166:169], v[210:213], v[68:71]
	v_mfma_f32_16x16x32_bf16 v[64:67], v[174:177], v[210:213], v[64:67]
	v_mfma_f32_16x16x32_bf16 v[108:111], v[170:173], v[186:189], v[108:111]
	v_mfma_f32_16x16x32_bf16 v[104:107], v[178:181], v[186:189], v[104:107]
	v_mfma_f32_16x16x32_bf16 v[92:95], v[170:173], v[198:201], v[92:95]
	v_mfma_f32_16x16x32_bf16 v[88:91], v[178:181], v[198:201], v[88:91]
	v_mfma_f32_16x16x32_bf16 v[76:79], v[170:173], v[206:209], v[76:79]
	v_mfma_f32_16x16x32_bf16 v[72:75], v[178:181], v[206:209], v[72:75]
	v_mfma_f32_16x16x32_bf16 v[68:71], v[170:173], v[214:217], v[68:71]
	v_mfma_f32_16x16x32_bf16 v[64:67], v[178:181], v[214:217], v[64:67]
	s_setprio 0
	s_barrier
	s_add_i32 s59, s51, s3
	v_lshl_add_u64 v[190:191], s[38:39], 0, v[130:131]
	s_mov_b32 m0, s59
	ds_read_b128 v[182:185], v149 offset:16384
	ds_read_b128 v[186:189], v149 offset:17408
	ds_read_b128 v[194:197], v149 offset:18432
	ds_read_b128 v[198:201], v149 offset:19456
	ds_read_b128 v[202:205], v149 offset:20480
	ds_read_b128 v[206:209], v149 offset:21504
	ds_read_b128 v[210:213], v149 offset:22528
	ds_read_b128 v[214:217], v149 offset:23552
	global_load_lds_dwordx4 v[190:191], off
	s_add_i32 m0, s59, 0x2000
	s_add_u32 s60, s38, 0x20000
	v_lshl_add_u64 v[218:219], s[38:39], 0, v[134:135]
	s_addc_u32 s61, s39, 0
	s_add_i32 s59, s52, s3
	global_load_lds_dwordx4 v[218:219], off
	v_lshl_add_u64 v[220:221], s[60:61], 0, v[130:131]
	s_mov_b32 m0, s59
	v_lshl_add_u64 v[222:223], s[40:41], 0, v[132:133]
	global_load_lds_dwordx4 v[220:221], off
	v_lshl_add_u64 v[220:221], s[60:61], 0, v[134:135]
	s_add_i32 m0, s59, 0x2000
	s_nop 0
	global_load_lds_dwordx4 v[220:221], off
	v_lshl_add_u64 v[220:221], s[40:41], 0, v[128:129]
	s_mov_b32 m0, s23
	s_nop 0
	global_load_lds_dwordx4 v[220:221], off
	s_mov_b32 m0, s43
	s_nop 0
	global_load_lds_dwordx4 v[222:223], off
	s_waitcnt vmcnt(8)
	s_waitcnt lgkmcnt(0)
	s_barrier
; #define PG8_STAGE(bufoff, gbase, voff) do { _Pragma("unroll") for (int _i = 0; _i < 2; ++_i) \
;         __builtin_amdgcn_global_load_lds((const unsigned*)((const char*)(gbase) + (voff)[_i]), (PG8_LAS unsigned*)(lds + (bufoff) + ldsw + _i * 8192), 16, 0, 0); } while (0)
; #define PG8_LDA(dst, b, h) do { _Pragma("unroll") for (int m = 0; m < 4; ++m) _Pragma("unroll") for (int k = 0; k < 2; ++k) dst[m][k] = *(const PG8_LAS bf16x8*)(lds + PG8_SA(b, h) + aoff + m * 2048 + k * 1024); } while (0)
; #define PG8_LDB(dst, b, h) do { _Pragma("unroll") for (int n = 0; n < 2; ++n) _Pragma("unroll") for (int k = 0; k < 2; ++k) dst[n][k] = *(const PG8_LAS bf16x8*)(lds + PG8_SB(b, h) + boff + n * 2048 + k * 1024); } while (0)
; #define PG8_MMA(ai, bj, At, Bt) do { __builtin_amdgcn_s_setprio(1); _Pragma("unroll") for (int m = 0; m < 4; ++m) _Pragma("unroll") for (int n = 0; n < 2; ++n) _Pragma("unroll") for (int k = 0; k < 2; ++k) \
;         acc[ai][bj][m][n] = __builtin_amdgcn_mfma_f32_16x16x32_bf16(Bt[n][k], At[m][k], acc[ai][bj][m][n], 0, 0, 0); __builtin_amdgcn_s_setprio(0); } while (0)
; #define PG8_WAIT_V(n) asm volatile("s_waitcnt vmcnt(" #n ")" ::: "memory")
; #define PG8_WAIT_L(n) asm volatile("s_waitcnt lgkmcnt(" #n ")" ::: "memory")
; #define PG8_BAR __builtin_amdgcn_s_barrier()
; #define PG8_SCHED __builtin_amdgcn_sched_barrier(0)
; template <class Epi, class Sched, bool ALIGN_EPI = false, bool SP2 = false>
; __device__ __forceinline__ void gemm_phase(PG8_LAS unsigned char* lds, const Gemm g, const Sched& S, const Epi& E) {
;     ...
;             PG8_WAIT_V(8); PG8_WAIT_L(0); PG8_BAR; PG8_MMA(1, 0, At, B0); PG8_MMA(1, 1, At, B1); PG8_BAR; PG8_SCHED;
;             PG8_LDB(B0, 1, 0); PG8_LDB(B1, 1, 1); PG8_SCHED; PG8_LDA(At, 1, 0); PG8_STAGE(PG8_SA(0, 1), a2 + hstep, voffA);
;             PG8_WAIT_V(8); PG8_WAIT_L(0); PG8_BAR; PG8_MMA(0, 0, At, B0); PG8_MMA(0, 1, At, B1); PG8_BAR; PG8_SCHED;
	s_setprio 1
	s_waitcnt lgkmcnt(0)
	v_mfma_f32_16x16x32_bf16 v[60:63], v[150:153], v[182:185], v[60:63]
	v_mfma_f32_16x16x32_bf16 v[56:59], v[158:161], v[182:185], v[56:59]
	v_mfma_f32_16x16x32_bf16 v[52:55], v[150:153], v[194:197], v[52:55]
	v_mfma_f32_16x16x32_bf16 v[48:51], v[158:161], v[194:197], v[48:51]
	v_mfma_f32_16x16x32_bf16 v[36:39], v[150:153], v[202:205], v[36:39]
	v_mfma_f32_16x16x32_bf16 v[32:35], v[158:161], v[202:205], v[32:35]
	v_mfma_f32_16x16x32_bf16 v[20:23], v[150:153], v[210:213], v[20:23]
	v_mfma_f32_16x16x32_bf16 v[16:19], v[158:161], v[210:213], v[16:19]
	v_mfma_f32_16x16x32_bf16 v[60:63], v[154:157], v[186:189], v[60:63]
	v_mfma_f32_16x16x32_bf16 v[56:59], v[162:165], v[186:189], v[56:59]
	v_mfma_f32_16x16x32_bf16 v[52:55], v[154:157], v[198:201], v[52:55]
	v_mfma_f32_16x16x32_bf16 v[48:51], v[162:165], v[198:201], v[48:51]
	v_mfma_f32_16x16x32_bf16 v[36:39], v[154:157], v[206:209], v[36:39]
	v_mfma_f32_16x16x32_bf16 v[32:35], v[162:165], v[206:209], v[32:35]
	v_mfma_f32_16x16x32_bf16 v[20:23], v[154:157], v[214:217], v[20:23]
	v_mfma_f32_16x16x32_bf16 v[16:19], v[162:165], v[214:217], v[16:19]
	s_setprio 0
	s_setprio 1
	v_mfma_f32_16x16x32_bf16 v[44:47], v[166:169], v[182:185], v[44:47]
	v_mfma_f32_16x16x32_bf16 v[40:43], v[174:177], v[182:185], v[40:43]
	v_mfma_f32_16x16x32_bf16 v[28:31], v[166:169], v[194:197], v[28:31]
	v_mfma_f32_16x16x32_bf16 v[24:27], v[174:177], v[194:197], v[24:27]
	v_mfma_f32_16x16x32_bf16 v[12:15], v[166:169], v[202:205], v[12:15]
	v_mfma_f32_16x16x32_bf16 v[8:11], v[174:177], v[202:205], v[8:11]
	v_mfma_f32_16x16x32_bf16 v[4:7], v[166:169], v[210:213], v[4:7]
	v_mfma_f32_16x16x32_bf16 v[0:3], v[174:177], v[210:213], v[0:3]
	v_mfma_f32_16x16x32_bf16 v[44:47], v[170:173], v[186:189], v[44:47]
	v_mfma_f32_16x16x32_bf16 v[40:43], v[178:181], v[186:189], v[40:43]
	v_mfma_f32_16x16x32_bf16 v[28:31], v[170:173], v[198:201], v[28:31]
	v_mfma_f32_16x16x32_bf16 v[24:27], v[178:181], v[198:201], v[24:27]
	v_mfma_f32_16x16x32_bf16 v[12:15], v[170:173], v[206:209], v[12:15]
	v_mfma_f32_16x16x32_bf16 v[8:11], v[178:181], v[206:209], v[8:11]
	v_mfma_f32_16x16x32_bf16 v[4:7], v[170:173], v[214:217], v[4:7]
	v_mfma_f32_16x16x32_bf16 v[0:3], v[178:181], v[214:217], v[0:3]
	s_setprio 0
	s_barrier
	s_add_i32 s59, 0, 0x18000
	s_add_i32 s60, 0, 0x1c000
	v_add_u32_e32 v162, s59, v146
	v_add_u32_e32 v178, s60, v146
	ds_read_b128 v[150:153], v162
	ds_read_b128 v[154:157], v162 offset:1024
	ds_read_b128 v[158:161], v162 offset:2048
	ds_read_b128 v[162:165], v162 offset:3072
	ds_read_b128 v[166:169], v178
	ds_read_b128 v[170:173], v178 offset:1024
	ds_read_b128 v[174:177], v178 offset:2048
	ds_read_b128 v[178:181], v178 offset:3072
	s_add_u32 s40, s40, 0x20000
	s_addc_u32 s41, s41, 0
	s_mov_b32 m0, s44
	v_lshl_add_u64 v[224:225], s[40:41], 0, v[128:129]
	ds_read_b128 v[182:185], v149 offset:32768
	ds_read_b128 v[186:189], v149 offset:33792
	ds_read_b128 v[194:197], v149 offset:34816
	ds_read_b128 v[198:201], v149 offset:35840
	ds_read_b128 v[202:205], v149 offset:36864
	ds_read_b128 v[206:209], v149 offset:37888
	ds_read_b128 v[210:213], v149 offset:38912
	ds_read_b128 v[214:217], v149 offset:39936
	global_load_lds_dwordx4 v[224:225], off
	v_lshl_add_u64 v[224:225], s[40:41], 0, v[132:133]
	s_mov_b32 m0, s45
	s_nop 0
	global_load_lds_dwordx4 v[224:225], off
	s_waitcnt vmcnt(8)
	s_waitcnt lgkmcnt(0)
	s_barrier
	s_setprio 1
	s_waitcnt lgkmcnt(0)
	v_mfma_f32_16x16x32_bf16 v[124:127], v[150:153], v[182:185], v[124:127]
	v_mfma_f32_16x16x32_bf16 v[120:123], v[158:161], v[182:185], v[120:123]
	v_mfma_f32_16x16x32_bf16 v[116:119], v[150:153], v[194:197], v[116:119]
	v_mfma_f32_16x16x32_bf16 v[112:115], v[158:161], v[194:197], v[112:115]
	v_mfma_f32_16x16x32_bf16 v[100:103], v[150:153], v[202:205], v[100:103]
	v_mfma_f32_16x16x32_bf16 v[96:99], v[158:161], v[202:205], v[96:99]
	v_mfma_f32_16x16x32_bf16 v[84:87], v[150:153], v[210:213], v[84:87]
	v_mfma_f32_16x16x32_bf16 v[80:83], v[158:161], v[210:213], v[80:83]
	v_mfma_f32_16x16x32_bf16 v[124:127], v[154:157], v[186:189], v[124:127]
	v_mfma_f32_16x16x32_bf16 v[120:123], v[162:165], v[186:189], v[120:123]
	v_mfma_f32_16x16x32_bf16 v[116:119], v[154:157], v[198:201], v[116:119]
	v_mfma_f32_16x16x32_bf16 v[112:115], v[162:165], v[198:201], v[112:115]
	v_mfma_f32_16x16x32_bf16 v[100:103], v[154:157], v[206:209], v[100:103]
	v_mfma_f32_16x16x32_bf16 v[96:99], v[162:165], v[206:209], v[96:99]
	v_mfma_f32_16x16x32_bf16 v[84:87], v[154:157], v[214:217], v[84:87]
	v_mfma_f32_16x16x32_bf16 v[80:83], v[162:165], v[214:217], v[80:83]
	s_setprio 0
	s_setprio 1
	v_mfma_f32_16x16x32_bf16 v[108:111], v[166:169], v[182:185], v[108:111]
	v_mfma_f32_16x16x32_bf16 v[104:107], v[174:177], v[182:185], v[104:107]
	v_mfma_f32_16x16x32_bf16 v[92:95], v[166:169], v[194:197], v[92:95]
	v_mfma_f32_16x16x32_bf16 v[88:91], v[174:177], v[194:197], v[88:91]
	v_mfma_f32_16x16x32_bf16 v[76:79], v[166:169], v[202:205], v[76:79]
	v_mfma_f32_16x16x32_bf16 v[72:75], v[174:177], v[202:205], v[72:75]
	v_mfma_f32_16x16x32_bf16 v[68:71], v[166:169], v[210:213], v[68:71]
	v_mfma_f32_16x16x32_bf16 v[64:67], v[174:177], v[210:213], v[64:67]
	v_mfma_f32_16x16x32_bf16 v[108:111], v[170:173], v[186:189], v[108:111]
	v_mfma_f32_16x16x32_bf16 v[104:107], v[178:181], v[186:189], v[104:107]
	v_mfma_f32_16x16x32_bf16 v[92:95], v[170:173], v[198:201], v[92:95]
	v_mfma_f32_16x16x32_bf16 v[88:91], v[178:181], v[198:201], v[88:91]
	v_mfma_f32_16x16x32_bf16 v[76:79], v[170:173], v[206:209], v[76:79]
	v_mfma_f32_16x16x32_bf16 v[72:75], v[178:181], v[206:209], v[72:75]
	v_mfma_f32_16x16x32_bf16 v[68:71], v[170:173], v[214:217], v[68:71]
	v_mfma_f32_16x16x32_bf16 v[64:67], v[178:181], v[214:217], v[64:67]
	s_setprio 0
	s_barrier
; #define PG8_STAGE(bufoff, gbase, voff) do { _Pragma("unroll") for (int _i = 0; _i < 2; ++_i) \
;         __builtin_amdgcn_global_load_lds((const unsigned*)((const char*)(gbase) + (voff)[_i]), (PG8_LAS unsigned*)(lds + (bufoff) + ldsw + _i * 8192), 16, 0, 0); } while (0)
; #define PG8_LDA(dst, b, h) do { _Pragma("unroll") for (int m = 0; m < 4; ++m) _Pragma("unroll") for (int k = 0; k < 2; ++k) dst[m][k] = *(const PG8_LAS bf16x8*)(lds + PG8_SA(b, h) + aoff + m * 2048 + k * 1024); } while (0)
; #define PG8_MMA(ai, bj, At, Bt) do { __builtin_amdgcn_s_setprio(1); _Pragma("unroll") for (int m = 0; m < 4; ++m) _Pragma("unroll") for (int n = 0; n < 2; ++n) _Pragma("unroll") for (int k = 0; k < 2; ++k) \
;         acc[ai][bj][m][n] = __builtin_amdgcn_mfma_f32_16x16x32_bf16(Bt[n][k], At[m][k], acc[ai][bj][m][n], 0, 0, 0); __builtin_amdgcn_s_setprio(0); } while (0)
; #define PG8_WAIT_V(n) asm volatile("s_waitcnt vmcnt(" #n ")" ::: "memory")
; #define PG8_WAIT_L(n) asm volatile("s_waitcnt lgkmcnt(" #n ")" ::: "memory")
; #define PG8_BAR __builtin_amdgcn_s_barrier()
; #define PG8_SCHED __builtin_amdgcn_sched_barrier(0)
; template <class Epi, class Sched, bool ALIGN_EPI = false, bool SP2 = false>
; __device__ __forceinline__ void gemm_phase(PG8_LAS unsigned char* lds, const Gemm g, const Sched& S, const Epi& E) {
;     ...
;             PG8_LDA(At, 1, 1); PG8_STAGE(PG8_SB(1, 0), b3, voffB); PG8_STAGE(PG8_SB(1, 1), b3 + hstep, voffB); PG8_STAGE(PG8_SA(1, 0), a3, voffA);
;             PG8_WAIT_V(8); PG8_WAIT_L(0); PG8_BAR; PG8_MMA(1, 0, At, B0); PG8_MMA(1, 1, At, B1); PG8_BAR; PG8_SCHED;
;     ...
;         if constexpr (ALIGN_EPI) { if (wr == 0) PG8_BAR; }
	s_add_i32 s40, s59, s3
	v_lshl_add_u64 v[190:191], v[190:191], 0, s[6:7]
	s_mov_b32 m0, s40
	ds_read_b128 v[182:185], v149 offset:49152
	ds_read_b128 v[186:189], v149 offset:50176
	ds_read_b128 v[194:197], v149 offset:51200
	ds_read_b128 v[198:201], v149 offset:52224
	ds_read_b128 v[202:205], v149 offset:53248
	ds_read_b128 v[206:209], v149 offset:54272
	ds_read_b128 v[210:213], v149 offset:55296
	ds_read_b128 v[214:217], v149 offset:56320
	global_load_lds_dwordx4 v[190:191], off
	s_add_i32 m0, s40, 0x2000
	s_add_u32 s38, s38, 0x20080
	v_lshl_add_u64 v[190:191], v[218:219], 0, s[6:7]
	s_addc_u32 s39, s39, 0
	s_add_i32 s40, s60, s3
	global_load_lds_dwordx4 v[190:191], off
	v_lshl_add_u64 v[190:191], s[38:39], 0, v[130:131]
	s_mov_b32 m0, s40
	s_nop 0
	global_load_lds_dwordx4 v[190:191], off
	v_lshl_add_u64 v[190:191], s[38:39], 0, v[134:135]
	s_add_i32 m0, s40, 0x2000
	s_nop 0
	global_load_lds_dwordx4 v[190:191], off
	v_lshl_add_u64 v[190:191], v[220:221], 0, s[6:7]
	s_mov_b32 m0, s47
	s_nop 0
	global_load_lds_dwordx4 v[190:191], off
	v_lshl_add_u64 v[190:191], v[222:223], 0, s[6:7]
	s_mov_b32 m0, s48
	s_nop 0
	global_load_lds_dwordx4 v[190:191], off
	s_waitcnt vmcnt(8)
	s_waitcnt lgkmcnt(0)
	s_barrier
	s_setprio 1
	s_waitcnt lgkmcnt(0)
	v_mfma_f32_16x16x32_bf16 v[60:63], v[150:153], v[182:185], v[60:63]
	v_mfma_f32_16x16x32_bf16 v[56:59], v[158:161], v[182:185], v[56:59]
	v_mfma_f32_16x16x32_bf16 v[52:55], v[150:153], v[194:197], v[52:55]
	v_mfma_f32_16x16x32_bf16 v[48:51], v[158:161], v[194:197], v[48:51]
	v_mfma_f32_16x16x32_bf16 v[36:39], v[150:153], v[202:205], v[36:39]
	v_mfma_f32_16x16x32_bf16 v[32:35], v[158:161], v[202:205], v[32:35]
	v_mfma_f32_16x16x32_bf16 v[20:23], v[150:153], v[210:213], v[20:23]
	v_mfma_f32_16x16x32_bf16 v[16:19], v[158:161], v[210:213], v[16:19]
	v_mfma_f32_16x16x32_bf16 v[60:63], v[154:157], v[186:189], v[60:63]
	v_mfma_f32_16x16x32_bf16 v[56:59], v[162:165], v[186:189], v[56:59]
	v_mfma_f32_16x16x32_bf16 v[52:55], v[154:157], v[198:201], v[52:55]
	v_mfma_f32_16x16x32_bf16 v[48:51], v[162:165], v[198:201], v[48:51]
	v_mfma_f32_16x16x32_bf16 v[36:39], v[154:157], v[206:209], v[36:39]
	v_mfma_f32_16x16x32_bf16 v[32:35], v[162:165], v[206:209], v[32:35]
	v_mfma_f32_16x16x32_bf16 v[20:23], v[154:157], v[214:217], v[20:23]
	v_mfma_f32_16x16x32_bf16 v[16:19], v[162:165], v[214:217], v[16:19]
	s_setprio 0
	s_setprio 1
	v_mfma_f32_16x16x32_bf16 v[44:47], v[166:169], v[182:185], v[44:47]
	v_mfma_f32_16x16x32_bf16 v[40:43], v[174:177], v[182:185], v[40:43]
	v_mfma_f32_16x16x32_bf16 v[28:31], v[166:169], v[194:197], v[28:31]
	v_mfma_f32_16x16x32_bf16 v[24:27], v[174:177], v[194:197], v[24:27]
	v_mfma_f32_16x16x32_bf16 v[12:15], v[166:169], v[202:205], v[12:15]
	v_mfma_f32_16x16x32_bf16 v[8:11], v[174:177], v[202:205], v[8:11]
	v_mfma_f32_16x16x32_bf16 v[4:7], v[166:169], v[210:213], v[4:7]
	v_mfma_f32_16x16x32_bf16 v[0:3], v[174:177], v[210:213], v[0:3]
	v_mfma_f32_16x16x32_bf16 v[44:47], v[170:173], v[186:189], v[44:47]
	v_mfma_f32_16x16x32_bf16 v[40:43], v[178:181], v[186:189], v[40:43]
	v_mfma_f32_16x16x32_bf16 v[28:31], v[170:173], v[198:201], v[28:31]
	v_mfma_f32_16x16x32_bf16 v[24:27], v[178:181], v[198:201], v[24:27]
	v_mfma_f32_16x16x32_bf16 v[12:15], v[170:173], v[206:209], v[12:15]
	v_mfma_f32_16x16x32_bf16 v[8:11], v[178:181], v[206:209], v[8:11]
	v_mfma_f32_16x16x32_bf16 v[4:7], v[170:173], v[214:217], v[4:7]
	v_mfma_f32_16x16x32_bf16 v[0:3], v[178:181], v[214:217], v[0:3]
	s_setprio 0
	s_barrier
	s_add_i32 s58, s58, 2
	s_add_u32 s36, s36, 0x100
	s_addc_u32 s37, s37, 0
	s_add_u32 s56, s56, 0x100
	s_addc_u32 s57, s57, 0
	s_cmp_gt_u32 s58, 5
	s_cbranch_scc0 .LBB0_430
	s_and_b64 vcc, exec, s[8:9]
	s_cbranch_vccz .LBB0_433
	s_barrier

; __device__ __forceinline__ void attn_phase(const Ctx& C, const bf16* Q, const bf16* KN, const bf16* KR, const bf16* VT, bf16* OA) {
;     for (int p = C.bid; p < 512; p += C.G) {
;         const int bh = p >> 2, j = p & 3, b = bh >> 4, h = bh & 15;
;         attn_unit(C, b, h, 7 - j, Q, KN, KR, VT, OA);
;         attn_unit(C, b, h, j, Q, KN, KR, VT, OA);
;     }
.LBB0_489:
	s_or_b64 exec, exec, s[0:1]
	s_waitcnt lgkmcnt(0)
	v_cndmask_b32_e64 v0, 0, 1, s[24:25]
	v_cmp_ne_u32_e64 s[0:1], 1, v0
	s_andn2_b64 vcc, exec, s[24:25]
	s_nop 0
	v_writelane_b32 v232, s0, 46
	s_barrier
	s_nop 0
	v_writelane_b32 v232, s1, 47
	s_cbranch_vccnz .LBB0_542
	s_cmp_eq_u32 s98, 0
	s_cbranch_scc1 .Lattn_prio_done
	s_setprio 1
.Lattn_prio_done:
	s_add_u32 s16, s90, 0x600000
	s_movk_i32 s22, 0xff00
	s_addc_u32 s17, s91, 0
	s_movk_i32 s44, 0x1800
	v_mov_b64_e32 v[166:167], s[66:67]
	v_mov_b32_e32 v194, 0x1800
	s_mov_b32 s21, 0
	v_mov_b32_e32 v1, 0
	s_mov_b32 s45, 0x2aaaaaab
	s_mov_b32 s23, -1
	s_movk_i32 s46, 0x140
	s_movk_i32 s47, 0x190
	s_mov_b64 s[24:25], 0x40000
	s_mov_b64 s[26:27], 0x2000
	v_mbcnt_hi_u32_b32 v195, -1, v193
	v_mov_b32_e32 v196, 0xf149f2ca
	s_mov_b32 s48, s74
	s_mov_b32 s49, s74
	s_branch .LBB0_492

; __device__ __forceinline__ void xcd_barrier(const XcdBarrier& b) {
;     asm volatile("s_waitcnt vmcnt(0)" ::: "memory");
;     __syncthreads();
;     if (threadIdx.x == 0) {
;         unsigned* bar = b.bar;
;         __builtin_amdgcn_s_waitcnt(0);
;         unsigned nloc = b.st[0], nx = b.st[1];
;         if (nloc == 0u) { xcd_barrier_complete(bar, b.x, nloc, nx); b.st[0] = nloc; b.st[1] = nx; }
.LBB0_542:
	s_setprio 0
	s_waitcnt vmcnt(0)
	s_barrier
	s_and_saveexec_b64 s[0:1], s[78:79]
	s_cbranch_execz .LBB0_594
	s_add_i32 s2, 0, 0x20040
	v_mov_b32_e32 v0, s2
	s_waitcnt vmcnt(0) expcnt(0) lgkmcnt(0)
	ds_read_b32 v2, v0
	s_add_i32 s2, 0, 0x20044
	v_mov_b32_e32 v0, s2
	ds_read_b32 v0, v0
	s_waitcnt lgkmcnt(1)
	v_cmp_ne_u32_e32 vcc, 0, v2
	s_cbranch_vccnz .LBB0_558
	s_add_u32 s4, s90, 0x1200
	s_addc_u32 s5, s91, 0
	s_add_u32 s6, s90, 0x1400
	s_addc_u32 s7, s91, 0
	s_add_u32 s8, s90, 0x1500
	s_addc_u32 s9, s91, 0
	s_add_u32 s10, s90, 0x1600
	s_addc_u32 s11, s91, 0
	s_add_u32 s16, s90, 0x1700
	s_addc_u32 s17, s91, 0
	s_add_u32 s18, s90, 0x1800
	s_addc_u32 s19, s91, 0
	s_add_u32 s20, s90, 0x1900
	s_addc_u32 s21, s91, 0
	s_add_u32 s22, s90, 0x1a00
	s_addc_u32 s23, s91, 0
	s_add_u32 s24, s90, 0x1b00
	s_addc_u32 s25, s91, 0
	s_add_u32 s26, s90, 0x1c00
	s_addc_u32 s27, s91, 0
	s_add_u32 s28, s90, 0x1d00
	s_addc_u32 s29, s91, 0
	s_add_u32 s30, s90, 0x1e00
	s_addc_u32 s31, s91, 0
	s_add_u32 s34, s90, 0x1f00
	s_addc_u32 s35, s91, 0
	s_add_u32 s36, s90, 0x2000
	s_addc_u32 s37, s91, 0
	s_add_u32 s38, s90, 0x2100
	s_addc_u32 s39, s91, 0
	s_add_u32 s40, s90, 0x2200
	s_addc_u32 s41, s91, 0
	s_mul_i32 s2, s77, s71
	s_add_u32 s42, s90, 0x2300
	s_mul_i32 s2, s2, s76
	s_addc_u32 s43, s91, 0
	s_mov_b32 s3, 1
	v_mov_b32_e32 v16, 0
	s_branch .LBB0_546

; #define PG8_STAGE(bufoff, gbase, voff) do { _Pragma("unroll") for (int _i = 0; _i < 2; ++_i) \
;         __builtin_amdgcn_global_load_lds((const unsigned*)((const char*)(gbase) + (voff)[_i]), (PG8_LAS unsigned*)(lds + (bufoff) + ldsw + _i * 8192), 16, 0, 0); } while (0)
; #define PG8_LDA(dst, b, h) do { _Pragma("unroll") for (int m = 0; m < 4; ++m) _Pragma("unroll") for (int k = 0; k < 2; ++k) dst[m][k] = *(const PG8_LAS bf16x8*)(lds + PG8_SA(b, h) + aoff + m * 2048 + k * 1024); } while (0)
; #define PG8_LDB(dst, b, h) do { _Pragma("unroll") for (int n = 0; n < 2; ++n) _Pragma("unroll") for (int k = 0; k < 2; ++k) dst[n][k] = *(const PG8_LAS bf16x8*)(lds + PG8_SB(b, h) + boff + n * 2048 + k * 1024); } while (0)
; #define PG8_MMA(ai, bj, At, Bt) do { __builtin_amdgcn_s_setprio(1); _Pragma("unroll") for (int m = 0; m < 4; ++m) _Pragma("unroll") for (int n = 0; n < 2; ++n) _Pragma("unroll") for (int k = 0; k < 2; ++k) \
;         acc[ai][bj][m][n] = __builtin_amdgcn_mfma_f32_16x16x32_bf16(Bt[n][k], At[m][k], acc[ai][bj][m][n], 0, 0, 0); __builtin_amdgcn_s_setprio(0); } while (0)
; #define PG8_WAIT_V(n) asm volatile("s_waitcnt vmcnt(" #n ")" ::: "memory")
; #define PG8_BAR __builtin_amdgcn_s_barrier()
; template <class Epi, class Sched, bool ALIGN_EPI = false, bool SP2 = false>
; __device__ __forceinline__ void gemm_phase(PG8_LAS unsigned char* lds, const Gemm g, const Sched& S, const Epi& E) {
;     ...
;         for (int t = 0; t < nt; t += 2) {
;             const bool last = (t == nt - 2);
;             const char* a1 = cA + (size_t)(t + 1) * kstep;
;             const char* a2 = last ? nA : cA + (size_t)(t + 2) * kstep; const char* b2 = last ? nB : cB + (size_t)(t + 2) * kstep;
;             const char* a3 = a2 + kstep; const char* b3 = b2 + kstep;
;             if (last && has_next) S.a_ready(nxt);
;             if constexpr (SP2) {
;             PG8_LDB(B0, 0, 0); PG8_LDB(B1, 0, 1); PG8_SCHED; PG8_LDA(At, 0, 0); PG8_STAGE(PG8_SA(1, 1), a1 + hstep, voffA);
;             PG8_WAIT_V(8); PG8_WAIT_L(0); PG8_BAR; PG8_MMA(0, 0, At, B0); PG8_MMA(0, 1, At, B1); PG8_BAR; PG8_SCHED;
;             PG8_LDA(At, 0, 1); PG8_STAGE(PG8_SB(0, 0), b2, voffB); PG8_STAGE(PG8_SB(0, 1), b2 + hstep, voffB); PG8_STAGE(PG8_SA(0, 0), a2, voffA);
;             PG8_WAIT_V(8); PG8_WAIT_L(0); PG8_BAR; PG8_MMA(1, 0, At, B0); PG8_MMA(1, 1, At, B1); PG8_BAR; PG8_SCHED;
.LBB0_605:
	ds_read_b128 v[96:99], v163
	ds_read_b128 v[100:103], v163 offset:1024
	ds_read_b128 v[154:157], v163 offset:2048
	ds_read_b128 v[168:171], v163 offset:3072
	ds_read_b128 v[172:175], v164
	ds_read_b128 v[176:179], v164 offset:1024
	ds_read_b128 v[180:183], v164 offset:2048
	ds_read_b128 v[184:187], v164 offset:3072
	s_add_u32 s38, s36, 0xfff80080
	s_addc_u32 s39, s37, -1
	s_cmp_eq_u32 s33, 28
	s_cselect_b32 s41, s1, s39
	s_cselect_b32 s40, s2, s38
	s_cselect_b32 s39, s3, s29
	s_cselect_b32 s38, s7, s27
	v_lshl_add_u64 v[158:159], s[36:37], 0, v[146:147]
	s_add_i32 m0, s43, 0xc000
	ds_read_b128 v[188:191], v165
	ds_read_b128 v[194:197], v165 offset:1024
	ds_read_b128 v[198:201], v165 offset:2048
	ds_read_b128 v[202:205], v165 offset:3072
	ds_read_b128 v[206:209], v165 offset:4096
	ds_read_b128 v[210:213], v165 offset:5120
	ds_read_b128 v[214:217], v165 offset:6144
	ds_read_b128 v[218:221], v165 offset:7168
	global_load_lds_dwordx4 v[158:159], off
	v_lshl_add_u64 v[158:159], s[36:37], 0, v[148:149]
	s_add_i32 m0, s43, 0xe000
	s_nop 0
	global_load_lds_dwordx4 v[158:159], off
	s_waitcnt vmcnt(8)
	s_waitcnt lgkmcnt(0)
	s_barrier
	s_setprio 1
	s_waitcnt lgkmcnt(0)
	v_mfma_f32_16x16x32_bf16 v[132:135], v[96:99], v[188:191], v[132:135]
	v_mfma_f32_16x16x32_bf16 v[128:131], v[154:157], v[188:191], v[128:131]
	v_mfma_f32_16x16x32_bf16 v[124:127], v[96:99], v[198:201], v[124:127]
	v_mfma_f32_16x16x32_bf16 v[120:123], v[154:157], v[198:201], v[120:123]
	v_mfma_f32_16x16x32_bf16 v[116:119], v[96:99], v[206:209], v[116:119]
	v_mfma_f32_16x16x32_bf16 v[112:115], v[154:157], v[206:209], v[112:115]
	v_mfma_f32_16x16x32_bf16 v[108:111], v[96:99], v[214:217], v[108:111]
	v_mfma_f32_16x16x32_bf16 v[104:107], v[154:157], v[214:217], v[104:107]
	v_mfma_f32_16x16x32_bf16 v[132:135], v[100:103], v[194:197], v[132:135]
	v_mfma_f32_16x16x32_bf16 v[128:131], v[168:171], v[194:197], v[128:131]
	v_mfma_f32_16x16x32_bf16 v[124:127], v[100:103], v[202:205], v[124:127]
	v_mfma_f32_16x16x32_bf16 v[120:123], v[168:171], v[202:205], v[120:123]
	v_mfma_f32_16x16x32_bf16 v[116:119], v[100:103], v[210:213], v[116:119]
	v_mfma_f32_16x16x32_bf16 v[112:115], v[168:171], v[210:213], v[112:115]
	v_mfma_f32_16x16x32_bf16 v[108:111], v[100:103], v[218:221], v[108:111]
	v_mfma_f32_16x16x32_bf16 v[104:107], v[168:171], v[218:221], v[104:107]
	s_setprio 0
	s_setprio 1
	v_mfma_f32_16x16x32_bf16 v[60:63], v[172:175], v[188:191], v[60:63]
	v_mfma_f32_16x16x32_bf16 v[56:59], v[180:183], v[188:191], v[56:59]
	v_mfma_f32_16x16x32_bf16 v[52:55], v[172:175], v[198:201], v[52:55]
	v_mfma_f32_16x16x32_bf16 v[48:51], v[180:183], v[198:201], v[48:51]
	v_mfma_f32_16x16x32_bf16 v[44:47], v[172:175], v[206:209], v[44:47]
	v_mfma_f32_16x16x32_bf16 v[40:43], v[180:183], v[206:209], v[40:43]
	v_mfma_f32_16x16x32_bf16 v[36:39], v[172:175], v[214:217], v[36:39]
	v_mfma_f32_16x16x32_bf16 v[32:35], v[180:183], v[214:217], v[32:35]
	v_mfma_f32_16x16x32_bf16 v[60:63], v[176:179], v[194:197], v[60:63]
	v_mfma_f32_16x16x32_bf16 v[56:59], v[184:187], v[194:197], v[56:59]
	v_mfma_f32_16x16x32_bf16 v[52:55], v[176:179], v[202:205], v[52:55]
	v_mfma_f32_16x16x32_bf16 v[48:51], v[184:187], v[202:205], v[48:51]
	v_mfma_f32_16x16x32_bf16 v[44:47], v[176:179], v[210:213], v[44:47]
	v_mfma_f32_16x16x32_bf16 v[40:43], v[184:187], v[210:213], v[40:43]
	v_mfma_f32_16x16x32_bf16 v[36:39], v[176:179], v[218:221], v[36:39]
	v_mfma_f32_16x16x32_bf16 v[32:35], v[184:187], v[218:221], v[32:35]
	s_setprio 0
	s_barrier
	s_add_i32 s58, s53, s42
	v_lshl_add_u64 v[158:159], s[38:39], 0, v[138:139]
	s_mov_b32 m0, s58
	ds_read_b128 v[188:191], v165 offset:16384
	ds_read_b128 v[194:197], v165 offset:17408
	ds_read_b128 v[198:201], v165 offset:18432
	ds_read_b128 v[202:205], v165 offset:19456
	ds_read_b128 v[206:209], v165 offset:20480
	ds_read_b128 v[210:213], v165 offset:21504
	ds_read_b128 v[214:217], v165 offset:22528
	ds_read_b128 v[218:221], v165 offset:23552
	global_load_lds_dwordx4 v[158:159], off
	s_add_i32 m0, s58, 0x2000
	s_add_u32 s58, s38, 0x80000
	v_lshl_add_u64 v[222:223], s[38:39], 0, v[142:143]
	s_addc_u32 s59, s39, 0
	s_add_i32 s60, s54, s42
	global_load_lds_dwordx4 v[222:223], off
	v_lshl_add_u64 v[224:225], s[58:59], 0, v[138:139]
	s_mov_b32 m0, s60
	v_lshl_add_u64 v[226:227], s[40:41], 0, v[140:141]
	global_load_lds_dwordx4 v[224:225], off
	v_lshl_add_u64 v[224:225], s[58:59], 0, v[142:143]
	s_add_i32 m0, s60, 0x2000
	s_nop 0
	global_load_lds_dwordx4 v[224:225], off
	v_lshl_add_u64 v[224:225], s[40:41], 0, v[136:137]
	s_mov_b32 m0, s43
	s_nop 0
	global_load_lds_dwordx4 v[224:225], off
	s_mov_b32 m0, s44
	s_nop 0
	global_load_lds_dwordx4 v[226:227], off
	s_waitcnt vmcnt(8)
	s_waitcnt lgkmcnt(0)
	s_barrier
; #define PG8_STAGE(bufoff, gbase, voff) do { _Pragma("unroll") for (int _i = 0; _i < 2; ++_i) \
;         __builtin_amdgcn_global_load_lds((const unsigned*)((const char*)(gbase) + (voff)[_i]), (PG8_LAS unsigned*)(lds + (bufoff) + ldsw + _i * 8192), 16, 0, 0); } while (0)
; #define PG8_LDA(dst, b, h) do { _Pragma("unroll") for (int m = 0; m < 4; ++m) _Pragma("unroll") for (int k = 0; k < 2; ++k) dst[m][k] = *(const PG8_LAS bf16x8*)(lds + PG8_SA(b, h) + aoff + m * 2048 + k * 1024); } while (0)
; #define PG8_LDB(dst, b, h) do { _Pragma("unroll") for (int n = 0; n < 2; ++n) _Pragma("unroll") for (int k = 0; k < 2; ++k) dst[n][k] = *(const PG8_LAS bf16x8*)(lds + PG8_SB(b, h) + boff + n * 2048 + k * 1024); } while (0)
; #define PG8_MMA(ai, bj, At, Bt) do { __builtin_amdgcn_s_setprio(1); _Pragma("unroll") for (int m = 0; m < 4; ++m) _Pragma("unroll") for (int n = 0; n < 2; ++n) _Pragma("unroll") for (int k = 0; k < 2; ++k) \
;         acc[ai][bj][m][n] = __builtin_amdgcn_mfma_f32_16x16x32_bf16(Bt[n][k], At[m][k], acc[ai][bj][m][n], 0, 0, 0); __builtin_amdgcn_s_setprio(0); } while (0)
; #define PG8_WAIT_V(n) asm volatile("s_waitcnt vmcnt(" #n ")" ::: "memory")
; #define PG8_WAIT_L(n) asm volatile("s_waitcnt lgkmcnt(" #n ")" ::: "memory")
; #define PG8_BAR __builtin_amdgcn_s_barrier()
; #define PG8_SCHED __builtin_amdgcn_sched_barrier(0)
; template <class Epi, class Sched, bool ALIGN_EPI = false, bool SP2 = false>
; __device__ __forceinline__ void gemm_phase(PG8_LAS unsigned char* lds, const Gemm g, const Sched& S, const Epi& E) {
;     ...
;             PG8_WAIT_V(8); PG8_WAIT_L(0); PG8_BAR; PG8_MMA(1, 0, At, B0); PG8_MMA(1, 1, At, B1); PG8_BAR; PG8_SCHED;
;             PG8_LDB(B0, 1, 0); PG8_LDB(B1, 1, 1); PG8_SCHED; PG8_LDA(At, 1, 0); PG8_STAGE(PG8_SA(0, 1), a2 + hstep, voffA);
;             PG8_WAIT_V(8); PG8_WAIT_L(0); PG8_BAR; PG8_MMA(0, 0, At, B0); PG8_MMA(0, 1, At, B1); PG8_BAR; PG8_SCHED;
	s_setprio 1
	s_waitcnt lgkmcnt(0)
	v_mfma_f32_16x16x32_bf16 v[92:95], v[96:99], v[188:191], v[92:95]
	v_mfma_f32_16x16x32_bf16 v[88:91], v[154:157], v[188:191], v[88:91]
	v_mfma_f32_16x16x32_bf16 v[84:87], v[96:99], v[198:201], v[84:87]
	v_mfma_f32_16x16x32_bf16 v[80:83], v[154:157], v[198:201], v[80:83]
	v_mfma_f32_16x16x32_bf16 v[76:79], v[96:99], v[206:209], v[76:79]
	v_mfma_f32_16x16x32_bf16 v[72:75], v[154:157], v[206:209], v[72:75]
	v_mfma_f32_16x16x32_bf16 v[68:71], v[96:99], v[214:217], v[68:71]
	v_mfma_f32_16x16x32_bf16 v[64:67], v[154:157], v[214:217], v[64:67]
	v_mfma_f32_16x16x32_bf16 v[92:95], v[100:103], v[194:197], v[92:95]
	v_mfma_f32_16x16x32_bf16 v[88:91], v[168:171], v[194:197], v[88:91]
	v_mfma_f32_16x16x32_bf16 v[84:87], v[100:103], v[202:205], v[84:87]
	v_mfma_f32_16x16x32_bf16 v[80:83], v[168:171], v[202:205], v[80:83]
	v_mfma_f32_16x16x32_bf16 v[76:79], v[100:103], v[210:213], v[76:79]
	v_mfma_f32_16x16x32_bf16 v[72:75], v[168:171], v[210:213], v[72:75]
	v_mfma_f32_16x16x32_bf16 v[68:71], v[100:103], v[218:221], v[68:71]
	v_mfma_f32_16x16x32_bf16 v[64:67], v[168:171], v[218:221], v[64:67]
	s_setprio 0
	s_setprio 1
	v_mfma_f32_16x16x32_bf16 v[28:31], v[172:175], v[188:191], v[28:31]
	v_mfma_f32_16x16x32_bf16 v[24:27], v[180:183], v[188:191], v[24:27]
	v_mfma_f32_16x16x32_bf16 v[20:23], v[172:175], v[198:201], v[20:23]
	v_mfma_f32_16x16x32_bf16 v[16:19], v[180:183], v[198:201], v[16:19]
	v_mfma_f32_16x16x32_bf16 v[12:15], v[172:175], v[206:209], v[12:15]
	v_mfma_f32_16x16x32_bf16 v[8:11], v[180:183], v[206:209], v[8:11]
	v_mfma_f32_16x16x32_bf16 v[4:7], v[172:175], v[214:217], v[4:7]
	v_mfma_f32_16x16x32_bf16 v[0:3], v[180:183], v[214:217], v[0:3]
	v_mfma_f32_16x16x32_bf16 v[28:31], v[176:179], v[194:197], v[28:31]
	v_mfma_f32_16x16x32_bf16 v[24:27], v[184:187], v[194:197], v[24:27]
	v_mfma_f32_16x16x32_bf16 v[20:23], v[176:179], v[202:205], v[20:23]
	v_mfma_f32_16x16x32_bf16 v[16:19], v[184:187], v[202:205], v[16:19]
	v_mfma_f32_16x16x32_bf16 v[12:15], v[176:179], v[210:213], v[12:15]
	v_mfma_f32_16x16x32_bf16 v[8:11], v[184:187], v[210:213], v[8:11]
	v_mfma_f32_16x16x32_bf16 v[4:7], v[176:179], v[218:221], v[4:7]
	v_mfma_f32_16x16x32_bf16 v[0:3], v[184:187], v[218:221], v[0:3]
	s_setprio 0
	s_barrier
	s_add_i32 s58, 0, 0x18000
	v_add_u32_e32 v144, s58, v161
	s_add_i32 s59, 0, 0x1c000
	ds_read_b128 v[96:99], v144
	ds_read_b128 v[100:103], v144 offset:1024
	ds_read_b128 v[154:157], v144 offset:2048
	ds_read_b128 v[168:171], v144 offset:3072
	v_add_u32_e32 v144, s59, v161
	ds_read_b128 v[172:175], v144
	ds_read_b128 v[176:179], v144 offset:1024
	ds_read_b128 v[180:183], v144 offset:2048
	ds_read_b128 v[184:187], v144 offset:3072
	s_add_u32 s40, s40, 0x80000
	s_addc_u32 s41, s41, 0
	s_mov_b32 m0, s45
	v_lshl_add_u64 v[228:229], s[40:41], 0, v[136:137]
	ds_read_b128 v[188:191], v165 offset:32768
	ds_read_b128 v[194:197], v165 offset:33792
	ds_read_b128 v[198:201], v165 offset:34816
	ds_read_b128 v[202:205], v165 offset:35840
	ds_read_b128 v[206:209], v165 offset:36864
	ds_read_b128 v[210:213], v165 offset:37888
	ds_read_b128 v[214:217], v165 offset:38912
	ds_read_b128 v[218:221], v165 offset:39936
	global_load_lds_dwordx4 v[228:229], off
	v_lshl_add_u64 v[228:229], s[40:41], 0, v[140:141]
	s_mov_b32 m0, s46
	s_nop 0
	global_load_lds_dwordx4 v[228:229], off
	s_waitcnt vmcnt(8)
	s_waitcnt lgkmcnt(0)
	s_barrier
	s_setprio 1
	s_waitcnt lgkmcnt(0)
	v_mfma_f32_16x16x32_bf16 v[132:135], v[96:99], v[188:191], v[132:135]
	v_mfma_f32_16x16x32_bf16 v[128:131], v[154:157], v[188:191], v[128:131]
	v_mfma_f32_16x16x32_bf16 v[124:127], v[96:99], v[198:201], v[124:127]
	v_mfma_f32_16x16x32_bf16 v[120:123], v[154:157], v[198:201], v[120:123]
	v_mfma_f32_16x16x32_bf16 v[116:119], v[96:99], v[206:209], v[116:119]
	v_mfma_f32_16x16x32_bf16 v[112:115], v[154:157], v[206:209], v[112:115]
	v_mfma_f32_16x16x32_bf16 v[108:111], v[96:99], v[214:217], v[108:111]
	v_mfma_f32_16x16x32_bf16 v[104:107], v[154:157], v[214:217], v[104:107]
	v_mfma_f32_16x16x32_bf16 v[132:135], v[100:103], v[194:197], v[132:135]
	v_mfma_f32_16x16x32_bf16 v[128:131], v[168:171], v[194:197], v[128:131]
	v_mfma_f32_16x16x32_bf16 v[124:127], v[100:103], v[202:205], v[124:127]
	v_mfma_f32_16x16x32_bf16 v[120:123], v[168:171], v[202:205], v[120:123]
	v_mfma_f32_16x16x32_bf16 v[116:119], v[100:103], v[210:213], v[116:119]
	v_mfma_f32_16x16x32_bf16 v[112:115], v[168:171], v[210:213], v[112:115]
	v_mfma_f32_16x16x32_bf16 v[108:111], v[100:103], v[218:221], v[108:111]
	v_mfma_f32_16x16x32_bf16 v[104:107], v[168:171], v[218:221], v[104:107]
	s_setprio 0
	s_setprio 1
	v_mfma_f32_16x16x32_bf16 v[60:63], v[172:175], v[188:191], v[60:63]
	v_mfma_f32_16x16x32_bf16 v[56:59], v[180:183], v[188:191], v[56:59]
	v_mfma_f32_16x16x32_bf16 v[52:55], v[172:175], v[198:201], v[52:55]
	v_mfma_f32_16x16x32_bf16 v[48:51], v[180:183], v[198:201], v[48:51]
	v_mfma_f32_16x16x32_bf16 v[44:47], v[172:175], v[206:209], v[44:47]
	v_mfma_f32_16x16x32_bf16 v[40:43], v[180:183], v[206:209], v[40:43]
	v_mfma_f32_16x16x32_bf16 v[36:39], v[172:175], v[214:217], v[36:39]
	v_mfma_f32_16x16x32_bf16 v[32:35], v[180:183], v[214:217], v[32:35]
	v_mfma_f32_16x16x32_bf16 v[60:63], v[176:179], v[194:197], v[60:63]
	v_mfma_f32_16x16x32_bf16 v[56:59], v[184:187], v[194:197], v[56:59]
	v_mfma_f32_16x16x32_bf16 v[52:55], v[176:179], v[202:205], v[52:55]
	v_mfma_f32_16x16x32_bf16 v[48:51], v[184:187], v[202:205], v[48:51]
	v_mfma_f32_16x16x32_bf16 v[44:47], v[176:179], v[210:213], v[44:47]
	v_mfma_f32_16x16x32_bf16 v[40:43], v[184:187], v[210:213], v[40:43]
	v_mfma_f32_16x16x32_bf16 v[36:39], v[176:179], v[218:221], v[36:39]
	v_mfma_f32_16x16x32_bf16 v[32:35], v[184:187], v[218:221], v[32:35]
	s_setprio 0
	s_barrier
; #define PG8_STAGE(bufoff, gbase, voff) do { _Pragma("unroll") for (int _i = 0; _i < 2; ++_i) \
;         __builtin_amdgcn_global_load_lds((const unsigned*)((const char*)(gbase) + (voff)[_i]), (PG8_LAS unsigned*)(lds + (bufoff) + ldsw + _i * 8192), 16, 0, 0); } while (0)
; #define PG8_LDA(dst, b, h) do { _Pragma("unroll") for (int m = 0; m < 4; ++m) _Pragma("unroll") for (int k = 0; k < 2; ++k) dst[m][k] = *(const PG8_LAS bf16x8*)(lds + PG8_SA(b, h) + aoff + m * 2048 + k * 1024); } while (0)
; #define PG8_MMA(ai, bj, At, Bt) do { __builtin_amdgcn_s_setprio(1); _Pragma("unroll") for (int m = 0; m < 4; ++m) _Pragma("unroll") for (int n = 0; n < 2; ++n) _Pragma("unroll") for (int k = 0; k < 2; ++k) \
;         acc[ai][bj][m][n] = __builtin_amdgcn_mfma_f32_16x16x32_bf16(Bt[n][k], At[m][k], acc[ai][bj][m][n], 0, 0, 0); __builtin_amdgcn_s_setprio(0); } while (0)
; #define PG8_WAIT_V(n) asm volatile("s_waitcnt vmcnt(" #n ")" ::: "memory")
; #define PG8_WAIT_L(n) asm volatile("s_waitcnt lgkmcnt(" #n ")" ::: "memory")
; #define PG8_BAR __builtin_amdgcn_s_barrier()
; #define PG8_SCHED __builtin_amdgcn_sched_barrier(0)
; template <class Epi, class Sched, bool ALIGN_EPI = false, bool SP2 = false>
; __device__ __forceinline__ void gemm_phase(PG8_LAS unsigned char* lds, const Gemm g, const Sched& S, const Epi& E) {
;     ...
;             PG8_LDA(At, 1, 1); PG8_STAGE(PG8_SB(1, 0), b3, voffB); PG8_STAGE(PG8_SB(1, 1), b3 + hstep, voffB); PG8_STAGE(PG8_SA(1, 0), a3, voffA);
;             PG8_WAIT_V(8); PG8_WAIT_L(0); PG8_BAR; PG8_MMA(1, 0, At, B0); PG8_MMA(1, 1, At, B1); PG8_BAR; PG8_SCHED;
;     ...
;         if constexpr (ALIGN_EPI) { if (wr == 0) PG8_BAR; }
	s_add_i32 s40, s58, s42
	v_lshl_add_u64 v[158:159], v[158:159], 0, s[16:17]
	s_mov_b32 m0, s40
	ds_read_b128 v[188:191], v165 offset:49152
	ds_read_b128 v[194:197], v165 offset:50176
	ds_read_b128 v[198:201], v165 offset:51200
	ds_read_b128 v[202:205], v165 offset:52224
	ds_read_b128 v[206:209], v165 offset:53248
	ds_read_b128 v[210:213], v165 offset:54272
	ds_read_b128 v[214:217], v165 offset:55296
	ds_read_b128 v[218:221], v165 offset:56320
	global_load_lds_dwordx4 v[158:159], off
	s_add_i32 m0, s40, 0x2000
	s_add_u32 s38, s38, 0x80080
	v_lshl_add_u64 v[158:159], v[222:223], 0, s[16:17]
	s_addc_u32 s39, s39, 0
	s_add_i32 s40, s59, s42
	global_load_lds_dwordx4 v[158:159], off
	v_lshl_add_u64 v[158:159], s[38:39], 0, v[138:139]
	s_mov_b32 m0, s40
	s_nop 0
	global_load_lds_dwordx4 v[158:159], off
	v_lshl_add_u64 v[158:159], s[38:39], 0, v[142:143]
	s_add_i32 m0, s40, 0x2000
	s_nop 0
	global_load_lds_dwordx4 v[158:159], off
	v_lshl_add_u64 v[158:159], v[224:225], 0, s[16:17]
	s_mov_b32 m0, s48
	s_nop 0
	global_load_lds_dwordx4 v[158:159], off
	v_lshl_add_u64 v[158:159], v[226:227], 0, s[16:17]
	s_mov_b32 m0, s49
	s_nop 0
	global_load_lds_dwordx4 v[158:159], off
	s_waitcnt vmcnt(8)
	s_waitcnt lgkmcnt(0)
	s_barrier
	s_setprio 1
	s_waitcnt lgkmcnt(0)
	v_mfma_f32_16x16x32_bf16 v[92:95], v[96:99], v[188:191], v[92:95]
	v_mfma_f32_16x16x32_bf16 v[88:91], v[154:157], v[188:191], v[88:91]
	v_mfma_f32_16x16x32_bf16 v[84:87], v[96:99], v[198:201], v[84:87]
	v_mfma_f32_16x16x32_bf16 v[80:83], v[154:157], v[198:201], v[80:83]
	v_mfma_f32_16x16x32_bf16 v[76:79], v[96:99], v[206:209], v[76:79]
	v_mfma_f32_16x16x32_bf16 v[72:75], v[154:157], v[206:209], v[72:75]
	v_mfma_f32_16x16x32_bf16 v[68:71], v[96:99], v[214:217], v[68:71]
	v_mfma_f32_16x16x32_bf16 v[64:67], v[154:157], v[214:217], v[64:67]
	v_mfma_f32_16x16x32_bf16 v[92:95], v[100:103], v[194:197], v[92:95]
	v_mfma_f32_16x16x32_bf16 v[88:91], v[168:171], v[194:197], v[88:91]
	v_mfma_f32_16x16x32_bf16 v[84:87], v[100:103], v[202:205], v[84:87]
	v_mfma_f32_16x16x32_bf16 v[80:83], v[168:171], v[202:205], v[80:83]
	v_mfma_f32_16x16x32_bf16 v[76:79], v[100:103], v[210:213], v[76:79]
	v_mfma_f32_16x16x32_bf16 v[72:75], v[168:171], v[210:213], v[72:75]
	v_mfma_f32_16x16x32_bf16 v[68:71], v[100:103], v[218:221], v[68:71]
	v_mfma_f32_16x16x32_bf16 v[64:67], v[168:171], v[218:221], v[64:67]
	s_setprio 0
	s_setprio 1
	v_mfma_f32_16x16x32_bf16 v[28:31], v[172:175], v[188:191], v[28:31]
	v_mfma_f32_16x16x32_bf16 v[24:27], v[180:183], v[188:191], v[24:27]
	v_mfma_f32_16x16x32_bf16 v[20:23], v[172:175], v[198:201], v[20:23]
	v_mfma_f32_16x16x32_bf16 v[16:19], v[180:183], v[198:201], v[16:19]
	v_mfma_f32_16x16x32_bf16 v[12:15], v[172:175], v[206:209], v[12:15]
	v_mfma_f32_16x16x32_bf16 v[8:11], v[180:183], v[206:209], v[8:11]
	v_mfma_f32_16x16x32_bf16 v[4:7], v[172:175], v[214:217], v[4:7]
	v_mfma_f32_16x16x32_bf16 v[0:3], v[180:183], v[214:217], v[0:3]
	v_mfma_f32_16x16x32_bf16 v[28:31], v[176:179], v[194:197], v[28:31]
	v_mfma_f32_16x16x32_bf16 v[24:27], v[184:187], v[194:197], v[24:27]
	v_mfma_f32_16x16x32_bf16 v[20:23], v[176:179], v[202:205], v[20:23]
	v_mfma_f32_16x16x32_bf16 v[16:19], v[184:187], v[202:205], v[16:19]
	v_mfma_f32_16x16x32_bf16 v[12:15], v[176:179], v[210:213], v[12:15]
	v_mfma_f32_16x16x32_bf16 v[8:11], v[184:187], v[210:213], v[8:11]
	v_mfma_f32_16x16x32_bf16 v[4:7], v[176:179], v[218:221], v[4:7]
	v_mfma_f32_16x16x32_bf16 v[0:3], v[184:187], v[218:221], v[0:3]
	s_setprio 0
	s_barrier
	s_add_i32 s33, s33, 2
	s_add_u32 s36, s36, 0x100
	s_addc_u32 s37, s37, 0
	s_add_u32 s27, s27, 0x100
	s_addc_u32 s29, s29, 0
	s_cmp_gt_u32 s33, 29
	s_cbranch_scc0 .LBB0_605
	s_and_b64 vcc, exec, s[18:19]
	s_cbranch_vccz .LBB0_608
	s_barrier

; #define PG8_STAGE(bufoff, gbase, voff) do { _Pragma("unroll") for (int _i = 0; _i < 2; ++_i) \
;         __builtin_amdgcn_global_load_lds((const unsigned*)((const char*)(gbase) + (voff)[_i]), (PG8_LAS unsigned*)(lds + (bufoff) + ldsw + _i * 8192), 16, 0, 0); } while (0)
; #define PG8_LDA(dst, b, h) do { _Pragma("unroll") for (int m = 0; m < 4; ++m) _Pragma("unroll") for (int k = 0; k < 2; ++k) dst[m][k] = *(const PG8_LAS bf16x8*)(lds + PG8_SA(b, h) + aoff + m * 2048 + k * 1024); } while (0)
; #define PG8_LDB(dst, b, h) do { _Pragma("unroll") for (int n = 0; n < 2; ++n) _Pragma("unroll") for (int k = 0; k < 2; ++k) dst[n][k] = *(const PG8_LAS bf16x8*)(lds + PG8_SB(b, h) + boff + n * 2048 + k * 1024); } while (0)
; #define PG8_MMA(ai, bj, At, Bt) do { __builtin_amdgcn_s_setprio(1); _Pragma("unroll") for (int m = 0; m < 4; ++m) _Pragma("unroll") for (int n = 0; n < 2; ++n) _Pragma("unroll") for (int k = 0; k < 2; ++k) \
;         acc[ai][bj][m][n] = __builtin_amdgcn_mfma_f32_16x16x32_bf16(Bt[n][k], At[m][k], acc[ai][bj][m][n], 0, 0, 0); __builtin_amdgcn_s_setprio(0); } while (0)
; #define PG8_WAIT_V(n) asm volatile("s_waitcnt vmcnt(" #n ")" ::: "memory")
; #define PG8_BAR __builtin_amdgcn_s_barrier()
; template <class Epi, class Sched, bool ALIGN_EPI = false, bool SP2 = false>
; __device__ __forceinline__ void gemm_phase(PG8_LAS unsigned char* lds, const Gemm g, const Sched& S, const Epi& E) {
;     ...
;         for (int t = 0; t < nt; t += 2) {
;             const bool last = (t == nt - 2);
;             const char* a1 = cA + (size_t)(t + 1) * kstep;
;             const char* a2 = last ? nA : cA + (size_t)(t + 2) * kstep; const char* b2 = last ? nB : cB + (size_t)(t + 2) * kstep;
;             const char* a3 = a2 + kstep; const char* b3 = b2 + kstep;
;             if (last && has_next) S.a_ready(nxt);
;             if constexpr (SP2) {
;             PG8_LDB(B0, 0, 0); PG8_LDB(B1, 0, 1); PG8_SCHED; PG8_LDA(At, 0, 0); PG8_STAGE(PG8_SA(1, 1), a1 + hstep, voffA);
;             PG8_WAIT_V(8); PG8_WAIT_L(0); PG8_BAR; PG8_MMA(0, 0, At, B0); PG8_MMA(0, 1, At, B1); PG8_BAR; PG8_SCHED;
;             PG8_LDA(At, 0, 1); PG8_STAGE(PG8_SB(0, 0), b2, voffB); PG8_STAGE(PG8_SB(0, 1), b2 + hstep, voffB); PG8_STAGE(PG8_SA(0, 0), a2, voffA);
;             PG8_WAIT_V(8); PG8_WAIT_L(0); PG8_BAR; PG8_MMA(1, 0, At, B0); PG8_MMA(1, 1, At, B1); PG8_BAR; PG8_SCHED;
.LBB0_797:
	ds_read_b128 v[64:67], v168
	ds_read_b128 v[68:71], v168 offset:1024
	ds_read_b128 v[136:139], v168 offset:2048
	ds_read_b128 v[162:165], v168 offset:3072
	ds_read_b128 v[172:175], v169
	ds_read_b128 v[176:179], v169 offset:1024
	ds_read_b128 v[180:183], v169 offset:2048
	ds_read_b128 v[184:187], v169 offset:3072
	s_add_u32 s22, s20, 0xfff80080
	s_addc_u32 s23, s21, -1
	s_cmp_eq_u32 s44, 28
	s_cselect_b32 s25, s2, s23
	s_cselect_b32 s24, s3, s22
	s_cselect_b32 s23, s13, s43
	s_cselect_b32 s22, s15, s33
	v_lshl_add_u64 v[222:223], s[20:21], 0, v[154:155]
	s_add_i32 m0, s30, 0xc000
	ds_read_b128 v[188:191], v170
	ds_read_b128 v[194:197], v170 offset:1024
	ds_read_b128 v[198:201], v170 offset:2048
	ds_read_b128 v[202:205], v170 offset:3072
	ds_read_b128 v[206:209], v170 offset:4096
	ds_read_b128 v[210:213], v170 offset:5120
	ds_read_b128 v[214:217], v170 offset:6144
	ds_read_b128 v[218:221], v170 offset:7168
	global_load_lds_dwordx4 v[222:223], off
	v_lshl_add_u64 v[222:223], s[20:21], 0, v[156:157]
	s_add_i32 m0, s30, 0xe000
	s_nop 0
	global_load_lds_dwordx4 v[222:223], off
	s_waitcnt vmcnt(8)
	s_waitcnt lgkmcnt(0)
	s_barrier
	s_setprio 1
	s_waitcnt lgkmcnt(0)
	v_mfma_f32_16x16x32_bf16 v[132:135], v[64:67], v[188:191], v[132:135]
	v_mfma_f32_16x16x32_bf16 v[128:131], v[136:139], v[188:191], v[128:131]
	v_mfma_f32_16x16x32_bf16 v[116:119], v[64:67], v[198:201], v[116:119]
	v_mfma_f32_16x16x32_bf16 v[112:115], v[136:139], v[198:201], v[112:115]
	v_mfma_f32_16x16x32_bf16 v[100:103], v[64:67], v[206:209], v[100:103]
	v_mfma_f32_16x16x32_bf16 v[96:99], v[136:139], v[206:209], v[96:99]
	v_mfma_f32_16x16x32_bf16 v[84:87], v[64:67], v[214:217], v[84:87]
	v_mfma_f32_16x16x32_bf16 v[80:83], v[136:139], v[214:217], v[80:83]
	v_mfma_f32_16x16x32_bf16 v[132:135], v[68:71], v[194:197], v[132:135]
	v_mfma_f32_16x16x32_bf16 v[128:131], v[162:165], v[194:197], v[128:131]
	v_mfma_f32_16x16x32_bf16 v[116:119], v[68:71], v[202:205], v[116:119]
	v_mfma_f32_16x16x32_bf16 v[112:115], v[162:165], v[202:205], v[112:115]
	v_mfma_f32_16x16x32_bf16 v[100:103], v[68:71], v[210:213], v[100:103]
	v_mfma_f32_16x16x32_bf16 v[96:99], v[162:165], v[210:213], v[96:99]
	v_mfma_f32_16x16x32_bf16 v[84:87], v[68:71], v[218:221], v[84:87]
	v_mfma_f32_16x16x32_bf16 v[80:83], v[162:165], v[218:221], v[80:83]
	s_setprio 0
	s_setprio 1
	v_mfma_f32_16x16x32_bf16 v[124:127], v[172:175], v[188:191], v[124:127]
	v_mfma_f32_16x16x32_bf16 v[120:123], v[180:183], v[188:191], v[120:123]
	v_mfma_f32_16x16x32_bf16 v[108:111], v[172:175], v[198:201], v[108:111]
	v_mfma_f32_16x16x32_bf16 v[104:107], v[180:183], v[198:201], v[104:107]
	v_mfma_f32_16x16x32_bf16 v[92:95], v[172:175], v[206:209], v[92:95]
	v_mfma_f32_16x16x32_bf16 v[88:91], v[180:183], v[206:209], v[88:91]
	v_mfma_f32_16x16x32_bf16 v[76:79], v[172:175], v[214:217], v[76:79]
	v_mfma_f32_16x16x32_bf16 v[72:75], v[180:183], v[214:217], v[72:75]
	v_mfma_f32_16x16x32_bf16 v[124:127], v[176:179], v[194:197], v[124:127]
	v_mfma_f32_16x16x32_bf16 v[120:123], v[184:187], v[194:197], v[120:123]
	v_mfma_f32_16x16x32_bf16 v[108:111], v[176:179], v[202:205], v[108:111]
	v_mfma_f32_16x16x32_bf16 v[104:107], v[184:187], v[202:205], v[104:107]
	v_mfma_f32_16x16x32_bf16 v[92:95], v[176:179], v[210:213], v[92:95]
	v_mfma_f32_16x16x32_bf16 v[88:91], v[184:187], v[210:213], v[88:91]
	v_mfma_f32_16x16x32_bf16 v[76:79], v[176:179], v[218:221], v[76:79]
	v_mfma_f32_16x16x32_bf16 v[72:75], v[184:187], v[218:221], v[72:75]
	s_setprio 0
	s_barrier
	s_add_i32 s45, s41, s29
	v_lshl_add_u64 v[222:223], s[22:23], 0, v[142:143]
	s_mov_b32 m0, s45
	ds_read_b128 v[188:191], v170 offset:16384
	ds_read_b128 v[194:197], v170 offset:17408
	ds_read_b128 v[198:201], v170 offset:18432
	ds_read_b128 v[202:205], v170 offset:19456
	ds_read_b128 v[206:209], v170 offset:20480
	ds_read_b128 v[210:213], v170 offset:21504
	ds_read_b128 v[214:217], v170 offset:22528
	ds_read_b128 v[218:221], v170 offset:23552
	global_load_lds_dwordx4 v[222:223], off
	s_add_i32 m0, s45, 0x2000
	s_add_u32 s46, s22, 0x80000
	v_lshl_add_u64 v[224:225], s[22:23], 0, v[146:147]
	s_addc_u32 s47, s23, 0
	s_add_i32 s45, s42, s29
	global_load_lds_dwordx4 v[224:225], off
	v_lshl_add_u64 v[226:227], s[46:47], 0, v[142:143]
	s_mov_b32 m0, s45
	v_lshl_add_u64 v[228:229], s[24:25], 0, v[144:145]
	global_load_lds_dwordx4 v[226:227], off
	v_lshl_add_u64 v[226:227], s[46:47], 0, v[146:147]
	s_add_i32 m0, s45, 0x2000
	s_nop 0
	global_load_lds_dwordx4 v[226:227], off
	v_lshl_add_u64 v[226:227], s[24:25], 0, v[140:141]
	s_mov_b32 m0, s30
	s_nop 0
	global_load_lds_dwordx4 v[226:227], off
	s_mov_b32 m0, s31
	s_nop 0
	global_load_lds_dwordx4 v[228:229], off
	s_waitcnt vmcnt(8)
	s_waitcnt lgkmcnt(0)
	s_barrier
; #define PG8_STAGE(bufoff, gbase, voff) do { _Pragma("unroll") for (int _i = 0; _i < 2; ++_i) \
;         __builtin_amdgcn_global_load_lds((const unsigned*)((const char*)(gbase) + (voff)[_i]), (PG8_LAS unsigned*)(lds + (bufoff) + ldsw + _i * 8192), 16, 0, 0); } while (0)
; #define PG8_LDA(dst, b, h) do { _Pragma("unroll") for (int m = 0; m < 4; ++m) _Pragma("unroll") for (int k = 0; k < 2; ++k) dst[m][k] = *(const PG8_LAS bf16x8*)(lds + PG8_SA(b, h) + aoff + m * 2048 + k * 1024); } while (0)
; #define PG8_LDB(dst, b, h) do { _Pragma("unroll") for (int n = 0; n < 2; ++n) _Pragma("unroll") for (int k = 0; k < 2; ++k) dst[n][k] = *(const PG8_LAS bf16x8*)(lds + PG8_SB(b, h) + boff + n * 2048 + k * 1024); } while (0)
; #define PG8_MMA(ai, bj, At, Bt) do { __builtin_amdgcn_s_setprio(1); _Pragma("unroll") for (int m = 0; m < 4; ++m) _Pragma("unroll") for (int n = 0; n < 2; ++n) _Pragma("unroll") for (int k = 0; k < 2; ++k) \
;         acc[ai][bj][m][n] = __builtin_amdgcn_mfma_f32_16x16x32_bf16(Bt[n][k], At[m][k], acc[ai][bj][m][n], 0, 0, 0); __builtin_amdgcn_s_setprio(0); } while (0)
; #define PG8_WAIT_V(n) asm volatile("s_waitcnt vmcnt(" #n ")" ::: "memory")
; #define PG8_WAIT_L(n) asm volatile("s_waitcnt lgkmcnt(" #n ")" ::: "memory")
; #define PG8_BAR __builtin_amdgcn_s_barrier()
; #define PG8_SCHED __builtin_amdgcn_sched_barrier(0)
; template <class Epi, class Sched, bool ALIGN_EPI = false, bool SP2 = false>
; __device__ __forceinline__ void gemm_phase(PG8_LAS unsigned char* lds, const Gemm g, const Sched& S, const Epi& E) {
;     ...
;             PG8_WAIT_V(8); PG8_WAIT_L(0); PG8_BAR; PG8_MMA(1, 0, At, B0); PG8_MMA(1, 1, At, B1); PG8_BAR; PG8_SCHED;
;             PG8_LDB(B0, 1, 0); PG8_LDB(B1, 1, 1); PG8_SCHED; PG8_LDA(At, 1, 0); PG8_STAGE(PG8_SA(0, 1), a2 + hstep, voffA);
;             PG8_WAIT_V(8); PG8_WAIT_L(0); PG8_BAR; PG8_MMA(0, 0, At, B0); PG8_MMA(0, 1, At, B1); PG8_BAR; PG8_SCHED;
	s_setprio 1
	s_waitcnt lgkmcnt(0)
	v_mfma_f32_16x16x32_bf16 v[60:63], v[64:67], v[188:191], v[60:63]
	v_mfma_f32_16x16x32_bf16 v[56:59], v[136:139], v[188:191], v[56:59]
	v_mfma_f32_16x16x32_bf16 v[44:47], v[64:67], v[198:201], v[44:47]
	v_mfma_f32_16x16x32_bf16 v[40:43], v[136:139], v[198:201], v[40:43]
	v_mfma_f32_16x16x32_bf16 v[28:31], v[64:67], v[206:209], v[28:31]
	v_mfma_f32_16x16x32_bf16 v[24:27], v[136:139], v[206:209], v[24:27]
	v_mfma_f32_16x16x32_bf16 v[12:15], v[64:67], v[214:217], v[12:15]
	v_mfma_f32_16x16x32_bf16 v[8:11], v[136:139], v[214:217], v[8:11]
	v_mfma_f32_16x16x32_bf16 v[60:63], v[68:71], v[194:197], v[60:63]
	v_mfma_f32_16x16x32_bf16 v[56:59], v[162:165], v[194:197], v[56:59]
	v_mfma_f32_16x16x32_bf16 v[44:47], v[68:71], v[202:205], v[44:47]
	v_mfma_f32_16x16x32_bf16 v[40:43], v[162:165], v[202:205], v[40:43]
	v_mfma_f32_16x16x32_bf16 v[28:31], v[68:71], v[210:213], v[28:31]
	v_mfma_f32_16x16x32_bf16 v[24:27], v[162:165], v[210:213], v[24:27]
	v_mfma_f32_16x16x32_bf16 v[12:15], v[68:71], v[218:221], v[12:15]
	v_mfma_f32_16x16x32_bf16 v[8:11], v[162:165], v[218:221], v[8:11]
	s_setprio 0
	s_setprio 1
	v_mfma_f32_16x16x32_bf16 v[52:55], v[172:175], v[188:191], v[52:55]
	v_mfma_f32_16x16x32_bf16 v[48:51], v[180:183], v[188:191], v[48:51]
	v_mfma_f32_16x16x32_bf16 v[36:39], v[172:175], v[198:201], v[36:39]
	v_mfma_f32_16x16x32_bf16 v[32:35], v[180:183], v[198:201], v[32:35]
	v_mfma_f32_16x16x32_bf16 v[20:23], v[172:175], v[206:209], v[20:23]
	v_mfma_f32_16x16x32_bf16 v[16:19], v[180:183], v[206:209], v[16:19]
	v_mfma_f32_16x16x32_bf16 v[4:7], v[172:175], v[214:217], v[4:7]
	v_mfma_f32_16x16x32_bf16 v[0:3], v[180:183], v[214:217], v[0:3]
	v_mfma_f32_16x16x32_bf16 v[52:55], v[176:179], v[194:197], v[52:55]
	v_mfma_f32_16x16x32_bf16 v[48:51], v[184:187], v[194:197], v[48:51]
	v_mfma_f32_16x16x32_bf16 v[36:39], v[176:179], v[202:205], v[36:39]
	v_mfma_f32_16x16x32_bf16 v[32:35], v[184:187], v[202:205], v[32:35]
	v_mfma_f32_16x16x32_bf16 v[20:23], v[176:179], v[210:213], v[20:23]
	v_mfma_f32_16x16x32_bf16 v[16:19], v[184:187], v[210:213], v[16:19]
	v_mfma_f32_16x16x32_bf16 v[4:7], v[176:179], v[218:221], v[4:7]
	v_mfma_f32_16x16x32_bf16 v[0:3], v[184:187], v[218:221], v[0:3]
	s_setprio 0
	s_barrier
	s_add_i32 s45, 0, 0x18000
	s_add_i32 s46, 0, 0x1c000
	v_add_u32_e32 v162, s45, v167
	v_add_u32_e32 v184, s46, v167
	ds_read_b128 v[64:67], v162
	ds_read_b128 v[68:71], v162 offset:1024
	ds_read_b128 v[136:139], v162 offset:2048
	ds_read_b128 v[162:165], v162 offset:3072
	ds_read_b128 v[172:175], v184
	ds_read_b128 v[176:179], v184 offset:1024
	ds_read_b128 v[180:183], v184 offset:2048
	ds_read_b128 v[184:187], v184 offset:3072
	s_add_u32 s24, s24, 0x80000
	s_addc_u32 s25, s25, 0
	s_mov_b32 m0, s34
	v_lshl_add_u64 v[230:231], s[24:25], 0, v[140:141]
	ds_read_b128 v[188:191], v170 offset:32768
	ds_read_b128 v[194:197], v170 offset:33792
	ds_read_b128 v[198:201], v170 offset:34816
	ds_read_b128 v[202:205], v170 offset:35840
	ds_read_b128 v[206:209], v170 offset:36864
	ds_read_b128 v[210:213], v170 offset:37888
	ds_read_b128 v[214:217], v170 offset:38912
	ds_read_b128 v[218:221], v170 offset:39936
	global_load_lds_dwordx4 v[230:231], off
	v_lshl_add_u64 v[230:231], s[24:25], 0, v[144:145]
	s_mov_b32 m0, s35
	s_nop 0
	global_load_lds_dwordx4 v[230:231], off
	s_waitcnt vmcnt(8)
	s_waitcnt lgkmcnt(0)
	s_barrier
	s_setprio 1
	s_waitcnt lgkmcnt(0)
	v_mfma_f32_16x16x32_bf16 v[132:135], v[64:67], v[188:191], v[132:135]
	v_mfma_f32_16x16x32_bf16 v[128:131], v[136:139], v[188:191], v[128:131]
	v_mfma_f32_16x16x32_bf16 v[116:119], v[64:67], v[198:201], v[116:119]
	v_mfma_f32_16x16x32_bf16 v[112:115], v[136:139], v[198:201], v[112:115]
	v_mfma_f32_16x16x32_bf16 v[100:103], v[64:67], v[206:209], v[100:103]
	v_mfma_f32_16x16x32_bf16 v[96:99], v[136:139], v[206:209], v[96:99]
	v_mfma_f32_16x16x32_bf16 v[84:87], v[64:67], v[214:217], v[84:87]
	v_mfma_f32_16x16x32_bf16 v[80:83], v[136:139], v[214:217], v[80:83]
	v_mfma_f32_16x16x32_bf16 v[132:135], v[68:71], v[194:197], v[132:135]
	v_mfma_f32_16x16x32_bf16 v[128:131], v[162:165], v[194:197], v[128:131]
	v_mfma_f32_16x16x32_bf16 v[116:119], v[68:71], v[202:205], v[116:119]
	v_mfma_f32_16x16x32_bf16 v[112:115], v[162:165], v[202:205], v[112:115]
	v_mfma_f32_16x16x32_bf16 v[100:103], v[68:71], v[210:213], v[100:103]
	v_mfma_f32_16x16x32_bf16 v[96:99], v[162:165], v[210:213], v[96:99]
	v_mfma_f32_16x16x32_bf16 v[84:87], v[68:71], v[218:221], v[84:87]
	v_mfma_f32_16x16x32_bf16 v[80:83], v[162:165], v[218:221], v[80:83]
	s_setprio 0
	s_setprio 1
	v_mfma_f32_16x16x32_bf16 v[124:127], v[172:175], v[188:191], v[124:127]
	v_mfma_f32_16x16x32_bf16 v[120:123], v[180:183], v[188:191], v[120:123]
	v_mfma_f32_16x16x32_bf16 v[108:111], v[172:175], v[198:201], v[108:111]
	v_mfma_f32_16x16x32_bf16 v[104:107], v[180:183], v[198:201], v[104:107]
	v_mfma_f32_16x16x32_bf16 v[92:95], v[172:175], v[206:209], v[92:95]
	v_mfma_f32_16x16x32_bf16 v[88:91], v[180:183], v[206:209], v[88:91]
	v_mfma_f32_16x16x32_bf16 v[76:79], v[172:175], v[214:217], v[76:79]
	v_mfma_f32_16x16x32_bf16 v[72:75], v[180:183], v[214:217], v[72:75]
	v_mfma_f32_16x16x32_bf16 v[124:127], v[176:179], v[194:197], v[124:127]
	v_mfma_f32_16x16x32_bf16 v[120:123], v[184:187], v[194:197], v[120:123]
	v_mfma_f32_16x16x32_bf16 v[108:111], v[176:179], v[202:205], v[108:111]
	v_mfma_f32_16x16x32_bf16 v[104:107], v[184:187], v[202:205], v[104:107]
	v_mfma_f32_16x16x32_bf16 v[92:95], v[176:179], v[210:213], v[92:95]
	v_mfma_f32_16x16x32_bf16 v[88:91], v[184:187], v[210:213], v[88:91]
	v_mfma_f32_16x16x32_bf16 v[76:79], v[176:179], v[218:221], v[76:79]
	v_mfma_f32_16x16x32_bf16 v[72:75], v[184:187], v[218:221], v[72:75]
	s_setprio 0
	s_barrier
; #define PG8_STAGE(bufoff, gbase, voff) do { _Pragma("unroll") for (int _i = 0; _i < 2; ++_i) \
;         __builtin_amdgcn_global_load_lds((const unsigned*)((const char*)(gbase) + (voff)[_i]), (PG8_LAS unsigned*)(lds + (bufoff) + ldsw + _i * 8192), 16, 0, 0); } while (0)
; #define PG8_LDA(dst, b, h) do { _Pragma("unroll") for (int m = 0; m < 4; ++m) _Pragma("unroll") for (int k = 0; k < 2; ++k) dst[m][k] = *(const PG8_LAS bf16x8*)(lds + PG8_SA(b, h) + aoff + m * 2048 + k * 1024); } while (0)
; #define PG8_MMA(ai, bj, At, Bt) do { __builtin_amdgcn_s_setprio(1); _Pragma("unroll") for (int m = 0; m < 4; ++m) _Pragma("unroll") for (int n = 0; n < 2; ++n) _Pragma("unroll") for (int k = 0; k < 2; ++k) \
;         acc[ai][bj][m][n] = __builtin_amdgcn_mfma_f32_16x16x32_bf16(Bt[n][k], At[m][k], acc[ai][bj][m][n], 0, 0, 0); __builtin_amdgcn_s_setprio(0); } while (0)
; #define PG8_WAIT_V(n) asm volatile("s_waitcnt vmcnt(" #n ")" ::: "memory")
; #define PG8_WAIT_L(n) asm volatile("s_waitcnt lgkmcnt(" #n ")" ::: "memory")
; #define PG8_BAR __builtin_amdgcn_s_barrier()
; #define PG8_SCHED __builtin_amdgcn_sched_barrier(0)
; template <class Epi, class Sched, bool ALIGN_EPI = false, bool SP2 = false>
; __device__ __forceinline__ void gemm_phase(PG8_LAS unsigned char* lds, const Gemm g, const Sched& S, const Epi& E) {
;     ...
;             PG8_LDA(At, 1, 1); PG8_STAGE(PG8_SB(1, 0), b3, voffB); PG8_STAGE(PG8_SB(1, 1), b3 + hstep, voffB); PG8_STAGE(PG8_SA(1, 0), a3, voffA);
;             PG8_WAIT_V(8); PG8_WAIT_L(0); PG8_BAR; PG8_MMA(1, 0, At, B0); PG8_MMA(1, 1, At, B1); PG8_BAR; PG8_SCHED;
;     ...
;         if constexpr (ALIGN_EPI) { if (wr == 0) PG8_BAR; }
	s_add_i32 s24, s45, s29
	v_lshl_add_u64 v[222:223], v[222:223], 0, s[8:9]
	s_mov_b32 m0, s24
	ds_read_b128 v[188:191], v170 offset:49152
	ds_read_b128 v[194:197], v170 offset:50176
	ds_read_b128 v[198:201], v170 offset:51200
	ds_read_b128 v[202:205], v170 offset:52224
	ds_read_b128 v[206:209], v170 offset:53248
	ds_read_b128 v[210:213], v170 offset:54272
	ds_read_b128 v[214:217], v170 offset:55296
	ds_read_b128 v[218:221], v170 offset:56320
	global_load_lds_dwordx4 v[222:223], off
	s_add_i32 m0, s24, 0x2000
	s_add_u32 s22, s22, 0x80080
	v_lshl_add_u64 v[222:223], v[224:225], 0, s[8:9]
	s_addc_u32 s23, s23, 0
	s_add_i32 s24, s46, s29
	global_load_lds_dwordx4 v[222:223], off
	v_lshl_add_u64 v[222:223], s[22:23], 0, v[142:143]
	s_mov_b32 m0, s24
	s_nop 0
	global_load_lds_dwordx4 v[222:223], off
	v_lshl_add_u64 v[222:223], s[22:23], 0, v[146:147]
	s_add_i32 m0, s24, 0x2000
	s_nop 0
	global_load_lds_dwordx4 v[222:223], off
	v_lshl_add_u64 v[222:223], v[226:227], 0, s[8:9]
	s_mov_b32 m0, s37
	s_nop 0
	global_load_lds_dwordx4 v[222:223], off
	v_lshl_add_u64 v[222:223], v[228:229], 0, s[8:9]
	s_mov_b32 m0, s38
	s_nop 0
	global_load_lds_dwordx4 v[222:223], off
	s_waitcnt vmcnt(8)
	s_waitcnt lgkmcnt(0)
	s_barrier
	s_setprio 1
	s_waitcnt lgkmcnt(0)
	v_mfma_f32_16x16x32_bf16 v[60:63], v[64:67], v[188:191], v[60:63]
	v_mfma_f32_16x16x32_bf16 v[56:59], v[136:139], v[188:191], v[56:59]
	v_mfma_f32_16x16x32_bf16 v[44:47], v[64:67], v[198:201], v[44:47]
	v_mfma_f32_16x16x32_bf16 v[40:43], v[136:139], v[198:201], v[40:43]
	v_mfma_f32_16x16x32_bf16 v[28:31], v[64:67], v[206:209], v[28:31]
	v_mfma_f32_16x16x32_bf16 v[24:27], v[136:139], v[206:209], v[24:27]
	v_mfma_f32_16x16x32_bf16 v[12:15], v[64:67], v[214:217], v[12:15]
	v_mfma_f32_16x16x32_bf16 v[8:11], v[136:139], v[214:217], v[8:11]
	v_mfma_f32_16x16x32_bf16 v[60:63], v[68:71], v[194:197], v[60:63]
	v_mfma_f32_16x16x32_bf16 v[56:59], v[162:165], v[194:197], v[56:59]
	v_mfma_f32_16x16x32_bf16 v[44:47], v[68:71], v[202:205], v[44:47]
	v_mfma_f32_16x16x32_bf16 v[40:43], v[162:165], v[202:205], v[40:43]
	v_mfma_f32_16x16x32_bf16 v[28:31], v[68:71], v[210:213], v[28:31]
	v_mfma_f32_16x16x32_bf16 v[24:27], v[162:165], v[210:213], v[24:27]
	v_mfma_f32_16x16x32_bf16 v[12:15], v[68:71], v[218:221], v[12:15]
	v_mfma_f32_16x16x32_bf16 v[8:11], v[162:165], v[218:221], v[8:11]
	s_setprio 0
	s_setprio 1
	v_mfma_f32_16x16x32_bf16 v[52:55], v[172:175], v[188:191], v[52:55]
	v_mfma_f32_16x16x32_bf16 v[48:51], v[180:183], v[188:191], v[48:51]
	v_mfma_f32_16x16x32_bf16 v[36:39], v[172:175], v[198:201], v[36:39]
	v_mfma_f32_16x16x32_bf16 v[32:35], v[180:183], v[198:201], v[32:35]
	v_mfma_f32_16x16x32_bf16 v[20:23], v[172:175], v[206:209], v[20:23]
	v_mfma_f32_16x16x32_bf16 v[16:19], v[180:183], v[206:209], v[16:19]
	v_mfma_f32_16x16x32_bf16 v[4:7], v[172:175], v[214:217], v[4:7]
	v_mfma_f32_16x16x32_bf16 v[0:3], v[180:183], v[214:217], v[0:3]
	v_mfma_f32_16x16x32_bf16 v[52:55], v[176:179], v[194:197], v[52:55]
	v_mfma_f32_16x16x32_bf16 v[48:51], v[184:187], v[194:197], v[48:51]
	v_mfma_f32_16x16x32_bf16 v[36:39], v[176:179], v[202:205], v[36:39]
	v_mfma_f32_16x16x32_bf16 v[32:35], v[184:187], v[202:205], v[32:35]
	v_mfma_f32_16x16x32_bf16 v[20:23], v[176:179], v[210:213], v[20:23]
	v_mfma_f32_16x16x32_bf16 v[16:19], v[184:187], v[210:213], v[16:19]
	v_mfma_f32_16x16x32_bf16 v[4:7], v[176:179], v[218:221], v[4:7]
	v_mfma_f32_16x16x32_bf16 v[0:3], v[184:187], v[218:221], v[0:3]
	s_setprio 0
	s_barrier
	s_add_i32 s44, s44, 2
	s_add_u32 s20, s20, 0x100
	s_addc_u32 s21, s21, 0
	s_add_u32 s33, s33, 0x100
	s_addc_u32 s43, s43, 0
	s_cmp_gt_u32 s44, 29
	s_cbranch_scc0 .LBB0_797
	s_and_b64 vcc, exec, s[10:11]
	s_cbranch_vccz .LBB0_800
	s_barrier

; #define PG8_STAGE(bufoff, gbase, voff) do { _Pragma("unroll") for (int _i = 0; _i < 2; ++_i) \
;         __builtin_amdgcn_global_load_lds((const unsigned*)((const char*)(gbase) + (voff)[_i]), (PG8_LAS unsigned*)(lds + (bufoff) + ldsw + _i * 8192), 16, 0, 0); } while (0)
; #define PG8_LDA(dst, b, h) do { _Pragma("unroll") for (int m = 0; m < 4; ++m) _Pragma("unroll") for (int k = 0; k < 2; ++k) dst[m][k] = *(const PG8_LAS bf16x8*)(lds + PG8_SA(b, h) + aoff + m * 2048 + k * 1024); } while (0)
; #define PG8_LDB(dst, b, h) do { _Pragma("unroll") for (int n = 0; n < 2; ++n) _Pragma("unroll") for (int k = 0; k < 2; ++k) dst[n][k] = *(const PG8_LAS bf16x8*)(lds + PG8_SB(b, h) + boff + n * 2048 + k * 1024); } while (0)
; #define PG8_MMA(ai, bj, At, Bt) do { __builtin_amdgcn_s_setprio(1); _Pragma("unroll") for (int m = 0; m < 4; ++m) _Pragma("unroll") for (int n = 0; n < 2; ++n) _Pragma("unroll") for (int k = 0; k < 2; ++k) \
;         acc[ai][bj][m][n] = __builtin_amdgcn_mfma_f32_16x16x32_bf16(Bt[n][k], At[m][k], acc[ai][bj][m][n], 0, 0, 0); __builtin_amdgcn_s_setprio(0); } while (0)
; #define PG8_WAIT_V(n) asm volatile("s_waitcnt vmcnt(" #n ")" ::: "memory")
; #define PG8_BAR __builtin_amdgcn_s_barrier()
; template <class Epi, class Sched, bool ALIGN_EPI = false, bool SP2 = false>
; __device__ __forceinline__ void gemm_phase(PG8_LAS unsigned char* lds, const Gemm g, const Sched& S, const Epi& E) {
;     ...
;         for (int t = 0; t < nt; t += 2) {
;             const bool last = (t == nt - 2);
;             const char* a1 = cA + (size_t)(t + 1) * kstep;
;             const char* a2 = last ? nA : cA + (size_t)(t + 2) * kstep; const char* b2 = last ? nB : cB + (size_t)(t + 2) * kstep;
;             const char* a3 = a2 + kstep; const char* b3 = b2 + kstep;
;             if (last && has_next) S.a_ready(nxt);
;             if constexpr (SP2) {
;             PG8_LDB(B0, 0, 0); PG8_LDB(B1, 0, 1); PG8_SCHED; PG8_LDA(At, 0, 0); PG8_STAGE(PG8_SA(1, 1), a1 + hstep, voffA);
;             PG8_WAIT_V(8); PG8_WAIT_L(0); PG8_BAR; PG8_MMA(0, 0, At, B0); PG8_MMA(0, 1, At, B1); PG8_BAR; PG8_SCHED;
;             PG8_LDA(At, 0, 1); PG8_STAGE(PG8_SB(0, 0), b2, voffB); PG8_STAGE(PG8_SB(0, 1), b2 + hstep, voffB); PG8_STAGE(PG8_SA(0, 0), a2, voffA);
;             PG8_WAIT_V(8); PG8_WAIT_L(0); PG8_BAR; PG8_MMA(1, 0, At, B0); PG8_MMA(1, 1, At, B1); PG8_BAR; PG8_SCHED;
.LBB0_821:
	ds_read_b128 v[146:149], v155
	ds_read_b128 v[158:161], v155 offset:1024
	ds_read_b128 v[162:165], v155 offset:2048
	ds_read_b128 v[166:169], v155 offset:3072
	ds_read_b128 v[170:173], v156
	ds_read_b128 v[174:177], v156 offset:1024
	ds_read_b128 v[178:181], v156 offset:2048
	ds_read_b128 v[182:185], v156 offset:3072
	s_add_u32 s28, s26, 0xfff80080
	s_addc_u32 s29, s27, -1
	s_cmp_eq_u32 s54, 28
	s_cselect_b32 s31, s19, s29
	s_cselect_b32 s30, s33, s28
	s_cselect_b32 s29, s1, s53
	s_cselect_b32 s28, s51, s52
	v_lshl_add_u64 v[150:151], s[26:27], 0, v[138:139]
	s_add_i32 m0, s25, 0xc000
	ds_read_b128 v[186:189], v157
	ds_read_b128 v[194:197], v157 offset:1024
	ds_read_b128 v[198:201], v157 offset:2048
	ds_read_b128 v[202:205], v157 offset:3072
	ds_read_b128 v[206:209], v157 offset:4096
	ds_read_b128 v[210:213], v157 offset:5120
	ds_read_b128 v[214:217], v157 offset:6144
	ds_read_b128 v[218:221], v157 offset:7168
	global_load_lds_dwordx4 v[150:151], off
	v_lshl_add_u64 v[150:151], s[26:27], 0, v[140:141]
	s_add_i32 m0, s25, 0xe000
	s_nop 0
	global_load_lds_dwordx4 v[150:151], off
	s_waitcnt vmcnt(8)
	s_waitcnt lgkmcnt(0)
	s_barrier
	s_setprio 1
	s_waitcnt lgkmcnt(0)
	v_mfma_f32_16x16x32_bf16 v[124:127], v[146:149], v[186:189], v[124:127]
	v_mfma_f32_16x16x32_bf16 v[120:123], v[162:165], v[186:189], v[120:123]
	v_mfma_f32_16x16x32_bf16 v[108:111], v[146:149], v[198:201], v[108:111]
	v_mfma_f32_16x16x32_bf16 v[104:107], v[162:165], v[198:201], v[104:107]
	v_mfma_f32_16x16x32_bf16 v[92:95], v[146:149], v[206:209], v[92:95]
	v_mfma_f32_16x16x32_bf16 v[88:91], v[162:165], v[206:209], v[88:91]
	v_mfma_f32_16x16x32_bf16 v[76:79], v[146:149], v[214:217], v[76:79]
	v_mfma_f32_16x16x32_bf16 v[72:75], v[162:165], v[214:217], v[72:75]
	v_mfma_f32_16x16x32_bf16 v[124:127], v[158:161], v[194:197], v[124:127]
	v_mfma_f32_16x16x32_bf16 v[120:123], v[166:169], v[194:197], v[120:123]
	v_mfma_f32_16x16x32_bf16 v[108:111], v[158:161], v[202:205], v[108:111]
	v_mfma_f32_16x16x32_bf16 v[104:107], v[166:169], v[202:205], v[104:107]
	v_mfma_f32_16x16x32_bf16 v[92:95], v[158:161], v[210:213], v[92:95]
	v_mfma_f32_16x16x32_bf16 v[88:91], v[166:169], v[210:213], v[88:91]
	v_mfma_f32_16x16x32_bf16 v[76:79], v[158:161], v[218:221], v[76:79]
	v_mfma_f32_16x16x32_bf16 v[72:75], v[166:169], v[218:221], v[72:75]
	s_setprio 0
	s_setprio 1
	v_mfma_f32_16x16x32_bf16 v[116:119], v[170:173], v[186:189], v[116:119]
	v_mfma_f32_16x16x32_bf16 v[112:115], v[178:181], v[186:189], v[112:115]
	v_mfma_f32_16x16x32_bf16 v[100:103], v[170:173], v[198:201], v[100:103]
	v_mfma_f32_16x16x32_bf16 v[96:99], v[178:181], v[198:201], v[96:99]
	v_mfma_f32_16x16x32_bf16 v[84:87], v[170:173], v[206:209], v[84:87]
	v_mfma_f32_16x16x32_bf16 v[80:83], v[178:181], v[206:209], v[80:83]
	v_mfma_f32_16x16x32_bf16 v[68:71], v[170:173], v[214:217], v[68:71]
	v_mfma_f32_16x16x32_bf16 v[64:67], v[178:181], v[214:217], v[64:67]
	v_mfma_f32_16x16x32_bf16 v[116:119], v[174:177], v[194:197], v[116:119]
	v_mfma_f32_16x16x32_bf16 v[112:115], v[182:185], v[194:197], v[112:115]
	v_mfma_f32_16x16x32_bf16 v[100:103], v[174:177], v[202:205], v[100:103]
	v_mfma_f32_16x16x32_bf16 v[96:99], v[182:185], v[202:205], v[96:99]
	v_mfma_f32_16x16x32_bf16 v[84:87], v[174:177], v[210:213], v[84:87]
	v_mfma_f32_16x16x32_bf16 v[80:83], v[182:185], v[210:213], v[80:83]
	v_mfma_f32_16x16x32_bf16 v[68:71], v[174:177], v[218:221], v[68:71]
	v_mfma_f32_16x16x32_bf16 v[64:67], v[182:185], v[218:221], v[64:67]
	s_setprio 0
	s_barrier
	s_add_i32 s55, s46, s37
	v_lshl_add_u64 v[150:151], s[28:29], 0, v[130:131]
	s_mov_b32 m0, s55
	ds_read_b128 v[186:189], v157 offset:16384
	ds_read_b128 v[194:197], v157 offset:17408
	ds_read_b128 v[198:201], v157 offset:18432
	ds_read_b128 v[202:205], v157 offset:19456
	ds_read_b128 v[206:209], v157 offset:20480
	ds_read_b128 v[210:213], v157 offset:21504
	ds_read_b128 v[214:217], v157 offset:22528
	ds_read_b128 v[218:221], v157 offset:23552
	global_load_lds_dwordx4 v[150:151], off
	s_add_i32 m0, s55, 0x2000
	s_add_u32 s56, s28, 0x80000
	v_lshl_add_u64 v[190:191], s[28:29], 0, v[134:135]
	s_addc_u32 s57, s29, 0
	s_add_i32 s55, s47, s37
	global_load_lds_dwordx4 v[190:191], off
	v_lshl_add_u64 v[222:223], s[56:57], 0, v[130:131]
	s_mov_b32 m0, s55
	v_lshl_add_u64 v[224:225], s[30:31], 0, v[132:133]
	global_load_lds_dwordx4 v[222:223], off
	v_lshl_add_u64 v[222:223], s[56:57], 0, v[134:135]
	s_add_i32 m0, s55, 0x2000
	s_nop 0
	global_load_lds_dwordx4 v[222:223], off
	v_lshl_add_u64 v[222:223], s[30:31], 0, v[128:129]
	s_mov_b32 m0, s25
	s_nop 0
	global_load_lds_dwordx4 v[222:223], off
	s_mov_b32 m0, s38
	s_nop 0
	global_load_lds_dwordx4 v[224:225], off
	s_waitcnt vmcnt(8)
	s_waitcnt lgkmcnt(0)
	s_barrier
; #define PG8_STAGE(bufoff, gbase, voff) do { _Pragma("unroll") for (int _i = 0; _i < 2; ++_i) \
;         __builtin_amdgcn_global_load_lds((const unsigned*)((const char*)(gbase) + (voff)[_i]), (PG8_LAS unsigned*)(lds + (bufoff) + ldsw + _i * 8192), 16, 0, 0); } while (0)
; #define PG8_LDA(dst, b, h) do { _Pragma("unroll") for (int m = 0; m < 4; ++m) _Pragma("unroll") for (int k = 0; k < 2; ++k) dst[m][k] = *(const PG8_LAS bf16x8*)(lds + PG8_SA(b, h) + aoff + m * 2048 + k * 1024); } while (0)
; #define PG8_LDB(dst, b, h) do { _Pragma("unroll") for (int n = 0; n < 2; ++n) _Pragma("unroll") for (int k = 0; k < 2; ++k) dst[n][k] = *(const PG8_LAS bf16x8*)(lds + PG8_SB(b, h) + boff + n * 2048 + k * 1024); } while (0)
; #define PG8_MMA(ai, bj, At, Bt) do { __builtin_amdgcn_s_setprio(1); _Pragma("unroll") for (int m = 0; m < 4; ++m) _Pragma("unroll") for (int n = 0; n < 2; ++n) _Pragma("unroll") for (int k = 0; k < 2; ++k) \
;         acc[ai][bj][m][n] = __builtin_amdgcn_mfma_f32_16x16x32_bf16(Bt[n][k], At[m][k], acc[ai][bj][m][n], 0, 0, 0); __builtin_amdgcn_s_setprio(0); } while (0)
; #define PG8_WAIT_V(n) asm volatile("s_waitcnt vmcnt(" #n ")" ::: "memory")
; #define PG8_WAIT_L(n) asm volatile("s_waitcnt lgkmcnt(" #n ")" ::: "memory")
; #define PG8_BAR __builtin_amdgcn_s_barrier()
; #define PG8_SCHED __builtin_amdgcn_sched_barrier(0)
; template <class Epi, class Sched, bool ALIGN_EPI = false, bool SP2 = false>
; __device__ __forceinline__ void gemm_phase(PG8_LAS unsigned char* lds, const Gemm g, const Sched& S, const Epi& E) {
;     ...
;             PG8_WAIT_V(8); PG8_WAIT_L(0); PG8_BAR; PG8_MMA(1, 0, At, B0); PG8_MMA(1, 1, At, B1); PG8_BAR; PG8_SCHED;
;             PG8_LDB(B0, 1, 0); PG8_LDB(B1, 1, 1); PG8_SCHED; PG8_LDA(At, 1, 0); PG8_STAGE(PG8_SA(0, 1), a2 + hstep, voffA);
;             PG8_WAIT_V(8); PG8_WAIT_L(0); PG8_BAR; PG8_MMA(0, 0, At, B0); PG8_MMA(0, 1, At, B1); PG8_BAR; PG8_SCHED;
	s_setprio 1
	s_waitcnt lgkmcnt(0)
	v_mfma_f32_16x16x32_bf16 v[60:63], v[146:149], v[186:189], v[60:63]
	v_mfma_f32_16x16x32_bf16 v[56:59], v[162:165], v[186:189], v[56:59]
	v_mfma_f32_16x16x32_bf16 v[44:47], v[146:149], v[198:201], v[44:47]
	v_mfma_f32_16x16x32_bf16 v[40:43], v[162:165], v[198:201], v[40:43]
	v_mfma_f32_16x16x32_bf16 v[28:31], v[146:149], v[206:209], v[28:31]
	v_mfma_f32_16x16x32_bf16 v[24:27], v[162:165], v[206:209], v[24:27]
	v_mfma_f32_16x16x32_bf16 v[12:15], v[146:149], v[214:217], v[12:15]
	v_mfma_f32_16x16x32_bf16 v[8:11], v[162:165], v[214:217], v[8:11]
	v_mfma_f32_16x16x32_bf16 v[60:63], v[158:161], v[194:197], v[60:63]
	v_mfma_f32_16x16x32_bf16 v[56:59], v[166:169], v[194:197], v[56:59]
	v_mfma_f32_16x16x32_bf16 v[44:47], v[158:161], v[202:205], v[44:47]
	v_mfma_f32_16x16x32_bf16 v[40:43], v[166:169], v[202:205], v[40:43]
	v_mfma_f32_16x16x32_bf16 v[28:31], v[158:161], v[210:213], v[28:31]
	v_mfma_f32_16x16x32_bf16 v[24:27], v[166:169], v[210:213], v[24:27]
	v_mfma_f32_16x16x32_bf16 v[12:15], v[158:161], v[218:221], v[12:15]
	v_mfma_f32_16x16x32_bf16 v[8:11], v[166:169], v[218:221], v[8:11]
	s_setprio 0
	s_setprio 1
	v_mfma_f32_16x16x32_bf16 v[52:55], v[170:173], v[186:189], v[52:55]
	v_mfma_f32_16x16x32_bf16 v[48:51], v[178:181], v[186:189], v[48:51]
	v_mfma_f32_16x16x32_bf16 v[36:39], v[170:173], v[198:201], v[36:39]
	v_mfma_f32_16x16x32_bf16 v[32:35], v[178:181], v[198:201], v[32:35]
	v_mfma_f32_16x16x32_bf16 v[20:23], v[170:173], v[206:209], v[20:23]
	v_mfma_f32_16x16x32_bf16 v[16:19], v[178:181], v[206:209], v[16:19]
	v_mfma_f32_16x16x32_bf16 v[4:7], v[170:173], v[214:217], v[4:7]
	v_mfma_f32_16x16x32_bf16 v[0:3], v[178:181], v[214:217], v[0:3]
	v_mfma_f32_16x16x32_bf16 v[52:55], v[174:177], v[194:197], v[52:55]
	v_mfma_f32_16x16x32_bf16 v[48:51], v[182:185], v[194:197], v[48:51]
	v_mfma_f32_16x16x32_bf16 v[36:39], v[174:177], v[202:205], v[36:39]
	v_mfma_f32_16x16x32_bf16 v[32:35], v[182:185], v[202:205], v[32:35]
	v_mfma_f32_16x16x32_bf16 v[20:23], v[174:177], v[210:213], v[20:23]
	v_mfma_f32_16x16x32_bf16 v[16:19], v[182:185], v[210:213], v[16:19]
	v_mfma_f32_16x16x32_bf16 v[4:7], v[174:177], v[218:221], v[4:7]
	v_mfma_f32_16x16x32_bf16 v[0:3], v[182:185], v[218:221], v[0:3]
	s_setprio 0
	s_barrier
	s_add_i32 s55, 0, 0x18000
	v_add_u32_e32 v136, s55, v153
	s_add_i32 s56, 0, 0x1c000
	ds_read_b128 v[146:149], v136
	ds_read_b128 v[158:161], v136 offset:1024
	ds_read_b128 v[162:165], v136 offset:2048
	ds_read_b128 v[166:169], v136 offset:3072
	v_add_u32_e32 v136, s56, v153
	ds_read_b128 v[170:173], v136
	ds_read_b128 v[174:177], v136 offset:1024
	ds_read_b128 v[178:181], v136 offset:2048
	ds_read_b128 v[182:185], v136 offset:3072
	s_add_u32 s30, s30, 0x80000
	s_addc_u32 s31, s31, 0
	s_mov_b32 m0, s39
	v_lshl_add_u64 v[226:227], s[30:31], 0, v[128:129]
	ds_read_b128 v[186:189], v157 offset:32768
	ds_read_b128 v[194:197], v157 offset:33792
	ds_read_b128 v[198:201], v157 offset:34816
	ds_read_b128 v[202:205], v157 offset:35840
	ds_read_b128 v[206:209], v157 offset:36864
	ds_read_b128 v[210:213], v157 offset:37888
	ds_read_b128 v[214:217], v157 offset:38912
	ds_read_b128 v[218:221], v157 offset:39936
	global_load_lds_dwordx4 v[226:227], off
	v_lshl_add_u64 v[226:227], s[30:31], 0, v[132:133]
	s_mov_b32 m0, s40
	s_nop 0
	global_load_lds_dwordx4 v[226:227], off
	s_waitcnt vmcnt(8)
	s_waitcnt lgkmcnt(0)
	s_barrier
	s_setprio 1
	s_waitcnt lgkmcnt(0)
	v_mfma_f32_16x16x32_bf16 v[124:127], v[146:149], v[186:189], v[124:127]
	v_mfma_f32_16x16x32_bf16 v[120:123], v[162:165], v[186:189], v[120:123]
	v_mfma_f32_16x16x32_bf16 v[108:111], v[146:149], v[198:201], v[108:111]
	v_mfma_f32_16x16x32_bf16 v[104:107], v[162:165], v[198:201], v[104:107]
	v_mfma_f32_16x16x32_bf16 v[92:95], v[146:149], v[206:209], v[92:95]
	v_mfma_f32_16x16x32_bf16 v[88:91], v[162:165], v[206:209], v[88:91]
	v_mfma_f32_16x16x32_bf16 v[76:79], v[146:149], v[214:217], v[76:79]
	v_mfma_f32_16x16x32_bf16 v[72:75], v[162:165], v[214:217], v[72:75]
	v_mfma_f32_16x16x32_bf16 v[124:127], v[158:161], v[194:197], v[124:127]
	v_mfma_f32_16x16x32_bf16 v[120:123], v[166:169], v[194:197], v[120:123]
	v_mfma_f32_16x16x32_bf16 v[108:111], v[158:161], v[202:205], v[108:111]
	v_mfma_f32_16x16x32_bf16 v[104:107], v[166:169], v[202:205], v[104:107]
	v_mfma_f32_16x16x32_bf16 v[92:95], v[158:161], v[210:213], v[92:95]
	v_mfma_f32_16x16x32_bf16 v[88:91], v[166:169], v[210:213], v[88:91]
	v_mfma_f32_16x16x32_bf16 v[76:79], v[158:161], v[218:221], v[76:79]
	v_mfma_f32_16x16x32_bf16 v[72:75], v[166:169], v[218:221], v[72:75]
	s_setprio 0
	s_setprio 1
	v_mfma_f32_16x16x32_bf16 v[116:119], v[170:173], v[186:189], v[116:119]
	v_mfma_f32_16x16x32_bf16 v[112:115], v[178:181], v[186:189], v[112:115]
	v_mfma_f32_16x16x32_bf16 v[100:103], v[170:173], v[198:201], v[100:103]
	v_mfma_f32_16x16x32_bf16 v[96:99], v[178:181], v[198:201], v[96:99]
	v_mfma_f32_16x16x32_bf16 v[84:87], v[170:173], v[206:209], v[84:87]
	v_mfma_f32_16x16x32_bf16 v[80:83], v[178:181], v[206:209], v[80:83]
	v_mfma_f32_16x16x32_bf16 v[68:71], v[170:173], v[214:217], v[68:71]
	v_mfma_f32_16x16x32_bf16 v[64:67], v[178:181], v[214:217], v[64:67]
	v_mfma_f32_16x16x32_bf16 v[116:119], v[174:177], v[194:197], v[116:119]
	v_mfma_f32_16x16x32_bf16 v[112:115], v[182:185], v[194:197], v[112:115]
	v_mfma_f32_16x16x32_bf16 v[100:103], v[174:177], v[202:205], v[100:103]
	v_mfma_f32_16x16x32_bf16 v[96:99], v[182:185], v[202:205], v[96:99]
	v_mfma_f32_16x16x32_bf16 v[84:87], v[174:177], v[210:213], v[84:87]
	v_mfma_f32_16x16x32_bf16 v[80:83], v[182:185], v[210:213], v[80:83]
	v_mfma_f32_16x16x32_bf16 v[68:71], v[174:177], v[218:221], v[68:71]
	v_mfma_f32_16x16x32_bf16 v[64:67], v[182:185], v[218:221], v[64:67]
	s_setprio 0
	s_barrier
; #define PG8_STAGE(bufoff, gbase, voff) do { _Pragma("unroll") for (int _i = 0; _i < 2; ++_i) \
;         __builtin_amdgcn_global_load_lds((const unsigned*)((const char*)(gbase) + (voff)[_i]), (PG8_LAS unsigned*)(lds + (bufoff) + ldsw + _i * 8192), 16, 0, 0); } while (0)
; #define PG8_LDA(dst, b, h) do { _Pragma("unroll") for (int m = 0; m < 4; ++m) _Pragma("unroll") for (int k = 0; k < 2; ++k) dst[m][k] = *(const PG8_LAS bf16x8*)(lds + PG8_SA(b, h) + aoff + m * 2048 + k * 1024); } while (0)
; #define PG8_LDB(dst, b, h) do { _Pragma("unroll") for (int n = 0; n < 2; ++n) _Pragma("unroll") for (int k = 0; k < 2; ++k) dst[n][k] = *(const PG8_LAS bf16x8*)(lds + PG8_SB(b, h) + boff + n * 2048 + k * 1024); } while (0)
; #define PG8_MMA(ai, bj, At, Bt) do { __builtin_amdgcn_s_setprio(1); _Pragma("unroll") for (int m = 0; m < 4; ++m) _Pragma("unroll") for (int n = 0; n < 2; ++n) _Pragma("unroll") for (int k = 0; k < 2; ++k) \
;         acc[ai][bj][m][n] = __builtin_amdgcn_mfma_f32_16x16x32_bf16(Bt[n][k], At[m][k], acc[ai][bj][m][n], 0, 0, 0); __builtin_amdgcn_s_setprio(0); } while (0)
; #define PG8_WAIT_V(n) asm volatile("s_waitcnt vmcnt(" #n ")" ::: "memory")
; #define PG8_WAIT_L(n) asm volatile("s_waitcnt lgkmcnt(" #n ")" ::: "memory")
; #define PG8_BAR __builtin_amdgcn_s_barrier()
; #define PG8_SCHED __builtin_amdgcn_sched_barrier(0)
; template <class Epi, class Sched, bool ALIGN_EPI = false, bool SP2 = false>
; __device__ __forceinline__ void gemm_phase(PG8_LAS unsigned char* lds, const Gemm g, const Sched& S, const Epi& E) {
;     ...
;             PG8_LDB(B0, 1, 0); PG8_LDB(B1, 1, 1); PG8_SCHED; PG8_LDA(At, 1, 0); PG8_STAGE(PG8_SA(0, 1), a2 + hstep, voffA);
;             PG8_WAIT_V(8); PG8_WAIT_L(0); PG8_BAR; PG8_MMA(0, 0, At, B0); PG8_MMA(0, 1, At, B1); PG8_BAR; PG8_SCHED;
;             PG8_LDA(At, 1, 1); PG8_STAGE(PG8_SB(1, 0), b3, voffB); PG8_STAGE(PG8_SB(1, 1), b3 + hstep, voffB); PG8_STAGE(PG8_SA(1, 0), a3, voffA);
;             PG8_WAIT_V(8); PG8_WAIT_L(0); PG8_BAR; PG8_MMA(1, 0, At, B0); PG8_MMA(1, 1, At, B1); PG8_BAR; PG8_SCHED;
	s_add_i32 s30, s55, s37
	v_lshl_add_u64 v[150:151], v[150:151], 0, s[8:9]
	s_mov_b32 m0, s30
	ds_read_b128 v[186:189], v157 offset:49152
	ds_read_b128 v[194:197], v157 offset:50176
	ds_read_b128 v[198:201], v157 offset:51200
	ds_read_b128 v[202:205], v157 offset:52224
	ds_read_b128 v[206:209], v157 offset:53248
	ds_read_b128 v[210:213], v157 offset:54272
	ds_read_b128 v[214:217], v157 offset:55296
	ds_read_b128 v[218:221], v157 offset:56320
	global_load_lds_dwordx4 v[150:151], off
	s_add_i32 m0, s30, 0x2000
	s_add_u32 s28, s28, 0x80080
	v_lshl_add_u64 v[150:151], v[190:191], 0, s[8:9]
	s_addc_u32 s29, s29, 0
	s_add_i32 s30, s56, s37
	global_load_lds_dwordx4 v[150:151], off
	v_lshl_add_u64 v[150:151], s[28:29], 0, v[130:131]
	s_mov_b32 m0, s30
	s_nop 0
	global_load_lds_dwordx4 v[150:151], off
	v_lshl_add_u64 v[150:151], s[28:29], 0, v[134:135]
	s_add_i32 m0, s30, 0x2000
	s_nop 0
	global_load_lds_dwordx4 v[150:151], off
	v_lshl_add_u64 v[150:151], v[222:223], 0, s[8:9]
	s_mov_b32 m0, s42
	s_nop 0
	global_load_lds_dwordx4 v[150:151], off
	v_lshl_add_u64 v[150:151], v[224:225], 0, s[8:9]
	s_mov_b32 m0, s43
	s_nop 0
	global_load_lds_dwordx4 v[150:151], off
	s_waitcnt vmcnt(8)
	s_waitcnt lgkmcnt(0)
	s_barrier
	s_setprio 1
	s_waitcnt lgkmcnt(0)
	v_mfma_f32_16x16x32_bf16 v[60:63], v[146:149], v[186:189], v[60:63]
	v_mfma_f32_16x16x32_bf16 v[56:59], v[162:165], v[186:189], v[56:59]
	v_mfma_f32_16x16x32_bf16 v[44:47], v[146:149], v[198:201], v[44:47]
	v_mfma_f32_16x16x32_bf16 v[40:43], v[162:165], v[198:201], v[40:43]
	v_mfma_f32_16x16x32_bf16 v[28:31], v[146:149], v[206:209], v[28:31]
	v_mfma_f32_16x16x32_bf16 v[24:27], v[162:165], v[206:209], v[24:27]
	v_mfma_f32_16x16x32_bf16 v[12:15], v[146:149], v[214:217], v[12:15]
	v_mfma_f32_16x16x32_bf16 v[8:11], v[162:165], v[214:217], v[8:11]
	v_mfma_f32_16x16x32_bf16 v[60:63], v[158:161], v[194:197], v[60:63]
	v_mfma_f32_16x16x32_bf16 v[56:59], v[166:169], v[194:197], v[56:59]
	v_mfma_f32_16x16x32_bf16 v[44:47], v[158:161], v[202:205], v[44:47]
	v_mfma_f32_16x16x32_bf16 v[40:43], v[166:169], v[202:205], v[40:43]
	v_mfma_f32_16x16x32_bf16 v[28:31], v[158:161], v[210:213], v[28:31]
	v_mfma_f32_16x16x32_bf16 v[24:27], v[166:169], v[210:213], v[24:27]
	v_mfma_f32_16x16x32_bf16 v[12:15], v[158:161], v[218:221], v[12:15]
	v_mfma_f32_16x16x32_bf16 v[8:11], v[166:169], v[218:221], v[8:11]
	s_setprio 0
	s_setprio 1
	v_mfma_f32_16x16x32_bf16 v[52:55], v[170:173], v[186:189], v[52:55]
	v_mfma_f32_16x16x32_bf16 v[48:51], v[178:181], v[186:189], v[48:51]
	v_mfma_f32_16x16x32_bf16 v[36:39], v[170:173], v[198:201], v[36:39]
	v_mfma_f32_16x16x32_bf16 v[32:35], v[178:181], v[198:201], v[32:35]
	v_mfma_f32_16x16x32_bf16 v[20:23], v[170:173], v[206:209], v[20:23]
	v_mfma_f32_16x16x32_bf16 v[16:19], v[178:181], v[206:209], v[16:19]
	v_mfma_f32_16x16x32_bf16 v[4:7], v[170:173], v[214:217], v[4:7]
	v_mfma_f32_16x16x32_bf16 v[0:3], v[178:181], v[214:217], v[0:3]
	v_mfma_f32_16x16x32_bf16 v[52:55], v[174:177], v[194:197], v[52:55]
	v_mfma_f32_16x16x32_bf16 v[48:51], v[182:185], v[194:197], v[48:51]
	v_mfma_f32_16x16x32_bf16 v[36:39], v[174:177], v[202:205], v[36:39]
	v_mfma_f32_16x16x32_bf16 v[32:35], v[182:185], v[202:205], v[32:35]
	v_mfma_f32_16x16x32_bf16 v[20:23], v[174:177], v[210:213], v[20:23]
	v_mfma_f32_16x16x32_bf16 v[16:19], v[182:185], v[210:213], v[16:19]
	v_mfma_f32_16x16x32_bf16 v[4:7], v[174:177], v[218:221], v[4:7]
	v_mfma_f32_16x16x32_bf16 v[0:3], v[182:185], v[218:221], v[0:3]
	s_setprio 0
	s_barrier
	s_add_i32 s54, s54, 2
	s_add_u32 s26, s26, 0x100
	s_addc_u32 s27, s27, 0
	s_add_u32 s52, s52, 0x100
	s_addc_u32 s53, s53, 0
	s_cmp_gt_u32 s54, 29
	s_cbranch_scc0 .LBB0_821
	s_and_b64 vcc, exec, s[10:11]
	s_cbranch_vccz .LBB0_824
	s_barrier

; #define PG8_STAGE(bufoff, gbase, voff) do { _Pragma("unroll") for (int _i = 0; _i < 2; ++_i) \
;         __builtin_amdgcn_global_load_lds((const unsigned*)((const char*)(gbase) + (voff)[_i]), (PG8_LAS unsigned*)(lds + (bufoff) + ldsw + _i * 8192), 16, 0, 0); } while (0)
; #define PG8_LDA(dst, b, h) do { _Pragma("unroll") for (int m = 0; m < 4; ++m) _Pragma("unroll") for (int k = 0; k < 2; ++k) dst[m][k] = *(const PG8_LAS bf16x8*)(lds + PG8_SA(b, h) + aoff + m * 2048 + k * 1024); } while (0)
; #define PG8_LDB(dst, b, h) do { _Pragma("unroll") for (int n = 0; n < 2; ++n) _Pragma("unroll") for (int k = 0; k < 2; ++k) dst[n][k] = *(const PG8_LAS bf16x8*)(lds + PG8_SB(b, h) + boff + n * 2048 + k * 1024); } while (0)
; #define PG8_MMA(ai, bj, At, Bt) do { __builtin_amdgcn_s_setprio(1); _Pragma("unroll") for (int m = 0; m < 4; ++m) _Pragma("unroll") for (int n = 0; n < 2; ++n) _Pragma("unroll") for (int k = 0; k < 2; ++k) \
;         acc[ai][bj][m][n] = __builtin_amdgcn_mfma_f32_16x16x32_bf16(Bt[n][k], At[m][k], acc[ai][bj][m][n], 0, 0, 0); __builtin_amdgcn_s_setprio(0); } while (0)
; #define PG8_WAIT_V(n) asm volatile("s_waitcnt vmcnt(" #n ")" ::: "memory")
; #define PG8_BAR __builtin_amdgcn_s_barrier()
; template <class Epi, class Sched, bool ALIGN_EPI = false, bool SP2 = false>
; __device__ __forceinline__ void gemm_phase(PG8_LAS unsigned char* lds, const Gemm g, const Sched& S, const Epi& E) {
;     ...
;         for (int t = 0; t < nt; t += 2) {
;             const bool last = (t == nt - 2);
;             const char* a1 = cA + (size_t)(t + 1) * kstep;
;             const char* a2 = last ? nA : cA + (size_t)(t + 2) * kstep; const char* b2 = last ? nB : cB + (size_t)(t + 2) * kstep;
;             const char* a3 = a2 + kstep; const char* b3 = b2 + kstep;
;             if (last && has_next) S.a_ready(nxt);
;             if constexpr (SP2) {
;             PG8_LDB(B0, 0, 0); PG8_LDB(B1, 0, 1); PG8_SCHED; PG8_LDA(At, 0, 0); PG8_STAGE(PG8_SA(1, 1), a1 + hstep, voffA);
;             PG8_WAIT_V(8); PG8_WAIT_L(0); PG8_BAR; PG8_MMA(0, 0, At, B0); PG8_MMA(0, 1, At, B1); PG8_BAR; PG8_SCHED;
;             PG8_LDA(At, 0, 1); PG8_STAGE(PG8_SB(0, 0), b2, voffB); PG8_STAGE(PG8_SB(0, 1), b2 + hstep, voffB); PG8_STAGE(PG8_SA(0, 0), a2, voffA);
;             PG8_WAIT_V(8); PG8_WAIT_L(0); PG8_BAR; PG8_MMA(1, 0, At, B0); PG8_MMA(1, 1, At, B1); PG8_BAR; PG8_SCHED;
.LBB0_845:
	ds_read_b128 v[128:131], v163
	ds_read_b128 v[132:135], v163 offset:1024
	ds_read_b128 v[152:155], v163 offset:2048
	ds_read_b128 v[156:159], v163 offset:3072
	ds_read_b128 v[166:169], v164
	ds_read_b128 v[170:173], v164 offset:1024
	ds_read_b128 v[174:177], v164 offset:2048
	ds_read_b128 v[178:181], v164 offset:3072
	s_add_u32 s30, s28, 0xfff80080
	s_addc_u32 s31, s29, -1
	s_cmp_eq_u32 s50, 28
	s_cselect_b32 s35, s21, s31
	s_cselect_b32 s34, s46, s30
	s_cselect_b32 s31, s19, s49
	s_cselect_b32 s30, s47, s48
	v_lshl_add_u64 v[190:191], s[28:29], 0, v[144:145]
	s_add_i32 m0, s27, 0xc000
	ds_read_b128 v[182:185], v165
	ds_read_b128 v[186:189], v165 offset:1024
	ds_read_b128 v[194:197], v165 offset:2048
	ds_read_b128 v[198:201], v165 offset:3072
	ds_read_b128 v[202:205], v165 offset:4096
	ds_read_b128 v[206:209], v165 offset:5120
	ds_read_b128 v[210:213], v165 offset:6144
	ds_read_b128 v[214:217], v165 offset:7168
	global_load_lds_dwordx4 v[190:191], off
	v_lshl_add_u64 v[190:191], s[28:29], 0, v[146:147]
	s_add_i32 m0, s27, 0xe000
	s_nop 0
	global_load_lds_dwordx4 v[190:191], off
	s_waitcnt vmcnt(8)
	s_waitcnt lgkmcnt(0)
	s_barrier
	s_setprio 1
	s_waitcnt lgkmcnt(0)
	v_mfma_f32_16x16x32_bf16 v[124:127], v[128:131], v[182:185], v[124:127]
	v_mfma_f32_16x16x32_bf16 v[120:123], v[152:155], v[182:185], v[120:123]
	v_mfma_f32_16x16x32_bf16 v[116:119], v[128:131], v[194:197], v[116:119]
	v_mfma_f32_16x16x32_bf16 v[112:115], v[152:155], v[194:197], v[112:115]
	v_mfma_f32_16x16x32_bf16 v[92:95], v[128:131], v[202:205], v[92:95]
	v_mfma_f32_16x16x32_bf16 v[88:91], v[152:155], v[202:205], v[88:91]
	v_mfma_f32_16x16x32_bf16 v[84:87], v[128:131], v[210:213], v[84:87]
	v_mfma_f32_16x16x32_bf16 v[76:79], v[152:155], v[210:213], v[76:79]
	v_mfma_f32_16x16x32_bf16 v[124:127], v[132:135], v[186:189], v[124:127]
	v_mfma_f32_16x16x32_bf16 v[120:123], v[156:159], v[186:189], v[120:123]
	v_mfma_f32_16x16x32_bf16 v[116:119], v[132:135], v[198:201], v[116:119]
	v_mfma_f32_16x16x32_bf16 v[112:115], v[156:159], v[198:201], v[112:115]
	v_mfma_f32_16x16x32_bf16 v[92:95], v[132:135], v[206:209], v[92:95]
	v_mfma_f32_16x16x32_bf16 v[88:91], v[156:159], v[206:209], v[88:91]
	v_mfma_f32_16x16x32_bf16 v[84:87], v[132:135], v[214:217], v[84:87]
	v_mfma_f32_16x16x32_bf16 v[76:79], v[156:159], v[214:217], v[76:79]
	s_setprio 0
	s_setprio 1
	v_mfma_f32_16x16x32_bf16 v[108:111], v[166:169], v[182:185], v[108:111]
	v_mfma_f32_16x16x32_bf16 v[104:107], v[174:177], v[182:185], v[104:107]
	v_mfma_f32_16x16x32_bf16 v[100:103], v[166:169], v[194:197], v[100:103]
	v_mfma_f32_16x16x32_bf16 v[96:99], v[174:177], v[194:197], v[96:99]
	v_mfma_f32_16x16x32_bf16 v[80:83], v[166:169], v[202:205], v[80:83]
	v_mfma_f32_16x16x32_bf16 v[72:75], v[174:177], v[202:205], v[72:75]
	v_mfma_f32_16x16x32_bf16 v[68:71], v[166:169], v[210:213], v[68:71]
	v_mfma_f32_16x16x32_bf16 v[64:67], v[174:177], v[210:213], v[64:67]
	v_mfma_f32_16x16x32_bf16 v[108:111], v[170:173], v[186:189], v[108:111]
	v_mfma_f32_16x16x32_bf16 v[104:107], v[178:181], v[186:189], v[104:107]
	v_mfma_f32_16x16x32_bf16 v[100:103], v[170:173], v[198:201], v[100:103]
	v_mfma_f32_16x16x32_bf16 v[96:99], v[178:181], v[198:201], v[96:99]
	v_mfma_f32_16x16x32_bf16 v[80:83], v[170:173], v[206:209], v[80:83]
	v_mfma_f32_16x16x32_bf16 v[72:75], v[178:181], v[206:209], v[72:75]
	v_mfma_f32_16x16x32_bf16 v[68:71], v[170:173], v[214:217], v[68:71]
	v_mfma_f32_16x16x32_bf16 v[64:67], v[178:181], v[214:217], v[64:67]
	s_setprio 0
	s_barrier
	s_add_i32 s51, s43, s37
	v_lshl_add_u64 v[190:191], s[30:31], 0, v[138:139]
	s_mov_b32 m0, s51
	ds_read_b128 v[182:185], v165 offset:16384
	ds_read_b128 v[186:189], v165 offset:17408
	ds_read_b128 v[194:197], v165 offset:18432
	ds_read_b128 v[198:201], v165 offset:19456
	ds_read_b128 v[202:205], v165 offset:20480
	ds_read_b128 v[206:209], v165 offset:21504
	ds_read_b128 v[210:213], v165 offset:22528
	ds_read_b128 v[214:217], v165 offset:23552
	global_load_lds_dwordx4 v[190:191], off
	s_add_i32 m0, s51, 0x2000
	s_add_u32 s52, s30, 0x80000
	v_lshl_add_u64 v[218:219], s[30:31], 0, v[142:143]
	s_addc_u32 s53, s31, 0
	s_add_i32 s51, s44, s37
	global_load_lds_dwordx4 v[218:219], off
	v_lshl_add_u64 v[220:221], s[52:53], 0, v[138:139]
	s_mov_b32 m0, s51
	v_lshl_add_u64 v[222:223], s[34:35], 0, v[140:141]
	global_load_lds_dwordx4 v[220:221], off
	v_lshl_add_u64 v[220:221], s[52:53], 0, v[142:143]
	s_add_i32 m0, s51, 0x2000
	s_nop 0
	global_load_lds_dwordx4 v[220:221], off
	v_lshl_add_u64 v[220:221], s[34:35], 0, v[136:137]
	s_mov_b32 m0, s27
	s_nop 0
	global_load_lds_dwordx4 v[220:221], off
	s_mov_b32 m0, s38
	s_nop 0
	global_load_lds_dwordx4 v[222:223], off
	s_waitcnt vmcnt(8)
	s_waitcnt lgkmcnt(0)
	s_barrier
; #define PG8_STAGE(bufoff, gbase, voff) do { _Pragma("unroll") for (int _i = 0; _i < 2; ++_i) \
;         __builtin_amdgcn_global_load_lds((const unsigned*)((const char*)(gbase) + (voff)[_i]), (PG8_LAS unsigned*)(lds + (bufoff) + ldsw + _i * 8192), 16, 0, 0); } while (0)
; #define PG8_LDA(dst, b, h) do { _Pragma("unroll") for (int m = 0; m < 4; ++m) _Pragma("unroll") for (int k = 0; k < 2; ++k) dst[m][k] = *(const PG8_LAS bf16x8*)(lds + PG8_SA(b, h) + aoff + m * 2048 + k * 1024); } while (0)
; #define PG8_LDB(dst, b, h) do { _Pragma("unroll") for (int n = 0; n < 2; ++n) _Pragma("unroll") for (int k = 0; k < 2; ++k) dst[n][k] = *(const PG8_LAS bf16x8*)(lds + PG8_SB(b, h) + boff + n * 2048 + k * 1024); } while (0)
; #define PG8_MMA(ai, bj, At, Bt) do { __builtin_amdgcn_s_setprio(1); _Pragma("unroll") for (int m = 0; m < 4; ++m) _Pragma("unroll") for (int n = 0; n < 2; ++n) _Pragma("unroll") for (int k = 0; k < 2; ++k) \
;         acc[ai][bj][m][n] = __builtin_amdgcn_mfma_f32_16x16x32_bf16(Bt[n][k], At[m][k], acc[ai][bj][m][n], 0, 0, 0); __builtin_amdgcn_s_setprio(0); } while (0)
; #define PG8_WAIT_V(n) asm volatile("s_waitcnt vmcnt(" #n ")" ::: "memory")
; #define PG8_WAIT_L(n) asm volatile("s_waitcnt lgkmcnt(" #n ")" ::: "memory")
; #define PG8_BAR __builtin_amdgcn_s_barrier()
; #define PG8_SCHED __builtin_amdgcn_sched_barrier(0)
; template <class Epi, class Sched, bool ALIGN_EPI = false, bool SP2 = false>
; __device__ __forceinline__ void gemm_phase(PG8_LAS unsigned char* lds, const Gemm g, const Sched& S, const Epi& E) {
;     ...
;             PG8_WAIT_V(8); PG8_WAIT_L(0); PG8_BAR; PG8_MMA(1, 0, At, B0); PG8_MMA(1, 1, At, B1); PG8_BAR; PG8_SCHED;
;             PG8_LDB(B0, 1, 0); PG8_LDB(B1, 1, 1); PG8_SCHED; PG8_LDA(At, 1, 0); PG8_STAGE(PG8_SA(0, 1), a2 + hstep, voffA);
;             PG8_WAIT_V(8); PG8_WAIT_L(0); PG8_BAR; PG8_MMA(0, 0, At, B0); PG8_MMA(0, 1, At, B1); PG8_BAR; PG8_SCHED;
	s_setprio 1
	s_waitcnt lgkmcnt(0)
	v_mfma_f32_16x16x32_bf16 v[60:63], v[128:131], v[182:185], v[60:63]
	v_mfma_f32_16x16x32_bf16 v[56:59], v[152:155], v[182:185], v[56:59]
	v_mfma_f32_16x16x32_bf16 v[52:55], v[128:131], v[194:197], v[52:55]
	v_mfma_f32_16x16x32_bf16 v[44:47], v[152:155], v[194:197], v[44:47]
	v_mfma_f32_16x16x32_bf16 v[36:39], v[128:131], v[202:205], v[36:39]
	v_mfma_f32_16x16x32_bf16 v[24:27], v[152:155], v[202:205], v[24:27]
	v_mfma_f32_16x16x32_bf16 v[16:19], v[128:131], v[210:213], v[16:19]
	v_mfma_f32_16x16x32_bf16 v[8:11], v[152:155], v[210:213], v[8:11]
	v_mfma_f32_16x16x32_bf16 v[60:63], v[132:135], v[186:189], v[60:63]
	v_mfma_f32_16x16x32_bf16 v[56:59], v[156:159], v[186:189], v[56:59]
	v_mfma_f32_16x16x32_bf16 v[52:55], v[132:135], v[198:201], v[52:55]
	v_mfma_f32_16x16x32_bf16 v[44:47], v[156:159], v[198:201], v[44:47]
	v_mfma_f32_16x16x32_bf16 v[36:39], v[132:135], v[206:209], v[36:39]
	v_mfma_f32_16x16x32_bf16 v[24:27], v[156:159], v[206:209], v[24:27]
	v_mfma_f32_16x16x32_bf16 v[16:19], v[132:135], v[214:217], v[16:19]
	v_mfma_f32_16x16x32_bf16 v[8:11], v[156:159], v[214:217], v[8:11]
	s_setprio 0
	s_setprio 1
	v_mfma_f32_16x16x32_bf16 v[48:51], v[166:169], v[182:185], v[48:51]
	v_mfma_f32_16x16x32_bf16 v[40:43], v[174:177], v[182:185], v[40:43]
	v_mfma_f32_16x16x32_bf16 v[32:35], v[166:169], v[194:197], v[32:35]
	v_mfma_f32_16x16x32_bf16 v[28:31], v[174:177], v[194:197], v[28:31]
	v_mfma_f32_16x16x32_bf16 v[20:23], v[166:169], v[202:205], v[20:23]
	v_mfma_f32_16x16x32_bf16 v[12:15], v[174:177], v[202:205], v[12:15]
	v_mfma_f32_16x16x32_bf16 v[4:7], v[166:169], v[210:213], v[4:7]
	v_mfma_f32_16x16x32_bf16 v[0:3], v[174:177], v[210:213], v[0:3]
	v_mfma_f32_16x16x32_bf16 v[48:51], v[170:173], v[186:189], v[48:51]
	v_mfma_f32_16x16x32_bf16 v[40:43], v[178:181], v[186:189], v[40:43]
	v_mfma_f32_16x16x32_bf16 v[32:35], v[170:173], v[198:201], v[32:35]
	v_mfma_f32_16x16x32_bf16 v[28:31], v[178:181], v[198:201], v[28:31]
	v_mfma_f32_16x16x32_bf16 v[20:23], v[170:173], v[206:209], v[20:23]
	v_mfma_f32_16x16x32_bf16 v[12:15], v[178:181], v[206:209], v[12:15]
	v_mfma_f32_16x16x32_bf16 v[4:7], v[170:173], v[214:217], v[4:7]
	v_mfma_f32_16x16x32_bf16 v[0:3], v[178:181], v[214:217], v[0:3]
	s_setprio 0
	s_barrier
	s_add_i32 s51, 0, 0x18000
	s_add_i32 s52, 0, 0x1c000
	v_add_u32_e32 v156, s51, v161
	v_add_u32_e32 v178, s52, v161
	ds_read_b128 v[128:131], v156
	ds_read_b128 v[132:135], v156 offset:1024
	ds_read_b128 v[152:155], v156 offset:2048
	ds_read_b128 v[156:159], v156 offset:3072
	ds_read_b128 v[166:169], v178
	ds_read_b128 v[170:173], v178 offset:1024
	ds_read_b128 v[174:177], v178 offset:2048
	ds_read_b128 v[178:181], v178 offset:3072
	s_add_u32 s34, s34, 0x80000
	s_addc_u32 s35, s35, 0
	s_mov_b32 m0, s39
	v_lshl_add_u64 v[224:225], s[34:35], 0, v[136:137]
	ds_read_b128 v[182:185], v165 offset:32768
	ds_read_b128 v[186:189], v165 offset:33792
	ds_read_b128 v[194:197], v165 offset:34816
	ds_read_b128 v[198:201], v165 offset:35840
	ds_read_b128 v[202:205], v165 offset:36864
	ds_read_b128 v[206:209], v165 offset:37888
	ds_read_b128 v[210:213], v165 offset:38912
	ds_read_b128 v[214:217], v165 offset:39936
	global_load_lds_dwordx4 v[224:225], off
	v_lshl_add_u64 v[224:225], s[34:35], 0, v[140:141]
	s_mov_b32 m0, s40
	s_nop 0
	global_load_lds_dwordx4 v[224:225], off
	s_waitcnt vmcnt(8)
	s_waitcnt lgkmcnt(0)
	s_barrier
	s_setprio 1
	s_waitcnt lgkmcnt(0)
	v_mfma_f32_16x16x32_bf16 v[124:127], v[128:131], v[182:185], v[124:127]
	v_mfma_f32_16x16x32_bf16 v[120:123], v[152:155], v[182:185], v[120:123]
	v_mfma_f32_16x16x32_bf16 v[116:119], v[128:131], v[194:197], v[116:119]
	v_mfma_f32_16x16x32_bf16 v[112:115], v[152:155], v[194:197], v[112:115]
	v_mfma_f32_16x16x32_bf16 v[92:95], v[128:131], v[202:205], v[92:95]
	v_mfma_f32_16x16x32_bf16 v[88:91], v[152:155], v[202:205], v[88:91]
	v_mfma_f32_16x16x32_bf16 v[84:87], v[128:131], v[210:213], v[84:87]
	v_mfma_f32_16x16x32_bf16 v[76:79], v[152:155], v[210:213], v[76:79]
	v_mfma_f32_16x16x32_bf16 v[124:127], v[132:135], v[186:189], v[124:127]
	v_mfma_f32_16x16x32_bf16 v[120:123], v[156:159], v[186:189], v[120:123]
	v_mfma_f32_16x16x32_bf16 v[116:119], v[132:135], v[198:201], v[116:119]
	v_mfma_f32_16x16x32_bf16 v[112:115], v[156:159], v[198:201], v[112:115]
	v_mfma_f32_16x16x32_bf16 v[92:95], v[132:135], v[206:209], v[92:95]
	v_mfma_f32_16x16x32_bf16 v[88:91], v[156:159], v[206:209], v[88:91]
	v_mfma_f32_16x16x32_bf16 v[84:87], v[132:135], v[214:217], v[84:87]
	v_mfma_f32_16x16x32_bf16 v[76:79], v[156:159], v[214:217], v[76:79]
	s_setprio 0
	s_setprio 1
	v_mfma_f32_16x16x32_bf16 v[108:111], v[166:169], v[182:185], v[108:111]
	v_mfma_f32_16x16x32_bf16 v[104:107], v[174:177], v[182:185], v[104:107]
	v_mfma_f32_16x16x32_bf16 v[100:103], v[166:169], v[194:197], v[100:103]
	v_mfma_f32_16x16x32_bf16 v[96:99], v[174:177], v[194:197], v[96:99]
	v_mfma_f32_16x16x32_bf16 v[80:83], v[166:169], v[202:205], v[80:83]
	v_mfma_f32_16x16x32_bf16 v[72:75], v[174:177], v[202:205], v[72:75]
	v_mfma_f32_16x16x32_bf16 v[68:71], v[166:169], v[210:213], v[68:71]
	v_mfma_f32_16x16x32_bf16 v[64:67], v[174:177], v[210:213], v[64:67]
	v_mfma_f32_16x16x32_bf16 v[108:111], v[170:173], v[186:189], v[108:111]
	v_mfma_f32_16x16x32_bf16 v[104:107], v[178:181], v[186:189], v[104:107]
	v_mfma_f32_16x16x32_bf16 v[100:103], v[170:173], v[198:201], v[100:103]
	v_mfma_f32_16x16x32_bf16 v[96:99], v[178:181], v[198:201], v[96:99]
	v_mfma_f32_16x16x32_bf16 v[80:83], v[170:173], v[206:209], v[80:83]
	v_mfma_f32_16x16x32_bf16 v[72:75], v[178:181], v[206:209], v[72:75]
	v_mfma_f32_16x16x32_bf16 v[68:71], v[170:173], v[214:217], v[68:71]
	v_mfma_f32_16x16x32_bf16 v[64:67], v[178:181], v[214:217], v[64:67]
	s_setprio 0
	s_barrier
; #define PG8_STAGE(bufoff, gbase, voff) do { _Pragma("unroll") for (int _i = 0; _i < 2; ++_i) \
;         __builtin_amdgcn_global_load_lds((const unsigned*)((const char*)(gbase) + (voff)[_i]), (PG8_LAS unsigned*)(lds + (bufoff) + ldsw + _i * 8192), 16, 0, 0); } while (0)
; #define PG8_LDA(dst, b, h) do { _Pragma("unroll") for (int m = 0; m < 4; ++m) _Pragma("unroll") for (int k = 0; k < 2; ++k) dst[m][k] = *(const PG8_LAS bf16x8*)(lds + PG8_SA(b, h) + aoff + m * 2048 + k * 1024); } while (0)
; #define PG8_MMA(ai, bj, At, Bt) do { __builtin_amdgcn_s_setprio(1); _Pragma("unroll") for (int m = 0; m < 4; ++m) _Pragma("unroll") for (int n = 0; n < 2; ++n) _Pragma("unroll") for (int k = 0; k < 2; ++k) \
;         acc[ai][bj][m][n] = __builtin_amdgcn_mfma_f32_16x16x32_bf16(Bt[n][k], At[m][k], acc[ai][bj][m][n], 0, 0, 0); __builtin_amdgcn_s_setprio(0); } while (0)
; #define PG8_WAIT_V(n) asm volatile("s_waitcnt vmcnt(" #n ")" ::: "memory")
; #define PG8_WAIT_L(n) asm volatile("s_waitcnt lgkmcnt(" #n ")" ::: "memory")
; #define PG8_BAR __builtin_amdgcn_s_barrier()
; #define PG8_SCHED __builtin_amdgcn_sched_barrier(0)
; template <class Epi, class Sched, bool ALIGN_EPI = false, bool SP2 = false>
; __device__ __forceinline__ void gemm_phase(PG8_LAS unsigned char* lds, const Gemm g, const Sched& S, const Epi& E) {
;     ...
;             PG8_LDA(At, 1, 1); PG8_STAGE(PG8_SB(1, 0), b3, voffB); PG8_STAGE(PG8_SB(1, 1), b3 + hstep, voffB); PG8_STAGE(PG8_SA(1, 0), a3, voffA);
;             PG8_WAIT_V(8); PG8_WAIT_L(0); PG8_BAR; PG8_MMA(1, 0, At, B0); PG8_MMA(1, 1, At, B1); PG8_BAR; PG8_SCHED;
	s_add_i32 s34, s51, s37
	v_lshl_add_u64 v[190:191], v[190:191], 0, s[0:1]
	s_mov_b32 m0, s34
	ds_read_b128 v[182:185], v165 offset:49152
	ds_read_b128 v[186:189], v165 offset:50176
	ds_read_b128 v[194:197], v165 offset:51200
	ds_read_b128 v[198:201], v165 offset:52224
	ds_read_b128 v[202:205], v165 offset:53248
	ds_read_b128 v[206:209], v165 offset:54272
	ds_read_b128 v[210:213], v165 offset:55296
	ds_read_b128 v[214:217], v165 offset:56320
	global_load_lds_dwordx4 v[190:191], off
	s_add_i32 m0, s34, 0x2000
	s_add_u32 s30, s30, 0x80080
	v_lshl_add_u64 v[190:191], v[218:219], 0, s[0:1]
	s_addc_u32 s31, s31, 0
	s_add_i32 s34, s52, s37
	global_load_lds_dwordx4 v[190:191], off
	v_lshl_add_u64 v[190:191], s[30:31], 0, v[138:139]
	s_mov_b32 m0, s34
	s_nop 0
	global_load_lds_dwordx4 v[190:191], off
	v_lshl_add_u64 v[190:191], s[30:31], 0, v[142:143]
	s_add_i32 m0, s34, 0x2000
	s_nop 0
	global_load_lds_dwordx4 v[190:191], off
	v_lshl_add_u64 v[190:191], v[220:221], 0, s[0:1]
	s_mov_b32 m0, s2
	s_nop 0
	global_load_lds_dwordx4 v[190:191], off
	v_lshl_add_u64 v[190:191], v[222:223], 0, s[0:1]
	s_mov_b32 m0, s3
	s_nop 0
	global_load_lds_dwordx4 v[190:191], off
	s_waitcnt vmcnt(8)
	s_waitcnt lgkmcnt(0)
	s_barrier
	s_setprio 1
	s_waitcnt lgkmcnt(0)
	v_mfma_f32_16x16x32_bf16 v[60:63], v[128:131], v[182:185], v[60:63]
	v_mfma_f32_16x16x32_bf16 v[56:59], v[152:155], v[182:185], v[56:59]
	v_mfma_f32_16x16x32_bf16 v[52:55], v[128:131], v[194:197], v[52:55]
	v_mfma_f32_16x16x32_bf16 v[44:47], v[152:155], v[194:197], v[44:47]
	v_mfma_f32_16x16x32_bf16 v[36:39], v[128:131], v[202:205], v[36:39]
	v_mfma_f32_16x16x32_bf16 v[24:27], v[152:155], v[202:205], v[24:27]
	v_mfma_f32_16x16x32_bf16 v[16:19], v[128:131], v[210:213], v[16:19]
	v_mfma_f32_16x16x32_bf16 v[8:11], v[152:155], v[210:213], v[8:11]
	v_mfma_f32_16x16x32_bf16 v[60:63], v[132:135], v[186:189], v[60:63]
	v_mfma_f32_16x16x32_bf16 v[56:59], v[156:159], v[186:189], v[56:59]
	v_mfma_f32_16x16x32_bf16 v[52:55], v[132:135], v[198:201], v[52:55]
	v_mfma_f32_16x16x32_bf16 v[44:47], v[156:159], v[198:201], v[44:47]
	v_mfma_f32_16x16x32_bf16 v[36:39], v[132:135], v[206:209], v[36:39]
	v_mfma_f32_16x16x32_bf16 v[24:27], v[156:159], v[206:209], v[24:27]
	v_mfma_f32_16x16x32_bf16 v[16:19], v[132:135], v[214:217], v[16:19]
	v_mfma_f32_16x16x32_bf16 v[8:11], v[156:159], v[214:217], v[8:11]
	s_setprio 0
	s_setprio 1
	v_mfma_f32_16x16x32_bf16 v[48:51], v[166:169], v[182:185], v[48:51]
	v_mfma_f32_16x16x32_bf16 v[40:43], v[174:177], v[182:185], v[40:43]
	v_mfma_f32_16x16x32_bf16 v[32:35], v[166:169], v[194:197], v[32:35]
	v_mfma_f32_16x16x32_bf16 v[28:31], v[174:177], v[194:197], v[28:31]
	v_mfma_f32_16x16x32_bf16 v[20:23], v[166:169], v[202:205], v[20:23]
	v_mfma_f32_16x16x32_bf16 v[12:15], v[174:177], v[202:205], v[12:15]
	v_mfma_f32_16x16x32_bf16 v[4:7], v[166:169], v[210:213], v[4:7]
	v_mfma_f32_16x16x32_bf16 v[0:3], v[174:177], v[210:213], v[0:3]
	v_mfma_f32_16x16x32_bf16 v[48:51], v[170:173], v[186:189], v[48:51]
	v_mfma_f32_16x16x32_bf16 v[40:43], v[178:181], v[186:189], v[40:43]
	v_mfma_f32_16x16x32_bf16 v[32:35], v[170:173], v[198:201], v[32:35]
	v_mfma_f32_16x16x32_bf16 v[28:31], v[178:181], v[198:201], v[28:31]
	v_mfma_f32_16x16x32_bf16 v[20:23], v[170:173], v[206:209], v[20:23]
	v_mfma_f32_16x16x32_bf16 v[12:15], v[178:181], v[206:209], v[12:15]
	v_mfma_f32_16x16x32_bf16 v[4:7], v[170:173], v[214:217], v[4:7]
	v_mfma_f32_16x16x32_bf16 v[0:3], v[178:181], v[214:217], v[0:3]
	s_setprio 0
	s_barrier
	s_add_i32 s50, s50, 2
	s_add_u32 s28, s28, 0x100
	s_addc_u32 s29, s29, 0
	s_add_u32 s48, s48, 0x100
	s_addc_u32 s49, s49, 0
	s_cmp_gt_u32 s50, 29
	s_cbranch_scc0 .LBB0_845
	s_and_b64 vcc, exec, s[10:11]
	s_cbranch_vccz .LBB0_848
	s_barrier

; #define PG8_STAGE(bufoff, gbase, voff) do { _Pragma("unroll") for (int _i = 0; _i < 2; ++_i) \
;         __builtin_amdgcn_global_load_lds((const unsigned*)((const char*)(gbase) + (voff)[_i]), (PG8_LAS unsigned*)(lds + (bufoff) + ldsw + _i * 8192), 16, 0, 0); } while (0)
; #define PG8_LDA(dst, b, h) do { _Pragma("unroll") for (int m = 0; m < 4; ++m) _Pragma("unroll") for (int k = 0; k < 2; ++k) dst[m][k] = *(const PG8_LAS bf16x8*)(lds + PG8_SA(b, h) + aoff + m * 2048 + k * 1024); } while (0)
; #define PG8_LDB(dst, b, h) do { _Pragma("unroll") for (int n = 0; n < 2; ++n) _Pragma("unroll") for (int k = 0; k < 2; ++k) dst[n][k] = *(const PG8_LAS bf16x8*)(lds + PG8_SB(b, h) + boff + n * 2048 + k * 1024); } while (0)
; #define PG8_MMA(ai, bj, At, Bt) do { __builtin_amdgcn_s_setprio(1); _Pragma("unroll") for (int m = 0; m < 4; ++m) _Pragma("unroll") for (int n = 0; n < 2; ++n) _Pragma("unroll") for (int k = 0; k < 2; ++k) \
;         acc[ai][bj][m][n] = __builtin_amdgcn_mfma_f32_16x16x32_bf16(Bt[n][k], At[m][k], acc[ai][bj][m][n], 0, 0, 0); __builtin_amdgcn_s_setprio(0); } while (0)
; #define PG8_WAIT_V(n) asm volatile("s_waitcnt vmcnt(" #n ")" ::: "memory")
; #define PG8_BAR __builtin_amdgcn_s_barrier()
; template <class Epi, class Sched, bool ALIGN_EPI = false, bool SP2 = false>
; __device__ __forceinline__ void gemm_phase(PG8_LAS unsigned char* lds, const Gemm g, const Sched& S, const Epi& E) {
;     ...
;         for (int t = 0; t < nt; t += 2) {
;             const bool last = (t == nt - 2);
;             const char* a1 = cA + (size_t)(t + 1) * kstep;
;             const char* a2 = last ? nA : cA + (size_t)(t + 2) * kstep; const char* b2 = last ? nB : cB + (size_t)(t + 2) * kstep;
;             const char* a3 = a2 + kstep; const char* b3 = b2 + kstep;
;             if (last && has_next) S.a_ready(nxt);
;             if constexpr (SP2) {
;             PG8_LDB(B0, 0, 0); PG8_LDB(B1, 0, 1); PG8_SCHED; PG8_LDA(At, 0, 0); PG8_STAGE(PG8_SA(1, 1), a1 + hstep, voffA);
;             PG8_WAIT_V(8); PG8_WAIT_L(0); PG8_BAR; PG8_MMA(0, 0, At, B0); PG8_MMA(0, 1, At, B1); PG8_BAR; PG8_SCHED;
;             PG8_LDA(At, 0, 1); PG8_STAGE(PG8_SB(0, 0), b2, voffB); PG8_STAGE(PG8_SB(0, 1), b2 + hstep, voffB); PG8_STAGE(PG8_SA(0, 0), a2, voffA);
;             PG8_WAIT_V(8); PG8_WAIT_L(0); PG8_BAR; PG8_MMA(1, 0, At, B0); PG8_MMA(1, 1, At, B1); PG8_BAR; PG8_SCHED;
.LBB0_869:
	ds_read_b128 v[146:149], v155
	ds_read_b128 v[158:161], v155 offset:1024
	ds_read_b128 v[162:165], v155 offset:2048
	ds_read_b128 v[166:169], v155 offset:3072
	ds_read_b128 v[170:173], v156
	ds_read_b128 v[174:177], v156 offset:1024
	ds_read_b128 v[178:181], v156 offset:2048
	ds_read_b128 v[182:185], v156 offset:3072
	s_add_u32 s30, s28, 0xfff80080
	s_addc_u32 s31, s29, -1
	s_cmp_eq_u32 s56, 28
	s_cselect_b32 s35, s21, s31
	s_cselect_b32 s34, s52, s30
	s_cselect_b32 s31, s1, s55
	s_cselect_b32 s30, s53, s54
	v_lshl_add_u64 v[150:151], s[28:29], 0, v[138:139]
	s_add_i32 m0, s27, 0xc000
	ds_read_b128 v[186:189], v157
	ds_read_b128 v[194:197], v157 offset:1024
	ds_read_b128 v[198:201], v157 offset:2048
	ds_read_b128 v[202:205], v157 offset:3072
	ds_read_b128 v[206:209], v157 offset:4096
	ds_read_b128 v[210:213], v157 offset:5120
	ds_read_b128 v[214:217], v157 offset:6144
	ds_read_b128 v[218:221], v157 offset:7168
	global_load_lds_dwordx4 v[150:151], off
	v_lshl_add_u64 v[150:151], s[28:29], 0, v[140:141]
	s_add_i32 m0, s27, 0xe000
	s_nop 0
	global_load_lds_dwordx4 v[150:151], off
	s_waitcnt vmcnt(8)
	s_waitcnt lgkmcnt(0)
	s_barrier
	s_setprio 1
	s_waitcnt lgkmcnt(0)
	v_mfma_f32_16x16x32_bf16 v[124:127], v[146:149], v[186:189], v[124:127]
	v_mfma_f32_16x16x32_bf16 v[120:123], v[162:165], v[186:189], v[120:123]
	v_mfma_f32_16x16x32_bf16 v[108:111], v[146:149], v[198:201], v[108:111]
	v_mfma_f32_16x16x32_bf16 v[104:107], v[162:165], v[198:201], v[104:107]
	v_mfma_f32_16x16x32_bf16 v[92:95], v[146:149], v[206:209], v[92:95]
	v_mfma_f32_16x16x32_bf16 v[88:91], v[162:165], v[206:209], v[88:91]
	v_mfma_f32_16x16x32_bf16 v[76:79], v[146:149], v[214:217], v[76:79]
	v_mfma_f32_16x16x32_bf16 v[72:75], v[162:165], v[214:217], v[72:75]
	v_mfma_f32_16x16x32_bf16 v[124:127], v[158:161], v[194:197], v[124:127]
	v_mfma_f32_16x16x32_bf16 v[120:123], v[166:169], v[194:197], v[120:123]
	v_mfma_f32_16x16x32_bf16 v[108:111], v[158:161], v[202:205], v[108:111]
	v_mfma_f32_16x16x32_bf16 v[104:107], v[166:169], v[202:205], v[104:107]
	v_mfma_f32_16x16x32_bf16 v[92:95], v[158:161], v[210:213], v[92:95]
	v_mfma_f32_16x16x32_bf16 v[88:91], v[166:169], v[210:213], v[88:91]
	v_mfma_f32_16x16x32_bf16 v[76:79], v[158:161], v[218:221], v[76:79]
	v_mfma_f32_16x16x32_bf16 v[72:75], v[166:169], v[218:221], v[72:75]
	s_setprio 0
	s_setprio 1
	v_mfma_f32_16x16x32_bf16 v[116:119], v[170:173], v[186:189], v[116:119]
	v_mfma_f32_16x16x32_bf16 v[112:115], v[178:181], v[186:189], v[112:115]
	v_mfma_f32_16x16x32_bf16 v[100:103], v[170:173], v[198:201], v[100:103]
	v_mfma_f32_16x16x32_bf16 v[96:99], v[178:181], v[198:201], v[96:99]
	v_mfma_f32_16x16x32_bf16 v[84:87], v[170:173], v[206:209], v[84:87]
	v_mfma_f32_16x16x32_bf16 v[80:83], v[178:181], v[206:209], v[80:83]
	v_mfma_f32_16x16x32_bf16 v[68:71], v[170:173], v[214:217], v[68:71]
	v_mfma_f32_16x16x32_bf16 v[64:67], v[178:181], v[214:217], v[64:67]
	v_mfma_f32_16x16x32_bf16 v[116:119], v[174:177], v[194:197], v[116:119]
	v_mfma_f32_16x16x32_bf16 v[112:115], v[182:185], v[194:197], v[112:115]
	v_mfma_f32_16x16x32_bf16 v[100:103], v[174:177], v[202:205], v[100:103]
	v_mfma_f32_16x16x32_bf16 v[96:99], v[182:185], v[202:205], v[96:99]
	v_mfma_f32_16x16x32_bf16 v[84:87], v[174:177], v[210:213], v[84:87]
	v_mfma_f32_16x16x32_bf16 v[80:83], v[182:185], v[210:213], v[80:83]
	v_mfma_f32_16x16x32_bf16 v[68:71], v[174:177], v[218:221], v[68:71]
	v_mfma_f32_16x16x32_bf16 v[64:67], v[182:185], v[218:221], v[64:67]
	s_setprio 0
	s_barrier
	s_add_i32 s57, s47, s38
	v_lshl_add_u64 v[150:151], s[30:31], 0, v[130:131]
	s_mov_b32 m0, s57
	ds_read_b128 v[186:189], v157 offset:16384
	ds_read_b128 v[194:197], v157 offset:17408
	ds_read_b128 v[198:201], v157 offset:18432
	ds_read_b128 v[202:205], v157 offset:19456
	ds_read_b128 v[206:209], v157 offset:20480
	ds_read_b128 v[210:213], v157 offset:21504
	ds_read_b128 v[214:217], v157 offset:22528
	ds_read_b128 v[218:221], v157 offset:23552
	global_load_lds_dwordx4 v[150:151], off
	s_add_i32 m0, s57, 0x2000
	s_add_u32 s58, s30, 0x80000
	v_lshl_add_u64 v[190:191], s[30:31], 0, v[134:135]
	s_addc_u32 s59, s31, 0
	s_add_i32 s57, s48, s38
	global_load_lds_dwordx4 v[190:191], off
	v_lshl_add_u64 v[222:223], s[58:59], 0, v[130:131]
	s_mov_b32 m0, s57
	v_lshl_add_u64 v[224:225], s[34:35], 0, v[132:133]
	global_load_lds_dwordx4 v[222:223], off
	v_lshl_add_u64 v[222:223], s[58:59], 0, v[134:135]
	s_add_i32 m0, s57, 0x2000
	s_nop 0
	global_load_lds_dwordx4 v[222:223], off
	v_lshl_add_u64 v[222:223], s[34:35], 0, v[128:129]
	s_mov_b32 m0, s27
	s_nop 0
	global_load_lds_dwordx4 v[222:223], off
	s_mov_b32 m0, s39
	s_nop 0
	global_load_lds_dwordx4 v[224:225], off
	s_waitcnt vmcnt(8)
	s_waitcnt lgkmcnt(0)
	s_barrier
; #define PG8_STAGE(bufoff, gbase, voff) do { _Pragma("unroll") for (int _i = 0; _i < 2; ++_i) \
;         __builtin_amdgcn_global_load_lds((const unsigned*)((const char*)(gbase) + (voff)[_i]), (PG8_LAS unsigned*)(lds + (bufoff) + ldsw + _i * 8192), 16, 0, 0); } while (0)
; #define PG8_LDA(dst, b, h) do { _Pragma("unroll") for (int m = 0; m < 4; ++m) _Pragma("unroll") for (int k = 0; k < 2; ++k) dst[m][k] = *(const PG8_LAS bf16x8*)(lds + PG8_SA(b, h) + aoff + m * 2048 + k * 1024); } while (0)
; #define PG8_LDB(dst, b, h) do { _Pragma("unroll") for (int n = 0; n < 2; ++n) _Pragma("unroll") for (int k = 0; k < 2; ++k) dst[n][k] = *(const PG8_LAS bf16x8*)(lds + PG8_SB(b, h) + boff + n * 2048 + k * 1024); } while (0)
; #define PG8_MMA(ai, bj, At, Bt) do { __builtin_amdgcn_s_setprio(1); _Pragma("unroll") for (int m = 0; m < 4; ++m) _Pragma("unroll") for (int n = 0; n < 2; ++n) _Pragma("unroll") for (int k = 0; k < 2; ++k) \
;         acc[ai][bj][m][n] = __builtin_amdgcn_mfma_f32_16x16x32_bf16(Bt[n][k], At[m][k], acc[ai][bj][m][n], 0, 0, 0); __builtin_amdgcn_s_setprio(0); } while (0)
; #define PG8_WAIT_V(n) asm volatile("s_waitcnt vmcnt(" #n ")" ::: "memory")
; #define PG8_WAIT_L(n) asm volatile("s_waitcnt lgkmcnt(" #n ")" ::: "memory")
; #define PG8_BAR __builtin_amdgcn_s_barrier()
; #define PG8_SCHED __builtin_amdgcn_sched_barrier(0)
; template <class Epi, class Sched, bool ALIGN_EPI = false, bool SP2 = false>
; __device__ __forceinline__ void gemm_phase(PG8_LAS unsigned char* lds, const Gemm g, const Sched& S, const Epi& E) {
;     ...
;             PG8_WAIT_V(8); PG8_WAIT_L(0); PG8_BAR; PG8_MMA(1, 0, At, B0); PG8_MMA(1, 1, At, B1); PG8_BAR; PG8_SCHED;
;             PG8_LDB(B0, 1, 0); PG8_LDB(B1, 1, 1); PG8_SCHED; PG8_LDA(At, 1, 0); PG8_STAGE(PG8_SA(0, 1), a2 + hstep, voffA);
;             PG8_WAIT_V(8); PG8_WAIT_L(0); PG8_BAR; PG8_MMA(0, 0, At, B0); PG8_MMA(0, 1, At, B1); PG8_BAR; PG8_SCHED;
	s_setprio 1
	s_waitcnt lgkmcnt(0)
	v_mfma_f32_16x16x32_bf16 v[60:63], v[146:149], v[186:189], v[60:63]
	v_mfma_f32_16x16x32_bf16 v[56:59], v[162:165], v[186:189], v[56:59]
	v_mfma_f32_16x16x32_bf16 v[44:47], v[146:149], v[198:201], v[44:47]
	v_mfma_f32_16x16x32_bf16 v[40:43], v[162:165], v[198:201], v[40:43]
	v_mfma_f32_16x16x32_bf16 v[28:31], v[146:149], v[206:209], v[28:31]
	v_mfma_f32_16x16x32_bf16 v[24:27], v[162:165], v[206:209], v[24:27]
	v_mfma_f32_16x16x32_bf16 v[12:15], v[146:149], v[214:217], v[12:15]
	v_mfma_f32_16x16x32_bf16 v[8:11], v[162:165], v[214:217], v[8:11]
	v_mfma_f32_16x16x32_bf16 v[60:63], v[158:161], v[194:197], v[60:63]
	v_mfma_f32_16x16x32_bf16 v[56:59], v[166:169], v[194:197], v[56:59]
	v_mfma_f32_16x16x32_bf16 v[44:47], v[158:161], v[202:205], v[44:47]
	v_mfma_f32_16x16x32_bf16 v[40:43], v[166:169], v[202:205], v[40:43]
	v_mfma_f32_16x16x32_bf16 v[28:31], v[158:161], v[210:213], v[28:31]
	v_mfma_f32_16x16x32_bf16 v[24:27], v[166:169], v[210:213], v[24:27]
	v_mfma_f32_16x16x32_bf16 v[12:15], v[158:161], v[218:221], v[12:15]
	v_mfma_f32_16x16x32_bf16 v[8:11], v[166:169], v[218:221], v[8:11]
	s_setprio 0
	s_setprio 1
	v_mfma_f32_16x16x32_bf16 v[52:55], v[170:173], v[186:189], v[52:55]
	v_mfma_f32_16x16x32_bf16 v[48:51], v[178:181], v[186:189], v[48:51]
	v_mfma_f32_16x16x32_bf16 v[36:39], v[170:173], v[198:201], v[36:39]
	v_mfma_f32_16x16x32_bf16 v[32:35], v[178:181], v[198:201], v[32:35]
	v_mfma_f32_16x16x32_bf16 v[20:23], v[170:173], v[206:209], v[20:23]
	v_mfma_f32_16x16x32_bf16 v[16:19], v[178:181], v[206:209], v[16:19]
	v_mfma_f32_16x16x32_bf16 v[4:7], v[170:173], v[214:217], v[4:7]
	v_mfma_f32_16x16x32_bf16 v[0:3], v[178:181], v[214:217], v[0:3]
	v_mfma_f32_16x16x32_bf16 v[52:55], v[174:177], v[194:197], v[52:55]
	v_mfma_f32_16x16x32_bf16 v[48:51], v[182:185], v[194:197], v[48:51]
	v_mfma_f32_16x16x32_bf16 v[36:39], v[174:177], v[202:205], v[36:39]
	v_mfma_f32_16x16x32_bf16 v[32:35], v[182:185], v[202:205], v[32:35]
	v_mfma_f32_16x16x32_bf16 v[20:23], v[174:177], v[210:213], v[20:23]
	v_mfma_f32_16x16x32_bf16 v[16:19], v[182:185], v[210:213], v[16:19]
	v_mfma_f32_16x16x32_bf16 v[4:7], v[174:177], v[218:221], v[4:7]
	v_mfma_f32_16x16x32_bf16 v[0:3], v[182:185], v[218:221], v[0:3]
	s_setprio 0
	s_barrier
	s_add_i32 s57, 0, 0x18000
	v_add_u32_e32 v136, s57, v153
	s_add_i32 s58, 0, 0x1c000
	ds_read_b128 v[146:149], v136
	ds_read_b128 v[158:161], v136 offset:1024
	ds_read_b128 v[162:165], v136 offset:2048
	ds_read_b128 v[166:169], v136 offset:3072
	v_add_u32_e32 v136, s58, v153
	ds_read_b128 v[170:173], v136
	ds_read_b128 v[174:177], v136 offset:1024
	ds_read_b128 v[178:181], v136 offset:2048
	ds_read_b128 v[182:185], v136 offset:3072
	s_add_u32 s34, s34, 0x80000
	s_addc_u32 s35, s35, 0
	s_mov_b32 m0, s40
	v_lshl_add_u64 v[226:227], s[34:35], 0, v[128:129]
	ds_read_b128 v[186:189], v157 offset:32768
	ds_read_b128 v[194:197], v157 offset:33792
	ds_read_b128 v[198:201], v157 offset:34816
	ds_read_b128 v[202:205], v157 offset:35840
	ds_read_b128 v[206:209], v157 offset:36864
	ds_read_b128 v[210:213], v157 offset:37888
	ds_read_b128 v[214:217], v157 offset:38912
	ds_read_b128 v[218:221], v157 offset:39936
	global_load_lds_dwordx4 v[226:227], off
	v_lshl_add_u64 v[226:227], s[34:35], 0, v[132:133]
	s_mov_b32 m0, s41
	s_nop 0
	global_load_lds_dwordx4 v[226:227], off
	s_waitcnt vmcnt(8)
	s_waitcnt lgkmcnt(0)
	s_barrier
	s_setprio 1
	s_waitcnt lgkmcnt(0)
	v_mfma_f32_16x16x32_bf16 v[124:127], v[146:149], v[186:189], v[124:127]
	v_mfma_f32_16x16x32_bf16 v[120:123], v[162:165], v[186:189], v[120:123]
	v_mfma_f32_16x16x32_bf16 v[108:111], v[146:149], v[198:201], v[108:111]
	v_mfma_f32_16x16x32_bf16 v[104:107], v[162:165], v[198:201], v[104:107]
	v_mfma_f32_16x16x32_bf16 v[92:95], v[146:149], v[206:209], v[92:95]
	v_mfma_f32_16x16x32_bf16 v[88:91], v[162:165], v[206:209], v[88:91]
	v_mfma_f32_16x16x32_bf16 v[76:79], v[146:149], v[214:217], v[76:79]
	v_mfma_f32_16x16x32_bf16 v[72:75], v[162:165], v[214:217], v[72:75]
	v_mfma_f32_16x16x32_bf16 v[124:127], v[158:161], v[194:197], v[124:127]
	v_mfma_f32_16x16x32_bf16 v[120:123], v[166:169], v[194:197], v[120:123]
	v_mfma_f32_16x16x32_bf16 v[108:111], v[158:161], v[202:205], v[108:111]
	v_mfma_f32_16x16x32_bf16 v[104:107], v[166:169], v[202:205], v[104:107]
	v_mfma_f32_16x16x32_bf16 v[92:95], v[158:161], v[210:213], v[92:95]
	v_mfma_f32_16x16x32_bf16 v[88:91], v[166:169], v[210:213], v[88:91]
	v_mfma_f32_16x16x32_bf16 v[76:79], v[158:161], v[218:221], v[76:79]
	v_mfma_f32_16x16x32_bf16 v[72:75], v[166:169], v[218:221], v[72:75]
	s_setprio 0
	s_setprio 1
	v_mfma_f32_16x16x32_bf16 v[116:119], v[170:173], v[186:189], v[116:119]
	v_mfma_f32_16x16x32_bf16 v[112:115], v[178:181], v[186:189], v[112:115]
	v_mfma_f32_16x16x32_bf16 v[100:103], v[170:173], v[198:201], v[100:103]
	v_mfma_f32_16x16x32_bf16 v[96:99], v[178:181], v[198:201], v[96:99]
	v_mfma_f32_16x16x32_bf16 v[84:87], v[170:173], v[206:209], v[84:87]
	v_mfma_f32_16x16x32_bf16 v[80:83], v[178:181], v[206:209], v[80:83]
	v_mfma_f32_16x16x32_bf16 v[68:71], v[170:173], v[214:217], v[68:71]
	v_mfma_f32_16x16x32_bf16 v[64:67], v[178:181], v[214:217], v[64:67]
	v_mfma_f32_16x16x32_bf16 v[116:119], v[174:177], v[194:197], v[116:119]
	v_mfma_f32_16x16x32_bf16 v[112:115], v[182:185], v[194:197], v[112:115]
	v_mfma_f32_16x16x32_bf16 v[100:103], v[174:177], v[202:205], v[100:103]
	v_mfma_f32_16x16x32_bf16 v[96:99], v[182:185], v[202:205], v[96:99]
	v_mfma_f32_16x16x32_bf16 v[84:87], v[174:177], v[210:213], v[84:87]
	v_mfma_f32_16x16x32_bf16 v[80:83], v[182:185], v[210:213], v[80:83]
	v_mfma_f32_16x16x32_bf16 v[68:71], v[174:177], v[218:221], v[68:71]
	v_mfma_f32_16x16x32_bf16 v[64:67], v[182:185], v[218:221], v[64:67]
	s_setprio 0
	s_barrier
; #define PG8_STAGE(bufoff, gbase, voff) do { _Pragma("unroll") for (int _i = 0; _i < 2; ++_i) \
;         __builtin_amdgcn_global_load_lds((const unsigned*)((const char*)(gbase) + (voff)[_i]), (PG8_LAS unsigned*)(lds + (bufoff) + ldsw + _i * 8192), 16, 0, 0); } while (0)
; #define PG8_LDA(dst, b, h) do { _Pragma("unroll") for (int m = 0; m < 4; ++m) _Pragma("unroll") for (int k = 0; k < 2; ++k) dst[m][k] = *(const PG8_LAS bf16x8*)(lds + PG8_SA(b, h) + aoff + m * 2048 + k * 1024); } while (0)
; #define PG8_MMA(ai, bj, At, Bt) do { __builtin_amdgcn_s_setprio(1); _Pragma("unroll") for (int m = 0; m < 4; ++m) _Pragma("unroll") for (int n = 0; n < 2; ++n) _Pragma("unroll") for (int k = 0; k < 2; ++k) \
;         acc[ai][bj][m][n] = __builtin_amdgcn_mfma_f32_16x16x32_bf16(Bt[n][k], At[m][k], acc[ai][bj][m][n], 0, 0, 0); __builtin_amdgcn_s_setprio(0); } while (0)
; #define PG8_WAIT_V(n) asm volatile("s_waitcnt vmcnt(" #n ")" ::: "memory")
; #define PG8_WAIT_L(n) asm volatile("s_waitcnt lgkmcnt(" #n ")" ::: "memory")
; #define PG8_BAR __builtin_amdgcn_s_barrier()
; #define PG8_SCHED __builtin_amdgcn_sched_barrier(0)
; template <class Epi, class Sched, bool ALIGN_EPI = false, bool SP2 = false>
; __device__ __forceinline__ void gemm_phase(PG8_LAS unsigned char* lds, const Gemm g, const Sched& S, const Epi& E) {
;     ...
;             PG8_LDA(At, 1, 1); PG8_STAGE(PG8_SB(1, 0), b3, voffB); PG8_STAGE(PG8_SB(1, 1), b3 + hstep, voffB); PG8_STAGE(PG8_SA(1, 0), a3, voffA);
;             PG8_WAIT_V(8); PG8_WAIT_L(0); PG8_BAR; PG8_MMA(1, 0, At, B0); PG8_MMA(1, 1, At, B1); PG8_BAR; PG8_SCHED;
	s_add_i32 s34, s57, s38
	v_lshl_add_u64 v[150:151], v[150:151], 0, s[10:11]
	s_mov_b32 m0, s34
	ds_read_b128 v[186:189], v157 offset:49152
	ds_read_b128 v[194:197], v157 offset:50176
	ds_read_b128 v[198:201], v157 offset:51200
	ds_read_b128 v[202:205], v157 offset:52224
	ds_read_b128 v[206:209], v157 offset:53248
	ds_read_b128 v[210:213], v157 offset:54272
	ds_read_b128 v[214:217], v157 offset:55296
	ds_read_b128 v[218:221], v157 offset:56320
	global_load_lds_dwordx4 v[150:151], off
	s_add_i32 m0, s34, 0x2000
	s_add_u32 s30, s30, 0x80080
	v_lshl_add_u64 v[150:151], v[190:191], 0, s[10:11]
	s_addc_u32 s31, s31, 0
	s_add_i32 s34, s58, s38
	global_load_lds_dwordx4 v[150:151], off
	v_lshl_add_u64 v[150:151], s[30:31], 0, v[130:131]
	s_mov_b32 m0, s34
	s_nop 0
	global_load_lds_dwordx4 v[150:151], off
	v_lshl_add_u64 v[150:151], s[30:31], 0, v[134:135]
	s_add_i32 m0, s34, 0x2000
	s_nop 0
	global_load_lds_dwordx4 v[150:151], off
	v_lshl_add_u64 v[150:151], v[222:223], 0, s[10:11]
	s_mov_b32 m0, s43
	s_nop 0
	global_load_lds_dwordx4 v[150:151], off
	v_lshl_add_u64 v[150:151], v[224:225], 0, s[10:11]
	s_mov_b32 m0, s44
	s_nop 0
	global_load_lds_dwordx4 v[150:151], off
	s_waitcnt vmcnt(8)
	s_waitcnt lgkmcnt(0)
	s_barrier
	s_setprio 1
	s_waitcnt lgkmcnt(0)
	v_mfma_f32_16x16x32_bf16 v[60:63], v[146:149], v[186:189], v[60:63]
	v_mfma_f32_16x16x32_bf16 v[56:59], v[162:165], v[186:189], v[56:59]
	v_mfma_f32_16x16x32_bf16 v[44:47], v[146:149], v[198:201], v[44:47]
	v_mfma_f32_16x16x32_bf16 v[40:43], v[162:165], v[198:201], v[40:43]
	v_mfma_f32_16x16x32_bf16 v[28:31], v[146:149], v[206:209], v[28:31]
	v_mfma_f32_16x16x32_bf16 v[24:27], v[162:165], v[206:209], v[24:27]
	v_mfma_f32_16x16x32_bf16 v[12:15], v[146:149], v[214:217], v[12:15]
	v_mfma_f32_16x16x32_bf16 v[8:11], v[162:165], v[214:217], v[8:11]
	v_mfma_f32_16x16x32_bf16 v[60:63], v[158:161], v[194:197], v[60:63]
	v_mfma_f32_16x16x32_bf16 v[56:59], v[166:169], v[194:197], v[56:59]
	v_mfma_f32_16x16x32_bf16 v[44:47], v[158:161], v[202:205], v[44:47]
	v_mfma_f32_16x16x32_bf16 v[40:43], v[166:169], v[202:205], v[40:43]
	v_mfma_f32_16x16x32_bf16 v[28:31], v[158:161], v[210:213], v[28:31]
	v_mfma_f32_16x16x32_bf16 v[24:27], v[166:169], v[210:213], v[24:27]
	v_mfma_f32_16x16x32_bf16 v[12:15], v[158:161], v[218:221], v[12:15]
	v_mfma_f32_16x16x32_bf16 v[8:11], v[166:169], v[218:221], v[8:11]
	s_setprio 0
	s_setprio 1
	v_mfma_f32_16x16x32_bf16 v[52:55], v[170:173], v[186:189], v[52:55]
	v_mfma_f32_16x16x32_bf16 v[48:51], v[178:181], v[186:189], v[48:51]
	v_mfma_f32_16x16x32_bf16 v[36:39], v[170:173], v[198:201], v[36:39]
	v_mfma_f32_16x16x32_bf16 v[32:35], v[178:181], v[198:201], v[32:35]
	v_mfma_f32_16x16x32_bf16 v[20:23], v[170:173], v[206:209], v[20:23]
	v_mfma_f32_16x16x32_bf16 v[16:19], v[178:181], v[206:209], v[16:19]
	v_mfma_f32_16x16x32_bf16 v[4:7], v[170:173], v[214:217], v[4:7]
	v_mfma_f32_16x16x32_bf16 v[0:3], v[178:181], v[214:217], v[0:3]
	v_mfma_f32_16x16x32_bf16 v[52:55], v[174:177], v[194:197], v[52:55]
	v_mfma_f32_16x16x32_bf16 v[48:51], v[182:185], v[194:197], v[48:51]
	v_mfma_f32_16x16x32_bf16 v[36:39], v[174:177], v[202:205], v[36:39]
	v_mfma_f32_16x16x32_bf16 v[32:35], v[182:185], v[202:205], v[32:35]
	v_mfma_f32_16x16x32_bf16 v[20:23], v[174:177], v[210:213], v[20:23]
	v_mfma_f32_16x16x32_bf16 v[16:19], v[182:185], v[210:213], v[16:19]
	v_mfma_f32_16x16x32_bf16 v[4:7], v[174:177], v[218:221], v[4:7]
	v_mfma_f32_16x16x32_bf16 v[0:3], v[182:185], v[218:221], v[0:3]
	s_setprio 0
	s_barrier
	s_add_i32 s56, s56, 2
	s_add_u32 s28, s28, 0x100
	s_addc_u32 s29, s29, 0
	s_add_u32 s54, s54, 0x100
	s_addc_u32 s55, s55, 0
	s_cmp_gt_u32 s56, 29
	s_cbranch_scc0 .LBB0_869
	s_and_b64 vcc, exec, s[12:13]
	s_cbranch_vccz .LBB0_872
	s_barrier

; #define PG8_STAGE(bufoff, gbase, voff) do { _Pragma("unroll") for (int _i = 0; _i < 2; ++_i) \
;         __builtin_amdgcn_global_load_lds((const unsigned*)((const char*)(gbase) + (voff)[_i]), (PG8_LAS unsigned*)(lds + (bufoff) + ldsw + _i * 8192), 16, 0, 0); } while (0)
; #define PG8_LDA(dst, b, h) do { _Pragma("unroll") for (int m = 0; m < 4; ++m) _Pragma("unroll") for (int k = 0; k < 2; ++k) dst[m][k] = *(const PG8_LAS bf16x8*)(lds + PG8_SA(b, h) + aoff + m * 2048 + k * 1024); } while (0)
; #define PG8_LDB(dst, b, h) do { _Pragma("unroll") for (int n = 0; n < 2; ++n) _Pragma("unroll") for (int k = 0; k < 2; ++k) dst[n][k] = *(const PG8_LAS bf16x8*)(lds + PG8_SB(b, h) + boff + n * 2048 + k * 1024); } while (0)
; #define PG8_MMA(ai, bj, At, Bt) do { __builtin_amdgcn_s_setprio(1); _Pragma("unroll") for (int m = 0; m < 4; ++m) _Pragma("unroll") for (int n = 0; n < 2; ++n) _Pragma("unroll") for (int k = 0; k < 2; ++k) \
;         acc[ai][bj][m][n] = __builtin_amdgcn_mfma_f32_16x16x32_bf16(Bt[n][k], At[m][k], acc[ai][bj][m][n], 0, 0, 0); __builtin_amdgcn_s_setprio(0); } while (0)
; #define PG8_WAIT_V(n) asm volatile("s_waitcnt vmcnt(" #n ")" ::: "memory")
; #define PG8_BAR __builtin_amdgcn_s_barrier()
; template <class Epi, class Sched, bool ALIGN_EPI = false, bool SP2 = false>
; __device__ __forceinline__ void gemm_phase(PG8_LAS unsigned char* lds, const Gemm g, const Sched& S, const Epi& E) {
;     ...
;         for (int t = 0; t < nt; t += 2) {
;             const bool last = (t == nt - 2);
;             const char* a1 = cA + (size_t)(t + 1) * kstep;
;             const char* a2 = last ? nA : cA + (size_t)(t + 2) * kstep; const char* b2 = last ? nB : cB + (size_t)(t + 2) * kstep;
;             const char* a3 = a2 + kstep; const char* b3 = b2 + kstep;
;             if (last && has_next) S.a_ready(nxt);
;             if constexpr (SP2) {
;             PG8_LDB(B0, 0, 0); PG8_LDB(B1, 0, 1); PG8_SCHED; PG8_LDA(At, 0, 0); PG8_STAGE(PG8_SA(1, 1), a1 + hstep, voffA);
;             PG8_WAIT_V(8); PG8_WAIT_L(0); PG8_BAR; PG8_MMA(0, 0, At, B0); PG8_MMA(0, 1, At, B1); PG8_BAR; PG8_SCHED;
;             PG8_LDA(At, 0, 1); PG8_STAGE(PG8_SB(0, 0), b2, voffB); PG8_STAGE(PG8_SB(0, 1), b2 + hstep, voffB); PG8_STAGE(PG8_SA(0, 0), a2, voffA);
;             PG8_WAIT_V(8); PG8_WAIT_L(0); PG8_BAR; PG8_MMA(1, 0, At, B0); PG8_MMA(1, 1, At, B1); PG8_BAR; PG8_SCHED;
.LBB0_945:
	ds_read_b128 v[144:147], v153
	ds_read_b128 v[156:159], v153 offset:1024
	ds_read_b128 v[160:163], v153 offset:2048
	ds_read_b128 v[164:167], v153 offset:3072
	ds_read_b128 v[168:171], v154
	ds_read_b128 v[172:175], v154 offset:1024
	ds_read_b128 v[176:179], v154 offset:2048
	ds_read_b128 v[180:183], v154 offset:3072
	s_add_u32 s22, s20, 0xfff80080
	s_addc_u32 s23, s21, -1
	s_cmp_eq_u32 s42, 28
	s_cselect_b32 s25, s15, s23
	s_cselect_b32 s24, s33, s22
	s_cselect_b32 s23, s13, s41
	s_cselect_b32 s22, s39, s40
	v_lshl_add_u64 v[148:149], s[20:21], 0, v[136:137]
	s_add_i32 m0, s19, 0xc000
	ds_read_b128 v[184:187], v155
	ds_read_b128 v[188:191], v155 offset:1024
	ds_read_b128 v[194:197], v155 offset:2048
	ds_read_b128 v[198:201], v155 offset:3072
	ds_read_b128 v[202:205], v155 offset:4096
	ds_read_b128 v[206:209], v155 offset:5120
	ds_read_b128 v[210:213], v155 offset:6144
	ds_read_b128 v[214:217], v155 offset:7168
	global_load_lds_dwordx4 v[148:149], off
	v_lshl_add_u64 v[148:149], s[20:21], 0, v[138:139]
	s_add_i32 m0, s19, 0xe000
	s_nop 0
	global_load_lds_dwordx4 v[148:149], off
	s_waitcnt vmcnt(8)
	s_waitcnt lgkmcnt(0)
	s_barrier
	s_setprio 1
	s_waitcnt lgkmcnt(0)
	v_mfma_f32_16x16x32_bf16 v[124:127], v[144:147], v[184:187], v[124:127]
	v_mfma_f32_16x16x32_bf16 v[120:123], v[160:163], v[184:187], v[120:123]
	v_mfma_f32_16x16x32_bf16 v[112:115], v[144:147], v[194:197], v[112:115]
	v_mfma_f32_16x16x32_bf16 v[104:107], v[160:163], v[194:197], v[104:107]
	v_mfma_f32_16x16x32_bf16 v[92:95], v[144:147], v[202:205], v[92:95]
	v_mfma_f32_16x16x32_bf16 v[88:91], v[160:163], v[202:205], v[88:91]
	v_mfma_f32_16x16x32_bf16 v[76:79], v[144:147], v[210:213], v[76:79]
	v_mfma_f32_16x16x32_bf16 v[72:75], v[160:163], v[210:213], v[72:75]
	v_mfma_f32_16x16x32_bf16 v[124:127], v[156:159], v[188:191], v[124:127]
	v_mfma_f32_16x16x32_bf16 v[120:123], v[164:167], v[188:191], v[120:123]
	v_mfma_f32_16x16x32_bf16 v[112:115], v[156:159], v[198:201], v[112:115]
	v_mfma_f32_16x16x32_bf16 v[104:107], v[164:167], v[198:201], v[104:107]
	v_mfma_f32_16x16x32_bf16 v[92:95], v[156:159], v[206:209], v[92:95]
	v_mfma_f32_16x16x32_bf16 v[88:91], v[164:167], v[206:209], v[88:91]
	v_mfma_f32_16x16x32_bf16 v[76:79], v[156:159], v[214:217], v[76:79]
	v_mfma_f32_16x16x32_bf16 v[72:75], v[164:167], v[214:217], v[72:75]
	s_setprio 0
	s_setprio 1
	v_mfma_f32_16x16x32_bf16 v[116:119], v[168:171], v[184:187], v[116:119]
	v_mfma_f32_16x16x32_bf16 v[108:111], v[176:179], v[184:187], v[108:111]
	v_mfma_f32_16x16x32_bf16 v[100:103], v[168:171], v[194:197], v[100:103]
	v_mfma_f32_16x16x32_bf16 v[96:99], v[176:179], v[194:197], v[96:99]
	v_mfma_f32_16x16x32_bf16 v[84:87], v[168:171], v[202:205], v[84:87]
	v_mfma_f32_16x16x32_bf16 v[80:83], v[176:179], v[202:205], v[80:83]
	v_mfma_f32_16x16x32_bf16 v[68:71], v[168:171], v[210:213], v[68:71]
	v_mfma_f32_16x16x32_bf16 v[64:67], v[176:179], v[210:213], v[64:67]
	v_mfma_f32_16x16x32_bf16 v[116:119], v[172:175], v[188:191], v[116:119]
	v_mfma_f32_16x16x32_bf16 v[108:111], v[180:183], v[188:191], v[108:111]
	v_mfma_f32_16x16x32_bf16 v[100:103], v[172:175], v[198:201], v[100:103]
	v_mfma_f32_16x16x32_bf16 v[96:99], v[180:183], v[198:201], v[96:99]
	v_mfma_f32_16x16x32_bf16 v[84:87], v[172:175], v[206:209], v[84:87]
	v_mfma_f32_16x16x32_bf16 v[80:83], v[180:183], v[206:209], v[80:83]
	v_mfma_f32_16x16x32_bf16 v[68:71], v[172:175], v[214:217], v[68:71]
	v_mfma_f32_16x16x32_bf16 v[64:67], v[180:183], v[214:217], v[64:67]
	s_setprio 0
	s_barrier
	s_add_i32 s43, s37, s26
	v_lshl_add_u64 v[148:149], s[22:23], 0, v[130:131]
	s_mov_b32 m0, s43
	ds_read_b128 v[184:187], v155 offset:16384
	ds_read_b128 v[188:191], v155 offset:17408
	ds_read_b128 v[194:197], v155 offset:18432
	ds_read_b128 v[198:201], v155 offset:19456
	ds_read_b128 v[202:205], v155 offset:20480
	ds_read_b128 v[206:209], v155 offset:21504
	ds_read_b128 v[210:213], v155 offset:22528
	ds_read_b128 v[214:217], v155 offset:23552
	global_load_lds_dwordx4 v[148:149], off
	s_add_i32 m0, s43, 0x2000
	s_add_u32 s44, s22, 0x80000
	v_lshl_add_u64 v[218:219], s[22:23], 0, v[134:135]
	s_addc_u32 s45, s23, 0
	s_add_i32 s43, s38, s26
	global_load_lds_dwordx4 v[218:219], off
	v_lshl_add_u64 v[220:221], s[44:45], 0, v[130:131]
	s_mov_b32 m0, s43
	v_lshl_add_u64 v[222:223], s[24:25], 0, v[132:133]
	global_load_lds_dwordx4 v[220:221], off
	v_lshl_add_u64 v[220:221], s[44:45], 0, v[134:135]
	s_add_i32 m0, s43, 0x2000
	s_nop 0
	global_load_lds_dwordx4 v[220:221], off
	v_lshl_add_u64 v[220:221], s[24:25], 0, v[128:129]
	s_mov_b32 m0, s19
	s_nop 0
	global_load_lds_dwordx4 v[220:221], off
	s_mov_b32 m0, s27
	s_nop 0
	global_load_lds_dwordx4 v[222:223], off
	s_waitcnt vmcnt(8)
	s_waitcnt lgkmcnt(0)
	s_barrier
; #define PG8_STAGE(bufoff, gbase, voff) do { _Pragma("unroll") for (int _i = 0; _i < 2; ++_i) \
;         __builtin_amdgcn_global_load_lds((const unsigned*)((const char*)(gbase) + (voff)[_i]), (PG8_LAS unsigned*)(lds + (bufoff) + ldsw + _i * 8192), 16, 0, 0); } while (0)
; #define PG8_LDA(dst, b, h) do { _Pragma("unroll") for (int m = 0; m < 4; ++m) _Pragma("unroll") for (int k = 0; k < 2; ++k) dst[m][k] = *(const PG8_LAS bf16x8*)(lds + PG8_SA(b, h) + aoff + m * 2048 + k * 1024); } while (0)
; #define PG8_LDB(dst, b, h) do { _Pragma("unroll") for (int n = 0; n < 2; ++n) _Pragma("unroll") for (int k = 0; k < 2; ++k) dst[n][k] = *(const PG8_LAS bf16x8*)(lds + PG8_SB(b, h) + boff + n * 2048 + k * 1024); } while (0)
; #define PG8_MMA(ai, bj, At, Bt) do { __builtin_amdgcn_s_setprio(1); _Pragma("unroll") for (int m = 0; m < 4; ++m) _Pragma("unroll") for (int n = 0; n < 2; ++n) _Pragma("unroll") for (int k = 0; k < 2; ++k) \
;         acc[ai][bj][m][n] = __builtin_amdgcn_mfma_f32_16x16x32_bf16(Bt[n][k], At[m][k], acc[ai][bj][m][n], 0, 0, 0); __builtin_amdgcn_s_setprio(0); } while (0)
; #define PG8_WAIT_V(n) asm volatile("s_waitcnt vmcnt(" #n ")" ::: "memory")
; #define PG8_WAIT_L(n) asm volatile("s_waitcnt lgkmcnt(" #n ")" ::: "memory")
; #define PG8_BAR __builtin_amdgcn_s_barrier()
; #define PG8_SCHED __builtin_amdgcn_sched_barrier(0)
; template <class Epi, class Sched, bool ALIGN_EPI = false, bool SP2 = false>
; __device__ __forceinline__ void gemm_phase(PG8_LAS unsigned char* lds, const Gemm g, const Sched& S, const Epi& E) {
;     ...
;             PG8_WAIT_V(8); PG8_WAIT_L(0); PG8_BAR; PG8_MMA(1, 0, At, B0); PG8_MMA(1, 1, At, B1); PG8_BAR; PG8_SCHED;
;             PG8_LDB(B0, 1, 0); PG8_LDB(B1, 1, 1); PG8_SCHED; PG8_LDA(At, 1, 0); PG8_STAGE(PG8_SA(0, 1), a2 + hstep, voffA);
;             PG8_WAIT_V(8); PG8_WAIT_L(0); PG8_BAR; PG8_MMA(0, 0, At, B0); PG8_MMA(0, 1, At, B1); PG8_BAR; PG8_SCHED;
	s_setprio 1
	s_waitcnt lgkmcnt(0)
	v_mfma_f32_16x16x32_bf16 v[60:63], v[144:147], v[184:187], v[60:63]
	v_mfma_f32_16x16x32_bf16 v[56:59], v[160:163], v[184:187], v[56:59]
	v_mfma_f32_16x16x32_bf16 v[44:47], v[144:147], v[194:197], v[44:47]
	v_mfma_f32_16x16x32_bf16 v[40:43], v[160:163], v[194:197], v[40:43]
	v_mfma_f32_16x16x32_bf16 v[28:31], v[144:147], v[202:205], v[28:31]
	v_mfma_f32_16x16x32_bf16 v[24:27], v[160:163], v[202:205], v[24:27]
	v_mfma_f32_16x16x32_bf16 v[12:15], v[144:147], v[210:213], v[12:15]
	v_mfma_f32_16x16x32_bf16 v[8:11], v[160:163], v[210:213], v[8:11]
	v_mfma_f32_16x16x32_bf16 v[60:63], v[156:159], v[188:191], v[60:63]
	v_mfma_f32_16x16x32_bf16 v[56:59], v[164:167], v[188:191], v[56:59]
	v_mfma_f32_16x16x32_bf16 v[44:47], v[156:159], v[198:201], v[44:47]
	v_mfma_f32_16x16x32_bf16 v[40:43], v[164:167], v[198:201], v[40:43]
	v_mfma_f32_16x16x32_bf16 v[28:31], v[156:159], v[206:209], v[28:31]
	v_mfma_f32_16x16x32_bf16 v[24:27], v[164:167], v[206:209], v[24:27]
	v_mfma_f32_16x16x32_bf16 v[12:15], v[156:159], v[214:217], v[12:15]
	v_mfma_f32_16x16x32_bf16 v[8:11], v[164:167], v[214:217], v[8:11]
	s_setprio 0
	s_setprio 1
	v_mfma_f32_16x16x32_bf16 v[52:55], v[168:171], v[184:187], v[52:55]
	v_mfma_f32_16x16x32_bf16 v[48:51], v[176:179], v[184:187], v[48:51]
	v_mfma_f32_16x16x32_bf16 v[36:39], v[168:171], v[194:197], v[36:39]
	v_mfma_f32_16x16x32_bf16 v[32:35], v[176:179], v[194:197], v[32:35]
	v_mfma_f32_16x16x32_bf16 v[20:23], v[168:171], v[202:205], v[20:23]
	v_mfma_f32_16x16x32_bf16 v[16:19], v[176:179], v[202:205], v[16:19]
	v_mfma_f32_16x16x32_bf16 v[4:7], v[168:171], v[210:213], v[4:7]
	v_mfma_f32_16x16x32_bf16 v[0:3], v[176:179], v[210:213], v[0:3]
	v_mfma_f32_16x16x32_bf16 v[52:55], v[172:175], v[188:191], v[52:55]
	v_mfma_f32_16x16x32_bf16 v[48:51], v[180:183], v[188:191], v[48:51]
	v_mfma_f32_16x16x32_bf16 v[36:39], v[172:175], v[198:201], v[36:39]
	v_mfma_f32_16x16x32_bf16 v[32:35], v[180:183], v[198:201], v[32:35]
	v_mfma_f32_16x16x32_bf16 v[20:23], v[172:175], v[206:209], v[20:23]
	v_mfma_f32_16x16x32_bf16 v[16:19], v[180:183], v[206:209], v[16:19]
	v_mfma_f32_16x16x32_bf16 v[4:7], v[172:175], v[214:217], v[4:7]
	v_mfma_f32_16x16x32_bf16 v[0:3], v[180:183], v[214:217], v[0:3]
	s_setprio 0
	s_barrier
	s_add_i32 s43, 0, 0x18000
	s_add_i32 s44, 0, 0x1c000
	v_add_u32_e32 v164, s43, v151
	v_add_u32_e32 v180, s44, v151
	ds_read_b128 v[144:147], v164
	ds_read_b128 v[156:159], v164 offset:1024
	ds_read_b128 v[160:163], v164 offset:2048
	ds_read_b128 v[164:167], v164 offset:3072
	ds_read_b128 v[168:171], v180
	ds_read_b128 v[172:175], v180 offset:1024
	ds_read_b128 v[176:179], v180 offset:2048
	ds_read_b128 v[180:183], v180 offset:3072
	s_add_u32 s24, s24, 0x80000
	s_addc_u32 s25, s25, 0
	s_mov_b32 m0, s28
	v_lshl_add_u64 v[224:225], s[24:25], 0, v[128:129]
	ds_read_b128 v[184:187], v155 offset:32768
	ds_read_b128 v[188:191], v155 offset:33792
	ds_read_b128 v[194:197], v155 offset:34816
	ds_read_b128 v[198:201], v155 offset:35840
	ds_read_b128 v[202:205], v155 offset:36864
	ds_read_b128 v[206:209], v155 offset:37888
	ds_read_b128 v[210:213], v155 offset:38912
	ds_read_b128 v[214:217], v155 offset:39936
	global_load_lds_dwordx4 v[224:225], off
	v_lshl_add_u64 v[224:225], s[24:25], 0, v[132:133]
	s_mov_b32 m0, s29
	s_nop 0
	global_load_lds_dwordx4 v[224:225], off
	s_waitcnt vmcnt(8)
	s_waitcnt lgkmcnt(0)
	s_barrier
	s_setprio 1
	s_waitcnt lgkmcnt(0)
	v_mfma_f32_16x16x32_bf16 v[124:127], v[144:147], v[184:187], v[124:127]
	v_mfma_f32_16x16x32_bf16 v[120:123], v[160:163], v[184:187], v[120:123]
	v_mfma_f32_16x16x32_bf16 v[112:115], v[144:147], v[194:197], v[112:115]
	v_mfma_f32_16x16x32_bf16 v[104:107], v[160:163], v[194:197], v[104:107]
	v_mfma_f32_16x16x32_bf16 v[92:95], v[144:147], v[202:205], v[92:95]
	v_mfma_f32_16x16x32_bf16 v[88:91], v[160:163], v[202:205], v[88:91]
	v_mfma_f32_16x16x32_bf16 v[76:79], v[144:147], v[210:213], v[76:79]
	v_mfma_f32_16x16x32_bf16 v[72:75], v[160:163], v[210:213], v[72:75]
	v_mfma_f32_16x16x32_bf16 v[124:127], v[156:159], v[188:191], v[124:127]
	v_mfma_f32_16x16x32_bf16 v[120:123], v[164:167], v[188:191], v[120:123]
	v_mfma_f32_16x16x32_bf16 v[112:115], v[156:159], v[198:201], v[112:115]
	v_mfma_f32_16x16x32_bf16 v[104:107], v[164:167], v[198:201], v[104:107]
	v_mfma_f32_16x16x32_bf16 v[92:95], v[156:159], v[206:209], v[92:95]
	v_mfma_f32_16x16x32_bf16 v[88:91], v[164:167], v[206:209], v[88:91]
	v_mfma_f32_16x16x32_bf16 v[76:79], v[156:159], v[214:217], v[76:79]
	v_mfma_f32_16x16x32_bf16 v[72:75], v[164:167], v[214:217], v[72:75]
	s_setprio 0
	s_setprio 1
	v_mfma_f32_16x16x32_bf16 v[116:119], v[168:171], v[184:187], v[116:119]
	v_mfma_f32_16x16x32_bf16 v[108:111], v[176:179], v[184:187], v[108:111]
	v_mfma_f32_16x16x32_bf16 v[100:103], v[168:171], v[194:197], v[100:103]
	v_mfma_f32_16x16x32_bf16 v[96:99], v[176:179], v[194:197], v[96:99]
	v_mfma_f32_16x16x32_bf16 v[84:87], v[168:171], v[202:205], v[84:87]
	v_mfma_f32_16x16x32_bf16 v[80:83], v[176:179], v[202:205], v[80:83]
	v_mfma_f32_16x16x32_bf16 v[68:71], v[168:171], v[210:213], v[68:71]
	v_mfma_f32_16x16x32_bf16 v[64:67], v[176:179], v[210:213], v[64:67]
	v_mfma_f32_16x16x32_bf16 v[116:119], v[172:175], v[188:191], v[116:119]
	v_mfma_f32_16x16x32_bf16 v[108:111], v[180:183], v[188:191], v[108:111]
	v_mfma_f32_16x16x32_bf16 v[100:103], v[172:175], v[198:201], v[100:103]
	v_mfma_f32_16x16x32_bf16 v[96:99], v[180:183], v[198:201], v[96:99]
	v_mfma_f32_16x16x32_bf16 v[84:87], v[172:175], v[206:209], v[84:87]
	v_mfma_f32_16x16x32_bf16 v[80:83], v[180:183], v[206:209], v[80:83]
	v_mfma_f32_16x16x32_bf16 v[68:71], v[172:175], v[214:217], v[68:71]
	v_mfma_f32_16x16x32_bf16 v[64:67], v[180:183], v[214:217], v[64:67]
	s_setprio 0
	s_barrier
; #define PG8_STAGE(bufoff, gbase, voff) do { _Pragma("unroll") for (int _i = 0; _i < 2; ++_i) \
;         __builtin_amdgcn_global_load_lds((const unsigned*)((const char*)(gbase) + (voff)[_i]), (PG8_LAS unsigned*)(lds + (bufoff) + ldsw + _i * 8192), 16, 0, 0); } while (0)
; #define PG8_LDA(dst, b, h) do { _Pragma("unroll") for (int m = 0; m < 4; ++m) _Pragma("unroll") for (int k = 0; k < 2; ++k) dst[m][k] = *(const PG8_LAS bf16x8*)(lds + PG8_SA(b, h) + aoff + m * 2048 + k * 1024); } while (0)
; #define PG8_MMA(ai, bj, At, Bt) do { __builtin_amdgcn_s_setprio(1); _Pragma("unroll") for (int m = 0; m < 4; ++m) _Pragma("unroll") for (int n = 0; n < 2; ++n) _Pragma("unroll") for (int k = 0; k < 2; ++k) \
;         acc[ai][bj][m][n] = __builtin_amdgcn_mfma_f32_16x16x32_bf16(Bt[n][k], At[m][k], acc[ai][bj][m][n], 0, 0, 0); __builtin_amdgcn_s_setprio(0); } while (0)
; #define PG8_WAIT_V(n) asm volatile("s_waitcnt vmcnt(" #n ")" ::: "memory")
; #define PG8_WAIT_L(n) asm volatile("s_waitcnt lgkmcnt(" #n ")" ::: "memory")
; #define PG8_BAR __builtin_amdgcn_s_barrier()
; #define PG8_SCHED __builtin_amdgcn_sched_barrier(0)
; template <class Epi, class Sched, bool ALIGN_EPI = false, bool SP2 = false>
; __device__ __forceinline__ void gemm_phase(PG8_LAS unsigned char* lds, const Gemm g, const Sched& S, const Epi& E) {
;     ...
;             PG8_LDA(At, 1, 1); PG8_STAGE(PG8_SB(1, 0), b3, voffB); PG8_STAGE(PG8_SB(1, 1), b3 + hstep, voffB); PG8_STAGE(PG8_SA(1, 0), a3, voffA);
;             PG8_WAIT_V(8); PG8_WAIT_L(0); PG8_BAR; PG8_MMA(1, 0, At, B0); PG8_MMA(1, 1, At, B1); PG8_BAR; PG8_SCHED;
	s_add_i32 s24, s43, s26
	v_lshl_add_u64 v[148:149], v[148:149], 0, s[8:9]
	s_mov_b32 m0, s24
	ds_read_b128 v[184:187], v155 offset:49152
	ds_read_b128 v[188:191], v155 offset:50176
	ds_read_b128 v[194:197], v155 offset:51200
	ds_read_b128 v[198:201], v155 offset:52224
	ds_read_b128 v[202:205], v155 offset:53248
	ds_read_b128 v[206:209], v155 offset:54272
	ds_read_b128 v[210:213], v155 offset:55296
	ds_read_b128 v[214:217], v155 offset:56320
	global_load_lds_dwordx4 v[148:149], off
	s_add_i32 m0, s24, 0x2000
	s_add_u32 s22, s22, 0x80080
	v_lshl_add_u64 v[148:149], v[218:219], 0, s[8:9]
	s_addc_u32 s23, s23, 0
	s_add_i32 s24, s44, s26
	global_load_lds_dwordx4 v[148:149], off
	v_lshl_add_u64 v[148:149], s[22:23], 0, v[130:131]
	s_mov_b32 m0, s24
	s_nop 0
	global_load_lds_dwordx4 v[148:149], off
	v_lshl_add_u64 v[148:149], s[22:23], 0, v[134:135]
	s_add_i32 m0, s24, 0x2000
	s_nop 0
	global_load_lds_dwordx4 v[148:149], off
	v_lshl_add_u64 v[148:149], v[220:221], 0, s[8:9]
	s_mov_b32 m0, s31
	s_nop 0
	global_load_lds_dwordx4 v[148:149], off
	v_lshl_add_u64 v[148:149], v[222:223], 0, s[8:9]
	s_mov_b32 m0, s34
	s_nop 0
	global_load_lds_dwordx4 v[148:149], off
	s_waitcnt vmcnt(8)
	s_waitcnt lgkmcnt(0)
	s_barrier
	s_setprio 1
	s_waitcnt lgkmcnt(0)
	v_mfma_f32_16x16x32_bf16 v[60:63], v[144:147], v[184:187], v[60:63]
	v_mfma_f32_16x16x32_bf16 v[56:59], v[160:163], v[184:187], v[56:59]
	v_mfma_f32_16x16x32_bf16 v[44:47], v[144:147], v[194:197], v[44:47]
	v_mfma_f32_16x16x32_bf16 v[40:43], v[160:163], v[194:197], v[40:43]
	v_mfma_f32_16x16x32_bf16 v[28:31], v[144:147], v[202:205], v[28:31]
	v_mfma_f32_16x16x32_bf16 v[24:27], v[160:163], v[202:205], v[24:27]
	v_mfma_f32_16x16x32_bf16 v[12:15], v[144:147], v[210:213], v[12:15]
	v_mfma_f32_16x16x32_bf16 v[8:11], v[160:163], v[210:213], v[8:11]
	v_mfma_f32_16x16x32_bf16 v[60:63], v[156:159], v[188:191], v[60:63]
	v_mfma_f32_16x16x32_bf16 v[56:59], v[164:167], v[188:191], v[56:59]
	v_mfma_f32_16x16x32_bf16 v[44:47], v[156:159], v[198:201], v[44:47]
	v_mfma_f32_16x16x32_bf16 v[40:43], v[164:167], v[198:201], v[40:43]
	v_mfma_f32_16x16x32_bf16 v[28:31], v[156:159], v[206:209], v[28:31]
	v_mfma_f32_16x16x32_bf16 v[24:27], v[164:167], v[206:209], v[24:27]
	v_mfma_f32_16x16x32_bf16 v[12:15], v[156:159], v[214:217], v[12:15]
	v_mfma_f32_16x16x32_bf16 v[8:11], v[164:167], v[214:217], v[8:11]
	s_setprio 0
	s_setprio 1
	v_mfma_f32_16x16x32_bf16 v[52:55], v[168:171], v[184:187], v[52:55]
	v_mfma_f32_16x16x32_bf16 v[48:51], v[176:179], v[184:187], v[48:51]
	v_mfma_f32_16x16x32_bf16 v[36:39], v[168:171], v[194:197], v[36:39]
	v_mfma_f32_16x16x32_bf16 v[32:35], v[176:179], v[194:197], v[32:35]
	v_mfma_f32_16x16x32_bf16 v[20:23], v[168:171], v[202:205], v[20:23]
	v_mfma_f32_16x16x32_bf16 v[16:19], v[176:179], v[202:205], v[16:19]
	v_mfma_f32_16x16x32_bf16 v[4:7], v[168:171], v[210:213], v[4:7]
	v_mfma_f32_16x16x32_bf16 v[0:3], v[176:179], v[210:213], v[0:3]
	v_mfma_f32_16x16x32_bf16 v[52:55], v[172:175], v[188:191], v[52:55]
	v_mfma_f32_16x16x32_bf16 v[48:51], v[180:183], v[188:191], v[48:51]
	v_mfma_f32_16x16x32_bf16 v[36:39], v[172:175], v[198:201], v[36:39]
	v_mfma_f32_16x16x32_bf16 v[32:35], v[180:183], v[198:201], v[32:35]
	v_mfma_f32_16x16x32_bf16 v[20:23], v[172:175], v[206:209], v[20:23]
	v_mfma_f32_16x16x32_bf16 v[16:19], v[180:183], v[206:209], v[16:19]
	v_mfma_f32_16x16x32_bf16 v[4:7], v[172:175], v[214:217], v[4:7]
	v_mfma_f32_16x16x32_bf16 v[0:3], v[180:183], v[214:217], v[0:3]
	s_setprio 0
	s_barrier
	s_add_i32 s42, s42, 2
	s_add_u32 s20, s20, 0x100
	s_addc_u32 s21, s21, 0
	s_add_u32 s40, s40, 0x100
	s_addc_u32 s41, s41, 0
	s_cmp_gt_u32 s42, 29
	s_cbranch_scc0 .LBB0_945
	s_and_b64 vcc, exec, s[10:11]
	s_cbranch_vccz .LBB0_948
	s_barrier

; #define PG8_STAGE(bufoff, gbase, voff) do { _Pragma("unroll") for (int _i = 0; _i < 2; ++_i) \
;         __builtin_amdgcn_global_load_lds((const unsigned*)((const char*)(gbase) + (voff)[_i]), (PG8_LAS unsigned*)(lds + (bufoff) + ldsw + _i * 8192), 16, 0, 0); } while (0)
; #define PG8_LDA(dst, b, h) do { _Pragma("unroll") for (int m = 0; m < 4; ++m) _Pragma("unroll") for (int k = 0; k < 2; ++k) dst[m][k] = *(const PG8_LAS bf16x8*)(lds + PG8_SA(b, h) + aoff + m * 2048 + k * 1024); } while (0)
; #define PG8_LDB(dst, b, h) do { _Pragma("unroll") for (int n = 0; n < 2; ++n) _Pragma("unroll") for (int k = 0; k < 2; ++k) dst[n][k] = *(const PG8_LAS bf16x8*)(lds + PG8_SB(b, h) + boff + n * 2048 + k * 1024); } while (0)
; #define PG8_MMA(ai, bj, At, Bt) do { __builtin_amdgcn_s_setprio(1); _Pragma("unroll") for (int m = 0; m < 4; ++m) _Pragma("unroll") for (int n = 0; n < 2; ++n) _Pragma("unroll") for (int k = 0; k < 2; ++k) \
;         acc[ai][bj][m][n] = __builtin_amdgcn_mfma_f32_16x16x32_bf16(Bt[n][k], At[m][k], acc[ai][bj][m][n], 0, 0, 0); __builtin_amdgcn_s_setprio(0); } while (0)
; #define PG8_WAIT_V(n) asm volatile("s_waitcnt vmcnt(" #n ")" ::: "memory")
; #define PG8_BAR __builtin_amdgcn_s_barrier()
; template <class Epi, class Sched, bool ALIGN_EPI = false, bool SP2 = false>
; __device__ __forceinline__ void gemm_phase(PG8_LAS unsigned char* lds, const Gemm g, const Sched& S, const Epi& E) {
;     ...
;         for (int t = 0; t < nt; t += 2) {
;             const bool last = (t == nt - 2);
;             const char* a1 = cA + (size_t)(t + 1) * kstep;
;             const char* a2 = last ? nA : cA + (size_t)(t + 2) * kstep; const char* b2 = last ? nB : cB + (size_t)(t + 2) * kstep;
;             const char* a3 = a2 + kstep; const char* b3 = b2 + kstep;
;             if (last && has_next) S.a_ready(nxt);
;             if constexpr (SP2) {
;             PG8_LDB(B0, 0, 0); PG8_LDB(B1, 0, 1); PG8_SCHED; PG8_LDA(At, 0, 0); PG8_STAGE(PG8_SA(1, 1), a1 + hstep, voffA);
;             PG8_WAIT_V(8); PG8_WAIT_L(0); PG8_BAR; PG8_MMA(0, 0, At, B0); PG8_MMA(0, 1, At, B1); PG8_BAR; PG8_SCHED;
;             PG8_LDA(At, 0, 1); PG8_STAGE(PG8_SB(0, 0), b2, voffB); PG8_STAGE(PG8_SB(0, 1), b2 + hstep, voffB); PG8_STAGE(PG8_SA(0, 0), a2, voffA);
;             PG8_WAIT_V(8); PG8_WAIT_L(0); PG8_BAR; PG8_MMA(1, 0, At, B0); PG8_MMA(1, 1, At, B1); PG8_BAR; PG8_SCHED;
.LBB0_1013:
	ds_read_b128 v[150:153], v147
	ds_read_b128 v[154:157], v147 offset:1024
	ds_read_b128 v[158:161], v147 offset:2048
	ds_read_b128 v[162:165], v147 offset:3072
	ds_read_b128 v[166:169], v148
	ds_read_b128 v[170:173], v148 offset:1024
	ds_read_b128 v[174:177], v148 offset:2048
	ds_read_b128 v[178:181], v148 offset:3072
	s_add_u32 s30, s28, 0xfff80080
	s_addc_u32 s31, s29, -1
	s_cmp_eq_u32 s54, 28
	s_cselect_b32 s35, s23, s31
	s_cselect_b32 s34, s50, s30
	s_cselect_b32 s31, s21, s53
	s_cselect_b32 s30, s51, s52
	v_lshl_add_u64 v[190:191], s[28:29], 0, v[136:137]
	s_add_i32 m0, s19, 0xc000
	ds_read_b128 v[182:185], v149
	ds_read_b128 v[186:189], v149 offset:1024
	ds_read_b128 v[194:197], v149 offset:2048
	ds_read_b128 v[198:201], v149 offset:3072
	ds_read_b128 v[202:205], v149 offset:4096
	ds_read_b128 v[206:209], v149 offset:5120
	ds_read_b128 v[210:213], v149 offset:6144
	ds_read_b128 v[214:217], v149 offset:7168
	global_load_lds_dwordx4 v[190:191], off
	v_lshl_add_u64 v[190:191], s[28:29], 0, v[138:139]
	s_add_i32 m0, s19, 0xe000
	s_nop 0
	global_load_lds_dwordx4 v[190:191], off
	s_waitcnt vmcnt(8)
	s_waitcnt lgkmcnt(0)
	s_barrier
	s_setprio 1
	s_waitcnt lgkmcnt(0)
	v_mfma_f32_16x16x32_bf16 v[124:127], v[150:153], v[182:185], v[124:127]
	v_mfma_f32_16x16x32_bf16 v[120:123], v[158:161], v[182:185], v[120:123]
	v_mfma_f32_16x16x32_bf16 v[116:119], v[150:153], v[194:197], v[116:119]
	v_mfma_f32_16x16x32_bf16 v[112:115], v[158:161], v[194:197], v[112:115]
	v_mfma_f32_16x16x32_bf16 v[100:103], v[150:153], v[202:205], v[100:103]
	v_mfma_f32_16x16x32_bf16 v[96:99], v[158:161], v[202:205], v[96:99]
	v_mfma_f32_16x16x32_bf16 v[84:87], v[150:153], v[210:213], v[84:87]
	v_mfma_f32_16x16x32_bf16 v[80:83], v[158:161], v[210:213], v[80:83]
	v_mfma_f32_16x16x32_bf16 v[124:127], v[154:157], v[186:189], v[124:127]
	v_mfma_f32_16x16x32_bf16 v[120:123], v[162:165], v[186:189], v[120:123]
	v_mfma_f32_16x16x32_bf16 v[116:119], v[154:157], v[198:201], v[116:119]
	v_mfma_f32_16x16x32_bf16 v[112:115], v[162:165], v[198:201], v[112:115]
	v_mfma_f32_16x16x32_bf16 v[100:103], v[154:157], v[206:209], v[100:103]
	v_mfma_f32_16x16x32_bf16 v[96:99], v[162:165], v[206:209], v[96:99]
	v_mfma_f32_16x16x32_bf16 v[84:87], v[154:157], v[214:217], v[84:87]
	v_mfma_f32_16x16x32_bf16 v[80:83], v[162:165], v[214:217], v[80:83]
	s_setprio 0
	s_setprio 1
	v_mfma_f32_16x16x32_bf16 v[108:111], v[166:169], v[182:185], v[108:111]
	v_mfma_f32_16x16x32_bf16 v[104:107], v[174:177], v[182:185], v[104:107]
	v_mfma_f32_16x16x32_bf16 v[92:95], v[166:169], v[194:197], v[92:95]
	v_mfma_f32_16x16x32_bf16 v[88:91], v[174:177], v[194:197], v[88:91]
	v_mfma_f32_16x16x32_bf16 v[76:79], v[166:169], v[202:205], v[76:79]
	v_mfma_f32_16x16x32_bf16 v[72:75], v[174:177], v[202:205], v[72:75]
	v_mfma_f32_16x16x32_bf16 v[68:71], v[166:169], v[210:213], v[68:71]
	v_mfma_f32_16x16x32_bf16 v[64:67], v[174:177], v[210:213], v[64:67]
	v_mfma_f32_16x16x32_bf16 v[108:111], v[170:173], v[186:189], v[108:111]
	v_mfma_f32_16x16x32_bf16 v[104:107], v[178:181], v[186:189], v[104:107]
	v_mfma_f32_16x16x32_bf16 v[92:95], v[170:173], v[198:201], v[92:95]
	v_mfma_f32_16x16x32_bf16 v[88:91], v[178:181], v[198:201], v[88:91]
	v_mfma_f32_16x16x32_bf16 v[76:79], v[170:173], v[206:209], v[76:79]
	v_mfma_f32_16x16x32_bf16 v[72:75], v[178:181], v[206:209], v[72:75]
	v_mfma_f32_16x16x32_bf16 v[68:71], v[170:173], v[214:217], v[68:71]
	v_mfma_f32_16x16x32_bf16 v[64:67], v[178:181], v[214:217], v[64:67]
	s_setprio 0
	s_barrier
	s_add_i32 s55, s43, s2
	v_lshl_add_u64 v[190:191], s[30:31], 0, v[132:133]
	s_mov_b32 m0, s55
	ds_read_b128 v[182:185], v149 offset:16384
	ds_read_b128 v[186:189], v149 offset:17408
	ds_read_b128 v[194:197], v149 offset:18432
	ds_read_b128 v[198:201], v149 offset:19456
	ds_read_b128 v[202:205], v149 offset:20480
	ds_read_b128 v[206:209], v149 offset:21504
	ds_read_b128 v[210:213], v149 offset:22528
	ds_read_b128 v[214:217], v149 offset:23552
	global_load_lds_dwordx4 v[190:191], off
	s_add_i32 m0, s55, 0x2000
	s_add_u32 s56, s30, 0x80000
	v_lshl_add_u64 v[218:219], s[30:31], 0, v[128:129]
	s_addc_u32 s57, s31, 0
	s_add_i32 s55, s44, s2
	global_load_lds_dwordx4 v[218:219], off
	v_lshl_add_u64 v[220:221], s[56:57], 0, v[132:133]
	s_mov_b32 m0, s55
	v_lshl_add_u64 v[222:223], s[34:35], 0, v[130:131]
	global_load_lds_dwordx4 v[220:221], off
	v_lshl_add_u64 v[220:221], s[56:57], 0, v[128:129]
	s_add_i32 m0, s55, 0x2000
	s_nop 0
	global_load_lds_dwordx4 v[220:221], off
	v_lshl_add_u64 v[220:221], s[34:35], 0, v[134:135]
	s_mov_b32 m0, s19
	s_nop 0
	global_load_lds_dwordx4 v[220:221], off
	s_mov_b32 m0, s33
	s_nop 0
	global_load_lds_dwordx4 v[222:223], off
	s_waitcnt vmcnt(8)
	s_waitcnt lgkmcnt(0)
	s_barrier
; #define PG8_STAGE(bufoff, gbase, voff) do { _Pragma("unroll") for (int _i = 0; _i < 2; ++_i) \
;         __builtin_amdgcn_global_load_lds((const unsigned*)((const char*)(gbase) + (voff)[_i]), (PG8_LAS unsigned*)(lds + (bufoff) + ldsw + _i * 8192), 16, 0, 0); } while (0)
; #define PG8_LDA(dst, b, h) do { _Pragma("unroll") for (int m = 0; m < 4; ++m) _Pragma("unroll") for (int k = 0; k < 2; ++k) dst[m][k] = *(const PG8_LAS bf16x8*)(lds + PG8_SA(b, h) + aoff + m * 2048 + k * 1024); } while (0)
; #define PG8_LDB(dst, b, h) do { _Pragma("unroll") for (int n = 0; n < 2; ++n) _Pragma("unroll") for (int k = 0; k < 2; ++k) dst[n][k] = *(const PG8_LAS bf16x8*)(lds + PG8_SB(b, h) + boff + n * 2048 + k * 1024); } while (0)
; #define PG8_MMA(ai, bj, At, Bt) do { __builtin_amdgcn_s_setprio(1); _Pragma("unroll") for (int m = 0; m < 4; ++m) _Pragma("unroll") for (int n = 0; n < 2; ++n) _Pragma("unroll") for (int k = 0; k < 2; ++k) \
;         acc[ai][bj][m][n] = __builtin_amdgcn_mfma_f32_16x16x32_bf16(Bt[n][k], At[m][k], acc[ai][bj][m][n], 0, 0, 0); __builtin_amdgcn_s_setprio(0); } while (0)
; #define PG8_WAIT_V(n) asm volatile("s_waitcnt vmcnt(" #n ")" ::: "memory")
; #define PG8_WAIT_L(n) asm volatile("s_waitcnt lgkmcnt(" #n ")" ::: "memory")
; #define PG8_BAR __builtin_amdgcn_s_barrier()
; #define PG8_SCHED __builtin_amdgcn_sched_barrier(0)
; template <class Epi, class Sched, bool ALIGN_EPI = false, bool SP2 = false>
; __device__ __forceinline__ void gemm_phase(PG8_LAS unsigned char* lds, const Gemm g, const Sched& S, const Epi& E) {
;     ...
;             PG8_WAIT_V(8); PG8_WAIT_L(0); PG8_BAR; PG8_MMA(1, 0, At, B0); PG8_MMA(1, 1, At, B1); PG8_BAR; PG8_SCHED;
;             PG8_LDB(B0, 1, 0); PG8_LDB(B1, 1, 1); PG8_SCHED; PG8_LDA(At, 1, 0); PG8_STAGE(PG8_SA(0, 1), a2 + hstep, voffA);
;             PG8_WAIT_V(8); PG8_WAIT_L(0); PG8_BAR; PG8_MMA(0, 0, At, B0); PG8_MMA(0, 1, At, B1); PG8_BAR; PG8_SCHED;
	s_setprio 1
	s_waitcnt lgkmcnt(0)
	v_mfma_f32_16x16x32_bf16 v[60:63], v[150:153], v[182:185], v[60:63]
	v_mfma_f32_16x16x32_bf16 v[56:59], v[158:161], v[182:185], v[56:59]
	v_mfma_f32_16x16x32_bf16 v[52:55], v[150:153], v[194:197], v[52:55]
	v_mfma_f32_16x16x32_bf16 v[48:51], v[158:161], v[194:197], v[48:51]
	v_mfma_f32_16x16x32_bf16 v[36:39], v[150:153], v[202:205], v[36:39]
	v_mfma_f32_16x16x32_bf16 v[32:35], v[158:161], v[202:205], v[32:35]
	v_mfma_f32_16x16x32_bf16 v[20:23], v[150:153], v[210:213], v[20:23]
	v_mfma_f32_16x16x32_bf16 v[16:19], v[158:161], v[210:213], v[16:19]
	v_mfma_f32_16x16x32_bf16 v[60:63], v[154:157], v[186:189], v[60:63]
	v_mfma_f32_16x16x32_bf16 v[56:59], v[162:165], v[186:189], v[56:59]
	v_mfma_f32_16x16x32_bf16 v[52:55], v[154:157], v[198:201], v[52:55]
	v_mfma_f32_16x16x32_bf16 v[48:51], v[162:165], v[198:201], v[48:51]
	v_mfma_f32_16x16x32_bf16 v[36:39], v[154:157], v[206:209], v[36:39]
	v_mfma_f32_16x16x32_bf16 v[32:35], v[162:165], v[206:209], v[32:35]
	v_mfma_f32_16x16x32_bf16 v[20:23], v[154:157], v[214:217], v[20:23]
	v_mfma_f32_16x16x32_bf16 v[16:19], v[162:165], v[214:217], v[16:19]
	s_setprio 0
	s_setprio 1
	v_mfma_f32_16x16x32_bf16 v[44:47], v[166:169], v[182:185], v[44:47]
	v_mfma_f32_16x16x32_bf16 v[40:43], v[174:177], v[182:185], v[40:43]
	v_mfma_f32_16x16x32_bf16 v[28:31], v[166:169], v[194:197], v[28:31]
	v_mfma_f32_16x16x32_bf16 v[24:27], v[174:177], v[194:197], v[24:27]
	v_mfma_f32_16x16x32_bf16 v[12:15], v[166:169], v[202:205], v[12:15]
	v_mfma_f32_16x16x32_bf16 v[8:11], v[174:177], v[202:205], v[8:11]
	v_mfma_f32_16x16x32_bf16 v[4:7], v[166:169], v[210:213], v[4:7]
	v_mfma_f32_16x16x32_bf16 v[0:3], v[174:177], v[210:213], v[0:3]
	v_mfma_f32_16x16x32_bf16 v[44:47], v[170:173], v[186:189], v[44:47]
	v_mfma_f32_16x16x32_bf16 v[40:43], v[178:181], v[186:189], v[40:43]
	v_mfma_f32_16x16x32_bf16 v[28:31], v[170:173], v[198:201], v[28:31]
	v_mfma_f32_16x16x32_bf16 v[24:27], v[178:181], v[198:201], v[24:27]
	v_mfma_f32_16x16x32_bf16 v[12:15], v[170:173], v[206:209], v[12:15]
	v_mfma_f32_16x16x32_bf16 v[8:11], v[178:181], v[206:209], v[8:11]
	v_mfma_f32_16x16x32_bf16 v[4:7], v[170:173], v[214:217], v[4:7]
	v_mfma_f32_16x16x32_bf16 v[0:3], v[178:181], v[214:217], v[0:3]
	s_setprio 0
	s_barrier
	s_add_i32 s55, 0, 0x18000
	s_add_i32 s56, 0, 0x1c000
	v_add_u32_e32 v162, s55, v145
	v_add_u32_e32 v178, s56, v145
	ds_read_b128 v[150:153], v162
	ds_read_b128 v[154:157], v162 offset:1024
	ds_read_b128 v[158:161], v162 offset:2048
	ds_read_b128 v[162:165], v162 offset:3072
	ds_read_b128 v[166:169], v178
	ds_read_b128 v[170:173], v178 offset:1024
	ds_read_b128 v[174:177], v178 offset:2048
	ds_read_b128 v[178:181], v178 offset:3072
	s_add_u32 s34, s34, 0x80000
	s_addc_u32 s35, s35, 0
	s_mov_b32 m0, s36
	v_lshl_add_u64 v[224:225], s[34:35], 0, v[134:135]
	ds_read_b128 v[182:185], v149 offset:32768
	ds_read_b128 v[186:189], v149 offset:33792
	ds_read_b128 v[194:197], v149 offset:34816
	ds_read_b128 v[198:201], v149 offset:35840
	ds_read_b128 v[202:205], v149 offset:36864
	ds_read_b128 v[206:209], v149 offset:37888
	ds_read_b128 v[210:213], v149 offset:38912
	ds_read_b128 v[214:217], v149 offset:39936
	global_load_lds_dwordx4 v[224:225], off
	v_lshl_add_u64 v[224:225], s[34:35], 0, v[130:131]
	s_mov_b32 m0, s37
	s_nop 0
	global_load_lds_dwordx4 v[224:225], off
	s_waitcnt vmcnt(8)
	s_waitcnt lgkmcnt(0)
	s_barrier
	s_setprio 1
	s_waitcnt lgkmcnt(0)
	v_mfma_f32_16x16x32_bf16 v[124:127], v[150:153], v[182:185], v[124:127]
	v_mfma_f32_16x16x32_bf16 v[120:123], v[158:161], v[182:185], v[120:123]
	v_mfma_f32_16x16x32_bf16 v[116:119], v[150:153], v[194:197], v[116:119]
	v_mfma_f32_16x16x32_bf16 v[112:115], v[158:161], v[194:197], v[112:115]
	v_mfma_f32_16x16x32_bf16 v[100:103], v[150:153], v[202:205], v[100:103]
	v_mfma_f32_16x16x32_bf16 v[96:99], v[158:161], v[202:205], v[96:99]
	v_mfma_f32_16x16x32_bf16 v[84:87], v[150:153], v[210:213], v[84:87]
	v_mfma_f32_16x16x32_bf16 v[80:83], v[158:161], v[210:213], v[80:83]
	v_mfma_f32_16x16x32_bf16 v[124:127], v[154:157], v[186:189], v[124:127]
	v_mfma_f32_16x16x32_bf16 v[120:123], v[162:165], v[186:189], v[120:123]
	v_mfma_f32_16x16x32_bf16 v[116:119], v[154:157], v[198:201], v[116:119]
	v_mfma_f32_16x16x32_bf16 v[112:115], v[162:165], v[198:201], v[112:115]
	v_mfma_f32_16x16x32_bf16 v[100:103], v[154:157], v[206:209], v[100:103]
	v_mfma_f32_16x16x32_bf16 v[96:99], v[162:165], v[206:209], v[96:99]
	v_mfma_f32_16x16x32_bf16 v[84:87], v[154:157], v[214:217], v[84:87]
	v_mfma_f32_16x16x32_bf16 v[80:83], v[162:165], v[214:217], v[80:83]
	s_setprio 0
	s_setprio 1
	v_mfma_f32_16x16x32_bf16 v[108:111], v[166:169], v[182:185], v[108:111]
	v_mfma_f32_16x16x32_bf16 v[104:107], v[174:177], v[182:185], v[104:107]
	v_mfma_f32_16x16x32_bf16 v[92:95], v[166:169], v[194:197], v[92:95]
	v_mfma_f32_16x16x32_bf16 v[88:91], v[174:177], v[194:197], v[88:91]
	v_mfma_f32_16x16x32_bf16 v[76:79], v[166:169], v[202:205], v[76:79]
	v_mfma_f32_16x16x32_bf16 v[72:75], v[174:177], v[202:205], v[72:75]
	v_mfma_f32_16x16x32_bf16 v[68:71], v[166:169], v[210:213], v[68:71]
	v_mfma_f32_16x16x32_bf16 v[64:67], v[174:177], v[210:213], v[64:67]
	v_mfma_f32_16x16x32_bf16 v[108:111], v[170:173], v[186:189], v[108:111]
	v_mfma_f32_16x16x32_bf16 v[104:107], v[178:181], v[186:189], v[104:107]
	v_mfma_f32_16x16x32_bf16 v[92:95], v[170:173], v[198:201], v[92:95]
	v_mfma_f32_16x16x32_bf16 v[88:91], v[178:181], v[198:201], v[88:91]
	v_mfma_f32_16x16x32_bf16 v[76:79], v[170:173], v[206:209], v[76:79]
	v_mfma_f32_16x16x32_bf16 v[72:75], v[178:181], v[206:209], v[72:75]
	v_mfma_f32_16x16x32_bf16 v[68:71], v[170:173], v[214:217], v[68:71]
	v_mfma_f32_16x16x32_bf16 v[64:67], v[178:181], v[214:217], v[64:67]
	s_setprio 0
	s_barrier
; #define PG8_STAGE(bufoff, gbase, voff) do { _Pragma("unroll") for (int _i = 0; _i < 2; ++_i) \
;         __builtin_amdgcn_global_load_lds((const unsigned*)((const char*)(gbase) + (voff)[_i]), (PG8_LAS unsigned*)(lds + (bufoff) + ldsw + _i * 8192), 16, 0, 0); } while (0)
; #define PG8_LDA(dst, b, h) do { _Pragma("unroll") for (int m = 0; m < 4; ++m) _Pragma("unroll") for (int k = 0; k < 2; ++k) dst[m][k] = *(const PG8_LAS bf16x8*)(lds + PG8_SA(b, h) + aoff + m * 2048 + k * 1024); } while (0)
; #define PG8_MMA(ai, bj, At, Bt) do { __builtin_amdgcn_s_setprio(1); _Pragma("unroll") for (int m = 0; m < 4; ++m) _Pragma("unroll") for (int n = 0; n < 2; ++n) _Pragma("unroll") for (int k = 0; k < 2; ++k) \
;         acc[ai][bj][m][n] = __builtin_amdgcn_mfma_f32_16x16x32_bf16(Bt[n][k], At[m][k], acc[ai][bj][m][n], 0, 0, 0); __builtin_amdgcn_s_setprio(0); } while (0)
; #define PG8_WAIT_V(n) asm volatile("s_waitcnt vmcnt(" #n ")" ::: "memory")
; #define PG8_WAIT_L(n) asm volatile("s_waitcnt lgkmcnt(" #n ")" ::: "memory")
; #define PG8_BAR __builtin_amdgcn_s_barrier()
; #define PG8_SCHED __builtin_amdgcn_sched_barrier(0)
; template <class Epi, class Sched, bool ALIGN_EPI = false, bool SP2 = false>
; __device__ __forceinline__ void gemm_phase(PG8_LAS unsigned char* lds, const Gemm g, const Sched& S, const Epi& E) {
;     ...
;             PG8_LDA(At, 1, 1); PG8_STAGE(PG8_SB(1, 0), b3, voffB); PG8_STAGE(PG8_SB(1, 1), b3 + hstep, voffB); PG8_STAGE(PG8_SA(1, 0), a3, voffA);
;             PG8_WAIT_V(8); PG8_WAIT_L(0); PG8_BAR; PG8_MMA(1, 0, At, B0); PG8_MMA(1, 1, At, B1); PG8_BAR; PG8_SCHED;
	s_add_i32 s34, s55, s2
	v_lshl_add_u64 v[190:191], v[190:191], 0, s[8:9]
	s_mov_b32 m0, s34
	ds_read_b128 v[182:185], v149 offset:49152
	ds_read_b128 v[186:189], v149 offset:50176
	ds_read_b128 v[194:197], v149 offset:51200
	ds_read_b128 v[198:201], v149 offset:52224
	ds_read_b128 v[202:205], v149 offset:53248
	ds_read_b128 v[206:209], v149 offset:54272
	ds_read_b128 v[210:213], v149 offset:55296
	ds_read_b128 v[214:217], v149 offset:56320
	global_load_lds_dwordx4 v[190:191], off
	s_add_i32 m0, s34, 0x2000
	s_add_u32 s30, s30, 0x80080
	v_lshl_add_u64 v[190:191], v[218:219], 0, s[8:9]
	s_addc_u32 s31, s31, 0
	s_add_i32 s34, s56, s2
	global_load_lds_dwordx4 v[190:191], off
	v_lshl_add_u64 v[190:191], s[30:31], 0, v[132:133]
	s_mov_b32 m0, s34
	s_nop 0
	global_load_lds_dwordx4 v[190:191], off
	v_lshl_add_u64 v[190:191], s[30:31], 0, v[128:129]
	s_add_i32 m0, s34, 0x2000
	s_nop 0
	global_load_lds_dwordx4 v[190:191], off
	v_lshl_add_u64 v[190:191], v[220:221], 0, s[8:9]
	s_mov_b32 m0, s39
	s_nop 0
	global_load_lds_dwordx4 v[190:191], off
	v_lshl_add_u64 v[190:191], v[222:223], 0, s[8:9]
	s_mov_b32 m0, s40
	s_nop 0
	global_load_lds_dwordx4 v[190:191], off
	s_waitcnt vmcnt(8)
	s_waitcnt lgkmcnt(0)
	s_barrier
	s_setprio 1
	s_waitcnt lgkmcnt(0)
	v_mfma_f32_16x16x32_bf16 v[60:63], v[150:153], v[182:185], v[60:63]
	v_mfma_f32_16x16x32_bf16 v[56:59], v[158:161], v[182:185], v[56:59]
	v_mfma_f32_16x16x32_bf16 v[52:55], v[150:153], v[194:197], v[52:55]
	v_mfma_f32_16x16x32_bf16 v[48:51], v[158:161], v[194:197], v[48:51]
	v_mfma_f32_16x16x32_bf16 v[36:39], v[150:153], v[202:205], v[36:39]
	v_mfma_f32_16x16x32_bf16 v[32:35], v[158:161], v[202:205], v[32:35]
	v_mfma_f32_16x16x32_bf16 v[20:23], v[150:153], v[210:213], v[20:23]
	v_mfma_f32_16x16x32_bf16 v[16:19], v[158:161], v[210:213], v[16:19]
	v_mfma_f32_16x16x32_bf16 v[60:63], v[154:157], v[186:189], v[60:63]
	v_mfma_f32_16x16x32_bf16 v[56:59], v[162:165], v[186:189], v[56:59]
	v_mfma_f32_16x16x32_bf16 v[52:55], v[154:157], v[198:201], v[52:55]
	v_mfma_f32_16x16x32_bf16 v[48:51], v[162:165], v[198:201], v[48:51]
	v_mfma_f32_16x16x32_bf16 v[36:39], v[154:157], v[206:209], v[36:39]
	v_mfma_f32_16x16x32_bf16 v[32:35], v[162:165], v[206:209], v[32:35]
	v_mfma_f32_16x16x32_bf16 v[20:23], v[154:157], v[214:217], v[20:23]
	v_mfma_f32_16x16x32_bf16 v[16:19], v[162:165], v[214:217], v[16:19]
	s_setprio 0
	s_setprio 1
	v_mfma_f32_16x16x32_bf16 v[44:47], v[166:169], v[182:185], v[44:47]
	v_mfma_f32_16x16x32_bf16 v[40:43], v[174:177], v[182:185], v[40:43]
	v_mfma_f32_16x16x32_bf16 v[28:31], v[166:169], v[194:197], v[28:31]
	v_mfma_f32_16x16x32_bf16 v[24:27], v[174:177], v[194:197], v[24:27]
	v_mfma_f32_16x16x32_bf16 v[12:15], v[166:169], v[202:205], v[12:15]
	v_mfma_f32_16x16x32_bf16 v[8:11], v[174:177], v[202:205], v[8:11]
	v_mfma_f32_16x16x32_bf16 v[4:7], v[166:169], v[210:213], v[4:7]
	v_mfma_f32_16x16x32_bf16 v[0:3], v[174:177], v[210:213], v[0:3]
	v_mfma_f32_16x16x32_bf16 v[44:47], v[170:173], v[186:189], v[44:47]
	v_mfma_f32_16x16x32_bf16 v[40:43], v[178:181], v[186:189], v[40:43]
	v_mfma_f32_16x16x32_bf16 v[28:31], v[170:173], v[198:201], v[28:31]
	v_mfma_f32_16x16x32_bf16 v[24:27], v[178:181], v[198:201], v[24:27]
	v_mfma_f32_16x16x32_bf16 v[12:15], v[170:173], v[206:209], v[12:15]
	v_mfma_f32_16x16x32_bf16 v[8:11], v[178:181], v[206:209], v[8:11]
	v_mfma_f32_16x16x32_bf16 v[4:7], v[170:173], v[214:217], v[4:7]
	v_mfma_f32_16x16x32_bf16 v[0:3], v[178:181], v[214:217], v[0:3]
	s_setprio 0
	s_barrier
	s_add_i32 s54, s54, 2
	s_add_u32 s28, s28, 0x100
	s_addc_u32 s29, s29, 0
	s_add_u32 s52, s52, 0x100
	s_addc_u32 s53, s53, 0
	s_cmp_gt_u32 s54, 29
	s_cbranch_scc0 .LBB0_1013
	s_and_b64 vcc, exec, s[10:11]
	s_cbranch_vccz .LBB0_1016
	s_barrier

; #define PG8_STAGE(bufoff, gbase, voff) do { _Pragma("unroll") for (int _i = 0; _i < 2; ++_i) \
;         __builtin_amdgcn_global_load_lds((const unsigned*)((const char*)(gbase) + (voff)[_i]), (PG8_LAS unsigned*)(lds + (bufoff) + ldsw + _i * 8192), 16, 0, 0); } while (0)
; #define PG8_LDA(dst, b, h) do { _Pragma("unroll") for (int m = 0; m < 4; ++m) _Pragma("unroll") for (int k = 0; k < 2; ++k) dst[m][k] = *(const PG8_LAS bf16x8*)(lds + PG8_SA(b, h) + aoff + m * 2048 + k * 1024); } while (0)
; #define PG8_LDB(dst, b, h) do { _Pragma("unroll") for (int n = 0; n < 2; ++n) _Pragma("unroll") for (int k = 0; k < 2; ++k) dst[n][k] = *(const PG8_LAS bf16x8*)(lds + PG8_SB(b, h) + boff + n * 2048 + k * 1024); } while (0)
; #define PG8_MMA(ai, bj, At, Bt) do { __builtin_amdgcn_s_setprio(1); _Pragma("unroll") for (int m = 0; m < 4; ++m) _Pragma("unroll") for (int n = 0; n < 2; ++n) _Pragma("unroll") for (int k = 0; k < 2; ++k) \
;         acc[ai][bj][m][n] = __builtin_amdgcn_mfma_f32_16x16x32_bf16(Bt[n][k], At[m][k], acc[ai][bj][m][n], 0, 0, 0); __builtin_amdgcn_s_setprio(0); } while (0)
; #define PG8_WAIT_V(n) asm volatile("s_waitcnt vmcnt(" #n ")" ::: "memory")
; #define PG8_BAR __builtin_amdgcn_s_barrier()
; template <class Epi, class Sched, bool ALIGN_EPI = false, bool SP2 = false>
; __device__ __forceinline__ void gemm_phase(PG8_LAS unsigned char* lds, const Gemm g, const Sched& S, const Epi& E) {
;     ...
;         for (int t = 0; t < nt; t += 2) {
;             const bool last = (t == nt - 2);
;             const char* a1 = cA + (size_t)(t + 1) * kstep;
;             const char* a2 = last ? nA : cA + (size_t)(t + 2) * kstep; const char* b2 = last ? nB : cB + (size_t)(t + 2) * kstep;
;             const char* a3 = a2 + kstep; const char* b3 = b2 + kstep;
;             if (last && has_next) S.a_ready(nxt);
;             if constexpr (SP2) {
;             PG8_LDB(B0, 0, 0); PG8_LDB(B1, 0, 1); PG8_SCHED; PG8_LDA(At, 0, 0); PG8_STAGE(PG8_SA(1, 1), a1 + hstep, voffA);
;             PG8_WAIT_V(8); PG8_WAIT_L(0); PG8_BAR; PG8_MMA(0, 0, At, B0); PG8_MMA(0, 1, At, B1); PG8_BAR; PG8_SCHED;
;             PG8_LDA(At, 0, 1); PG8_STAGE(PG8_SB(0, 0), b2, voffB); PG8_STAGE(PG8_SB(0, 1), b2 + hstep, voffB); PG8_STAGE(PG8_SA(0, 0), a2, voffA);
;             PG8_WAIT_V(8); PG8_WAIT_L(0); PG8_BAR; PG8_MMA(1, 0, At, B0); PG8_MMA(1, 1, At, B1); PG8_BAR; PG8_SCHED;
.LBB0_1138:
	ds_read_b128 v[150:153], v147
	ds_read_b128 v[154:157], v147 offset:1024
	ds_read_b128 v[158:161], v147 offset:2048
	ds_read_b128 v[162:165], v147 offset:3072
	ds_read_b128 v[166:169], v148
	ds_read_b128 v[170:173], v148 offset:1024
	ds_read_b128 v[174:177], v148 offset:2048
	ds_read_b128 v[178:181], v148 offset:3072
	s_add_u32 s22, s20, 0xfff80080
	s_addc_u32 s23, s21, -1
	s_cmp_eq_u32 s46, 28
	s_cselect_b32 s25, s13, s23
	s_cselect_b32 s24, s42, s22
	s_cselect_b32 s23, s11, s45
	s_cselect_b32 s22, s43, s44
	v_lshl_add_u64 v[190:191], s[20:21], 0, v[136:137]
	s_add_i32 m0, s19, 0xc000
	ds_read_b128 v[182:185], v149
	ds_read_b128 v[186:189], v149 offset:1024
	ds_read_b128 v[194:197], v149 offset:2048
	ds_read_b128 v[198:201], v149 offset:3072
	ds_read_b128 v[202:205], v149 offset:4096
	ds_read_b128 v[206:209], v149 offset:5120
	ds_read_b128 v[210:213], v149 offset:6144
	ds_read_b128 v[214:217], v149 offset:7168
	global_load_lds_dwordx4 v[190:191], off
	v_lshl_add_u64 v[190:191], s[20:21], 0, v[138:139]
	s_add_i32 m0, s19, 0xe000
	s_nop 0
	global_load_lds_dwordx4 v[190:191], off
	s_waitcnt vmcnt(8)
	s_waitcnt lgkmcnt(0)
	s_barrier
	s_setprio 1
	s_waitcnt lgkmcnt(0)
	v_mfma_f32_16x16x32_bf16 v[124:127], v[150:153], v[182:185], v[124:127]
	v_mfma_f32_16x16x32_bf16 v[120:123], v[158:161], v[182:185], v[120:123]
	v_mfma_f32_16x16x32_bf16 v[108:111], v[150:153], v[194:197], v[108:111]
	v_mfma_f32_16x16x32_bf16 v[104:107], v[158:161], v[194:197], v[104:107]
	v_mfma_f32_16x16x32_bf16 v[92:95], v[150:153], v[202:205], v[92:95]
	v_mfma_f32_16x16x32_bf16 v[88:91], v[158:161], v[202:205], v[88:91]
	v_mfma_f32_16x16x32_bf16 v[76:79], v[150:153], v[210:213], v[76:79]
	v_mfma_f32_16x16x32_bf16 v[72:75], v[158:161], v[210:213], v[72:75]
	v_mfma_f32_16x16x32_bf16 v[124:127], v[154:157], v[186:189], v[124:127]
	v_mfma_f32_16x16x32_bf16 v[120:123], v[162:165], v[186:189], v[120:123]
	v_mfma_f32_16x16x32_bf16 v[108:111], v[154:157], v[198:201], v[108:111]
	v_mfma_f32_16x16x32_bf16 v[104:107], v[162:165], v[198:201], v[104:107]
	v_mfma_f32_16x16x32_bf16 v[92:95], v[154:157], v[206:209], v[92:95]
	v_mfma_f32_16x16x32_bf16 v[88:91], v[162:165], v[206:209], v[88:91]
	v_mfma_f32_16x16x32_bf16 v[76:79], v[154:157], v[214:217], v[76:79]
	v_mfma_f32_16x16x32_bf16 v[72:75], v[162:165], v[214:217], v[72:75]
	s_setprio 0
	s_setprio 1
	v_mfma_f32_16x16x32_bf16 v[116:119], v[166:169], v[182:185], v[116:119]
	v_mfma_f32_16x16x32_bf16 v[112:115], v[174:177], v[182:185], v[112:115]
	v_mfma_f32_16x16x32_bf16 v[100:103], v[166:169], v[194:197], v[100:103]
	v_mfma_f32_16x16x32_bf16 v[96:99], v[174:177], v[194:197], v[96:99]
	v_mfma_f32_16x16x32_bf16 v[84:87], v[166:169], v[202:205], v[84:87]
	v_mfma_f32_16x16x32_bf16 v[80:83], v[174:177], v[202:205], v[80:83]
	v_mfma_f32_16x16x32_bf16 v[68:71], v[166:169], v[210:213], v[68:71]
	v_mfma_f32_16x16x32_bf16 v[64:67], v[174:177], v[210:213], v[64:67]
	v_mfma_f32_16x16x32_bf16 v[116:119], v[170:173], v[186:189], v[116:119]
	v_mfma_f32_16x16x32_bf16 v[112:115], v[178:181], v[186:189], v[112:115]
	v_mfma_f32_16x16x32_bf16 v[100:103], v[170:173], v[198:201], v[100:103]
	v_mfma_f32_16x16x32_bf16 v[96:99], v[178:181], v[198:201], v[96:99]
	v_mfma_f32_16x16x32_bf16 v[84:87], v[170:173], v[206:209], v[84:87]
	v_mfma_f32_16x16x32_bf16 v[80:83], v[178:181], v[206:209], v[80:83]
	v_mfma_f32_16x16x32_bf16 v[68:71], v[170:173], v[214:217], v[68:71]
	v_mfma_f32_16x16x32_bf16 v[64:67], v[178:181], v[214:217], v[64:67]
	s_setprio 0
	s_barrier
	s_add_i32 s47, s38, s3
	v_lshl_add_u64 v[190:191], s[22:23], 0, v[132:133]
	s_mov_b32 m0, s47
	ds_read_b128 v[182:185], v149 offset:16384
	ds_read_b128 v[186:189], v149 offset:17408
	ds_read_b128 v[194:197], v149 offset:18432
	ds_read_b128 v[198:201], v149 offset:19456
	ds_read_b128 v[202:205], v149 offset:20480
	ds_read_b128 v[206:209], v149 offset:21504
	ds_read_b128 v[210:213], v149 offset:22528
	ds_read_b128 v[214:217], v149 offset:23552
	global_load_lds_dwordx4 v[190:191], off
	s_add_i32 m0, s47, 0x2000
	s_add_u32 s48, s22, 0x80000
	v_lshl_add_u64 v[218:219], s[22:23], 0, v[128:129]
	s_addc_u32 s49, s23, 0
	s_add_i32 s47, s39, s3
	global_load_lds_dwordx4 v[218:219], off
	v_lshl_add_u64 v[220:221], s[48:49], 0, v[132:133]
	s_mov_b32 m0, s47
	v_lshl_add_u64 v[222:223], s[24:25], 0, v[130:131]
	global_load_lds_dwordx4 v[220:221], off
	v_lshl_add_u64 v[220:221], s[48:49], 0, v[128:129]
	s_add_i32 m0, s47, 0x2000
	s_nop 0
	global_load_lds_dwordx4 v[220:221], off
	v_lshl_add_u64 v[220:221], s[24:25], 0, v[134:135]
	s_mov_b32 m0, s19
	s_nop 0
	global_load_lds_dwordx4 v[220:221], off
	s_mov_b32 m0, s29
	s_nop 0
	global_load_lds_dwordx4 v[222:223], off
	s_waitcnt vmcnt(8)
	s_waitcnt lgkmcnt(0)
	s_barrier
; #define PG8_STAGE(bufoff, gbase, voff) do { _Pragma("unroll") for (int _i = 0; _i < 2; ++_i) \
;         __builtin_amdgcn_global_load_lds((const unsigned*)((const char*)(gbase) + (voff)[_i]), (PG8_LAS unsigned*)(lds + (bufoff) + ldsw + _i * 8192), 16, 0, 0); } while (0)
; #define PG8_LDA(dst, b, h) do { _Pragma("unroll") for (int m = 0; m < 4; ++m) _Pragma("unroll") for (int k = 0; k < 2; ++k) dst[m][k] = *(const PG8_LAS bf16x8*)(lds + PG8_SA(b, h) + aoff + m * 2048 + k * 1024); } while (0)
; #define PG8_LDB(dst, b, h) do { _Pragma("unroll") for (int n = 0; n < 2; ++n) _Pragma("unroll") for (int k = 0; k < 2; ++k) dst[n][k] = *(const PG8_LAS bf16x8*)(lds + PG8_SB(b, h) + boff + n * 2048 + k * 1024); } while (0)
; #define PG8_MMA(ai, bj, At, Bt) do { __builtin_amdgcn_s_setprio(1); _Pragma("unroll") for (int m = 0; m < 4; ++m) _Pragma("unroll") for (int n = 0; n < 2; ++n) _Pragma("unroll") for (int k = 0; k < 2; ++k) \
;         acc[ai][bj][m][n] = __builtin_amdgcn_mfma_f32_16x16x32_bf16(Bt[n][k], At[m][k], acc[ai][bj][m][n], 0, 0, 0); __builtin_amdgcn_s_setprio(0); } while (0)
; #define PG8_WAIT_V(n) asm volatile("s_waitcnt vmcnt(" #n ")" ::: "memory")
; #define PG8_WAIT_L(n) asm volatile("s_waitcnt lgkmcnt(" #n ")" ::: "memory")
; #define PG8_BAR __builtin_amdgcn_s_barrier()
; #define PG8_SCHED __builtin_amdgcn_sched_barrier(0)
; template <class Epi, class Sched, bool ALIGN_EPI = false, bool SP2 = false>
; __device__ __forceinline__ void gemm_phase(PG8_LAS unsigned char* lds, const Gemm g, const Sched& S, const Epi& E) {
;     ...
;             PG8_WAIT_V(8); PG8_WAIT_L(0); PG8_BAR; PG8_MMA(1, 0, At, B0); PG8_MMA(1, 1, At, B1); PG8_BAR; PG8_SCHED;
;             PG8_LDB(B0, 1, 0); PG8_LDB(B1, 1, 1); PG8_SCHED; PG8_LDA(At, 1, 0); PG8_STAGE(PG8_SA(0, 1), a2 + hstep, voffA);
;             PG8_WAIT_V(8); PG8_WAIT_L(0); PG8_BAR; PG8_MMA(0, 0, At, B0); PG8_MMA(0, 1, At, B1); PG8_BAR; PG8_SCHED;
	s_setprio 1
	s_waitcnt lgkmcnt(0)
	v_mfma_f32_16x16x32_bf16 v[60:63], v[150:153], v[182:185], v[60:63]
	v_mfma_f32_16x16x32_bf16 v[56:59], v[158:161], v[182:185], v[56:59]
	v_mfma_f32_16x16x32_bf16 v[44:47], v[150:153], v[194:197], v[44:47]
	v_mfma_f32_16x16x32_bf16 v[40:43], v[158:161], v[194:197], v[40:43]
	v_mfma_f32_16x16x32_bf16 v[28:31], v[150:153], v[202:205], v[28:31]
	v_mfma_f32_16x16x32_bf16 v[24:27], v[158:161], v[202:205], v[24:27]
	v_mfma_f32_16x16x32_bf16 v[12:15], v[150:153], v[210:213], v[12:15]
	v_mfma_f32_16x16x32_bf16 v[8:11], v[158:161], v[210:213], v[8:11]
	v_mfma_f32_16x16x32_bf16 v[60:63], v[154:157], v[186:189], v[60:63]
	v_mfma_f32_16x16x32_bf16 v[56:59], v[162:165], v[186:189], v[56:59]
	v_mfma_f32_16x16x32_bf16 v[44:47], v[154:157], v[198:201], v[44:47]
	v_mfma_f32_16x16x32_bf16 v[40:43], v[162:165], v[198:201], v[40:43]
	v_mfma_f32_16x16x32_bf16 v[28:31], v[154:157], v[206:209], v[28:31]
	v_mfma_f32_16x16x32_bf16 v[24:27], v[162:165], v[206:209], v[24:27]
	v_mfma_f32_16x16x32_bf16 v[12:15], v[154:157], v[214:217], v[12:15]
	v_mfma_f32_16x16x32_bf16 v[8:11], v[162:165], v[214:217], v[8:11]
	s_setprio 0
	s_setprio 1
	v_mfma_f32_16x16x32_bf16 v[52:55], v[166:169], v[182:185], v[52:55]
	v_mfma_f32_16x16x32_bf16 v[48:51], v[174:177], v[182:185], v[48:51]
	v_mfma_f32_16x16x32_bf16 v[36:39], v[166:169], v[194:197], v[36:39]
	v_mfma_f32_16x16x32_bf16 v[32:35], v[174:177], v[194:197], v[32:35]
	v_mfma_f32_16x16x32_bf16 v[20:23], v[166:169], v[202:205], v[20:23]
	v_mfma_f32_16x16x32_bf16 v[16:19], v[174:177], v[202:205], v[16:19]
	v_mfma_f32_16x16x32_bf16 v[4:7], v[166:169], v[210:213], v[4:7]
	v_mfma_f32_16x16x32_bf16 v[0:3], v[174:177], v[210:213], v[0:3]
	v_mfma_f32_16x16x32_bf16 v[52:55], v[170:173], v[186:189], v[52:55]
	v_mfma_f32_16x16x32_bf16 v[48:51], v[178:181], v[186:189], v[48:51]
	v_mfma_f32_16x16x32_bf16 v[36:39], v[170:173], v[198:201], v[36:39]
	v_mfma_f32_16x16x32_bf16 v[32:35], v[178:181], v[198:201], v[32:35]
	v_mfma_f32_16x16x32_bf16 v[20:23], v[170:173], v[206:209], v[20:23]
	v_mfma_f32_16x16x32_bf16 v[16:19], v[178:181], v[206:209], v[16:19]
	v_mfma_f32_16x16x32_bf16 v[4:7], v[170:173], v[214:217], v[4:7]
	v_mfma_f32_16x16x32_bf16 v[0:3], v[178:181], v[214:217], v[0:3]
	s_setprio 0
	s_barrier
	s_add_i32 s47, 0, 0x18000
	s_add_i32 s48, 0, 0x1c000
	v_add_u32_e32 v162, s47, v145
	v_add_u32_e32 v178, s48, v145
	ds_read_b128 v[150:153], v162
	ds_read_b128 v[154:157], v162 offset:1024
	ds_read_b128 v[158:161], v162 offset:2048
	ds_read_b128 v[162:165], v162 offset:3072
	ds_read_b128 v[166:169], v178
	ds_read_b128 v[170:173], v178 offset:1024
	ds_read_b128 v[174:177], v178 offset:2048
	ds_read_b128 v[178:181], v178 offset:3072
	s_add_u32 s24, s24, 0x80000
	s_addc_u32 s25, s25, 0
	s_mov_b32 m0, s30
	v_lshl_add_u64 v[224:225], s[24:25], 0, v[134:135]
	ds_read_b128 v[182:185], v149 offset:32768
	ds_read_b128 v[186:189], v149 offset:33792
	ds_read_b128 v[194:197], v149 offset:34816
	ds_read_b128 v[198:201], v149 offset:35840
	ds_read_b128 v[202:205], v149 offset:36864
	ds_read_b128 v[206:209], v149 offset:37888
	ds_read_b128 v[210:213], v149 offset:38912
	ds_read_b128 v[214:217], v149 offset:39936
	global_load_lds_dwordx4 v[224:225], off
	v_lshl_add_u64 v[224:225], s[24:25], 0, v[130:131]
	s_mov_b32 m0, s31
	s_nop 0
	global_load_lds_dwordx4 v[224:225], off
	s_waitcnt vmcnt(8)
	s_waitcnt lgkmcnt(0)
	s_barrier
	s_setprio 1
	s_waitcnt lgkmcnt(0)
	v_mfma_f32_16x16x32_bf16 v[124:127], v[150:153], v[182:185], v[124:127]
	v_mfma_f32_16x16x32_bf16 v[120:123], v[158:161], v[182:185], v[120:123]
	v_mfma_f32_16x16x32_bf16 v[108:111], v[150:153], v[194:197], v[108:111]
	v_mfma_f32_16x16x32_bf16 v[104:107], v[158:161], v[194:197], v[104:107]
	v_mfma_f32_16x16x32_bf16 v[92:95], v[150:153], v[202:205], v[92:95]
	v_mfma_f32_16x16x32_bf16 v[88:91], v[158:161], v[202:205], v[88:91]
	v_mfma_f32_16x16x32_bf16 v[76:79], v[150:153], v[210:213], v[76:79]
	v_mfma_f32_16x16x32_bf16 v[72:75], v[158:161], v[210:213], v[72:75]
	v_mfma_f32_16x16x32_bf16 v[124:127], v[154:157], v[186:189], v[124:127]
	v_mfma_f32_16x16x32_bf16 v[120:123], v[162:165], v[186:189], v[120:123]
	v_mfma_f32_16x16x32_bf16 v[108:111], v[154:157], v[198:201], v[108:111]
	v_mfma_f32_16x16x32_bf16 v[104:107], v[162:165], v[198:201], v[104:107]
	v_mfma_f32_16x16x32_bf16 v[92:95], v[154:157], v[206:209], v[92:95]
	v_mfma_f32_16x16x32_bf16 v[88:91], v[162:165], v[206:209], v[88:91]
	v_mfma_f32_16x16x32_bf16 v[76:79], v[154:157], v[214:217], v[76:79]
	v_mfma_f32_16x16x32_bf16 v[72:75], v[162:165], v[214:217], v[72:75]
	s_setprio 0
	s_setprio 1
	v_mfma_f32_16x16x32_bf16 v[116:119], v[166:169], v[182:185], v[116:119]
	v_mfma_f32_16x16x32_bf16 v[112:115], v[174:177], v[182:185], v[112:115]
	v_mfma_f32_16x16x32_bf16 v[100:103], v[166:169], v[194:197], v[100:103]
	v_mfma_f32_16x16x32_bf16 v[96:99], v[174:177], v[194:197], v[96:99]
	v_mfma_f32_16x16x32_bf16 v[84:87], v[166:169], v[202:205], v[84:87]
	v_mfma_f32_16x16x32_bf16 v[80:83], v[174:177], v[202:205], v[80:83]
	v_mfma_f32_16x16x32_bf16 v[68:71], v[166:169], v[210:213], v[68:71]
	v_mfma_f32_16x16x32_bf16 v[64:67], v[174:177], v[210:213], v[64:67]
	v_mfma_f32_16x16x32_bf16 v[116:119], v[170:173], v[186:189], v[116:119]
	v_mfma_f32_16x16x32_bf16 v[112:115], v[178:181], v[186:189], v[112:115]
	v_mfma_f32_16x16x32_bf16 v[100:103], v[170:173], v[198:201], v[100:103]
	v_mfma_f32_16x16x32_bf16 v[96:99], v[178:181], v[198:201], v[96:99]
	v_mfma_f32_16x16x32_bf16 v[84:87], v[170:173], v[206:209], v[84:87]
	v_mfma_f32_16x16x32_bf16 v[80:83], v[178:181], v[206:209], v[80:83]
	v_mfma_f32_16x16x32_bf16 v[68:71], v[170:173], v[214:217], v[68:71]
	v_mfma_f32_16x16x32_bf16 v[64:67], v[178:181], v[214:217], v[64:67]
	s_setprio 0
	s_barrier
; #define PG8_STAGE(bufoff, gbase, voff) do { _Pragma("unroll") for (int _i = 0; _i < 2; ++_i) \
;         __builtin_amdgcn_global_load_lds((const unsigned*)((const char*)(gbase) + (voff)[_i]), (PG8_LAS unsigned*)(lds + (bufoff) + ldsw + _i * 8192), 16, 0, 0); } while (0)
; #define PG8_LDA(dst, b, h) do { _Pragma("unroll") for (int m = 0; m < 4; ++m) _Pragma("unroll") for (int k = 0; k < 2; ++k) dst[m][k] = *(const PG8_LAS bf16x8*)(lds + PG8_SA(b, h) + aoff + m * 2048 + k * 1024); } while (0)
; #define PG8_MMA(ai, bj, At, Bt) do { __builtin_amdgcn_s_setprio(1); _Pragma("unroll") for (int m = 0; m < 4; ++m) _Pragma("unroll") for (int n = 0; n < 2; ++n) _Pragma("unroll") for (int k = 0; k < 2; ++k) \
;         acc[ai][bj][m][n] = __builtin_amdgcn_mfma_f32_16x16x32_bf16(Bt[n][k], At[m][k], acc[ai][bj][m][n], 0, 0, 0); __builtin_amdgcn_s_setprio(0); } while (0)
; #define PG8_WAIT_V(n) asm volatile("s_waitcnt vmcnt(" #n ")" ::: "memory")
; #define PG8_WAIT_L(n) asm volatile("s_waitcnt lgkmcnt(" #n ")" ::: "memory")
; #define PG8_BAR __builtin_amdgcn_s_barrier()
; #define PG8_SCHED __builtin_amdgcn_sched_barrier(0)
; template <class Epi, class Sched, bool ALIGN_EPI = false, bool SP2 = false>
; __device__ __forceinline__ void gemm_phase(PG8_LAS unsigned char* lds, const Gemm g, const Sched& S, const Epi& E) {
;     ...
;             PG8_LDA(At, 1, 1); PG8_STAGE(PG8_SB(1, 0), b3, voffB); PG8_STAGE(PG8_SB(1, 1), b3 + hstep, voffB); PG8_STAGE(PG8_SA(1, 0), a3, voffA);
;             PG8_WAIT_V(8); PG8_WAIT_L(0); PG8_BAR; PG8_MMA(1, 0, At, B0); PG8_MMA(1, 1, At, B1); PG8_BAR; PG8_SCHED;
	s_add_i32 s24, s47, s3
	v_lshl_add_u64 v[190:191], v[190:191], 0, s[6:7]
	s_mov_b32 m0, s24
	ds_read_b128 v[182:185], v149 offset:49152
	ds_read_b128 v[186:189], v149 offset:50176
	ds_read_b128 v[194:197], v149 offset:51200
	ds_read_b128 v[198:201], v149 offset:52224
	ds_read_b128 v[202:205], v149 offset:53248
	ds_read_b128 v[206:209], v149 offset:54272
	ds_read_b128 v[210:213], v149 offset:55296
	ds_read_b128 v[214:217], v149 offset:56320
	global_load_lds_dwordx4 v[190:191], off
	s_add_i32 m0, s24, 0x2000
	s_add_u32 s22, s22, 0x80080
	v_lshl_add_u64 v[190:191], v[218:219], 0, s[6:7]
	s_addc_u32 s23, s23, 0
	s_add_i32 s24, s48, s3
	global_load_lds_dwordx4 v[190:191], off
	v_lshl_add_u64 v[190:191], s[22:23], 0, v[132:133]
	s_mov_b32 m0, s24
	s_nop 0
	global_load_lds_dwordx4 v[190:191], off
	v_lshl_add_u64 v[190:191], s[22:23], 0, v[128:129]
	s_add_i32 m0, s24, 0x2000
	s_nop 0
	global_load_lds_dwordx4 v[190:191], off
	v_lshl_add_u64 v[190:191], v[220:221], 0, s[6:7]
	s_mov_b32 m0, s34
	s_nop 0
	global_load_lds_dwordx4 v[190:191], off
	v_lshl_add_u64 v[190:191], v[222:223], 0, s[6:7]
	s_mov_b32 m0, s35
	s_nop 0
	global_load_lds_dwordx4 v[190:191], off
	s_waitcnt vmcnt(8)
	s_waitcnt lgkmcnt(0)
	s_barrier
	s_setprio 1
	s_waitcnt lgkmcnt(0)
	v_mfma_f32_16x16x32_bf16 v[60:63], v[150:153], v[182:185], v[60:63]
	v_mfma_f32_16x16x32_bf16 v[56:59], v[158:161], v[182:185], v[56:59]
	v_mfma_f32_16x16x32_bf16 v[44:47], v[150:153], v[194:197], v[44:47]
	v_mfma_f32_16x16x32_bf16 v[40:43], v[158:161], v[194:197], v[40:43]
	v_mfma_f32_16x16x32_bf16 v[28:31], v[150:153], v[202:205], v[28:31]
	v_mfma_f32_16x16x32_bf16 v[24:27], v[158:161], v[202:205], v[24:27]
	v_mfma_f32_16x16x32_bf16 v[12:15], v[150:153], v[210:213], v[12:15]
	v_mfma_f32_16x16x32_bf16 v[8:11], v[158:161], v[210:213], v[8:11]
	v_mfma_f32_16x16x32_bf16 v[60:63], v[154:157], v[186:189], v[60:63]
	v_mfma_f32_16x16x32_bf16 v[56:59], v[162:165], v[186:189], v[56:59]
	v_mfma_f32_16x16x32_bf16 v[44:47], v[154:157], v[198:201], v[44:47]
	v_mfma_f32_16x16x32_bf16 v[40:43], v[162:165], v[198:201], v[40:43]
	v_mfma_f32_16x16x32_bf16 v[28:31], v[154:157], v[206:209], v[28:31]
	v_mfma_f32_16x16x32_bf16 v[24:27], v[162:165], v[206:209], v[24:27]
	v_mfma_f32_16x16x32_bf16 v[12:15], v[154:157], v[214:217], v[12:15]
	v_mfma_f32_16x16x32_bf16 v[8:11], v[162:165], v[214:217], v[8:11]
	s_setprio 0
	s_setprio 1
	v_mfma_f32_16x16x32_bf16 v[52:55], v[166:169], v[182:185], v[52:55]
	v_mfma_f32_16x16x32_bf16 v[48:51], v[174:177], v[182:185], v[48:51]
	v_mfma_f32_16x16x32_bf16 v[36:39], v[166:169], v[194:197], v[36:39]
	v_mfma_f32_16x16x32_bf16 v[32:35], v[174:177], v[194:197], v[32:35]
	v_mfma_f32_16x16x32_bf16 v[20:23], v[166:169], v[202:205], v[20:23]
	v_mfma_f32_16x16x32_bf16 v[16:19], v[174:177], v[202:205], v[16:19]
	v_mfma_f32_16x16x32_bf16 v[4:7], v[166:169], v[210:213], v[4:7]
	v_mfma_f32_16x16x32_bf16 v[0:3], v[174:177], v[210:213], v[0:3]
	v_mfma_f32_16x16x32_bf16 v[52:55], v[170:173], v[186:189], v[52:55]
	v_mfma_f32_16x16x32_bf16 v[48:51], v[178:181], v[186:189], v[48:51]
	v_mfma_f32_16x16x32_bf16 v[36:39], v[170:173], v[198:201], v[36:39]
	v_mfma_f32_16x16x32_bf16 v[32:35], v[178:181], v[198:201], v[32:35]
	v_mfma_f32_16x16x32_bf16 v[20:23], v[170:173], v[206:209], v[20:23]
	v_mfma_f32_16x16x32_bf16 v[16:19], v[178:181], v[206:209], v[16:19]
	v_mfma_f32_16x16x32_bf16 v[4:7], v[170:173], v[214:217], v[4:7]
	v_mfma_f32_16x16x32_bf16 v[0:3], v[178:181], v[214:217], v[0:3]
	s_setprio 0
	s_barrier
	s_add_i32 s46, s46, 2
	s_add_u32 s20, s20, 0x100
	s_addc_u32 s21, s21, 0
	s_add_u32 s44, s44, 0x100
	s_addc_u32 s45, s45, 0
	s_cmp_gt_u32 s46, 29
	s_cbranch_scc0 .LBB0_1138
	s_and_b64 vcc, exec, s[8:9]
	s_cbranch_vccz .LBB0_1141
	s_barrier

; #define PG8_STAGE(bufoff, gbase, voff) do { _Pragma("unroll") for (int _i = 0; _i < 2; ++_i) \
;         __builtin_amdgcn_global_load_lds((const unsigned*)((const char*)(gbase) + (voff)[_i]), (PG8_LAS unsigned*)(lds + (bufoff) + ldsw + _i * 8192), 16, 0, 0); } while (0)
; #define PG8_LDA(dst, b, h) do { _Pragma("unroll") for (int m = 0; m < 4; ++m) _Pragma("unroll") for (int k = 0; k < 2; ++k) dst[m][k] = *(const PG8_LAS bf16x8*)(lds + PG8_SA(b, h) + aoff + m * 2048 + k * 1024); } while (0)
; #define PG8_LDB(dst, b, h) do { _Pragma("unroll") for (int n = 0; n < 2; ++n) _Pragma("unroll") for (int k = 0; k < 2; ++k) dst[n][k] = *(const PG8_LAS bf16x8*)(lds + PG8_SB(b, h) + boff + n * 2048 + k * 1024); } while (0)
; #define PG8_MMA(ai, bj, At, Bt) do { __builtin_amdgcn_s_setprio(1); _Pragma("unroll") for (int m = 0; m < 4; ++m) _Pragma("unroll") for (int n = 0; n < 2; ++n) _Pragma("unroll") for (int k = 0; k < 2; ++k) \
;         acc[ai][bj][m][n] = __builtin_amdgcn_mfma_f32_16x16x32_bf16(Bt[n][k], At[m][k], acc[ai][bj][m][n], 0, 0, 0); __builtin_amdgcn_s_setprio(0); } while (0)
; #define PG8_WAIT_V(n) asm volatile("s_waitcnt vmcnt(" #n ")" ::: "memory")
; #define PG8_BAR __builtin_amdgcn_s_barrier()
; template <class Epi, class Sched, bool ALIGN_EPI = false, bool SP2 = false>
; __device__ __forceinline__ void gemm_phase(PG8_LAS unsigned char* lds, const Gemm g, const Sched& S, const Epi& E) {
;     ...
;         for (int t = 0; t < nt; t += 2) {
;             const bool last = (t == nt - 2);
;             const char* a1 = cA + (size_t)(t + 1) * kstep;
;             const char* a2 = last ? nA : cA + (size_t)(t + 2) * kstep; const char* b2 = last ? nB : cB + (size_t)(t + 2) * kstep;
;             const char* a3 = a2 + kstep; const char* b3 = b2 + kstep;
;             if (last && has_next) S.a_ready(nxt);
;             if constexpr (SP2) {
;             PG8_LDB(B0, 0, 0); PG8_LDB(B1, 0, 1); PG8_SCHED; PG8_LDA(At, 0, 0); PG8_STAGE(PG8_SA(1, 1), a1 + hstep, voffA);
;             PG8_WAIT_V(8); PG8_WAIT_L(0); PG8_BAR; PG8_MMA(0, 0, At, B0); PG8_MMA(0, 1, At, B1); PG8_BAR; PG8_SCHED;
;             PG8_LDA(At, 0, 1); PG8_STAGE(PG8_SB(0, 0), b2, voffB); PG8_STAGE(PG8_SB(0, 1), b2 + hstep, voffB); PG8_STAGE(PG8_SA(0, 0), a2, voffA);
;             PG8_WAIT_V(8); PG8_WAIT_L(0); PG8_BAR; PG8_MMA(1, 0, At, B0); PG8_MMA(1, 1, At, B1); PG8_BAR; PG8_SCHED;
.LBB0_1210:
	ds_read_b128 v[150:153], v147
	ds_read_b128 v[154:157], v147 offset:1024
	ds_read_b128 v[158:161], v147 offset:2048
	ds_read_b128 v[162:165], v147 offset:3072
	ds_read_b128 v[166:169], v148
	ds_read_b128 v[170:173], v148 offset:1024
	ds_read_b128 v[174:177], v148 offset:2048
	ds_read_b128 v[178:181], v148 offset:3072
	s_add_u32 s24, s22, 0x100
	s_addc_u32 s25, s23, 0
	s_cmpk_eq_i32 s52, 0x54
	s_cselect_b32 s29, s5, s25
	s_cselect_b32 s28, s4, s24
	s_cselect_b32 s27, s21, s51
	s_cselect_b32 s26, s20, s50
	v_lshl_add_u64 v[190:191], s[22:23], 0, v[136:137]
	s_add_i32 m0, s30, 0xc000
	ds_read_b128 v[182:185], v149
	ds_read_b128 v[186:189], v149 offset:1024
	ds_read_b128 v[194:197], v149 offset:2048
	ds_read_b128 v[198:201], v149 offset:3072
	ds_read_b128 v[202:205], v149 offset:4096
	ds_read_b128 v[206:209], v149 offset:5120
	ds_read_b128 v[210:213], v149 offset:6144
	ds_read_b128 v[214:217], v149 offset:7168
	global_load_lds_dwordx4 v[190:191], off
	v_lshl_add_u64 v[190:191], s[22:23], 0, v[138:139]
	s_add_i32 m0, s30, 0xe000
	s_nop 0
	global_load_lds_dwordx4 v[190:191], off
	s_waitcnt vmcnt(8)
	s_waitcnt lgkmcnt(0)
	s_barrier
	s_setprio 1
	s_waitcnt lgkmcnt(0)
	v_mfma_f32_16x16x32_bf16 v[124:127], v[150:153], v[182:185], v[124:127]
	v_mfma_f32_16x16x32_bf16 v[120:123], v[158:161], v[182:185], v[120:123]
	v_mfma_f32_16x16x32_bf16 v[116:119], v[150:153], v[194:197], v[116:119]
	v_mfma_f32_16x16x32_bf16 v[112:115], v[158:161], v[194:197], v[112:115]
	v_mfma_f32_16x16x32_bf16 v[100:103], v[150:153], v[202:205], v[100:103]
	v_mfma_f32_16x16x32_bf16 v[96:99], v[158:161], v[202:205], v[96:99]
	v_mfma_f32_16x16x32_bf16 v[84:87], v[150:153], v[210:213], v[84:87]
	v_mfma_f32_16x16x32_bf16 v[80:83], v[158:161], v[210:213], v[80:83]
	v_mfma_f32_16x16x32_bf16 v[124:127], v[154:157], v[186:189], v[124:127]
	v_mfma_f32_16x16x32_bf16 v[120:123], v[162:165], v[186:189], v[120:123]
	v_mfma_f32_16x16x32_bf16 v[116:119], v[154:157], v[198:201], v[116:119]
	v_mfma_f32_16x16x32_bf16 v[112:115], v[162:165], v[198:201], v[112:115]
	v_mfma_f32_16x16x32_bf16 v[100:103], v[154:157], v[206:209], v[100:103]
	v_mfma_f32_16x16x32_bf16 v[96:99], v[162:165], v[206:209], v[96:99]
	v_mfma_f32_16x16x32_bf16 v[84:87], v[154:157], v[214:217], v[84:87]
	v_mfma_f32_16x16x32_bf16 v[80:83], v[162:165], v[214:217], v[80:83]
	s_setprio 0
	s_setprio 1
	v_mfma_f32_16x16x32_bf16 v[108:111], v[166:169], v[182:185], v[108:111]
	v_mfma_f32_16x16x32_bf16 v[104:107], v[174:177], v[182:185], v[104:107]
	v_mfma_f32_16x16x32_bf16 v[92:95], v[166:169], v[194:197], v[92:95]
	v_mfma_f32_16x16x32_bf16 v[88:91], v[174:177], v[194:197], v[88:91]
	v_mfma_f32_16x16x32_bf16 v[76:79], v[166:169], v[202:205], v[76:79]
	v_mfma_f32_16x16x32_bf16 v[72:75], v[174:177], v[202:205], v[72:75]
	v_mfma_f32_16x16x32_bf16 v[68:71], v[166:169], v[210:213], v[68:71]
	v_mfma_f32_16x16x32_bf16 v[64:67], v[174:177], v[210:213], v[64:67]
	v_mfma_f32_16x16x32_bf16 v[108:111], v[170:173], v[186:189], v[108:111]
	v_mfma_f32_16x16x32_bf16 v[104:107], v[178:181], v[186:189], v[104:107]
	v_mfma_f32_16x16x32_bf16 v[92:95], v[170:173], v[198:201], v[92:95]
	v_mfma_f32_16x16x32_bf16 v[88:91], v[178:181], v[198:201], v[88:91]
	v_mfma_f32_16x16x32_bf16 v[76:79], v[170:173], v[206:209], v[76:79]
	v_mfma_f32_16x16x32_bf16 v[72:75], v[178:181], v[206:209], v[72:75]
	v_mfma_f32_16x16x32_bf16 v[68:71], v[170:173], v[214:217], v[68:71]
	v_mfma_f32_16x16x32_bf16 v[64:67], v[178:181], v[214:217], v[64:67]
	s_setprio 0
	s_barrier
	s_add_i32 s22, s40, s2
	v_lshl_add_u64 v[190:191], s[26:27], 0, v[132:133]
	s_mov_b32 m0, s22
	ds_read_b128 v[182:185], v149 offset:16384
	ds_read_b128 v[186:189], v149 offset:17408
	ds_read_b128 v[194:197], v149 offset:18432
	ds_read_b128 v[198:201], v149 offset:19456
	ds_read_b128 v[202:205], v149 offset:20480
	ds_read_b128 v[206:209], v149 offset:21504
	ds_read_b128 v[210:213], v149 offset:22528
	ds_read_b128 v[214:217], v149 offset:23552
	global_load_lds_dwordx4 v[190:191], off
	s_add_i32 m0, s22, 0x2000
	s_add_u32 s22, s26, 0x160000
	v_lshl_add_u64 v[218:219], s[26:27], 0, v[128:129]
	s_addc_u32 s23, s27, 0
	s_add_i32 s53, s41, s2
	global_load_lds_dwordx4 v[218:219], off
	v_lshl_add_u64 v[220:221], s[22:23], 0, v[132:133]
	s_mov_b32 m0, s53
	v_lshl_add_u64 v[222:223], s[28:29], 0, v[130:131]
	global_load_lds_dwordx4 v[220:221], off
	v_lshl_add_u64 v[220:221], s[22:23], 0, v[128:129]
	s_add_i32 m0, s53, 0x2000
	s_nop 0
	global_load_lds_dwordx4 v[220:221], off
	v_lshl_add_u64 v[220:221], s[28:29], 0, v[134:135]
	s_mov_b32 m0, s30
	s_nop 0
	global_load_lds_dwordx4 v[220:221], off
	s_mov_b32 m0, s31
	s_nop 0
	global_load_lds_dwordx4 v[222:223], off
	s_waitcnt vmcnt(8)
	s_waitcnt lgkmcnt(0)
	s_barrier
; #define PG8_STAGE(bufoff, gbase, voff) do { _Pragma("unroll") for (int _i = 0; _i < 2; ++_i) \
;         __builtin_amdgcn_global_load_lds((const unsigned*)((const char*)(gbase) + (voff)[_i]), (PG8_LAS unsigned*)(lds + (bufoff) + ldsw + _i * 8192), 16, 0, 0); } while (0)
; #define PG8_LDA(dst, b, h) do { _Pragma("unroll") for (int m = 0; m < 4; ++m) _Pragma("unroll") for (int k = 0; k < 2; ++k) dst[m][k] = *(const PG8_LAS bf16x8*)(lds + PG8_SA(b, h) + aoff + m * 2048 + k * 1024); } while (0)
; #define PG8_LDB(dst, b, h) do { _Pragma("unroll") for (int n = 0; n < 2; ++n) _Pragma("unroll") for (int k = 0; k < 2; ++k) dst[n][k] = *(const PG8_LAS bf16x8*)(lds + PG8_SB(b, h) + boff + n * 2048 + k * 1024); } while (0)
; #define PG8_MMA(ai, bj, At, Bt) do { __builtin_amdgcn_s_setprio(1); _Pragma("unroll") for (int m = 0; m < 4; ++m) _Pragma("unroll") for (int n = 0; n < 2; ++n) _Pragma("unroll") for (int k = 0; k < 2; ++k) \
;         acc[ai][bj][m][n] = __builtin_amdgcn_mfma_f32_16x16x32_bf16(Bt[n][k], At[m][k], acc[ai][bj][m][n], 0, 0, 0); __builtin_amdgcn_s_setprio(0); } while (0)
; #define PG8_WAIT_V(n) asm volatile("s_waitcnt vmcnt(" #n ")" ::: "memory")
; #define PG8_WAIT_L(n) asm volatile("s_waitcnt lgkmcnt(" #n ")" ::: "memory")
; #define PG8_BAR __builtin_amdgcn_s_barrier()
; #define PG8_SCHED __builtin_amdgcn_sched_barrier(0)
; template <class Epi, class Sched, bool ALIGN_EPI = false, bool SP2 = false>
; __device__ __forceinline__ void gemm_phase(PG8_LAS unsigned char* lds, const Gemm g, const Sched& S, const Epi& E) {
;     ...
;             PG8_WAIT_V(8); PG8_WAIT_L(0); PG8_BAR; PG8_MMA(1, 0, At, B0); PG8_MMA(1, 1, At, B1); PG8_BAR; PG8_SCHED;
;             PG8_LDB(B0, 1, 0); PG8_LDB(B1, 1, 1); PG8_SCHED; PG8_LDA(At, 1, 0); PG8_STAGE(PG8_SA(0, 1), a2 + hstep, voffA);
;             PG8_WAIT_V(8); PG8_WAIT_L(0); PG8_BAR; PG8_MMA(0, 0, At, B0); PG8_MMA(0, 1, At, B1); PG8_BAR; PG8_SCHED;
	s_setprio 1
	s_waitcnt lgkmcnt(0)
	v_mfma_f32_16x16x32_bf16 v[60:63], v[150:153], v[182:185], v[60:63]
	v_mfma_f32_16x16x32_bf16 v[56:59], v[158:161], v[182:185], v[56:59]
	v_mfma_f32_16x16x32_bf16 v[52:55], v[150:153], v[194:197], v[52:55]
	v_mfma_f32_16x16x32_bf16 v[48:51], v[158:161], v[194:197], v[48:51]
	v_mfma_f32_16x16x32_bf16 v[36:39], v[150:153], v[202:205], v[36:39]
	v_mfma_f32_16x16x32_bf16 v[32:35], v[158:161], v[202:205], v[32:35]
	v_mfma_f32_16x16x32_bf16 v[20:23], v[150:153], v[210:213], v[20:23]
	v_mfma_f32_16x16x32_bf16 v[16:19], v[158:161], v[210:213], v[16:19]
	v_mfma_f32_16x16x32_bf16 v[60:63], v[154:157], v[186:189], v[60:63]
	v_mfma_f32_16x16x32_bf16 v[56:59], v[162:165], v[186:189], v[56:59]
	v_mfma_f32_16x16x32_bf16 v[52:55], v[154:157], v[198:201], v[52:55]
	v_mfma_f32_16x16x32_bf16 v[48:51], v[162:165], v[198:201], v[48:51]
	v_mfma_f32_16x16x32_bf16 v[36:39], v[154:157], v[206:209], v[36:39]
	v_mfma_f32_16x16x32_bf16 v[32:35], v[162:165], v[206:209], v[32:35]
	v_mfma_f32_16x16x32_bf16 v[20:23], v[154:157], v[214:217], v[20:23]
	v_mfma_f32_16x16x32_bf16 v[16:19], v[162:165], v[214:217], v[16:19]
	s_setprio 0
	s_setprio 1
	v_mfma_f32_16x16x32_bf16 v[44:47], v[166:169], v[182:185], v[44:47]
	v_mfma_f32_16x16x32_bf16 v[40:43], v[174:177], v[182:185], v[40:43]
	v_mfma_f32_16x16x32_bf16 v[28:31], v[166:169], v[194:197], v[28:31]
	v_mfma_f32_16x16x32_bf16 v[24:27], v[174:177], v[194:197], v[24:27]
	v_mfma_f32_16x16x32_bf16 v[12:15], v[166:169], v[202:205], v[12:15]
	v_mfma_f32_16x16x32_bf16 v[8:11], v[174:177], v[202:205], v[8:11]
	v_mfma_f32_16x16x32_bf16 v[4:7], v[166:169], v[210:213], v[4:7]
	v_mfma_f32_16x16x32_bf16 v[0:3], v[174:177], v[210:213], v[0:3]
	v_mfma_f32_16x16x32_bf16 v[44:47], v[170:173], v[186:189], v[44:47]
	v_mfma_f32_16x16x32_bf16 v[40:43], v[178:181], v[186:189], v[40:43]
	v_mfma_f32_16x16x32_bf16 v[28:31], v[170:173], v[198:201], v[28:31]
	v_mfma_f32_16x16x32_bf16 v[24:27], v[178:181], v[198:201], v[24:27]
	v_mfma_f32_16x16x32_bf16 v[12:15], v[170:173], v[206:209], v[12:15]
	v_mfma_f32_16x16x32_bf16 v[8:11], v[178:181], v[206:209], v[8:11]
	v_mfma_f32_16x16x32_bf16 v[4:7], v[170:173], v[214:217], v[4:7]
	v_mfma_f32_16x16x32_bf16 v[0:3], v[178:181], v[214:217], v[0:3]
	s_setprio 0
	s_barrier
	s_add_i32 s53, 0, 0x18000
	s_add_i32 s54, 0, 0x1c000
	v_add_u32_e32 v162, s53, v145
	v_add_u32_e32 v178, s54, v145
	ds_read_b128 v[150:153], v162
	ds_read_b128 v[154:157], v162 offset:1024
	ds_read_b128 v[158:161], v162 offset:2048
	ds_read_b128 v[162:165], v162 offset:3072
	ds_read_b128 v[166:169], v178
	ds_read_b128 v[170:173], v178 offset:1024
	ds_read_b128 v[174:177], v178 offset:2048
	ds_read_b128 v[178:181], v178 offset:3072
	s_add_u32 s22, s28, 0x160000
	s_addc_u32 s23, s29, 0
	s_mov_b32 m0, s33
	v_lshl_add_u64 v[224:225], s[22:23], 0, v[134:135]
	ds_read_b128 v[182:185], v149 offset:32768
	ds_read_b128 v[186:189], v149 offset:33792
	ds_read_b128 v[194:197], v149 offset:34816
	ds_read_b128 v[198:201], v149 offset:35840
	ds_read_b128 v[202:205], v149 offset:36864
	ds_read_b128 v[206:209], v149 offset:37888
	ds_read_b128 v[210:213], v149 offset:38912
	ds_read_b128 v[214:217], v149 offset:39936
	global_load_lds_dwordx4 v[224:225], off
	v_lshl_add_u64 v[224:225], s[22:23], 0, v[130:131]
	s_mov_b32 m0, s34
	s_nop 0
	global_load_lds_dwordx4 v[224:225], off
	s_waitcnt vmcnt(8)
	s_waitcnt lgkmcnt(0)
	s_barrier
	s_setprio 1
	s_waitcnt lgkmcnt(0)
	v_mfma_f32_16x16x32_bf16 v[124:127], v[150:153], v[182:185], v[124:127]
	v_mfma_f32_16x16x32_bf16 v[120:123], v[158:161], v[182:185], v[120:123]
	v_mfma_f32_16x16x32_bf16 v[116:119], v[150:153], v[194:197], v[116:119]
	v_mfma_f32_16x16x32_bf16 v[112:115], v[158:161], v[194:197], v[112:115]
	v_mfma_f32_16x16x32_bf16 v[100:103], v[150:153], v[202:205], v[100:103]
	v_mfma_f32_16x16x32_bf16 v[96:99], v[158:161], v[202:205], v[96:99]
	v_mfma_f32_16x16x32_bf16 v[84:87], v[150:153], v[210:213], v[84:87]
	v_mfma_f32_16x16x32_bf16 v[80:83], v[158:161], v[210:213], v[80:83]
	v_mfma_f32_16x16x32_bf16 v[124:127], v[154:157], v[186:189], v[124:127]
	v_mfma_f32_16x16x32_bf16 v[120:123], v[162:165], v[186:189], v[120:123]
	v_mfma_f32_16x16x32_bf16 v[116:119], v[154:157], v[198:201], v[116:119]
	v_mfma_f32_16x16x32_bf16 v[112:115], v[162:165], v[198:201], v[112:115]
	v_mfma_f32_16x16x32_bf16 v[100:103], v[154:157], v[206:209], v[100:103]
	v_mfma_f32_16x16x32_bf16 v[96:99], v[162:165], v[206:209], v[96:99]
	v_mfma_f32_16x16x32_bf16 v[84:87], v[154:157], v[214:217], v[84:87]
	v_mfma_f32_16x16x32_bf16 v[80:83], v[162:165], v[214:217], v[80:83]
	s_setprio 0
	s_setprio 1
	v_mfma_f32_16x16x32_bf16 v[108:111], v[166:169], v[182:185], v[108:111]
	v_mfma_f32_16x16x32_bf16 v[104:107], v[174:177], v[182:185], v[104:107]
	v_mfma_f32_16x16x32_bf16 v[92:95], v[166:169], v[194:197], v[92:95]
	v_mfma_f32_16x16x32_bf16 v[88:91], v[174:177], v[194:197], v[88:91]
	v_mfma_f32_16x16x32_bf16 v[76:79], v[166:169], v[202:205], v[76:79]
	v_mfma_f32_16x16x32_bf16 v[72:75], v[174:177], v[202:205], v[72:75]
	v_mfma_f32_16x16x32_bf16 v[68:71], v[166:169], v[210:213], v[68:71]
	v_mfma_f32_16x16x32_bf16 v[64:67], v[174:177], v[210:213], v[64:67]
	v_mfma_f32_16x16x32_bf16 v[108:111], v[170:173], v[186:189], v[108:111]
	v_mfma_f32_16x16x32_bf16 v[104:107], v[178:181], v[186:189], v[104:107]
	v_mfma_f32_16x16x32_bf16 v[92:95], v[170:173], v[198:201], v[92:95]
	v_mfma_f32_16x16x32_bf16 v[88:91], v[178:181], v[198:201], v[88:91]
	v_mfma_f32_16x16x32_bf16 v[76:79], v[170:173], v[206:209], v[76:79]
	v_mfma_f32_16x16x32_bf16 v[72:75], v[178:181], v[206:209], v[72:75]
	v_mfma_f32_16x16x32_bf16 v[68:71], v[170:173], v[214:217], v[68:71]
	v_mfma_f32_16x16x32_bf16 v[64:67], v[178:181], v[214:217], v[64:67]
	s_setprio 0
	s_barrier
; #define PG8_STAGE(bufoff, gbase, voff) do { _Pragma("unroll") for (int _i = 0; _i < 2; ++_i) \
;         __builtin_amdgcn_global_load_lds((const unsigned*)((const char*)(gbase) + (voff)[_i]), (PG8_LAS unsigned*)(lds + (bufoff) + ldsw + _i * 8192), 16, 0, 0); } while (0)
; #define PG8_LDA(dst, b, h) do { _Pragma("unroll") for (int m = 0; m < 4; ++m) _Pragma("unroll") for (int k = 0; k < 2; ++k) dst[m][k] = *(const PG8_LAS bf16x8*)(lds + PG8_SA(b, h) + aoff + m * 2048 + k * 1024); } while (0)
; #define PG8_MMA(ai, bj, At, Bt) do { __builtin_amdgcn_s_setprio(1); _Pragma("unroll") for (int m = 0; m < 4; ++m) _Pragma("unroll") for (int n = 0; n < 2; ++n) _Pragma("unroll") for (int k = 0; k < 2; ++k) \
;         acc[ai][bj][m][n] = __builtin_amdgcn_mfma_f32_16x16x32_bf16(Bt[n][k], At[m][k], acc[ai][bj][m][n], 0, 0, 0); __builtin_amdgcn_s_setprio(0); } while (0)
; #define PG8_WAIT_V(n) asm volatile("s_waitcnt vmcnt(" #n ")" ::: "memory")
; #define PG8_WAIT_L(n) asm volatile("s_waitcnt lgkmcnt(" #n ")" ::: "memory")
; #define PG8_BAR __builtin_amdgcn_s_barrier()
; #define PG8_SCHED __builtin_amdgcn_sched_barrier(0)
; template <class Epi, class Sched, bool ALIGN_EPI = false, bool SP2 = false>
; __device__ __forceinline__ void gemm_phase(PG8_LAS unsigned char* lds, const Gemm g, const Sched& S, const Epi& E) {
;     ...
;             PG8_LDA(At, 1, 1); PG8_STAGE(PG8_SB(1, 0), b3, voffB); PG8_STAGE(PG8_SB(1, 1), b3 + hstep, voffB); PG8_STAGE(PG8_SA(1, 0), a3, voffA);
;             PG8_WAIT_V(8); PG8_WAIT_L(0); PG8_BAR; PG8_MMA(1, 0, At, B0); PG8_MMA(1, 1, At, B1); PG8_BAR; PG8_SCHED;
	s_add_i32 s22, s53, s2
	v_lshl_add_u64 v[190:191], v[190:191], 0, s[8:9]
	s_mov_b32 m0, s22
	ds_read_b128 v[182:185], v149 offset:49152
	ds_read_b128 v[186:189], v149 offset:50176
	ds_read_b128 v[194:197], v149 offset:51200
	ds_read_b128 v[198:201], v149 offset:52224
	ds_read_b128 v[202:205], v149 offset:53248
	ds_read_b128 v[206:209], v149 offset:54272
	ds_read_b128 v[210:213], v149 offset:55296
	ds_read_b128 v[214:217], v149 offset:56320
	global_load_lds_dwordx4 v[190:191], off
	s_add_i32 m0, s22, 0x2000
	s_add_u32 s22, s26, 0x160080
	v_lshl_add_u64 v[190:191], v[218:219], 0, s[8:9]
	s_addc_u32 s23, s27, 0
	s_add_i32 s26, s54, s2
	global_load_lds_dwordx4 v[190:191], off
	v_lshl_add_u64 v[190:191], s[22:23], 0, v[132:133]
	s_mov_b32 m0, s26
	s_nop 0
	global_load_lds_dwordx4 v[190:191], off
	v_lshl_add_u64 v[190:191], s[22:23], 0, v[128:129]
	s_add_i32 m0, s26, 0x2000
	s_nop 0
	global_load_lds_dwordx4 v[190:191], off
	v_lshl_add_u64 v[190:191], v[220:221], 0, s[8:9]
	s_mov_b32 m0, s36
	s_nop 0
	global_load_lds_dwordx4 v[190:191], off
	v_lshl_add_u64 v[190:191], v[222:223], 0, s[8:9]
	s_mov_b32 m0, s37
	s_nop 0
	global_load_lds_dwordx4 v[190:191], off
	s_waitcnt vmcnt(8)
	s_waitcnt lgkmcnt(0)
	s_barrier
	s_setprio 1
	s_waitcnt lgkmcnt(0)
	v_mfma_f32_16x16x32_bf16 v[60:63], v[150:153], v[182:185], v[60:63]
	v_mfma_f32_16x16x32_bf16 v[56:59], v[158:161], v[182:185], v[56:59]
	v_mfma_f32_16x16x32_bf16 v[52:55], v[150:153], v[194:197], v[52:55]
	v_mfma_f32_16x16x32_bf16 v[48:51], v[158:161], v[194:197], v[48:51]
	v_mfma_f32_16x16x32_bf16 v[36:39], v[150:153], v[202:205], v[36:39]
	v_mfma_f32_16x16x32_bf16 v[32:35], v[158:161], v[202:205], v[32:35]
	v_mfma_f32_16x16x32_bf16 v[20:23], v[150:153], v[210:213], v[20:23]
	v_mfma_f32_16x16x32_bf16 v[16:19], v[158:161], v[210:213], v[16:19]
	v_mfma_f32_16x16x32_bf16 v[60:63], v[154:157], v[186:189], v[60:63]
	v_mfma_f32_16x16x32_bf16 v[56:59], v[162:165], v[186:189], v[56:59]
	v_mfma_f32_16x16x32_bf16 v[52:55], v[154:157], v[198:201], v[52:55]
	v_mfma_f32_16x16x32_bf16 v[48:51], v[162:165], v[198:201], v[48:51]
	v_mfma_f32_16x16x32_bf16 v[36:39], v[154:157], v[206:209], v[36:39]
	v_mfma_f32_16x16x32_bf16 v[32:35], v[162:165], v[206:209], v[32:35]
	v_mfma_f32_16x16x32_bf16 v[20:23], v[154:157], v[214:217], v[20:23]
	v_mfma_f32_16x16x32_bf16 v[16:19], v[162:165], v[214:217], v[16:19]
	s_setprio 0
	s_setprio 1
	v_mfma_f32_16x16x32_bf16 v[44:47], v[166:169], v[182:185], v[44:47]
	v_mfma_f32_16x16x32_bf16 v[40:43], v[174:177], v[182:185], v[40:43]
	v_mfma_f32_16x16x32_bf16 v[28:31], v[166:169], v[194:197], v[28:31]
	v_mfma_f32_16x16x32_bf16 v[24:27], v[174:177], v[194:197], v[24:27]
	v_mfma_f32_16x16x32_bf16 v[12:15], v[166:169], v[202:205], v[12:15]
	v_mfma_f32_16x16x32_bf16 v[8:11], v[174:177], v[202:205], v[8:11]
	v_mfma_f32_16x16x32_bf16 v[4:7], v[166:169], v[210:213], v[4:7]
	v_mfma_f32_16x16x32_bf16 v[0:3], v[174:177], v[210:213], v[0:3]
	v_mfma_f32_16x16x32_bf16 v[44:47], v[170:173], v[186:189], v[44:47]
	v_mfma_f32_16x16x32_bf16 v[40:43], v[178:181], v[186:189], v[40:43]
	v_mfma_f32_16x16x32_bf16 v[28:31], v[170:173], v[198:201], v[28:31]
	v_mfma_f32_16x16x32_bf16 v[24:27], v[178:181], v[198:201], v[24:27]
	v_mfma_f32_16x16x32_bf16 v[12:15], v[170:173], v[206:209], v[12:15]
	v_mfma_f32_16x16x32_bf16 v[8:11], v[178:181], v[206:209], v[8:11]
	v_mfma_f32_16x16x32_bf16 v[4:7], v[170:173], v[214:217], v[4:7]
	v_mfma_f32_16x16x32_bf16 v[0:3], v[178:181], v[214:217], v[0:3]
	s_setprio 0
	s_barrier
	s_add_i32 s52, s52, 2
	s_add_u32 s50, s50, 0x100
	s_addc_u32 s51, s51, 0
	s_cmpk_gt_u32 s52, 0x55
	s_mov_b64 s[22:23], s[24:25]
	s_cbranch_scc0 .LBB0_1210
	s_and_b64 vcc, exec, s[10:11]
	s_cbranch_vccz .LBB0_1213
	s_barrier

; #define LAS __attribute__((address_space(3)))
; #define FRESH() do { int t_ = threadIdx.x; asm volatile("" : "+v"(t_)); C.tid = t_; C.lane = t_ & 63; C.wave = __builtin_amdgcn_readfirstlane(t_ >> 6); } while (0)
; __global__ void __launch_bounds__(NTHR, 2) mega_fwd(Args a) {
;     extern __shared__ __attribute__((aligned(16))) unsigned char lds_raw[];
;     cg::grid_group grid = cg::this_grid();
;     Ctx C; C.lds = (LAS unsigned char*)lds_raw; C.G = gridDim.x; C.bid = blockIdx.x;
;     ...
;     FRESH();
	.amdhsa_kernel _Z8mega_fwd4Args
		.amdhsa_group_segment_fixed_size 0
		.amdhsa_private_segment_fixed_size 0
		.amdhsa_kernarg_size 464
		.amdhsa_user_sgpr_count 2
		.amdhsa_user_sgpr_dispatch_ptr 0
		.amdhsa_user_sgpr_queue_ptr 0
		.amdhsa_user_sgpr_kernarg_segment_ptr 1
		.amdhsa_user_sgpr_dispatch_id 0
		.amdhsa_user_sgpr_kernarg_preload_length 0
		.amdhsa_user_sgpr_kernarg_preload_offset 0
		.amdhsa_user_sgpr_private_segment_size 0
		.amdhsa_uses_dynamic_stack 0
		.amdhsa_enable_private_segment 0
		.amdhsa_system_sgpr_workgroup_id_x 1
		.amdhsa_system_sgpr_workgroup_id_y 0
		.amdhsa_system_sgpr_workgroup_id_z 0
		.amdhsa_system_sgpr_workgroup_info 0
		.amdhsa_system_vgpr_workitem_id 2
		.amdhsa_next_free_vgpr 233
		.amdhsa_next_free_sgpr 100
		.amdhsa_accum_offset 236
		.amdhsa_reserve_vcc 1
		.amdhsa_float_round_mode_32 0
		.amdhsa_float_round_mode_16_64 0
		.amdhsa_float_denorm_mode_32 3
		.amdhsa_float_denorm_mode_16_64 3
		.amdhsa_dx10_clamp 1
		.amdhsa_ieee_mode 1
		.amdhsa_fp16_overflow 0
		.amdhsa_tg_split 0
		.amdhsa_exception_fp_ieee_invalid_op 0
		.amdhsa_exception_fp_denorm_src 0
		.amdhsa_exception_fp_ieee_div_zero 0
		.amdhsa_exception_fp_ieee_overflow 0
		.amdhsa_exception_fp_ieee_underflow 0
		.amdhsa_exception_fp_ieee_inexact 0
		.amdhsa_exception_int_div_zero 0
	.end_amdhsa_kernel

; #define LAS __attribute__((address_space(3)))
; #define FRESH() do { int t_ = threadIdx.x; asm volatile("" : "+v"(t_)); C.tid = t_; C.lane = t_ & 63; C.wave = __builtin_amdgcn_readfirstlane(t_ >> 6); } while (0)
; __global__ void __launch_bounds__(NTHR, 2) mega_fwd(Args a) {
;     extern __shared__ __attribute__((aligned(16))) unsigned char lds_raw[];
;     cg::grid_group grid = cg::this_grid();
;     Ctx C; C.lds = (LAS unsigned char*)lds_raw; C.G = gridDim.x; C.bid = blockIdx.x;
;     ...
;     FRESH();
amdhsa.kernels:
  - .agpr_count:     0
    .args:
      - .offset:         0
        .size:           208
        .value_kind:     by_value
      - .offset:         208
        .size:           4
        .value_kind:     hidden_block_count_x
      - .offset:         212
        .size:           4
        .value_kind:     hidden_block_count_y
      - .offset:         216
        .size:           4
        .value_kind:     hidden_block_count_z
      - .offset:         220
        .size:           2
        .value_kind:     hidden_group_size_x
      - .offset:         222
        .size:           2
        .value_kind:     hidden_group_size_y
      - .offset:         224
        .size:           2
        .value_kind:     hidden_group_size_z
      - .offset:         226
        .size:           2
        .value_kind:     hidden_remainder_x
      - .offset:         228
        .size:           2
        .value_kind:     hidden_remainder_y
      - .offset:         230
        .size:           2
        .value_kind:     hidden_remainder_z
      - .offset:         248
        .size:           8
        .value_kind:     hidden_global_offset_x
      - .offset:         256
        .size:           8
        .value_kind:     hidden_global_offset_y
      - .offset:         264
        .size:           8
        .value_kind:     hidden_global_offset_z
      - .offset:         272
        .size:           2
        .value_kind:     hidden_grid_dims
      - .offset:         296
        .size:           8
        .value_kind:     hidden_multigrid_sync_arg
      - .offset:         328
        .size:           4
        .value_kind:     hidden_dynamic_lds_size
    .group_segment_fixed_size: 0
    .kernarg_segment_align: 8
    .kernarg_segment_size: 464
    .language:       OpenCL C
    .language_version:
      - 2
      - 0
    .max_flat_workgroup_size: 512
    .name:           _Z8mega_fwd4Args
    .private_segment_fixed_size: 0
    .sgpr_count:     106
    .sgpr_spill_count: 63
    .symbol:         _Z8mega_fwd4Args.kd
    .uniform_work_group_size: 1
    .uses_dynamic_stack: false
    .vgpr_count:     233
    .vgpr_spill_count: 0
    .wavefront_size: 64
